# K-loop LDS-DMA issue rebalanced to 4 per phase and switched to SGPR-base plus 32-bit VGPR offset addressing (drops 16 VALU 64-bit adds per iteration)
# baseline (speedup 1.0000x reference)
; #define PG8_STAGE(bufoff, gbase, voff) do { _Pragma("unroll") for (int _i = 0; _i < 2; ++_i) \
;         __builtin_amdgcn_global_load_lds((const unsigned*)((const char*)(gbase) + (voff)[_i]), (LAS unsigned*)(lds + (bufoff) + ldsw + _i * 8192), 16, 0, 0); } while (0)
; #define PG8_LDA(dst, b, h) do { _Pragma("unroll") for (int m = 0; m < 4; ++m) _Pragma("unroll") for (int k = 0; k < 2; ++k) dst[m][k] = *(const LAS bf16x8*)(lds + PG8_SA(b, h) + aoff + m * 2048 + k * 1024); } while (0)
; #define PG8_LDB(dst, b, h) do { _Pragma("unroll") for (int n = 0; n < 2; ++n) _Pragma("unroll") for (int k = 0; k < 2; ++k) dst[n][k] = *(const LAS bf16x8*)(lds + PG8_SB(b, h) + boff + n * 2048 + k * 1024); } while (0)
; #define PG8_MMA(ai, bj, At, Bt) do { __builtin_amdgcn_s_setprio(1); _Pragma("unroll") for (int m = 0; m < 4; ++m) _Pragma("unroll") for (int n = 0; n < 2; ++n) _Pragma("unroll") for (int k = 0; k < 2; ++k) \
;         acc[ai][bj][m][n] = __builtin_amdgcn_mfma_f32_16x16x32_bf16(Bt[n][k], At[m][k], acc[ai][bj][m][n], 0, 0, 0); __builtin_amdgcn_s_setprio(0); } while (0)
; #define PG8_WAIT_V(n) asm volatile("s_waitcnt vmcnt(" #n ")" ::: "memory")
; template <class Epi, bool ALIGN_EPI = true>
; __device__ __forceinline__ void gemm_phase(LAS unsigned char* lds, const Gemm g, const Sched& S, const Epi& E) {
;     ...
;         for (int t = t_lo; t < t_hi; t += 2) {
;             const bool last = (t == nt - 2);
;             const char* a1 = cA + (size_t)(t + 1) * kstep;
;             const char* a2 = last ? nA : cA + (size_t)(t + 2) * kstep; const char* b2 = last ? nB : cB + (size_t)(t + 2) * kstep;
;             const char* a3 = a2 + kstep; const char* b3 = b2 + kstep;
;             const int rflag = __builtin_amdgcn_readfirstlane(t | (int)(ui == 0));
;             PG8_LDB(B0, 0, 0); PG8_LDB(B1, 0, 1); PG8_SCHED; PG8_LDA(At, 0, 0); PG8_STAGE(PG8_SA(1, 1), a1 + hstepA, voffA);
;             if constexpr (Epi::NSTORES > 0) PG8_WAIT_RELAX(rflag, 8 + Epi::NSTORES); else PG8_WAIT_V(8);
;             PG8_WAIT_L(0); PG8_BAR; PG8_MMA(0, 0, At, B0); PG8_MMA(0, 1, At, B1); PG8_BAR; PG8_SCHED;
;             PG8_LDA(At, 0, 1); PG8_STAGE(PG8_SB(0, 0), b2, voffB); PG8_STAGE(PG8_SB(0, 1), b2 + hstepB, voffB); PG8_STAGE(PG8_SA(0, 0), a2, voffA);
;             if constexpr (Epi::NSTORES > 0) PG8_WAIT_RELAX(rflag, 8 + Epi::NSTORES); else PG8_WAIT_V(8);
.LBB0_314:
	ds_read_b128 v[154:157], v149
	ds_read_b128 v[158:161], v149 offset:1024
	ds_read_b128 v[162:165], v149 offset:2048
	ds_read_b128 v[166:169], v149 offset:3072
	ds_read_b128 v[170:173], v151
	ds_read_b128 v[174:177], v151 offset:1024
	ds_read_b128 v[178:181], v151 offset:2048
	ds_read_b128 v[182:185], v151 offset:3072
	s_add_i32 s49, s44, 2
	s_add_u32 s42, s40, 0xfff80080
	s_addc_u32 s43, s41, -1
	s_cmp_eq_u32 s70, s44
	v_add_u32_e32 v146, s44, v138
	s_cselect_b32 s44, s23, s42
	s_cselect_b32 s45, s21, s43
	s_cselect_b32 s43, s37, s48
	s_cselect_b32 s42, s46, s47
	s_add_i32 m0, s59, 0xc000
	ds_read_b128 v[186:189], v153
	ds_read_b128 v[190:193], v153 offset:1024
	ds_read_b128 v[194:197], v153 offset:2048
	ds_read_b128 v[198:201], v153 offset:3072
	ds_read_b128 v[202:205], v153 offset:4096
	ds_read_b128 v[206:209], v153 offset:5120
	ds_read_b128 v[210:213], v153 offset:6144
	ds_read_b128 v[214:217], v153 offset:7168
	s_add_u32 s100, s40, 0xfff80000
	s_addc_u32 s101, s41, -1
	s_mov_b32 m0, s68
	s_nop 0
	global_load_lds_dwordx4 v140, s[100:101]
	s_mov_b32 m0, s69
	s_nop 0
	global_load_lds_dwordx4 v142, s[100:101]
	s_add_i32 m0, s59, 0xc000
	s_nop 0
	global_load_lds_dwordx4 v140, s[40:41]
	s_add_i32 m0, s59, 0xe000
	v_readfirstlane_b32 s52, v146
	global_load_lds_dwordx4 v142, s[40:41]
	s_cmp_eq_u32 s52, 0
	s_cbranch_scc1 .Lrw0
	s_waitcnt vmcnt(8)
.Lrw0:
	s_waitcnt vmcnt(24)
	s_waitcnt lgkmcnt(0)
	s_barrier
	s_setprio 1
	s_waitcnt lgkmcnt(0)
	v_mfma_f32_16x16x32_bf16 v[122:125], v[154:157], v[186:189], v[122:125]
	v_mfma_f32_16x16x32_bf16 v[126:129], v[162:165], v[186:189], v[126:129]
	v_mfma_f32_16x16x32_bf16 v[110:113], v[154:157], v[194:197], v[110:113]
	v_mfma_f32_16x16x32_bf16 v[106:109], v[162:165], v[194:197], v[106:109]
	v_mfma_f32_16x16x32_bf16 v[94:97], v[154:157], v[202:205], v[94:97]
	v_mfma_f32_16x16x32_bf16 v[90:93], v[162:165], v[202:205], v[90:93]
	v_mfma_f32_16x16x32_bf16 v[78:81], v[154:157], v[210:213], v[78:81]
	v_mfma_f32_16x16x32_bf16 v[74:77], v[162:165], v[210:213], v[74:77]
	v_mfma_f32_16x16x32_bf16 v[122:125], v[158:161], v[190:193], v[122:125]
	v_mfma_f32_16x16x32_bf16 v[126:129], v[166:169], v[190:193], v[126:129]
	v_mfma_f32_16x16x32_bf16 v[110:113], v[158:161], v[198:201], v[110:113]
	v_mfma_f32_16x16x32_bf16 v[106:109], v[166:169], v[198:201], v[106:109]
	v_mfma_f32_16x16x32_bf16 v[94:97], v[158:161], v[206:209], v[94:97]
	v_mfma_f32_16x16x32_bf16 v[90:93], v[166:169], v[206:209], v[90:93]
	v_mfma_f32_16x16x32_bf16 v[78:81], v[158:161], v[214:217], v[78:81]
	v_mfma_f32_16x16x32_bf16 v[74:77], v[166:169], v[214:217], v[74:77]
	s_setprio 0
	s_setprio 1
	v_mfma_f32_16x16x32_bf16 v[118:121], v[170:173], v[186:189], v[118:121]
	v_mfma_f32_16x16x32_bf16 v[114:117], v[178:181], v[186:189], v[114:117]
	v_mfma_f32_16x16x32_bf16 v[102:105], v[170:173], v[194:197], v[102:105]
	v_mfma_f32_16x16x32_bf16 v[98:101], v[178:181], v[194:197], v[98:101]
	v_mfma_f32_16x16x32_bf16 v[86:89], v[170:173], v[202:205], v[86:89]
	v_mfma_f32_16x16x32_bf16 v[82:85], v[178:181], v[202:205], v[82:85]
	v_mfma_f32_16x16x32_bf16 v[70:73], v[170:173], v[210:213], v[70:73]
	v_mfma_f32_16x16x32_bf16 v[66:69], v[178:181], v[210:213], v[66:69]
	v_mfma_f32_16x16x32_bf16 v[118:121], v[174:177], v[190:193], v[118:121]
	v_mfma_f32_16x16x32_bf16 v[114:117], v[182:185], v[190:193], v[114:117]
	v_mfma_f32_16x16x32_bf16 v[102:105], v[174:177], v[198:201], v[102:105]
	v_mfma_f32_16x16x32_bf16 v[98:101], v[182:185], v[198:201], v[98:101]
	v_mfma_f32_16x16x32_bf16 v[86:89], v[174:177], v[206:209], v[86:89]
	v_mfma_f32_16x16x32_bf16 v[82:85], v[182:185], v[206:209], v[82:85]
	v_mfma_f32_16x16x32_bf16 v[70:73], v[174:177], v[214:217], v[70:73]
	v_mfma_f32_16x16x32_bf16 v[66:69], v[182:185], v[214:217], v[66:69]
	s_setprio 0
	s_barrier
	s_add_i32 s50, s72, s58
	s_mov_b32 m0, s50
	ds_read_b128 v[186:189], v153 offset:16384
	ds_read_b128 v[190:193], v153 offset:17408
	ds_read_b128 v[194:197], v153 offset:18432
	ds_read_b128 v[198:201], v153 offset:19456
	ds_read_b128 v[202:205], v153 offset:20480
	ds_read_b128 v[206:209], v153 offset:21504
	ds_read_b128 v[210:213], v153 offset:22528
	ds_read_b128 v[214:217], v153 offset:23552
	global_load_lds_dwordx4 v132, s[42:43]
	s_add_i32 m0, s50, 0x2000
	s_add_u32 s50, s42, 0x80000
	s_addc_u32 s51, s43, 0
	s_add_i32 s53, s73, s58
	global_load_lds_dwordx4 v136, s[42:43]
	s_mov_b32 m0, s53
	s_nop 0
	global_load_lds_dwordx4 v132, s[50:51]
	s_add_i32 m0, s53, 0x2000
	s_nop 0
	global_load_lds_dwordx4 v136, s[50:51]
	s_cmp_eq_u32 s52, 0
	s_cbranch_scc1 .Lrw1
	s_waitcnt vmcnt(6)
; #define PG8_STAGE(bufoff, gbase, voff) do { _Pragma("unroll") for (int _i = 0; _i < 2; ++_i) \
;         __builtin_amdgcn_global_load_lds((const unsigned*)((const char*)(gbase) + (voff)[_i]), (LAS unsigned*)(lds + (bufoff) + ldsw + _i * 8192), 16, 0, 0); } while (0)
; #define PG8_LDA(dst, b, h) do { _Pragma("unroll") for (int m = 0; m < 4; ++m) _Pragma("unroll") for (int k = 0; k < 2; ++k) dst[m][k] = *(const LAS bf16x8*)(lds + PG8_SA(b, h) + aoff + m * 2048 + k * 1024); } while (0)
; #define PG8_LDB(dst, b, h) do { _Pragma("unroll") for (int n = 0; n < 2; ++n) _Pragma("unroll") for (int k = 0; k < 2; ++k) dst[n][k] = *(const LAS bf16x8*)(lds + PG8_SB(b, h) + boff + n * 2048 + k * 1024); } while (0)
; #define PG8_MMA(ai, bj, At, Bt) do { __builtin_amdgcn_s_setprio(1); _Pragma("unroll") for (int m = 0; m < 4; ++m) _Pragma("unroll") for (int n = 0; n < 2; ++n) _Pragma("unroll") for (int k = 0; k < 2; ++k) \
;         acc[ai][bj][m][n] = __builtin_amdgcn_mfma_f32_16x16x32_bf16(Bt[n][k], At[m][k], acc[ai][bj][m][n], 0, 0, 0); __builtin_amdgcn_s_setprio(0); } while (0)
; #define PG8_WAIT_V(n) asm volatile("s_waitcnt vmcnt(" #n ")" ::: "memory")
; #define PG8_WAIT_L(n) asm volatile("s_waitcnt lgkmcnt(" #n ")" ::: "memory")
; #define PG8_BAR __builtin_amdgcn_s_barrier()
; #define PG8_SCHED __builtin_amdgcn_sched_barrier(0)
; template <class Epi, bool ALIGN_EPI = true>
; __device__ __forceinline__ void gemm_phase(LAS unsigned char* lds, const Gemm g, const Sched& S, const Epi& E) {
;     ...
;             PG8_WAIT_L(0); PG8_BAR; PG8_MMA(1, 0, At, B0); PG8_MMA(1, 1, At, B1); PG8_BAR; PG8_SCHED;
;             PG8_LDB(B0, 1, 0); PG8_LDB(B1, 1, 1); PG8_SCHED; PG8_LDA(At, 1, 0); PG8_STAGE(PG8_SA(0, 1), a2 + hstepA, voffA);
;             PG8_WAIT_V(8); PG8_WAIT_L(0); PG8_BAR; PG8_MMA(0, 0, At, B0); PG8_MMA(0, 1, At, B1); PG8_BAR; PG8_SCHED;
.Lrw1:
	s_waitcnt vmcnt(6)
	s_waitcnt lgkmcnt(0)
	s_barrier
	s_setprio 1
	s_waitcnt lgkmcnt(0)
	v_mfma_f32_16x16x32_bf16 v[62:65], v[154:157], v[186:189], v[62:65]
	v_mfma_f32_16x16x32_bf16 v[58:61], v[162:165], v[186:189], v[58:61]
	v_mfma_f32_16x16x32_bf16 v[46:49], v[154:157], v[194:197], v[46:49]
	v_mfma_f32_16x16x32_bf16 v[42:45], v[162:165], v[194:197], v[42:45]
	v_mfma_f32_16x16x32_bf16 v[30:33], v[154:157], v[202:205], v[30:33]
	v_mfma_f32_16x16x32_bf16 v[26:29], v[162:165], v[202:205], v[26:29]
	v_mfma_f32_16x16x32_bf16 v[14:17], v[154:157], v[210:213], v[14:17]
	v_mfma_f32_16x16x32_bf16 v[10:13], v[162:165], v[210:213], v[10:13]
	v_mfma_f32_16x16x32_bf16 v[62:65], v[158:161], v[190:193], v[62:65]
	v_mfma_f32_16x16x32_bf16 v[58:61], v[166:169], v[190:193], v[58:61]
	v_mfma_f32_16x16x32_bf16 v[46:49], v[158:161], v[198:201], v[46:49]
	v_mfma_f32_16x16x32_bf16 v[42:45], v[166:169], v[198:201], v[42:45]
	v_mfma_f32_16x16x32_bf16 v[30:33], v[158:161], v[206:209], v[30:33]
	v_mfma_f32_16x16x32_bf16 v[26:29], v[166:169], v[206:209], v[26:29]
	v_mfma_f32_16x16x32_bf16 v[14:17], v[158:161], v[214:217], v[14:17]
	v_mfma_f32_16x16x32_bf16 v[10:13], v[166:169], v[214:217], v[10:13]
	s_setprio 0
	s_setprio 1
	v_mfma_f32_16x16x32_bf16 v[54:57], v[170:173], v[186:189], v[54:57]
	v_mfma_f32_16x16x32_bf16 v[50:53], v[178:181], v[186:189], v[50:53]
	v_mfma_f32_16x16x32_bf16 v[38:41], v[170:173], v[194:197], v[38:41]
	v_mfma_f32_16x16x32_bf16 v[34:37], v[178:181], v[194:197], v[34:37]
	v_mfma_f32_16x16x32_bf16 v[22:25], v[170:173], v[202:205], v[22:25]
	v_mfma_f32_16x16x32_bf16 v[18:21], v[178:181], v[202:205], v[18:21]
	v_mfma_f32_16x16x32_bf16 v[6:9], v[170:173], v[210:213], v[6:9]
	v_mfma_f32_16x16x32_bf16 v[2:5], v[178:181], v[210:213], v[2:5]
	v_mfma_f32_16x16x32_bf16 v[54:57], v[174:177], v[190:193], v[54:57]
	v_mfma_f32_16x16x32_bf16 v[50:53], v[182:185], v[190:193], v[50:53]
	v_mfma_f32_16x16x32_bf16 v[38:41], v[174:177], v[198:201], v[38:41]
	v_mfma_f32_16x16x32_bf16 v[34:37], v[182:185], v[198:201], v[34:37]
	v_mfma_f32_16x16x32_bf16 v[22:25], v[174:177], v[206:209], v[22:25]
	v_mfma_f32_16x16x32_bf16 v[18:21], v[182:185], v[206:209], v[18:21]
	v_mfma_f32_16x16x32_bf16 v[6:9], v[174:177], v[214:217], v[6:9]
	v_mfma_f32_16x16x32_bf16 v[2:5], v[182:185], v[214:217], v[2:5]
	s_setprio 0
	s_barrier
	s_add_i32 s50, 0, 0x18000
	v_add_u32_e32 v146, s50, v147
	s_add_i32 s51, 0, 0x1c000
	ds_read_b128 v[154:157], v146
	ds_read_b128 v[158:161], v146 offset:1024
	ds_read_b128 v[162:165], v146 offset:2048
	ds_read_b128 v[166:169], v146 offset:3072
	v_add_u32_e32 v146, s51, v147
	ds_read_b128 v[170:173], v146
	ds_read_b128 v[174:177], v146 offset:1024
	ds_read_b128 v[178:181], v146 offset:2048
	ds_read_b128 v[182:185], v146 offset:3072
	s_add_u32 s44, s44, 0x80000
	s_addc_u32 s45, s45, 0
	s_mov_b32 m0, s61
	ds_read_b128 v[186:189], v153 offset:32768
	ds_read_b128 v[190:193], v153 offset:33792
	ds_read_b128 v[194:197], v153 offset:34816
	ds_read_b128 v[198:201], v153 offset:35840
	ds_read_b128 v[202:205], v153 offset:36864
	ds_read_b128 v[206:209], v153 offset:37888
	ds_read_b128 v[210:213], v153 offset:38912
	ds_read_b128 v[214:217], v153 offset:39936
	s_add_u32 s100, s44, 0xfff80000
	s_addc_u32 s101, s45, -1
	s_mov_b32 m0, s59
	s_nop 0
	global_load_lds_dwordx4 v130, s[100:101]
	s_mov_b32 m0, s60
	s_nop 0
	global_load_lds_dwordx4 v134, s[100:101]
	s_mov_b32 m0, s61
	s_nop 0
	global_load_lds_dwordx4 v130, s[44:45]
	s_mov_b32 m0, s62
	s_nop 0
	global_load_lds_dwordx4 v134, s[44:45]
	s_waitcnt vmcnt(8)
	s_waitcnt lgkmcnt(0)
	s_barrier
; #define PG8_STAGE(bufoff, gbase, voff) do { _Pragma("unroll") for (int _i = 0; _i < 2; ++_i) \
;         __builtin_amdgcn_global_load_lds((const unsigned*)((const char*)(gbase) + (voff)[_i]), (LAS unsigned*)(lds + (bufoff) + ldsw + _i * 8192), 16, 0, 0); } while (0)
; #define PG8_LDA(dst, b, h) do { _Pragma("unroll") for (int m = 0; m < 4; ++m) _Pragma("unroll") for (int k = 0; k < 2; ++k) dst[m][k] = *(const LAS bf16x8*)(lds + PG8_SA(b, h) + aoff + m * 2048 + k * 1024); } while (0)
; #define PG8_MMA(ai, bj, At, Bt) do { __builtin_amdgcn_s_setprio(1); _Pragma("unroll") for (int m = 0; m < 4; ++m) _Pragma("unroll") for (int n = 0; n < 2; ++n) _Pragma("unroll") for (int k = 0; k < 2; ++k) \
;         acc[ai][bj][m][n] = __builtin_amdgcn_mfma_f32_16x16x32_bf16(Bt[n][k], At[m][k], acc[ai][bj][m][n], 0, 0, 0); __builtin_amdgcn_s_setprio(0); } while (0)
; #define PG8_WAIT_V(n) asm volatile("s_waitcnt vmcnt(" #n ")" ::: "memory")
; #define PG8_WAIT_L(n) asm volatile("s_waitcnt lgkmcnt(" #n ")" ::: "memory")
; #define PG8_BAR __builtin_amdgcn_s_barrier()
; #define PG8_SCHED __builtin_amdgcn_sched_barrier(0)
; template <class Epi, bool ALIGN_EPI = true>
; __device__ __forceinline__ void gemm_phase(LAS unsigned char* lds, const Gemm g, const Sched& S, const Epi& E) {
;     ...
;             PG8_WAIT_V(8); PG8_WAIT_L(0); PG8_BAR; PG8_MMA(0, 0, At, B0); PG8_MMA(0, 1, At, B1); PG8_BAR; PG8_SCHED;
;             PG8_LDA(At, 1, 1); PG8_STAGE(PG8_SB(1, 0), b3, voffB); PG8_STAGE(PG8_SB(1, 1), b3 + hstepB, voffB); PG8_STAGE(PG8_SA(1, 0), a3, voffA);
;             PG8_WAIT_V(8); PG8_WAIT_L(0); PG8_BAR; PG8_MMA(1, 0, At, B0); PG8_MMA(1, 1, At, B1); PG8_BAR; PG8_SCHED;
;         }
	s_setprio 1
	s_waitcnt lgkmcnt(0)
	v_mfma_f32_16x16x32_bf16 v[122:125], v[154:157], v[186:189], v[122:125]
	v_mfma_f32_16x16x32_bf16 v[126:129], v[162:165], v[186:189], v[126:129]
	v_mfma_f32_16x16x32_bf16 v[110:113], v[154:157], v[194:197], v[110:113]
	v_mfma_f32_16x16x32_bf16 v[106:109], v[162:165], v[194:197], v[106:109]
	v_mfma_f32_16x16x32_bf16 v[94:97], v[154:157], v[202:205], v[94:97]
	v_mfma_f32_16x16x32_bf16 v[90:93], v[162:165], v[202:205], v[90:93]
	v_mfma_f32_16x16x32_bf16 v[78:81], v[154:157], v[210:213], v[78:81]
	v_mfma_f32_16x16x32_bf16 v[74:77], v[162:165], v[210:213], v[74:77]
	v_mfma_f32_16x16x32_bf16 v[122:125], v[158:161], v[190:193], v[122:125]
	v_mfma_f32_16x16x32_bf16 v[126:129], v[166:169], v[190:193], v[126:129]
	v_mfma_f32_16x16x32_bf16 v[110:113], v[158:161], v[198:201], v[110:113]
	v_mfma_f32_16x16x32_bf16 v[106:109], v[166:169], v[198:201], v[106:109]
	v_mfma_f32_16x16x32_bf16 v[94:97], v[158:161], v[206:209], v[94:97]
	v_mfma_f32_16x16x32_bf16 v[90:93], v[166:169], v[206:209], v[90:93]
	v_mfma_f32_16x16x32_bf16 v[78:81], v[158:161], v[214:217], v[78:81]
	v_mfma_f32_16x16x32_bf16 v[74:77], v[166:169], v[214:217], v[74:77]
	s_setprio 0
	s_setprio 1
	v_mfma_f32_16x16x32_bf16 v[118:121], v[170:173], v[186:189], v[118:121]
	v_mfma_f32_16x16x32_bf16 v[114:117], v[178:181], v[186:189], v[114:117]
	v_mfma_f32_16x16x32_bf16 v[102:105], v[170:173], v[194:197], v[102:105]
	v_mfma_f32_16x16x32_bf16 v[98:101], v[178:181], v[194:197], v[98:101]
	v_mfma_f32_16x16x32_bf16 v[86:89], v[170:173], v[202:205], v[86:89]
	v_mfma_f32_16x16x32_bf16 v[82:85], v[178:181], v[202:205], v[82:85]
	v_mfma_f32_16x16x32_bf16 v[70:73], v[170:173], v[210:213], v[70:73]
	v_mfma_f32_16x16x32_bf16 v[66:69], v[178:181], v[210:213], v[66:69]
	v_mfma_f32_16x16x32_bf16 v[118:121], v[174:177], v[190:193], v[118:121]
	v_mfma_f32_16x16x32_bf16 v[114:117], v[182:185], v[190:193], v[114:117]
	v_mfma_f32_16x16x32_bf16 v[102:105], v[174:177], v[198:201], v[102:105]
	v_mfma_f32_16x16x32_bf16 v[98:101], v[182:185], v[198:201], v[98:101]
	v_mfma_f32_16x16x32_bf16 v[86:89], v[174:177], v[206:209], v[86:89]
	v_mfma_f32_16x16x32_bf16 v[82:85], v[182:185], v[206:209], v[82:85]
	v_mfma_f32_16x16x32_bf16 v[70:73], v[174:177], v[214:217], v[70:73]
	v_mfma_f32_16x16x32_bf16 v[66:69], v[182:185], v[214:217], v[66:69]
	s_setprio 0
	s_barrier
	s_add_u32 s100, s42, 0x80
	s_addc_u32 s101, s43, 0
	s_add_i32 s44, s50, s58
	s_mov_b32 m0, s44
	ds_read_b128 v[186:189], v153 offset:49152
	ds_read_b128 v[190:193], v153 offset:50176
	ds_read_b128 v[194:197], v153 offset:51200
	ds_read_b128 v[198:201], v153 offset:52224
	ds_read_b128 v[202:205], v153 offset:53248
	ds_read_b128 v[206:209], v153 offset:54272
	ds_read_b128 v[210:213], v153 offset:55296
	ds_read_b128 v[214:217], v153 offset:56320
	global_load_lds_dwordx4 v132, s[100:101]
	s_add_i32 m0, s44, 0x2000
	s_add_u32 s42, s42, 0x80080
	s_addc_u32 s43, s43, 0
	s_add_i32 s44, s51, s58
	global_load_lds_dwordx4 v136, s[100:101]
	s_mov_b32 m0, s44
	s_nop 0
	global_load_lds_dwordx4 v132, s[42:43]
	s_add_i32 m0, s44, 0x2000
	s_nop 0
	global_load_lds_dwordx4 v136, s[42:43]
	s_waitcnt vmcnt(6)
	s_waitcnt lgkmcnt(0)
	s_barrier
	s_setprio 1
	s_waitcnt lgkmcnt(0)
	v_mfma_f32_16x16x32_bf16 v[62:65], v[154:157], v[186:189], v[62:65]
	v_mfma_f32_16x16x32_bf16 v[58:61], v[162:165], v[186:189], v[58:61]
	v_mfma_f32_16x16x32_bf16 v[46:49], v[154:157], v[194:197], v[46:49]
	v_mfma_f32_16x16x32_bf16 v[42:45], v[162:165], v[194:197], v[42:45]
	v_mfma_f32_16x16x32_bf16 v[30:33], v[154:157], v[202:205], v[30:33]
	v_mfma_f32_16x16x32_bf16 v[26:29], v[162:165], v[202:205], v[26:29]
	v_mfma_f32_16x16x32_bf16 v[14:17], v[154:157], v[210:213], v[14:17]
	v_mfma_f32_16x16x32_bf16 v[10:13], v[162:165], v[210:213], v[10:13]
	v_mfma_f32_16x16x32_bf16 v[62:65], v[158:161], v[190:193], v[62:65]
	v_mfma_f32_16x16x32_bf16 v[58:61], v[166:169], v[190:193], v[58:61]
	v_mfma_f32_16x16x32_bf16 v[46:49], v[158:161], v[198:201], v[46:49]
	v_mfma_f32_16x16x32_bf16 v[42:45], v[166:169], v[198:201], v[42:45]
	v_mfma_f32_16x16x32_bf16 v[30:33], v[158:161], v[206:209], v[30:33]
	v_mfma_f32_16x16x32_bf16 v[26:29], v[166:169], v[206:209], v[26:29]
	v_mfma_f32_16x16x32_bf16 v[14:17], v[158:161], v[214:217], v[14:17]
	v_mfma_f32_16x16x32_bf16 v[10:13], v[166:169], v[214:217], v[10:13]
	s_setprio 0
	s_setprio 1
	v_mfma_f32_16x16x32_bf16 v[54:57], v[170:173], v[186:189], v[54:57]
	v_mfma_f32_16x16x32_bf16 v[50:53], v[178:181], v[186:189], v[50:53]
	v_mfma_f32_16x16x32_bf16 v[38:41], v[170:173], v[194:197], v[38:41]
	v_mfma_f32_16x16x32_bf16 v[34:37], v[178:181], v[194:197], v[34:37]
	v_mfma_f32_16x16x32_bf16 v[22:25], v[170:173], v[202:205], v[22:25]
	v_mfma_f32_16x16x32_bf16 v[18:21], v[178:181], v[202:205], v[18:21]
	v_mfma_f32_16x16x32_bf16 v[6:9], v[170:173], v[210:213], v[6:9]
	v_mfma_f32_16x16x32_bf16 v[2:5], v[178:181], v[210:213], v[2:5]
	v_mfma_f32_16x16x32_bf16 v[54:57], v[174:177], v[190:193], v[54:57]
	v_mfma_f32_16x16x32_bf16 v[50:53], v[182:185], v[190:193], v[50:53]
	v_mfma_f32_16x16x32_bf16 v[38:41], v[174:177], v[198:201], v[38:41]
	v_mfma_f32_16x16x32_bf16 v[34:37], v[182:185], v[198:201], v[34:37]
	v_mfma_f32_16x16x32_bf16 v[22:25], v[174:177], v[206:209], v[22:25]
	v_mfma_f32_16x16x32_bf16 v[18:21], v[182:185], v[206:209], v[18:21]
	v_mfma_f32_16x16x32_bf16 v[6:9], v[174:177], v[214:217], v[6:9]
	v_mfma_f32_16x16x32_bf16 v[2:5], v[182:185], v[214:217], v[2:5]
	s_setprio 0
	s_barrier
	s_add_u32 s40, s40, 0x100
	s_addc_u32 s41, s41, 0
	s_add_u32 s47, s47, 0x100
	s_addc_u32 s48, s48, 0
	s_cmp_ge_i32 s49, s65
	s_mov_b32 s44, s49
	s_cbranch_scc0 .LBB0_314

; #define PG8_STAGE(bufoff, gbase, voff) do { _Pragma("unroll") for (int _i = 0; _i < 2; ++_i) \
;         __builtin_amdgcn_global_load_lds((const unsigned*)((const char*)(gbase) + (voff)[_i]), (LAS unsigned*)(lds + (bufoff) + ldsw + _i * 8192), 16, 0, 0); } while (0)
; #define PG8_LDA(dst, b, h) do { _Pragma("unroll") for (int m = 0; m < 4; ++m) _Pragma("unroll") for (int k = 0; k < 2; ++k) dst[m][k] = *(const LAS bf16x8*)(lds + PG8_SA(b, h) + aoff + m * 2048 + k * 1024); } while (0)
; #define PG8_LDB(dst, b, h) do { _Pragma("unroll") for (int n = 0; n < 2; ++n) _Pragma("unroll") for (int k = 0; k < 2; ++k) dst[n][k] = *(const LAS bf16x8*)(lds + PG8_SB(b, h) + boff + n * 2048 + k * 1024); } while (0)
; #define PG8_MMA(ai, bj, At, Bt) do { __builtin_amdgcn_s_setprio(1); _Pragma("unroll") for (int m = 0; m < 4; ++m) _Pragma("unroll") for (int n = 0; n < 2; ++n) _Pragma("unroll") for (int k = 0; k < 2; ++k) \
;         acc[ai][bj][m][n] = __builtin_amdgcn_mfma_f32_16x16x32_bf16(Bt[n][k], At[m][k], acc[ai][bj][m][n], 0, 0, 0); __builtin_amdgcn_s_setprio(0); } while (0)
; #define PG8_WAIT_V(n) asm volatile("s_waitcnt vmcnt(" #n ")" ::: "memory")
; template <class Epi, bool ALIGN_EPI = true>
; __device__ __forceinline__ void gemm_phase(LAS unsigned char* lds, const Gemm g, const Sched& S, const Epi& E) {
;     ...
;         for (int t = t_lo; t < t_hi; t += 2) {
;             const bool last = (t == nt - 2);
;             const char* a1 = cA + (size_t)(t + 1) * kstep;
;             const char* a2 = last ? nA : cA + (size_t)(t + 2) * kstep; const char* b2 = last ? nB : cB + (size_t)(t + 2) * kstep;
;             const char* a3 = a2 + kstep; const char* b3 = b2 + kstep;
;             const int rflag = __builtin_amdgcn_readfirstlane(t | (int)(ui == 0));
;             PG8_LDB(B0, 0, 0); PG8_LDB(B1, 0, 1); PG8_SCHED; PG8_LDA(At, 0, 0); PG8_STAGE(PG8_SA(1, 1), a1 + hstepA, voffA);
;             if constexpr (Epi::NSTORES > 0) PG8_WAIT_RELAX(rflag, 8 + Epi::NSTORES); else PG8_WAIT_V(8);
;             PG8_WAIT_L(0); PG8_BAR; PG8_MMA(0, 0, At, B0); PG8_MMA(0, 1, At, B1); PG8_BAR; PG8_SCHED;
;             PG8_LDA(At, 0, 1); PG8_STAGE(PG8_SB(0, 0), b2, voffB); PG8_STAGE(PG8_SB(0, 1), b2 + hstepB, voffB); PG8_STAGE(PG8_SA(0, 0), a2, voffA);
;             if constexpr (Epi::NSTORES > 0) PG8_WAIT_RELAX(rflag, 8 + Epi::NSTORES); else PG8_WAIT_V(8);
.LBB0_388:
	ds_read_b128 v[150:153], v145
	ds_read_b128 v[154:157], v145 offset:1024
	ds_read_b128 v[158:161], v145 offset:2048
	ds_read_b128 v[162:165], v145 offset:3072
	ds_read_b128 v[166:169], v146
	ds_read_b128 v[170:173], v146 offset:1024
	ds_read_b128 v[174:177], v146 offset:2048
	ds_read_b128 v[178:181], v146 offset:3072
	s_add_i32 s72, s40, 2
	s_add_u32 s36, s34, 0xfff80080
	s_addc_u32 s37, s35, -1
	s_cmp_eq_u32 s59, s40
	v_add_u32_e32 v149, s40, v148
	s_cselect_b32 s40, s67, s36
	s_cselect_b32 s41, s21, s37
	s_cselect_b32 s37, s68, s71
	s_cselect_b32 s36, s69, s70
	s_add_i32 m0, s47, 0xc000
	ds_read_b128 v[182:185], v147
	ds_read_b128 v[186:189], v147 offset:1024
	ds_read_b128 v[190:193], v147 offset:2048
	ds_read_b128 v[194:197], v147 offset:3072
	ds_read_b128 v[198:201], v147 offset:4096
	ds_read_b128 v[202:205], v147 offset:5120
	ds_read_b128 v[206:209], v147 offset:6144
	ds_read_b128 v[210:213], v147 offset:7168
	s_add_u32 s100, s34, 0xfff80000
	s_addc_u32 s101, s35, -1
	s_mov_b32 m0, s57
	s_nop 0
	global_load_lds_dwordx4 v138, s[100:101]
	s_mov_b32 m0, s58
	s_nop 0
	global_load_lds_dwordx4 v140, s[100:101]
	s_add_i32 m0, s47, 0xc000
	s_nop 0
	global_load_lds_dwordx4 v138, s[34:35]
	s_add_i32 m0, s47, 0xe000
	v_readfirstlane_b32 s73, v149
	global_load_lds_dwordx4 v140, s[34:35]
	s_cmp_eq_u32 s73, 0
	s_cbranch_scc1 .Lrw2
	s_waitcnt vmcnt(8)
.Lrw2:
	s_waitcnt vmcnt(24)
	s_waitcnt lgkmcnt(0)
	s_barrier
	s_setprio 1
	s_waitcnt lgkmcnt(0)
	v_mfma_f32_16x16x32_bf16 v[122:125], v[150:153], v[182:185], v[122:125]
	v_mfma_f32_16x16x32_bf16 v[126:129], v[158:161], v[182:185], v[126:129]
	v_mfma_f32_16x16x32_bf16 v[110:113], v[150:153], v[190:193], v[110:113]
	v_mfma_f32_16x16x32_bf16 v[106:109], v[158:161], v[190:193], v[106:109]
	v_mfma_f32_16x16x32_bf16 v[94:97], v[150:153], v[198:201], v[94:97]
	v_mfma_f32_16x16x32_bf16 v[90:93], v[158:161], v[198:201], v[90:93]
	v_mfma_f32_16x16x32_bf16 v[78:81], v[150:153], v[206:209], v[78:81]
	v_mfma_f32_16x16x32_bf16 v[74:77], v[158:161], v[206:209], v[74:77]
	v_mfma_f32_16x16x32_bf16 v[122:125], v[154:157], v[186:189], v[122:125]
	v_mfma_f32_16x16x32_bf16 v[126:129], v[162:165], v[186:189], v[126:129]
	v_mfma_f32_16x16x32_bf16 v[110:113], v[154:157], v[194:197], v[110:113]
	v_mfma_f32_16x16x32_bf16 v[106:109], v[162:165], v[194:197], v[106:109]
	v_mfma_f32_16x16x32_bf16 v[94:97], v[154:157], v[202:205], v[94:97]
	v_mfma_f32_16x16x32_bf16 v[90:93], v[162:165], v[202:205], v[90:93]
	v_mfma_f32_16x16x32_bf16 v[78:81], v[154:157], v[210:213], v[78:81]
	v_mfma_f32_16x16x32_bf16 v[74:77], v[162:165], v[210:213], v[74:77]
	s_setprio 0
	s_setprio 1
	v_mfma_f32_16x16x32_bf16 v[118:121], v[166:169], v[182:185], v[118:121]
	v_mfma_f32_16x16x32_bf16 v[114:117], v[174:177], v[182:185], v[114:117]
	v_mfma_f32_16x16x32_bf16 v[102:105], v[166:169], v[190:193], v[102:105]
	v_mfma_f32_16x16x32_bf16 v[98:101], v[174:177], v[190:193], v[98:101]
	v_mfma_f32_16x16x32_bf16 v[86:89], v[166:169], v[198:201], v[86:89]
	v_mfma_f32_16x16x32_bf16 v[82:85], v[174:177], v[198:201], v[82:85]
	v_mfma_f32_16x16x32_bf16 v[70:73], v[166:169], v[206:209], v[70:73]
	v_mfma_f32_16x16x32_bf16 v[66:69], v[174:177], v[206:209], v[66:69]
	v_mfma_f32_16x16x32_bf16 v[118:121], v[170:173], v[186:189], v[118:121]
	v_mfma_f32_16x16x32_bf16 v[114:117], v[178:181], v[186:189], v[114:117]
	v_mfma_f32_16x16x32_bf16 v[102:105], v[170:173], v[194:197], v[102:105]
	v_mfma_f32_16x16x32_bf16 v[98:101], v[178:181], v[194:197], v[98:101]
	v_mfma_f32_16x16x32_bf16 v[86:89], v[170:173], v[202:205], v[86:89]
	v_mfma_f32_16x16x32_bf16 v[82:85], v[178:181], v[202:205], v[82:85]
	v_mfma_f32_16x16x32_bf16 v[70:73], v[170:173], v[210:213], v[70:73]
	v_mfma_f32_16x16x32_bf16 v[66:69], v[178:181], v[210:213], v[66:69]
	s_setprio 0
	s_barrier
	s_add_i32 s74, s61, s46
	s_mov_b32 m0, s74
	ds_read_b128 v[182:185], v147 offset:16384
	ds_read_b128 v[186:189], v147 offset:17408
	ds_read_b128 v[190:193], v147 offset:18432
	ds_read_b128 v[194:197], v147 offset:19456
	ds_read_b128 v[198:201], v147 offset:20480
	ds_read_b128 v[202:205], v147 offset:21504
	ds_read_b128 v[206:209], v147 offset:22528
	ds_read_b128 v[210:213], v147 offset:23552
	global_load_lds_dwordx4 v134, s[36:37]
	s_add_i32 m0, s74, 0x2000
	s_add_u32 s74, s36, 0x400000
	s_addc_u32 s75, s37, 0
	s_add_i32 s76, s62, s46
	global_load_lds_dwordx4 v130, s[36:37]
	s_mov_b32 m0, s76
	s_nop 0
	global_load_lds_dwordx4 v134, s[74:75]
	s_add_i32 m0, s76, 0x2000
	s_nop 0
	global_load_lds_dwordx4 v130, s[74:75]
	s_cmp_eq_u32 s73, 0
	s_cbranch_scc1 .Lrw3
	s_waitcnt vmcnt(6)
; #define PG8_STAGE(bufoff, gbase, voff) do { _Pragma("unroll") for (int _i = 0; _i < 2; ++_i) \
;         __builtin_amdgcn_global_load_lds((const unsigned*)((const char*)(gbase) + (voff)[_i]), (LAS unsigned*)(lds + (bufoff) + ldsw + _i * 8192), 16, 0, 0); } while (0)
; #define PG8_LDA(dst, b, h) do { _Pragma("unroll") for (int m = 0; m < 4; ++m) _Pragma("unroll") for (int k = 0; k < 2; ++k) dst[m][k] = *(const LAS bf16x8*)(lds + PG8_SA(b, h) + aoff + m * 2048 + k * 1024); } while (0)
; #define PG8_LDB(dst, b, h) do { _Pragma("unroll") for (int n = 0; n < 2; ++n) _Pragma("unroll") for (int k = 0; k < 2; ++k) dst[n][k] = *(const LAS bf16x8*)(lds + PG8_SB(b, h) + boff + n * 2048 + k * 1024); } while (0)
; #define PG8_MMA(ai, bj, At, Bt) do { __builtin_amdgcn_s_setprio(1); _Pragma("unroll") for (int m = 0; m < 4; ++m) _Pragma("unroll") for (int n = 0; n < 2; ++n) _Pragma("unroll") for (int k = 0; k < 2; ++k) \
;         acc[ai][bj][m][n] = __builtin_amdgcn_mfma_f32_16x16x32_bf16(Bt[n][k], At[m][k], acc[ai][bj][m][n], 0, 0, 0); __builtin_amdgcn_s_setprio(0); } while (0)
; #define PG8_WAIT_V(n) asm volatile("s_waitcnt vmcnt(" #n ")" ::: "memory")
; #define PG8_WAIT_L(n) asm volatile("s_waitcnt lgkmcnt(" #n ")" ::: "memory")
; #define PG8_BAR __builtin_amdgcn_s_barrier()
; #define PG8_SCHED __builtin_amdgcn_sched_barrier(0)
; template <class Epi, bool ALIGN_EPI = true>
; __device__ __forceinline__ void gemm_phase(LAS unsigned char* lds, const Gemm g, const Sched& S, const Epi& E) {
;     ...
;             PG8_WAIT_L(0); PG8_BAR; PG8_MMA(1, 0, At, B0); PG8_MMA(1, 1, At, B1); PG8_BAR; PG8_SCHED;
;             PG8_LDB(B0, 1, 0); PG8_LDB(B1, 1, 1); PG8_SCHED; PG8_LDA(At, 1, 0); PG8_STAGE(PG8_SA(0, 1), a2 + hstepA, voffA);
;             PG8_WAIT_V(8); PG8_WAIT_L(0); PG8_BAR; PG8_MMA(0, 0, At, B0); PG8_MMA(0, 1, At, B1); PG8_BAR; PG8_SCHED;
.Lrw3:
	s_waitcnt vmcnt(6)
	s_waitcnt lgkmcnt(0)
	s_barrier
	s_setprio 1
	s_waitcnt lgkmcnt(0)
	v_mfma_f32_16x16x32_bf16 v[62:65], v[150:153], v[182:185], v[62:65]
	v_mfma_f32_16x16x32_bf16 v[58:61], v[158:161], v[182:185], v[58:61]
	v_mfma_f32_16x16x32_bf16 v[46:49], v[150:153], v[190:193], v[46:49]
	v_mfma_f32_16x16x32_bf16 v[42:45], v[158:161], v[190:193], v[42:45]
	v_mfma_f32_16x16x32_bf16 v[30:33], v[150:153], v[198:201], v[30:33]
	v_mfma_f32_16x16x32_bf16 v[26:29], v[158:161], v[198:201], v[26:29]
	v_mfma_f32_16x16x32_bf16 v[14:17], v[150:153], v[206:209], v[14:17]
	v_mfma_f32_16x16x32_bf16 v[10:13], v[158:161], v[206:209], v[10:13]
	v_mfma_f32_16x16x32_bf16 v[62:65], v[154:157], v[186:189], v[62:65]
	v_mfma_f32_16x16x32_bf16 v[58:61], v[162:165], v[186:189], v[58:61]
	v_mfma_f32_16x16x32_bf16 v[46:49], v[154:157], v[194:197], v[46:49]
	v_mfma_f32_16x16x32_bf16 v[42:45], v[162:165], v[194:197], v[42:45]
	v_mfma_f32_16x16x32_bf16 v[30:33], v[154:157], v[202:205], v[30:33]
	v_mfma_f32_16x16x32_bf16 v[26:29], v[162:165], v[202:205], v[26:29]
	v_mfma_f32_16x16x32_bf16 v[14:17], v[154:157], v[210:213], v[14:17]
	v_mfma_f32_16x16x32_bf16 v[10:13], v[162:165], v[210:213], v[10:13]
	s_setprio 0
	s_setprio 1
	v_mfma_f32_16x16x32_bf16 v[54:57], v[166:169], v[182:185], v[54:57]
	v_mfma_f32_16x16x32_bf16 v[50:53], v[174:177], v[182:185], v[50:53]
	v_mfma_f32_16x16x32_bf16 v[38:41], v[166:169], v[190:193], v[38:41]
	v_mfma_f32_16x16x32_bf16 v[34:37], v[174:177], v[190:193], v[34:37]
	v_mfma_f32_16x16x32_bf16 v[22:25], v[166:169], v[198:201], v[22:25]
	v_mfma_f32_16x16x32_bf16 v[18:21], v[174:177], v[198:201], v[18:21]
	v_mfma_f32_16x16x32_bf16 v[6:9], v[166:169], v[206:209], v[6:9]
	v_mfma_f32_16x16x32_bf16 v[2:5], v[174:177], v[206:209], v[2:5]
	v_mfma_f32_16x16x32_bf16 v[54:57], v[170:173], v[186:189], v[54:57]
	v_mfma_f32_16x16x32_bf16 v[50:53], v[178:181], v[186:189], v[50:53]
	v_mfma_f32_16x16x32_bf16 v[38:41], v[170:173], v[194:197], v[38:41]
	v_mfma_f32_16x16x32_bf16 v[34:37], v[178:181], v[194:197], v[34:37]
	v_mfma_f32_16x16x32_bf16 v[22:25], v[170:173], v[202:205], v[22:25]
	v_mfma_f32_16x16x32_bf16 v[18:21], v[178:181], v[202:205], v[18:21]
	v_mfma_f32_16x16x32_bf16 v[6:9], v[170:173], v[210:213], v[6:9]
	v_mfma_f32_16x16x32_bf16 v[2:5], v[178:181], v[210:213], v[2:5]
	s_setprio 0
	s_barrier
	s_add_i32 s73, 0, 0x18000
	v_add_u32_e32 v149, s73, v144
	s_add_i32 s74, 0, 0x1c000
	ds_read_b128 v[150:153], v149
	ds_read_b128 v[154:157], v149 offset:1024
	ds_read_b128 v[158:161], v149 offset:2048
	ds_read_b128 v[162:165], v149 offset:3072
	v_add_u32_e32 v149, s74, v144
	ds_read_b128 v[166:169], v149
	ds_read_b128 v[170:173], v149 offset:1024
	ds_read_b128 v[174:177], v149 offset:2048
	ds_read_b128 v[178:181], v149 offset:3072
	s_add_u32 s40, s40, 0x80000
	s_addc_u32 s41, s41, 0
	s_mov_b32 m0, s49
	ds_read_b128 v[182:185], v147 offset:32768
	ds_read_b128 v[186:189], v147 offset:33792
	ds_read_b128 v[190:193], v147 offset:34816
	ds_read_b128 v[194:197], v147 offset:35840
	ds_read_b128 v[198:201], v147 offset:36864
	ds_read_b128 v[202:205], v147 offset:37888
	ds_read_b128 v[206:209], v147 offset:38912
	ds_read_b128 v[210:213], v147 offset:39936
	s_add_u32 s100, s40, 0xfff80000
	s_addc_u32 s101, s41, -1
	s_mov_b32 m0, s47
	s_nop 0
	global_load_lds_dwordx4 v136, s[100:101]
	s_mov_b32 m0, s48
	s_nop 0
	global_load_lds_dwordx4 v132, s[100:101]
	s_mov_b32 m0, s49
	s_nop 0
	global_load_lds_dwordx4 v136, s[40:41]
	s_mov_b32 m0, s50
	s_nop 0
	global_load_lds_dwordx4 v132, s[40:41]
	s_waitcnt vmcnt(8)
	s_waitcnt lgkmcnt(0)
	s_barrier
; #define PG8_STAGE(bufoff, gbase, voff) do { _Pragma("unroll") for (int _i = 0; _i < 2; ++_i) \
;         __builtin_amdgcn_global_load_lds((const unsigned*)((const char*)(gbase) + (voff)[_i]), (LAS unsigned*)(lds + (bufoff) + ldsw + _i * 8192), 16, 0, 0); } while (0)
; #define PG8_LDA(dst, b, h) do { _Pragma("unroll") for (int m = 0; m < 4; ++m) _Pragma("unroll") for (int k = 0; k < 2; ++k) dst[m][k] = *(const LAS bf16x8*)(lds + PG8_SA(b, h) + aoff + m * 2048 + k * 1024); } while (0)
; #define PG8_MMA(ai, bj, At, Bt) do { __builtin_amdgcn_s_setprio(1); _Pragma("unroll") for (int m = 0; m < 4; ++m) _Pragma("unroll") for (int n = 0; n < 2; ++n) _Pragma("unroll") for (int k = 0; k < 2; ++k) \
;         acc[ai][bj][m][n] = __builtin_amdgcn_mfma_f32_16x16x32_bf16(Bt[n][k], At[m][k], acc[ai][bj][m][n], 0, 0, 0); __builtin_amdgcn_s_setprio(0); } while (0)
; #define PG8_WAIT_V(n) asm volatile("s_waitcnt vmcnt(" #n ")" ::: "memory")
; #define PG8_WAIT_L(n) asm volatile("s_waitcnt lgkmcnt(" #n ")" ::: "memory")
; #define PG8_BAR __builtin_amdgcn_s_barrier()
; #define PG8_SCHED __builtin_amdgcn_sched_barrier(0)
; template <class Epi, bool ALIGN_EPI = true>
; __device__ __forceinline__ void gemm_phase(LAS unsigned char* lds, const Gemm g, const Sched& S, const Epi& E) {
;     ...
;             PG8_WAIT_V(8); PG8_WAIT_L(0); PG8_BAR; PG8_MMA(0, 0, At, B0); PG8_MMA(0, 1, At, B1); PG8_BAR; PG8_SCHED;
;             PG8_LDA(At, 1, 1); PG8_STAGE(PG8_SB(1, 0), b3, voffB); PG8_STAGE(PG8_SB(1, 1), b3 + hstepB, voffB); PG8_STAGE(PG8_SA(1, 0), a3, voffA);
;             PG8_WAIT_V(8); PG8_WAIT_L(0); PG8_BAR; PG8_MMA(1, 0, At, B0); PG8_MMA(1, 1, At, B1); PG8_BAR; PG8_SCHED;
;         }
	s_setprio 1
	s_waitcnt lgkmcnt(0)
	v_mfma_f32_16x16x32_bf16 v[122:125], v[150:153], v[182:185], v[122:125]
	v_mfma_f32_16x16x32_bf16 v[126:129], v[158:161], v[182:185], v[126:129]
	v_mfma_f32_16x16x32_bf16 v[110:113], v[150:153], v[190:193], v[110:113]
	v_mfma_f32_16x16x32_bf16 v[106:109], v[158:161], v[190:193], v[106:109]
	v_mfma_f32_16x16x32_bf16 v[94:97], v[150:153], v[198:201], v[94:97]
	v_mfma_f32_16x16x32_bf16 v[90:93], v[158:161], v[198:201], v[90:93]
	v_mfma_f32_16x16x32_bf16 v[78:81], v[150:153], v[206:209], v[78:81]
	v_mfma_f32_16x16x32_bf16 v[74:77], v[158:161], v[206:209], v[74:77]
	v_mfma_f32_16x16x32_bf16 v[122:125], v[154:157], v[186:189], v[122:125]
	v_mfma_f32_16x16x32_bf16 v[126:129], v[162:165], v[186:189], v[126:129]
	v_mfma_f32_16x16x32_bf16 v[110:113], v[154:157], v[194:197], v[110:113]
	v_mfma_f32_16x16x32_bf16 v[106:109], v[162:165], v[194:197], v[106:109]
	v_mfma_f32_16x16x32_bf16 v[94:97], v[154:157], v[202:205], v[94:97]
	v_mfma_f32_16x16x32_bf16 v[90:93], v[162:165], v[202:205], v[90:93]
	v_mfma_f32_16x16x32_bf16 v[78:81], v[154:157], v[210:213], v[78:81]
	v_mfma_f32_16x16x32_bf16 v[74:77], v[162:165], v[210:213], v[74:77]
	s_setprio 0
	s_setprio 1
	v_mfma_f32_16x16x32_bf16 v[118:121], v[166:169], v[182:185], v[118:121]
	v_mfma_f32_16x16x32_bf16 v[114:117], v[174:177], v[182:185], v[114:117]
	v_mfma_f32_16x16x32_bf16 v[102:105], v[166:169], v[190:193], v[102:105]
	v_mfma_f32_16x16x32_bf16 v[98:101], v[174:177], v[190:193], v[98:101]
	v_mfma_f32_16x16x32_bf16 v[86:89], v[166:169], v[198:201], v[86:89]
	v_mfma_f32_16x16x32_bf16 v[82:85], v[174:177], v[198:201], v[82:85]
	v_mfma_f32_16x16x32_bf16 v[70:73], v[166:169], v[206:209], v[70:73]
	v_mfma_f32_16x16x32_bf16 v[66:69], v[174:177], v[206:209], v[66:69]
	v_mfma_f32_16x16x32_bf16 v[118:121], v[170:173], v[186:189], v[118:121]
	v_mfma_f32_16x16x32_bf16 v[114:117], v[178:181], v[186:189], v[114:117]
	v_mfma_f32_16x16x32_bf16 v[102:105], v[170:173], v[194:197], v[102:105]
	v_mfma_f32_16x16x32_bf16 v[98:101], v[178:181], v[194:197], v[98:101]
	v_mfma_f32_16x16x32_bf16 v[86:89], v[170:173], v[202:205], v[86:89]
	v_mfma_f32_16x16x32_bf16 v[82:85], v[178:181], v[202:205], v[82:85]
	v_mfma_f32_16x16x32_bf16 v[70:73], v[170:173], v[210:213], v[70:73]
	v_mfma_f32_16x16x32_bf16 v[66:69], v[178:181], v[210:213], v[66:69]
	s_setprio 0
	s_barrier
	s_add_u32 s100, s36, 0x80
	s_addc_u32 s101, s37, 0
	s_add_i32 s40, s73, s46
	s_mov_b32 m0, s40
	ds_read_b128 v[182:185], v147 offset:49152
	ds_read_b128 v[186:189], v147 offset:50176
	ds_read_b128 v[190:193], v147 offset:51200
	ds_read_b128 v[194:197], v147 offset:52224
	ds_read_b128 v[198:201], v147 offset:53248
	ds_read_b128 v[202:205], v147 offset:54272
	ds_read_b128 v[206:209], v147 offset:55296
	ds_read_b128 v[210:213], v147 offset:56320
	global_load_lds_dwordx4 v134, s[100:101]
	s_add_i32 m0, s40, 0x2000
	s_add_u32 s36, s36, 0x400080
	s_addc_u32 s37, s37, 0
	s_add_i32 s40, s74, s46
	global_load_lds_dwordx4 v130, s[100:101]
	s_mov_b32 m0, s40
	s_nop 0
	global_load_lds_dwordx4 v134, s[36:37]
	s_add_i32 m0, s40, 0x2000
	s_nop 0
	global_load_lds_dwordx4 v130, s[36:37]
	s_waitcnt vmcnt(6)
	s_waitcnt lgkmcnt(0)
	s_barrier
	s_setprio 1
	s_waitcnt lgkmcnt(0)
	v_mfma_f32_16x16x32_bf16 v[62:65], v[150:153], v[182:185], v[62:65]
	v_mfma_f32_16x16x32_bf16 v[58:61], v[158:161], v[182:185], v[58:61]
	v_mfma_f32_16x16x32_bf16 v[46:49], v[150:153], v[190:193], v[46:49]
	v_mfma_f32_16x16x32_bf16 v[42:45], v[158:161], v[190:193], v[42:45]
	v_mfma_f32_16x16x32_bf16 v[30:33], v[150:153], v[198:201], v[30:33]
	v_mfma_f32_16x16x32_bf16 v[26:29], v[158:161], v[198:201], v[26:29]
	v_mfma_f32_16x16x32_bf16 v[14:17], v[150:153], v[206:209], v[14:17]
	v_mfma_f32_16x16x32_bf16 v[10:13], v[158:161], v[206:209], v[10:13]
	v_mfma_f32_16x16x32_bf16 v[62:65], v[154:157], v[186:189], v[62:65]
	v_mfma_f32_16x16x32_bf16 v[58:61], v[162:165], v[186:189], v[58:61]
	v_mfma_f32_16x16x32_bf16 v[46:49], v[154:157], v[194:197], v[46:49]
	v_mfma_f32_16x16x32_bf16 v[42:45], v[162:165], v[194:197], v[42:45]
	v_mfma_f32_16x16x32_bf16 v[30:33], v[154:157], v[202:205], v[30:33]
	v_mfma_f32_16x16x32_bf16 v[26:29], v[162:165], v[202:205], v[26:29]
	v_mfma_f32_16x16x32_bf16 v[14:17], v[154:157], v[210:213], v[14:17]
	v_mfma_f32_16x16x32_bf16 v[10:13], v[162:165], v[210:213], v[10:13]
	s_setprio 0
	s_setprio 1
	v_mfma_f32_16x16x32_bf16 v[54:57], v[166:169], v[182:185], v[54:57]
	v_mfma_f32_16x16x32_bf16 v[50:53], v[174:177], v[182:185], v[50:53]
	v_mfma_f32_16x16x32_bf16 v[38:41], v[166:169], v[190:193], v[38:41]
	v_mfma_f32_16x16x32_bf16 v[34:37], v[174:177], v[190:193], v[34:37]
	v_mfma_f32_16x16x32_bf16 v[22:25], v[166:169], v[198:201], v[22:25]
	v_mfma_f32_16x16x32_bf16 v[18:21], v[174:177], v[198:201], v[18:21]
	v_mfma_f32_16x16x32_bf16 v[6:9], v[166:169], v[206:209], v[6:9]
	v_mfma_f32_16x16x32_bf16 v[2:5], v[174:177], v[206:209], v[2:5]
	v_mfma_f32_16x16x32_bf16 v[54:57], v[170:173], v[186:189], v[54:57]
	v_mfma_f32_16x16x32_bf16 v[50:53], v[178:181], v[186:189], v[50:53]
	v_mfma_f32_16x16x32_bf16 v[38:41], v[170:173], v[194:197], v[38:41]
	v_mfma_f32_16x16x32_bf16 v[34:37], v[178:181], v[194:197], v[34:37]
	v_mfma_f32_16x16x32_bf16 v[22:25], v[170:173], v[202:205], v[22:25]
	v_mfma_f32_16x16x32_bf16 v[18:21], v[178:181], v[202:205], v[18:21]
	v_mfma_f32_16x16x32_bf16 v[6:9], v[170:173], v[210:213], v[6:9]
	v_mfma_f32_16x16x32_bf16 v[2:5], v[178:181], v[210:213], v[2:5]
	s_setprio 0
	s_barrier
	s_add_u32 s34, s34, 0x100
	s_addc_u32 s35, s35, 0
	s_add_u32 s70, s70, 0x100
	s_addc_u32 s71, s71, 0
	s_cmp_ge_i32 s72, s54
	s_mov_b32 s40, s72
	s_cbranch_scc0 .LBB0_388

; #define PG8_STAGE(bufoff, gbase, voff) do { _Pragma("unroll") for (int _i = 0; _i < 2; ++_i) \
;         __builtin_amdgcn_global_load_lds((const unsigned*)((const char*)(gbase) + (voff)[_i]), (LAS unsigned*)(lds + (bufoff) + ldsw + _i * 8192), 16, 0, 0); } while (0)
; #define PG8_LDA(dst, b, h) do { _Pragma("unroll") for (int m = 0; m < 4; ++m) _Pragma("unroll") for (int k = 0; k < 2; ++k) dst[m][k] = *(const LAS bf16x8*)(lds + PG8_SA(b, h) + aoff + m * 2048 + k * 1024); } while (0)
; #define PG8_LDB(dst, b, h) do { _Pragma("unroll") for (int n = 0; n < 2; ++n) _Pragma("unroll") for (int k = 0; k < 2; ++k) dst[n][k] = *(const LAS bf16x8*)(lds + PG8_SB(b, h) + boff + n * 2048 + k * 1024); } while (0)
; #define PG8_MMA(ai, bj, At, Bt) do { __builtin_amdgcn_s_setprio(1); _Pragma("unroll") for (int m = 0; m < 4; ++m) _Pragma("unroll") for (int n = 0; n < 2; ++n) _Pragma("unroll") for (int k = 0; k < 2; ++k) \
;         acc[ai][bj][m][n] = __builtin_amdgcn_mfma_f32_16x16x32_bf16(Bt[n][k], At[m][k], acc[ai][bj][m][n], 0, 0, 0); __builtin_amdgcn_s_setprio(0); } while (0)
; #define PG8_WAIT_V(n) asm volatile("s_waitcnt vmcnt(" #n ")" ::: "memory")
; template <class Epi, bool ALIGN_EPI = true>
; __device__ __forceinline__ void gemm_phase(LAS unsigned char* lds, const Gemm g, const Sched& S, const Epi& E) {
;     ...
;         for (int t = t_lo; t < t_hi; t += 2) {
;             const bool last = (t == nt - 2);
;             const char* a1 = cA + (size_t)(t + 1) * kstep;
;             const char* a2 = last ? nA : cA + (size_t)(t + 2) * kstep; const char* b2 = last ? nB : cB + (size_t)(t + 2) * kstep;
;             const char* a3 = a2 + kstep; const char* b3 = b2 + kstep;
;             const int rflag = __builtin_amdgcn_readfirstlane(t | (int)(ui == 0));
;             PG8_LDB(B0, 0, 0); PG8_LDB(B1, 0, 1); PG8_SCHED; PG8_LDA(At, 0, 0); PG8_STAGE(PG8_SA(1, 1), a1 + hstepA, voffA);
;             if constexpr (Epi::NSTORES > 0) PG8_WAIT_RELAX(rflag, 8 + Epi::NSTORES); else PG8_WAIT_V(8);
;             PG8_WAIT_L(0); PG8_BAR; PG8_MMA(0, 0, At, B0); PG8_MMA(0, 1, At, B1); PG8_BAR; PG8_SCHED;
;             PG8_LDA(At, 0, 1); PG8_STAGE(PG8_SB(0, 0), b2, voffB); PG8_STAGE(PG8_SB(0, 1), b2 + hstepB, voffB); PG8_STAGE(PG8_SA(0, 0), a2, voffA);
;             if constexpr (Epi::NSTORES > 0) PG8_WAIT_RELAX(rflag, 8 + Epi::NSTORES); else PG8_WAIT_V(8);
.LBB0_415:
	ds_read_b128 v[150:153], v145
	ds_read_b128 v[154:157], v145 offset:1024
	ds_read_b128 v[158:161], v145 offset:2048
	ds_read_b128 v[162:165], v145 offset:3072
	ds_read_b128 v[166:169], v146
	ds_read_b128 v[170:173], v146 offset:1024
	ds_read_b128 v[174:177], v146 offset:2048
	ds_read_b128 v[178:181], v146 offset:3072
	s_add_i32 s69, s36, 2
	s_add_u32 s34, s30, 0xffc00080
	s_addc_u32 s35, s31, -1
	s_cmp_eq_u32 s56, s36
	v_add_u32_e32 v149, s36, v148
	s_cselect_b32 s36, s64, s34
	s_cselect_b32 s37, s19, s35
	s_cselect_b32 s35, s65, s68
	s_cselect_b32 s34, s66, s67
	s_add_i32 m0, s45, 0xc000
	ds_read_b128 v[182:185], v147
	ds_read_b128 v[186:189], v147 offset:1024
	ds_read_b128 v[190:193], v147 offset:2048
	ds_read_b128 v[194:197], v147 offset:3072
	ds_read_b128 v[198:201], v147 offset:4096
	ds_read_b128 v[202:205], v147 offset:5120
	ds_read_b128 v[206:209], v147 offset:6144
	ds_read_b128 v[210:213], v147 offset:7168
	s_add_u32 s100, s30, 0xffc00000
	s_addc_u32 s101, s31, -1
	s_mov_b32 m0, s54
	s_nop 0
	global_load_lds_dwordx4 v138, s[100:101]
	s_mov_b32 m0, s55
	s_nop 0
	global_load_lds_dwordx4 v140, s[100:101]
	s_add_i32 m0, s45, 0xc000
	s_nop 0
	global_load_lds_dwordx4 v138, s[30:31]
	s_add_i32 m0, s45, 0xe000
	v_readfirstlane_b32 s72, v149
	global_load_lds_dwordx4 v140, s[30:31]
	s_cmp_eq_u32 s72, 0
	s_cbranch_scc1 .Lrw4
	s_waitcnt vmcnt(8)
.Lrw4:
	s_waitcnt vmcnt(24)
	s_waitcnt lgkmcnt(0)
	s_barrier
	s_setprio 1
	s_waitcnt lgkmcnt(0)
	v_mfma_f32_16x16x32_bf16 v[122:125], v[150:153], v[182:185], v[122:125]
	v_mfma_f32_16x16x32_bf16 v[126:129], v[158:161], v[182:185], v[126:129]
	v_mfma_f32_16x16x32_bf16 v[110:113], v[150:153], v[190:193], v[110:113]
	v_mfma_f32_16x16x32_bf16 v[106:109], v[158:161], v[190:193], v[106:109]
	v_mfma_f32_16x16x32_bf16 v[94:97], v[150:153], v[198:201], v[94:97]
	v_mfma_f32_16x16x32_bf16 v[90:93], v[158:161], v[198:201], v[90:93]
	v_mfma_f32_16x16x32_bf16 v[78:81], v[150:153], v[206:209], v[78:81]
	v_mfma_f32_16x16x32_bf16 v[74:77], v[158:161], v[206:209], v[74:77]
	v_mfma_f32_16x16x32_bf16 v[122:125], v[154:157], v[186:189], v[122:125]
	v_mfma_f32_16x16x32_bf16 v[126:129], v[162:165], v[186:189], v[126:129]
	v_mfma_f32_16x16x32_bf16 v[110:113], v[154:157], v[194:197], v[110:113]
	v_mfma_f32_16x16x32_bf16 v[106:109], v[162:165], v[194:197], v[106:109]
	v_mfma_f32_16x16x32_bf16 v[94:97], v[154:157], v[202:205], v[94:97]
	v_mfma_f32_16x16x32_bf16 v[90:93], v[162:165], v[202:205], v[90:93]
	v_mfma_f32_16x16x32_bf16 v[78:81], v[154:157], v[210:213], v[78:81]
	v_mfma_f32_16x16x32_bf16 v[74:77], v[162:165], v[210:213], v[74:77]
	s_setprio 0
	s_setprio 1
	v_mfma_f32_16x16x32_bf16 v[118:121], v[166:169], v[182:185], v[118:121]
	v_mfma_f32_16x16x32_bf16 v[114:117], v[174:177], v[182:185], v[114:117]
	v_mfma_f32_16x16x32_bf16 v[102:105], v[166:169], v[190:193], v[102:105]
	v_mfma_f32_16x16x32_bf16 v[98:101], v[174:177], v[190:193], v[98:101]
	v_mfma_f32_16x16x32_bf16 v[86:89], v[166:169], v[198:201], v[86:89]
	v_mfma_f32_16x16x32_bf16 v[82:85], v[174:177], v[198:201], v[82:85]
	v_mfma_f32_16x16x32_bf16 v[70:73], v[166:169], v[206:209], v[70:73]
	v_mfma_f32_16x16x32_bf16 v[66:69], v[174:177], v[206:209], v[66:69]
	v_mfma_f32_16x16x32_bf16 v[118:121], v[170:173], v[186:189], v[118:121]
	v_mfma_f32_16x16x32_bf16 v[114:117], v[178:181], v[186:189], v[114:117]
	v_mfma_f32_16x16x32_bf16 v[102:105], v[170:173], v[194:197], v[102:105]
	v_mfma_f32_16x16x32_bf16 v[98:101], v[178:181], v[194:197], v[98:101]
	v_mfma_f32_16x16x32_bf16 v[86:89], v[170:173], v[202:205], v[86:89]
	v_mfma_f32_16x16x32_bf16 v[82:85], v[178:181], v[202:205], v[82:85]
	v_mfma_f32_16x16x32_bf16 v[70:73], v[170:173], v[210:213], v[70:73]
	v_mfma_f32_16x16x32_bf16 v[66:69], v[178:181], v[210:213], v[66:69]
	s_setprio 0
	s_barrier
	s_add_i32 s70, s58, s44
	s_mov_b32 m0, s70
	ds_read_b128 v[182:185], v147 offset:16384
	ds_read_b128 v[186:189], v147 offset:17408
	ds_read_b128 v[190:193], v147 offset:18432
	ds_read_b128 v[194:197], v147 offset:19456
	ds_read_b128 v[198:201], v147 offset:20480
	ds_read_b128 v[202:205], v147 offset:21504
	ds_read_b128 v[206:209], v147 offset:22528
	ds_read_b128 v[210:213], v147 offset:23552
	global_load_lds_dwordx4 v132, s[34:35]
	s_add_i32 m0, s70, 0x2000
	s_add_u32 s70, s34, 0x80000
	s_addc_u32 s71, s35, 0
	s_add_i32 s73, s59, s44
	global_load_lds_dwordx4 v136, s[34:35]
	s_mov_b32 m0, s73
	s_nop 0
	global_load_lds_dwordx4 v132, s[70:71]
	s_add_i32 m0, s73, 0x2000
	s_nop 0
	global_load_lds_dwordx4 v136, s[70:71]
	s_cmp_eq_u32 s72, 0
	s_cbranch_scc1 .Lrw5
	s_waitcnt vmcnt(6)
; #define PG8_STAGE(bufoff, gbase, voff) do { _Pragma("unroll") for (int _i = 0; _i < 2; ++_i) \
;         __builtin_amdgcn_global_load_lds((const unsigned*)((const char*)(gbase) + (voff)[_i]), (LAS unsigned*)(lds + (bufoff) + ldsw + _i * 8192), 16, 0, 0); } while (0)
; #define PG8_LDA(dst, b, h) do { _Pragma("unroll") for (int m = 0; m < 4; ++m) _Pragma("unroll") for (int k = 0; k < 2; ++k) dst[m][k] = *(const LAS bf16x8*)(lds + PG8_SA(b, h) + aoff + m * 2048 + k * 1024); } while (0)
; #define PG8_LDB(dst, b, h) do { _Pragma("unroll") for (int n = 0; n < 2; ++n) _Pragma("unroll") for (int k = 0; k < 2; ++k) dst[n][k] = *(const LAS bf16x8*)(lds + PG8_SB(b, h) + boff + n * 2048 + k * 1024); } while (0)
; #define PG8_MMA(ai, bj, At, Bt) do { __builtin_amdgcn_s_setprio(1); _Pragma("unroll") for (int m = 0; m < 4; ++m) _Pragma("unroll") for (int n = 0; n < 2; ++n) _Pragma("unroll") for (int k = 0; k < 2; ++k) \
;         acc[ai][bj][m][n] = __builtin_amdgcn_mfma_f32_16x16x32_bf16(Bt[n][k], At[m][k], acc[ai][bj][m][n], 0, 0, 0); __builtin_amdgcn_s_setprio(0); } while (0)
; #define PG8_WAIT_V(n) asm volatile("s_waitcnt vmcnt(" #n ")" ::: "memory")
; #define PG8_WAIT_L(n) asm volatile("s_waitcnt lgkmcnt(" #n ")" ::: "memory")
; #define PG8_BAR __builtin_amdgcn_s_barrier()
; #define PG8_SCHED __builtin_amdgcn_sched_barrier(0)
; template <class Epi, bool ALIGN_EPI = true>
; __device__ __forceinline__ void gemm_phase(LAS unsigned char* lds, const Gemm g, const Sched& S, const Epi& E) {
;     ...
;             PG8_WAIT_L(0); PG8_BAR; PG8_MMA(1, 0, At, B0); PG8_MMA(1, 1, At, B1); PG8_BAR; PG8_SCHED;
;             PG8_LDB(B0, 1, 0); PG8_LDB(B1, 1, 1); PG8_SCHED; PG8_LDA(At, 1, 0); PG8_STAGE(PG8_SA(0, 1), a2 + hstepA, voffA);
;             PG8_WAIT_V(8); PG8_WAIT_L(0); PG8_BAR; PG8_MMA(0, 0, At, B0); PG8_MMA(0, 1, At, B1); PG8_BAR; PG8_SCHED;
.Lrw5:
	s_waitcnt vmcnt(6)
	s_waitcnt lgkmcnt(0)
	s_barrier
	s_setprio 1
	s_waitcnt lgkmcnt(0)
	v_mfma_f32_16x16x32_bf16 v[62:65], v[150:153], v[182:185], v[62:65]
	v_mfma_f32_16x16x32_bf16 v[58:61], v[158:161], v[182:185], v[58:61]
	v_mfma_f32_16x16x32_bf16 v[46:49], v[150:153], v[190:193], v[46:49]
	v_mfma_f32_16x16x32_bf16 v[42:45], v[158:161], v[190:193], v[42:45]
	v_mfma_f32_16x16x32_bf16 v[30:33], v[150:153], v[198:201], v[30:33]
	v_mfma_f32_16x16x32_bf16 v[26:29], v[158:161], v[198:201], v[26:29]
	v_mfma_f32_16x16x32_bf16 v[14:17], v[150:153], v[206:209], v[14:17]
	v_mfma_f32_16x16x32_bf16 v[10:13], v[158:161], v[206:209], v[10:13]
	v_mfma_f32_16x16x32_bf16 v[62:65], v[154:157], v[186:189], v[62:65]
	v_mfma_f32_16x16x32_bf16 v[58:61], v[162:165], v[186:189], v[58:61]
	v_mfma_f32_16x16x32_bf16 v[46:49], v[154:157], v[194:197], v[46:49]
	v_mfma_f32_16x16x32_bf16 v[42:45], v[162:165], v[194:197], v[42:45]
	v_mfma_f32_16x16x32_bf16 v[30:33], v[154:157], v[202:205], v[30:33]
	v_mfma_f32_16x16x32_bf16 v[26:29], v[162:165], v[202:205], v[26:29]
	v_mfma_f32_16x16x32_bf16 v[14:17], v[154:157], v[210:213], v[14:17]
	v_mfma_f32_16x16x32_bf16 v[10:13], v[162:165], v[210:213], v[10:13]
	s_setprio 0
	s_setprio 1
	v_mfma_f32_16x16x32_bf16 v[54:57], v[166:169], v[182:185], v[54:57]
	v_mfma_f32_16x16x32_bf16 v[50:53], v[174:177], v[182:185], v[50:53]
	v_mfma_f32_16x16x32_bf16 v[38:41], v[166:169], v[190:193], v[38:41]
	v_mfma_f32_16x16x32_bf16 v[34:37], v[174:177], v[190:193], v[34:37]
	v_mfma_f32_16x16x32_bf16 v[22:25], v[166:169], v[198:201], v[22:25]
	v_mfma_f32_16x16x32_bf16 v[18:21], v[174:177], v[198:201], v[18:21]
	v_mfma_f32_16x16x32_bf16 v[6:9], v[166:169], v[206:209], v[6:9]
	v_mfma_f32_16x16x32_bf16 v[2:5], v[174:177], v[206:209], v[2:5]
	v_mfma_f32_16x16x32_bf16 v[54:57], v[170:173], v[186:189], v[54:57]
	v_mfma_f32_16x16x32_bf16 v[50:53], v[178:181], v[186:189], v[50:53]
	v_mfma_f32_16x16x32_bf16 v[38:41], v[170:173], v[194:197], v[38:41]
	v_mfma_f32_16x16x32_bf16 v[34:37], v[178:181], v[194:197], v[34:37]
	v_mfma_f32_16x16x32_bf16 v[22:25], v[170:173], v[202:205], v[22:25]
	v_mfma_f32_16x16x32_bf16 v[18:21], v[178:181], v[202:205], v[18:21]
	v_mfma_f32_16x16x32_bf16 v[6:9], v[170:173], v[210:213], v[6:9]
	v_mfma_f32_16x16x32_bf16 v[2:5], v[178:181], v[210:213], v[2:5]
	s_setprio 0
	s_barrier
	s_add_i32 s70, 0, 0x18000
	v_add_u32_e32 v149, s70, v144
	s_add_i32 s71, 0, 0x1c000
	ds_read_b128 v[150:153], v149
	ds_read_b128 v[154:157], v149 offset:1024
	ds_read_b128 v[158:161], v149 offset:2048
	ds_read_b128 v[162:165], v149 offset:3072
	v_add_u32_e32 v149, s71, v144
	ds_read_b128 v[166:169], v149
	ds_read_b128 v[170:173], v149 offset:1024
	ds_read_b128 v[174:177], v149 offset:2048
	ds_read_b128 v[178:181], v149 offset:3072
	s_add_u32 s36, s36, 0x400000
	s_addc_u32 s37, s37, 0
	s_mov_b32 m0, s47
	ds_read_b128 v[182:185], v147 offset:32768
	ds_read_b128 v[186:189], v147 offset:33792
	ds_read_b128 v[190:193], v147 offset:34816
	ds_read_b128 v[194:197], v147 offset:35840
	ds_read_b128 v[198:201], v147 offset:36864
	ds_read_b128 v[202:205], v147 offset:37888
	ds_read_b128 v[206:209], v147 offset:38912
	ds_read_b128 v[210:213], v147 offset:39936
	s_add_u32 s100, s36, 0xffc00000
	s_addc_u32 s101, s37, -1
	s_mov_b32 m0, s45
	s_nop 0
	global_load_lds_dwordx4 v130, s[100:101]
	s_mov_b32 m0, s46
	s_nop 0
	global_load_lds_dwordx4 v134, s[100:101]
	s_mov_b32 m0, s47
	s_nop 0
	global_load_lds_dwordx4 v130, s[36:37]
	s_mov_b32 m0, s48
	s_nop 0
	global_load_lds_dwordx4 v134, s[36:37]
	s_waitcnt vmcnt(8)
	s_waitcnt lgkmcnt(0)
	s_barrier
; #define PG8_STAGE(bufoff, gbase, voff) do { _Pragma("unroll") for (int _i = 0; _i < 2; ++_i) \
;         __builtin_amdgcn_global_load_lds((const unsigned*)((const char*)(gbase) + (voff)[_i]), (LAS unsigned*)(lds + (bufoff) + ldsw + _i * 8192), 16, 0, 0); } while (0)
; #define PG8_LDA(dst, b, h) do { _Pragma("unroll") for (int m = 0; m < 4; ++m) _Pragma("unroll") for (int k = 0; k < 2; ++k) dst[m][k] = *(const LAS bf16x8*)(lds + PG8_SA(b, h) + aoff + m * 2048 + k * 1024); } while (0)
; #define PG8_MMA(ai, bj, At, Bt) do { __builtin_amdgcn_s_setprio(1); _Pragma("unroll") for (int m = 0; m < 4; ++m) _Pragma("unroll") for (int n = 0; n < 2; ++n) _Pragma("unroll") for (int k = 0; k < 2; ++k) \
;         acc[ai][bj][m][n] = __builtin_amdgcn_mfma_f32_16x16x32_bf16(Bt[n][k], At[m][k], acc[ai][bj][m][n], 0, 0, 0); __builtin_amdgcn_s_setprio(0); } while (0)
; #define PG8_WAIT_V(n) asm volatile("s_waitcnt vmcnt(" #n ")" ::: "memory")
; #define PG8_WAIT_L(n) asm volatile("s_waitcnt lgkmcnt(" #n ")" ::: "memory")
; #define PG8_BAR __builtin_amdgcn_s_barrier()
; #define PG8_SCHED __builtin_amdgcn_sched_barrier(0)
; template <class Epi, bool ALIGN_EPI = true>
; __device__ __forceinline__ void gemm_phase(LAS unsigned char* lds, const Gemm g, const Sched& S, const Epi& E) {
;     ...
;             PG8_WAIT_V(8); PG8_WAIT_L(0); PG8_BAR; PG8_MMA(0, 0, At, B0); PG8_MMA(0, 1, At, B1); PG8_BAR; PG8_SCHED;
;             PG8_LDA(At, 1, 1); PG8_STAGE(PG8_SB(1, 0), b3, voffB); PG8_STAGE(PG8_SB(1, 1), b3 + hstepB, voffB); PG8_STAGE(PG8_SA(1, 0), a3, voffA);
;             PG8_WAIT_V(8); PG8_WAIT_L(0); PG8_BAR; PG8_MMA(1, 0, At, B0); PG8_MMA(1, 1, At, B1); PG8_BAR; PG8_SCHED;
;         }
	s_setprio 1
	s_waitcnt lgkmcnt(0)
	v_mfma_f32_16x16x32_bf16 v[122:125], v[150:153], v[182:185], v[122:125]
	v_mfma_f32_16x16x32_bf16 v[126:129], v[158:161], v[182:185], v[126:129]
	v_mfma_f32_16x16x32_bf16 v[110:113], v[150:153], v[190:193], v[110:113]
	v_mfma_f32_16x16x32_bf16 v[106:109], v[158:161], v[190:193], v[106:109]
	v_mfma_f32_16x16x32_bf16 v[94:97], v[150:153], v[198:201], v[94:97]
	v_mfma_f32_16x16x32_bf16 v[90:93], v[158:161], v[198:201], v[90:93]
	v_mfma_f32_16x16x32_bf16 v[78:81], v[150:153], v[206:209], v[78:81]
	v_mfma_f32_16x16x32_bf16 v[74:77], v[158:161], v[206:209], v[74:77]
	v_mfma_f32_16x16x32_bf16 v[122:125], v[154:157], v[186:189], v[122:125]
	v_mfma_f32_16x16x32_bf16 v[126:129], v[162:165], v[186:189], v[126:129]
	v_mfma_f32_16x16x32_bf16 v[110:113], v[154:157], v[194:197], v[110:113]
	v_mfma_f32_16x16x32_bf16 v[106:109], v[162:165], v[194:197], v[106:109]
	v_mfma_f32_16x16x32_bf16 v[94:97], v[154:157], v[202:205], v[94:97]
	v_mfma_f32_16x16x32_bf16 v[90:93], v[162:165], v[202:205], v[90:93]
	v_mfma_f32_16x16x32_bf16 v[78:81], v[154:157], v[210:213], v[78:81]
	v_mfma_f32_16x16x32_bf16 v[74:77], v[162:165], v[210:213], v[74:77]
	s_setprio 0
	s_setprio 1
	v_mfma_f32_16x16x32_bf16 v[118:121], v[166:169], v[182:185], v[118:121]
	v_mfma_f32_16x16x32_bf16 v[114:117], v[174:177], v[182:185], v[114:117]
	v_mfma_f32_16x16x32_bf16 v[102:105], v[166:169], v[190:193], v[102:105]
	v_mfma_f32_16x16x32_bf16 v[98:101], v[174:177], v[190:193], v[98:101]
	v_mfma_f32_16x16x32_bf16 v[86:89], v[166:169], v[198:201], v[86:89]
	v_mfma_f32_16x16x32_bf16 v[82:85], v[174:177], v[198:201], v[82:85]
	v_mfma_f32_16x16x32_bf16 v[70:73], v[166:169], v[206:209], v[70:73]
	v_mfma_f32_16x16x32_bf16 v[66:69], v[174:177], v[206:209], v[66:69]
	v_mfma_f32_16x16x32_bf16 v[118:121], v[170:173], v[186:189], v[118:121]
	v_mfma_f32_16x16x32_bf16 v[114:117], v[178:181], v[186:189], v[114:117]
	v_mfma_f32_16x16x32_bf16 v[102:105], v[170:173], v[194:197], v[102:105]
	v_mfma_f32_16x16x32_bf16 v[98:101], v[178:181], v[194:197], v[98:101]
	v_mfma_f32_16x16x32_bf16 v[86:89], v[170:173], v[202:205], v[86:89]
	v_mfma_f32_16x16x32_bf16 v[82:85], v[178:181], v[202:205], v[82:85]
	v_mfma_f32_16x16x32_bf16 v[70:73], v[170:173], v[210:213], v[70:73]
	v_mfma_f32_16x16x32_bf16 v[66:69], v[178:181], v[210:213], v[66:69]
	s_setprio 0
	s_barrier
	s_add_u32 s100, s34, 0x80
	s_addc_u32 s101, s35, 0
	s_add_i32 s36, s70, s44
	s_mov_b32 m0, s36
	ds_read_b128 v[182:185], v147 offset:49152
	ds_read_b128 v[186:189], v147 offset:50176
	ds_read_b128 v[190:193], v147 offset:51200
	ds_read_b128 v[194:197], v147 offset:52224
	ds_read_b128 v[198:201], v147 offset:53248
	ds_read_b128 v[202:205], v147 offset:54272
	ds_read_b128 v[206:209], v147 offset:55296
	ds_read_b128 v[210:213], v147 offset:56320
	global_load_lds_dwordx4 v132, s[100:101]
	s_add_i32 m0, s36, 0x2000
	s_add_u32 s34, s34, 0x80080
	s_addc_u32 s35, s35, 0
	s_add_i32 s36, s71, s44
	global_load_lds_dwordx4 v136, s[100:101]
	s_mov_b32 m0, s36
	s_nop 0
	global_load_lds_dwordx4 v132, s[34:35]
	s_add_i32 m0, s36, 0x2000
	s_nop 0
	global_load_lds_dwordx4 v136, s[34:35]
	s_waitcnt vmcnt(6)
	s_waitcnt lgkmcnt(0)
	s_barrier
	s_setprio 1
	s_waitcnt lgkmcnt(0)
	v_mfma_f32_16x16x32_bf16 v[62:65], v[150:153], v[182:185], v[62:65]
	v_mfma_f32_16x16x32_bf16 v[58:61], v[158:161], v[182:185], v[58:61]
	v_mfma_f32_16x16x32_bf16 v[46:49], v[150:153], v[190:193], v[46:49]
	v_mfma_f32_16x16x32_bf16 v[42:45], v[158:161], v[190:193], v[42:45]
	v_mfma_f32_16x16x32_bf16 v[30:33], v[150:153], v[198:201], v[30:33]
	v_mfma_f32_16x16x32_bf16 v[26:29], v[158:161], v[198:201], v[26:29]
	v_mfma_f32_16x16x32_bf16 v[14:17], v[150:153], v[206:209], v[14:17]
	v_mfma_f32_16x16x32_bf16 v[10:13], v[158:161], v[206:209], v[10:13]
	v_mfma_f32_16x16x32_bf16 v[62:65], v[154:157], v[186:189], v[62:65]
	v_mfma_f32_16x16x32_bf16 v[58:61], v[162:165], v[186:189], v[58:61]
	v_mfma_f32_16x16x32_bf16 v[46:49], v[154:157], v[194:197], v[46:49]
	v_mfma_f32_16x16x32_bf16 v[42:45], v[162:165], v[194:197], v[42:45]
	v_mfma_f32_16x16x32_bf16 v[30:33], v[154:157], v[202:205], v[30:33]
	v_mfma_f32_16x16x32_bf16 v[26:29], v[162:165], v[202:205], v[26:29]
	v_mfma_f32_16x16x32_bf16 v[14:17], v[154:157], v[210:213], v[14:17]
	v_mfma_f32_16x16x32_bf16 v[10:13], v[162:165], v[210:213], v[10:13]
	s_setprio 0
	s_setprio 1
	v_mfma_f32_16x16x32_bf16 v[54:57], v[166:169], v[182:185], v[54:57]
	v_mfma_f32_16x16x32_bf16 v[50:53], v[174:177], v[182:185], v[50:53]
	v_mfma_f32_16x16x32_bf16 v[38:41], v[166:169], v[190:193], v[38:41]
	v_mfma_f32_16x16x32_bf16 v[34:37], v[174:177], v[190:193], v[34:37]
	v_mfma_f32_16x16x32_bf16 v[22:25], v[166:169], v[198:201], v[22:25]
	v_mfma_f32_16x16x32_bf16 v[18:21], v[174:177], v[198:201], v[18:21]
	v_mfma_f32_16x16x32_bf16 v[6:9], v[166:169], v[206:209], v[6:9]
	v_mfma_f32_16x16x32_bf16 v[2:5], v[174:177], v[206:209], v[2:5]
	v_mfma_f32_16x16x32_bf16 v[54:57], v[170:173], v[186:189], v[54:57]
	v_mfma_f32_16x16x32_bf16 v[50:53], v[178:181], v[186:189], v[50:53]
	v_mfma_f32_16x16x32_bf16 v[38:41], v[170:173], v[194:197], v[38:41]
	v_mfma_f32_16x16x32_bf16 v[34:37], v[178:181], v[194:197], v[34:37]
	v_mfma_f32_16x16x32_bf16 v[22:25], v[170:173], v[202:205], v[22:25]
	v_mfma_f32_16x16x32_bf16 v[18:21], v[178:181], v[202:205], v[18:21]
	v_mfma_f32_16x16x32_bf16 v[6:9], v[170:173], v[210:213], v[6:9]
	v_mfma_f32_16x16x32_bf16 v[2:5], v[178:181], v[210:213], v[2:5]
	s_setprio 0
	s_barrier
	s_add_u32 s30, s30, 0x100
	s_addc_u32 s31, s31, 0
	s_add_u32 s67, s67, 0x100
	s_addc_u32 s68, s68, 0
	s_cmp_ge_i32 s69, s51
	s_mov_b32 s36, s69
	s_cbranch_scc0 .LBB0_415

; #define PG8_STAGE(bufoff, gbase, voff) do { _Pragma("unroll") for (int _i = 0; _i < 2; ++_i) \
;         __builtin_amdgcn_global_load_lds((const unsigned*)((const char*)(gbase) + (voff)[_i]), (LAS unsigned*)(lds + (bufoff) + ldsw + _i * 8192), 16, 0, 0); } while (0)
; #define PG8_LDA(dst, b, h) do { _Pragma("unroll") for (int m = 0; m < 4; ++m) _Pragma("unroll") for (int k = 0; k < 2; ++k) dst[m][k] = *(const LAS bf16x8*)(lds + PG8_SA(b, h) + aoff + m * 2048 + k * 1024); } while (0)
; #define PG8_LDB(dst, b, h) do { _Pragma("unroll") for (int n = 0; n < 2; ++n) _Pragma("unroll") for (int k = 0; k < 2; ++k) dst[n][k] = *(const LAS bf16x8*)(lds + PG8_SB(b, h) + boff + n * 2048 + k * 1024); } while (0)
; #define PG8_MMA(ai, bj, At, Bt) do { __builtin_amdgcn_s_setprio(1); _Pragma("unroll") for (int m = 0; m < 4; ++m) _Pragma("unroll") for (int n = 0; n < 2; ++n) _Pragma("unroll") for (int k = 0; k < 2; ++k) \
;         acc[ai][bj][m][n] = __builtin_amdgcn_mfma_f32_16x16x32_bf16(Bt[n][k], At[m][k], acc[ai][bj][m][n], 0, 0, 0); __builtin_amdgcn_s_setprio(0); } while (0)
; #define PG8_WAIT_V(n) asm volatile("s_waitcnt vmcnt(" #n ")" ::: "memory")
; template <class Epi, bool ALIGN_EPI = true>
; __device__ __forceinline__ void gemm_phase(LAS unsigned char* lds, const Gemm g, const Sched& S, const Epi& E) {
;     ...
;         for (int t = t_lo; t < t_hi; t += 2) {
;             const bool last = (t == nt - 2);
;             const char* a1 = cA + (size_t)(t + 1) * kstep;
;             const char* a2 = last ? nA : cA + (size_t)(t + 2) * kstep; const char* b2 = last ? nB : cB + (size_t)(t + 2) * kstep;
;             const char* a3 = a2 + kstep; const char* b3 = b2 + kstep;
;             const int rflag = __builtin_amdgcn_readfirstlane(t | (int)(ui == 0));
;             PG8_LDB(B0, 0, 0); PG8_LDB(B1, 0, 1); PG8_SCHED; PG8_LDA(At, 0, 0); PG8_STAGE(PG8_SA(1, 1), a1 + hstepA, voffA);
;             if constexpr (Epi::NSTORES > 0) PG8_WAIT_RELAX(rflag, 8 + Epi::NSTORES); else PG8_WAIT_V(8);
;             PG8_WAIT_L(0); PG8_BAR; PG8_MMA(0, 0, At, B0); PG8_MMA(0, 1, At, B1); PG8_BAR; PG8_SCHED;
;             PG8_LDA(At, 0, 1); PG8_STAGE(PG8_SB(0, 0), b2, voffB); PG8_STAGE(PG8_SB(0, 1), b2 + hstepB, voffB); PG8_STAGE(PG8_SA(0, 0), a2, voffA);
;             if constexpr (Epi::NSTORES > 0) PG8_WAIT_RELAX(rflag, 8 + Epi::NSTORES); else PG8_WAIT_V(8);
.LBB0_500:
	s_add_i32 s22, s6, 2
	s_add_u32 s7, s4, 0xfff80080
	s_addc_u32 s14, s5, -1
	s_add_i32 s23, 0, 0x10000
	s_cmp_eq_u32 s94, s6
	v_add_u32_e32 v182, s6, v2
	s_cselect_b32 s15, s16, s14
	s_cselect_b32 s14, s17, s7
	s_waitcnt lgkmcnt(0)
	v_add_u32_e32 v4, s23, v185
	s_cselect_b32 s7, s18, s21
	s_cselect_b32 s6, s19, s20
	s_add_i32 s52, 0, 0x14000
	ds_read_b128 v[134:137], v4
	ds_read_b128 v[138:141], v4 offset:1024
	ds_read_b128 v[142:145], v4 offset:2048
	ds_read_b128 v[146:149], v4 offset:3072
	v_add_u32_e32 v4, s52, v185
	ds_read_b128 v[162:165], v4
	ds_read_b128 v[166:169], v4 offset:1024
	ds_read_b128 v[170:173], v4 offset:2048
	ds_read_b128 v[174:177], v4 offset:3072
	s_add_i32 m0, s50, 0xc000
	ds_read_b128 v[178:181], v186
	ds_read_b128 v[188:191], v186 offset:1024
	ds_read_b128 v[192:195], v186 offset:2048
	ds_read_b128 v[206:209], v186 offset:3072
	ds_read_b128 v[224:227], v186 offset:4096
	ds_read_b128 v[228:231], v186 offset:5120
	ds_read_b128 v[232:235], v186 offset:6144
	ds_read_b128 v[236:239], v186 offset:7168
	s_add_u32 s100, s4, 0xfff80000
	s_addc_u32 s101, s5, -1
	s_mov_b32 m0, s92
	s_nop 0
	global_load_lds_dwordx4 v158, s[100:101]
	s_mov_b32 m0, s93
	s_nop 0
	global_load_lds_dwordx4 v160, s[100:101]
	s_add_i32 m0, s50, 0xc000
	s_nop 0
	global_load_lds_dwordx4 v158, s[4:5]
	s_add_i32 m0, s50, 0xe000
	v_readfirstlane_b32 s53, v182
	global_load_lds_dwordx4 v160, s[4:5]
	s_cmp_eq_u32 s53, 0
	s_cbranch_scc1 .Lrw6
	s_waitcnt vmcnt(8)
.Lrw6:
	s_waitcnt vmcnt(24)
	s_waitcnt lgkmcnt(0)
	s_barrier
	s_setprio 1
	s_waitcnt lgkmcnt(0)
	v_mfma_f32_16x16x32_bf16 v[130:133], v[134:137], v[178:181], v[130:133]
	v_mfma_f32_16x16x32_bf16 v[126:129], v[142:145], v[178:181], v[126:129]
	v_mfma_f32_16x16x32_bf16 v[122:125], v[134:137], v[192:195], v[122:125]
	v_mfma_f32_16x16x32_bf16 v[118:121], v[142:145], v[192:195], v[118:121]
	v_mfma_f32_16x16x32_bf16 v[114:117], v[134:137], v[224:227], v[114:117]
	v_mfma_f32_16x16x32_bf16 v[110:113], v[142:145], v[224:227], v[110:113]
	v_mfma_f32_16x16x32_bf16 v[106:109], v[134:137], v[232:235], v[106:109]
	v_mfma_f32_16x16x32_bf16 v[102:105], v[142:145], v[232:235], v[102:105]
	v_mfma_f32_16x16x32_bf16 v[130:133], v[138:141], v[188:191], v[130:133]
	v_mfma_f32_16x16x32_bf16 v[126:129], v[146:149], v[188:191], v[126:129]
	v_mfma_f32_16x16x32_bf16 v[122:125], v[138:141], v[206:209], v[122:125]
	v_mfma_f32_16x16x32_bf16 v[118:121], v[146:149], v[206:209], v[118:121]
	v_mfma_f32_16x16x32_bf16 v[114:117], v[138:141], v[228:231], v[114:117]
	v_mfma_f32_16x16x32_bf16 v[110:113], v[146:149], v[228:231], v[110:113]
	v_mfma_f32_16x16x32_bf16 v[106:109], v[138:141], v[236:239], v[106:109]
	v_mfma_f32_16x16x32_bf16 v[102:105], v[146:149], v[236:239], v[102:105]
	s_setprio 0
	s_setprio 1
	v_mfma_f32_16x16x32_bf16 v[98:101], v[162:165], v[178:181], v[98:101]
	v_mfma_f32_16x16x32_bf16 v[94:97], v[170:173], v[178:181], v[94:97]
	v_mfma_f32_16x16x32_bf16 v[90:93], v[162:165], v[192:195], v[90:93]
	v_mfma_f32_16x16x32_bf16 v[86:89], v[170:173], v[192:195], v[86:89]
	v_mfma_f32_16x16x32_bf16 v[82:85], v[162:165], v[224:227], v[82:85]
	v_mfma_f32_16x16x32_bf16 v[78:81], v[170:173], v[224:227], v[78:81]
	v_mfma_f32_16x16x32_bf16 v[74:77], v[162:165], v[232:235], v[74:77]
	v_mfma_f32_16x16x32_bf16 v[70:73], v[170:173], v[232:235], v[70:73]
	v_mfma_f32_16x16x32_bf16 v[98:101], v[166:169], v[188:191], v[98:101]
	v_mfma_f32_16x16x32_bf16 v[94:97], v[174:177], v[188:191], v[94:97]
	v_mfma_f32_16x16x32_bf16 v[90:93], v[166:169], v[206:209], v[90:93]
	v_mfma_f32_16x16x32_bf16 v[86:89], v[174:177], v[206:209], v[86:89]
	v_mfma_f32_16x16x32_bf16 v[82:85], v[166:169], v[228:231], v[82:85]
	v_mfma_f32_16x16x32_bf16 v[78:81], v[174:177], v[228:231], v[78:81]
	v_mfma_f32_16x16x32_bf16 v[74:77], v[166:169], v[236:239], v[74:77]
	v_mfma_f32_16x16x32_bf16 v[70:73], v[174:177], v[236:239], v[70:73]
	s_setprio 0
	s_barrier
	s_add_i32 s23, s23, s27
	s_mov_b32 m0, s23
	ds_read_b128 v[178:181], v186 offset:16384
	ds_read_b128 v[188:191], v186 offset:17408
	ds_read_b128 v[192:195], v186 offset:18432
	ds_read_b128 v[206:209], v186 offset:19456
	ds_read_b128 v[224:227], v186 offset:20480
	ds_read_b128 v[228:231], v186 offset:21504
	ds_read_b128 v[232:235], v186 offset:22528
	ds_read_b128 v[236:239], v186 offset:23552
	global_load_lds_dwordx4 v152, s[6:7]
	s_add_i32 m0, s23, 0x2000
	s_add_u32 s24, s6, 0x80000
	s_addc_u32 s25, s7, 0
	s_add_i32 s23, s52, s27
	global_load_lds_dwordx4 v156, s[6:7]
	s_mov_b32 m0, s23
	s_nop 0
	global_load_lds_dwordx4 v152, s[24:25]
	s_add_i32 m0, s23, 0x2000
	s_nop 0
	global_load_lds_dwordx4 v156, s[24:25]
	s_cmp_eq_u32 s53, 0
	s_cbranch_scc1 .Lrw7
	s_waitcnt vmcnt(6)
; #define PG8_STAGE(bufoff, gbase, voff) do { _Pragma("unroll") for (int _i = 0; _i < 2; ++_i) \
;         __builtin_amdgcn_global_load_lds((const unsigned*)((const char*)(gbase) + (voff)[_i]), (LAS unsigned*)(lds + (bufoff) + ldsw + _i * 8192), 16, 0, 0); } while (0)
; #define PG8_LDA(dst, b, h) do { _Pragma("unroll") for (int m = 0; m < 4; ++m) _Pragma("unroll") for (int k = 0; k < 2; ++k) dst[m][k] = *(const LAS bf16x8*)(lds + PG8_SA(b, h) + aoff + m * 2048 + k * 1024); } while (0)
; #define PG8_LDB(dst, b, h) do { _Pragma("unroll") for (int n = 0; n < 2; ++n) _Pragma("unroll") for (int k = 0; k < 2; ++k) dst[n][k] = *(const LAS bf16x8*)(lds + PG8_SB(b, h) + boff + n * 2048 + k * 1024); } while (0)
; #define PG8_MMA(ai, bj, At, Bt) do { __builtin_amdgcn_s_setprio(1); _Pragma("unroll") for (int m = 0; m < 4; ++m) _Pragma("unroll") for (int n = 0; n < 2; ++n) _Pragma("unroll") for (int k = 0; k < 2; ++k) \
;         acc[ai][bj][m][n] = __builtin_amdgcn_mfma_f32_16x16x32_bf16(Bt[n][k], At[m][k], acc[ai][bj][m][n], 0, 0, 0); __builtin_amdgcn_s_setprio(0); } while (0)
; #define PG8_WAIT_V(n) asm volatile("s_waitcnt vmcnt(" #n ")" ::: "memory")
; #define PG8_WAIT_L(n) asm volatile("s_waitcnt lgkmcnt(" #n ")" ::: "memory")
; #define PG8_BAR __builtin_amdgcn_s_barrier()
; #define PG8_SCHED __builtin_amdgcn_sched_barrier(0)
; template <class Epi, bool ALIGN_EPI = true>
; __device__ __forceinline__ void gemm_phase(LAS unsigned char* lds, const Gemm g, const Sched& S, const Epi& E) {
;     ...
;             PG8_WAIT_L(0); PG8_BAR; PG8_MMA(1, 0, At, B0); PG8_MMA(1, 1, At, B1); PG8_BAR; PG8_SCHED;
;             PG8_LDB(B0, 1, 0); PG8_LDB(B1, 1, 1); PG8_SCHED; PG8_LDA(At, 1, 0); PG8_STAGE(PG8_SA(0, 1), a2 + hstepA, voffA);
;             PG8_WAIT_V(8); PG8_WAIT_L(0); PG8_BAR; PG8_MMA(0, 0, At, B0); PG8_MMA(0, 1, At, B1); PG8_BAR; PG8_SCHED;
.Lrw7:
	s_waitcnt vmcnt(6)
	s_waitcnt lgkmcnt(0)
	s_barrier
	s_setprio 1
	s_waitcnt lgkmcnt(0)
	v_mfma_f32_16x16x32_bf16 v[66:69], v[134:137], v[178:181], v[66:69]
	v_mfma_f32_16x16x32_bf16 v[62:65], v[142:145], v[178:181], v[62:65]
	v_mfma_f32_16x16x32_bf16 v[58:61], v[134:137], v[192:195], v[58:61]
	v_mfma_f32_16x16x32_bf16 v[54:57], v[142:145], v[192:195], v[54:57]
	v_mfma_f32_16x16x32_bf16 v[50:53], v[134:137], v[224:227], v[50:53]
	v_mfma_f32_16x16x32_bf16 v[46:49], v[142:145], v[224:227], v[46:49]
	v_mfma_f32_16x16x32_bf16 v[42:45], v[134:137], v[232:235], v[42:45]
	v_mfma_f32_16x16x32_bf16 v[38:41], v[142:145], v[232:235], v[38:41]
	v_mfma_f32_16x16x32_bf16 v[66:69], v[138:141], v[188:191], v[66:69]
	v_mfma_f32_16x16x32_bf16 v[62:65], v[146:149], v[188:191], v[62:65]
	v_mfma_f32_16x16x32_bf16 v[58:61], v[138:141], v[206:209], v[58:61]
	v_mfma_f32_16x16x32_bf16 v[54:57], v[146:149], v[206:209], v[54:57]
	v_mfma_f32_16x16x32_bf16 v[50:53], v[138:141], v[228:231], v[50:53]
	v_mfma_f32_16x16x32_bf16 v[46:49], v[146:149], v[228:231], v[46:49]
	v_mfma_f32_16x16x32_bf16 v[42:45], v[138:141], v[236:239], v[42:45]
	v_mfma_f32_16x16x32_bf16 v[38:41], v[146:149], v[236:239], v[38:41]
	s_setprio 0
	s_setprio 1
	v_mfma_f32_16x16x32_bf16 v[34:37], v[162:165], v[178:181], v[34:37]
	v_mfma_f32_16x16x32_bf16 v[30:33], v[170:173], v[178:181], v[30:33]
	v_mfma_f32_16x16x32_bf16 v[26:29], v[162:165], v[192:195], v[26:29]
	v_mfma_f32_16x16x32_bf16 v[22:25], v[170:173], v[192:195], v[22:25]
	v_mfma_f32_16x16x32_bf16 v[18:21], v[162:165], v[224:227], v[18:21]
	v_mfma_f32_16x16x32_bf16 v[14:17], v[170:173], v[224:227], v[14:17]
	v_mfma_f32_16x16x32_bf16 v[10:13], v[162:165], v[232:235], v[10:13]
	v_mfma_f32_16x16x32_bf16 v[4:7], v[170:173], v[232:235], v[6:9]
	v_mfma_f32_16x16x32_bf16 v[34:37], v[166:169], v[188:191], v[34:37]
	v_mfma_f32_16x16x32_bf16 v[30:33], v[174:177], v[188:191], v[30:33]
	v_mfma_f32_16x16x32_bf16 v[26:29], v[166:169], v[206:209], v[26:29]
	v_mfma_f32_16x16x32_bf16 v[22:25], v[174:177], v[206:209], v[22:25]
	v_mfma_f32_16x16x32_bf16 v[18:21], v[166:169], v[228:231], v[18:21]
	v_mfma_f32_16x16x32_bf16 v[14:17], v[174:177], v[228:231], v[14:17]
	v_mfma_f32_16x16x32_bf16 v[10:13], v[166:169], v[236:239], v[10:13]
	v_mfma_f32_16x16x32_bf16 v[4:7], v[174:177], v[236:239], v[4:7]
	s_setprio 0
	s_barrier
	s_add_i32 s23, 0, 0x18000
	v_add_u32_e32 v8, s23, v185
	s_add_i32 s24, 0, 0x1c000
	ds_read_b128 v[134:137], v8
	ds_read_b128 v[138:141], v8 offset:1024
	ds_read_b128 v[142:145], v8 offset:2048
	ds_read_b128 v[146:149], v8 offset:3072
	v_add_u32_e32 v8, s24, v185
	ds_read_b128 v[162:165], v8
	ds_read_b128 v[166:169], v8 offset:1024
	ds_read_b128 v[170:173], v8 offset:2048
	ds_read_b128 v[174:177], v8 offset:3072
	s_add_u32 s14, s14, 0x80000
	s_addc_u32 s15, s15, 0
	s_mov_b32 m0, s36
	ds_read_b128 v[178:181], v186 offset:32768
	ds_read_b128 v[188:191], v186 offset:33792
	ds_read_b128 v[192:195], v186 offset:34816
	ds_read_b128 v[206:209], v186 offset:35840
	ds_read_b128 v[224:227], v186 offset:36864
	ds_read_b128 v[228:231], v186 offset:37888
	ds_read_b128 v[232:235], v186 offset:38912
	ds_read_b128 v[236:239], v186 offset:39936
	s_add_u32 s100, s14, 0xfff80000
	s_addc_u32 s101, s15, -1
	s_mov_b32 m0, s50
	s_nop 0
	global_load_lds_dwordx4 v150, s[100:101]
	s_mov_b32 m0, s51
	s_nop 0
	global_load_lds_dwordx4 v154, s[100:101]
	s_mov_b32 m0, s36
	s_nop 0
	global_load_lds_dwordx4 v150, s[14:15]
	s_mov_b32 m0, s37
	s_nop 0
	global_load_lds_dwordx4 v154, s[14:15]
	s_waitcnt vmcnt(8)
	s_waitcnt lgkmcnt(0)
	s_barrier
; #define PG8_STAGE(bufoff, gbase, voff) do { _Pragma("unroll") for (int _i = 0; _i < 2; ++_i) \
;         __builtin_amdgcn_global_load_lds((const unsigned*)((const char*)(gbase) + (voff)[_i]), (LAS unsigned*)(lds + (bufoff) + ldsw + _i * 8192), 16, 0, 0); } while (0)
; #define PG8_LDA(dst, b, h) do { _Pragma("unroll") for (int m = 0; m < 4; ++m) _Pragma("unroll") for (int k = 0; k < 2; ++k) dst[m][k] = *(const LAS bf16x8*)(lds + PG8_SA(b, h) + aoff + m * 2048 + k * 1024); } while (0)
; #define PG8_MMA(ai, bj, At, Bt) do { __builtin_amdgcn_s_setprio(1); _Pragma("unroll") for (int m = 0; m < 4; ++m) _Pragma("unroll") for (int n = 0; n < 2; ++n) _Pragma("unroll") for (int k = 0; k < 2; ++k) \
;         acc[ai][bj][m][n] = __builtin_amdgcn_mfma_f32_16x16x32_bf16(Bt[n][k], At[m][k], acc[ai][bj][m][n], 0, 0, 0); __builtin_amdgcn_s_setprio(0); } while (0)
; #define PG8_WAIT_V(n) asm volatile("s_waitcnt vmcnt(" #n ")" ::: "memory")
; #define PG8_WAIT_L(n) asm volatile("s_waitcnt lgkmcnt(" #n ")" ::: "memory")
; #define PG8_BAR __builtin_amdgcn_s_barrier()
; #define PG8_SCHED __builtin_amdgcn_sched_barrier(0)
; template <class Epi, bool ALIGN_EPI = true>
; __device__ __forceinline__ void gemm_phase(LAS unsigned char* lds, const Gemm g, const Sched& S, const Epi& E) {
;     ...
;             PG8_WAIT_V(8); PG8_WAIT_L(0); PG8_BAR; PG8_MMA(0, 0, At, B0); PG8_MMA(0, 1, At, B1); PG8_BAR; PG8_SCHED;
;             PG8_LDA(At, 1, 1); PG8_STAGE(PG8_SB(1, 0), b3, voffB); PG8_STAGE(PG8_SB(1, 1), b3 + hstepB, voffB); PG8_STAGE(PG8_SA(1, 0), a3, voffA);
;             PG8_WAIT_V(8); PG8_WAIT_L(0); PG8_BAR; PG8_MMA(1, 0, At, B0); PG8_MMA(1, 1, At, B1); PG8_BAR; PG8_SCHED;
;         }
	s_setprio 1
	s_waitcnt lgkmcnt(0)
	v_mfma_f32_16x16x32_bf16 v[130:133], v[134:137], v[178:181], v[130:133]
	v_mfma_f32_16x16x32_bf16 v[126:129], v[142:145], v[178:181], v[126:129]
	v_mfma_f32_16x16x32_bf16 v[122:125], v[134:137], v[192:195], v[122:125]
	v_mfma_f32_16x16x32_bf16 v[118:121], v[142:145], v[192:195], v[118:121]
	v_mfma_f32_16x16x32_bf16 v[114:117], v[134:137], v[224:227], v[114:117]
	v_mfma_f32_16x16x32_bf16 v[110:113], v[142:145], v[224:227], v[110:113]
	v_mfma_f32_16x16x32_bf16 v[106:109], v[134:137], v[232:235], v[106:109]
	v_mfma_f32_16x16x32_bf16 v[102:105], v[142:145], v[232:235], v[102:105]
	v_mfma_f32_16x16x32_bf16 v[130:133], v[138:141], v[188:191], v[130:133]
	v_mfma_f32_16x16x32_bf16 v[126:129], v[146:149], v[188:191], v[126:129]
	v_mfma_f32_16x16x32_bf16 v[122:125], v[138:141], v[206:209], v[122:125]
	v_mfma_f32_16x16x32_bf16 v[118:121], v[146:149], v[206:209], v[118:121]
	v_mfma_f32_16x16x32_bf16 v[114:117], v[138:141], v[228:231], v[114:117]
	v_mfma_f32_16x16x32_bf16 v[110:113], v[146:149], v[228:231], v[110:113]
	v_mfma_f32_16x16x32_bf16 v[106:109], v[138:141], v[236:239], v[106:109]
	v_mfma_f32_16x16x32_bf16 v[102:105], v[146:149], v[236:239], v[102:105]
	s_setprio 0
	s_setprio 1
	v_mfma_f32_16x16x32_bf16 v[98:101], v[162:165], v[178:181], v[98:101]
	v_mfma_f32_16x16x32_bf16 v[94:97], v[170:173], v[178:181], v[94:97]
	v_mfma_f32_16x16x32_bf16 v[90:93], v[162:165], v[192:195], v[90:93]
	v_mfma_f32_16x16x32_bf16 v[86:89], v[170:173], v[192:195], v[86:89]
	v_mfma_f32_16x16x32_bf16 v[82:85], v[162:165], v[224:227], v[82:85]
	v_mfma_f32_16x16x32_bf16 v[78:81], v[170:173], v[224:227], v[78:81]
	v_mfma_f32_16x16x32_bf16 v[74:77], v[162:165], v[232:235], v[74:77]
	v_mfma_f32_16x16x32_bf16 v[70:73], v[170:173], v[232:235], v[70:73]
	v_mfma_f32_16x16x32_bf16 v[98:101], v[166:169], v[188:191], v[98:101]
	v_mfma_f32_16x16x32_bf16 v[94:97], v[174:177], v[188:191], v[94:97]
	v_mfma_f32_16x16x32_bf16 v[90:93], v[166:169], v[206:209], v[90:93]
	v_mfma_f32_16x16x32_bf16 v[86:89], v[174:177], v[206:209], v[86:89]
	v_mfma_f32_16x16x32_bf16 v[82:85], v[166:169], v[228:231], v[82:85]
	v_mfma_f32_16x16x32_bf16 v[78:81], v[174:177], v[228:231], v[78:81]
	v_mfma_f32_16x16x32_bf16 v[74:77], v[166:169], v[236:239], v[74:77]
	v_mfma_f32_16x16x32_bf16 v[70:73], v[174:177], v[236:239], v[70:73]
	s_setprio 0
	s_barrier
	s_add_u32 s100, s6, 0x80
	s_addc_u32 s101, s7, 0
	s_add_i32 s14, s23, s27
	s_mov_b32 m0, s14
	ds_read_b128 v[178:181], v186 offset:49152
	ds_read_b128 v[188:191], v186 offset:50176
	ds_read_b128 v[192:195], v186 offset:51200
	ds_read_b128 v[206:209], v186 offset:52224
	ds_read_b128 v[224:227], v186 offset:53248
	ds_read_b128 v[228:231], v186 offset:54272
	ds_read_b128 v[232:235], v186 offset:55296
	ds_read_b128 v[236:239], v186 offset:56320
	global_load_lds_dwordx4 v152, s[100:101]
	s_add_i32 m0, s14, 0x2000
	s_add_u32 s6, s6, 0x80080
	s_addc_u32 s7, s7, 0
	s_add_i32 s14, s24, s27
	global_load_lds_dwordx4 v156, s[100:101]
	s_mov_b32 m0, s14
	s_nop 0
	global_load_lds_dwordx4 v152, s[6:7]
	s_add_i32 m0, s14, 0x2000
	s_nop 0
	global_load_lds_dwordx4 v156, s[6:7]
	s_waitcnt vmcnt(6)
	s_waitcnt lgkmcnt(0)
	s_barrier
	s_setprio 1
	s_waitcnt lgkmcnt(0)
	v_mfma_f32_16x16x32_bf16 v[66:69], v[134:137], v[178:181], v[66:69]
	v_mfma_f32_16x16x32_bf16 v[62:65], v[142:145], v[178:181], v[62:65]
	v_mfma_f32_16x16x32_bf16 v[58:61], v[134:137], v[192:195], v[58:61]
	v_mfma_f32_16x16x32_bf16 v[54:57], v[142:145], v[192:195], v[54:57]
	v_mfma_f32_16x16x32_bf16 v[50:53], v[134:137], v[224:227], v[50:53]
	v_mfma_f32_16x16x32_bf16 v[46:49], v[142:145], v[224:227], v[46:49]
	v_mfma_f32_16x16x32_bf16 v[42:45], v[134:137], v[232:235], v[42:45]
	v_mfma_f32_16x16x32_bf16 v[38:41], v[142:145], v[232:235], v[38:41]
	v_mfma_f32_16x16x32_bf16 v[66:69], v[138:141], v[188:191], v[66:69]
	v_mfma_f32_16x16x32_bf16 v[62:65], v[146:149], v[188:191], v[62:65]
	v_mfma_f32_16x16x32_bf16 v[58:61], v[138:141], v[206:209], v[58:61]
	v_mfma_f32_16x16x32_bf16 v[54:57], v[146:149], v[206:209], v[54:57]
	v_mfma_f32_16x16x32_bf16 v[50:53], v[138:141], v[228:231], v[50:53]
	v_mfma_f32_16x16x32_bf16 v[46:49], v[146:149], v[228:231], v[46:49]
	v_mfma_f32_16x16x32_bf16 v[42:45], v[138:141], v[236:239], v[42:45]
	v_mfma_f32_16x16x32_bf16 v[38:41], v[146:149], v[236:239], v[38:41]
	s_setprio 0
	s_setprio 1
	v_mfma_f32_16x16x32_bf16 v[34:37], v[162:165], v[178:181], v[34:37]
	v_mfma_f32_16x16x32_bf16 v[30:33], v[170:173], v[178:181], v[30:33]
	v_mfma_f32_16x16x32_bf16 v[26:29], v[162:165], v[192:195], v[26:29]
	v_mfma_f32_16x16x32_bf16 v[22:25], v[170:173], v[192:195], v[22:25]
	v_mfma_f32_16x16x32_bf16 v[18:21], v[162:165], v[224:227], v[18:21]
	v_mfma_f32_16x16x32_bf16 v[14:17], v[170:173], v[224:227], v[14:17]
	v_mfma_f32_16x16x32_bf16 v[8:11], v[162:165], v[232:235], v[10:13]
	v_mfma_f32_16x16x32_bf16 v[4:7], v[170:173], v[232:235], v[4:7]
	v_mfma_f32_16x16x32_bf16 v[34:37], v[166:169], v[188:191], v[34:37]
	v_mfma_f32_16x16x32_bf16 v[30:33], v[174:177], v[188:191], v[30:33]
	v_mfma_f32_16x16x32_bf16 v[26:29], v[166:169], v[206:209], v[26:29]
	v_mfma_f32_16x16x32_bf16 v[22:25], v[174:177], v[206:209], v[22:25]
	v_mfma_f32_16x16x32_bf16 v[18:21], v[166:169], v[228:231], v[18:21]
	v_mfma_f32_16x16x32_bf16 v[14:17], v[174:177], v[228:231], v[14:17]
	v_mfma_f32_16x16x32_bf16 v[10:13], v[166:169], v[236:239], v[8:11]
	v_mfma_f32_16x16x32_bf16 v[6:9], v[174:177], v[236:239], v[4:7]
	s_setprio 0
	s_barrier
	s_add_u32 s4, s4, 0x100
	s_addc_u32 s5, s5, 0
	s_add_u32 s20, s20, 0x100
	s_addc_u32 s21, s21, 0
	s_cmp_ge_i32 s22, s46
	s_mov_b32 s6, s22
	s_cbranch_scc0 .LBB0_500

; #define PG8_STAGE(bufoff, gbase, voff) do { _Pragma("unroll") for (int _i = 0; _i < 2; ++_i) \
;         __builtin_amdgcn_global_load_lds((const unsigned*)((const char*)(gbase) + (voff)[_i]), (LAS unsigned*)(lds + (bufoff) + ldsw + _i * 8192), 16, 0, 0); } while (0)
; #define PG8_LDA(dst, b, h) do { _Pragma("unroll") for (int m = 0; m < 4; ++m) _Pragma("unroll") for (int k = 0; k < 2; ++k) dst[m][k] = *(const LAS bf16x8*)(lds + PG8_SA(b, h) + aoff + m * 2048 + k * 1024); } while (0)
; #define PG8_LDB(dst, b, h) do { _Pragma("unroll") for (int n = 0; n < 2; ++n) _Pragma("unroll") for (int k = 0; k < 2; ++k) dst[n][k] = *(const LAS bf16x8*)(lds + PG8_SB(b, h) + boff + n * 2048 + k * 1024); } while (0)
; #define PG8_MMA(ai, bj, At, Bt) do { __builtin_amdgcn_s_setprio(1); _Pragma("unroll") for (int m = 0; m < 4; ++m) _Pragma("unroll") for (int n = 0; n < 2; ++n) _Pragma("unroll") for (int k = 0; k < 2; ++k) \
;         acc[ai][bj][m][n] = __builtin_amdgcn_mfma_f32_16x16x32_bf16(Bt[n][k], At[m][k], acc[ai][bj][m][n], 0, 0, 0); __builtin_amdgcn_s_setprio(0); } while (0)
; #define PG8_WAIT_V(n) asm volatile("s_waitcnt vmcnt(" #n ")" ::: "memory")
; template <class Epi, bool ALIGN_EPI = true>
; __device__ __forceinline__ void gemm_phase(LAS unsigned char* lds, const Gemm g, const Sched& S, const Epi& E) {
;     ...
;         for (int t = t_lo; t < t_hi; t += 2) {
;             const bool last = (t == nt - 2);
;             const char* a1 = cA + (size_t)(t + 1) * kstep;
;             const char* a2 = last ? nA : cA + (size_t)(t + 2) * kstep; const char* b2 = last ? nB : cB + (size_t)(t + 2) * kstep;
;             const char* a3 = a2 + kstep; const char* b3 = b2 + kstep;
;             const int rflag = __builtin_amdgcn_readfirstlane(t | (int)(ui == 0));
;             PG8_LDB(B0, 0, 0); PG8_LDB(B1, 0, 1); PG8_SCHED; PG8_LDA(At, 0, 0); PG8_STAGE(PG8_SA(1, 1), a1 + hstepA, voffA);
;             if constexpr (Epi::NSTORES > 0) PG8_WAIT_RELAX(rflag, 8 + Epi::NSTORES); else PG8_WAIT_V(8);
;             PG8_WAIT_L(0); PG8_BAR; PG8_MMA(0, 0, At, B0); PG8_MMA(0, 1, At, B1); PG8_BAR; PG8_SCHED;
;             PG8_LDA(At, 0, 1); PG8_STAGE(PG8_SB(0, 0), b2, voffB); PG8_STAGE(PG8_SB(0, 1), b2 + hstepB, voffB); PG8_STAGE(PG8_SA(0, 0), a2, voffA);
;             if constexpr (Epi::NSTORES > 0) PG8_WAIT_RELAX(rflag, 8 + Epi::NSTORES); else PG8_WAIT_V(8);
.LBB0_752:
	s_add_i32 s69, s48, 2
	s_add_u32 s26, s40, 0xfffc0080
	s_addc_u32 s27, s41, -1
	s_add_i32 s70, 0, 0x10000
	s_cmp_eq_u32 s61, s48
	v_add_u32_e32 v133, s48, v132
	s_cselect_b32 s49, s19, s27
	s_cselect_b32 s48, s21, s26
	v_add_u32_e32 v146, s70, v163
	s_cselect_b32 s27, s65, s68
	s_cselect_b32 s26, s66, s67
	s_add_i32 s72, 0, 0x14000
	ds_read_b128 v[134:137], v146
	ds_read_b128 v[138:141], v146 offset:1024
	ds_read_b128 v[142:145], v146 offset:2048
	ds_read_b128 v[158:161], v146 offset:3072
	v_add_u32_e32 v146, s72, v163
	ds_read_b128 v[166:169], v146
	ds_read_b128 v[170:173], v146 offset:1024
	ds_read_b128 v[174:177], v146 offset:2048
	ds_read_b128 v[178:181], v146 offset:3072
	s_add_i32 m0, s36, 0xc000
	ds_read_b128 v[182:185], v164
	ds_read_b128 v[186:189], v164 offset:1024
	ds_read_b128 v[190:193], v164 offset:2048
	ds_read_b128 v[194:197], v164 offset:3072
	ds_read_b128 v[206:209], v164 offset:4096
	ds_read_b128 v[224:227], v164 offset:5120
	ds_read_b128 v[228:231], v164 offset:6144
	ds_read_b128 v[232:235], v164 offset:7168
	s_add_u32 s100, s40, 0xfffc0000
	s_addc_u32 s101, s41, -1
	s_mov_b32 m0, s59
	s_nop 0
	global_load_lds_dwordx4 v154, s[100:101]
	s_mov_b32 m0, s60
	s_nop 0
	global_load_lds_dwordx4 v156, s[100:101]
	s_add_i32 m0, s36, 0xc000
	s_nop 0
	global_load_lds_dwordx4 v154, s[40:41]
	s_add_i32 m0, s36, 0xe000
	v_readfirstlane_b32 s73, v133
	global_load_lds_dwordx4 v156, s[40:41]
	s_cmp_eq_u32 s73, 0
	s_cbranch_scc1 .Lrw8
	s_waitcnt vmcnt(8)
.Lrw8:
	s_waitcnt vmcnt(24)
	s_waitcnt lgkmcnt(0)
	s_barrier
	s_setprio 1
	s_waitcnt lgkmcnt(0)
	v_mfma_f32_16x16x32_bf16 v[128:131], v[134:137], v[182:185], v[128:131]
	v_mfma_f32_16x16x32_bf16 v[124:127], v[142:145], v[182:185], v[124:127]
	v_mfma_f32_16x16x32_bf16 v[112:115], v[134:137], v[190:193], v[112:115]
	v_mfma_f32_16x16x32_bf16 v[108:111], v[142:145], v[190:193], v[108:111]
	v_mfma_f32_16x16x32_bf16 v[96:99], v[134:137], v[206:209], v[96:99]
	v_mfma_f32_16x16x32_bf16 v[92:95], v[142:145], v[206:209], v[92:95]
	v_mfma_f32_16x16x32_bf16 v[80:83], v[134:137], v[228:231], v[80:83]
	v_mfma_f32_16x16x32_bf16 v[76:79], v[142:145], v[228:231], v[76:79]
	v_mfma_f32_16x16x32_bf16 v[128:131], v[138:141], v[186:189], v[128:131]
	v_mfma_f32_16x16x32_bf16 v[124:127], v[158:161], v[186:189], v[124:127]
	v_mfma_f32_16x16x32_bf16 v[112:115], v[138:141], v[194:197], v[112:115]
	v_mfma_f32_16x16x32_bf16 v[108:111], v[158:161], v[194:197], v[108:111]
	v_mfma_f32_16x16x32_bf16 v[96:99], v[138:141], v[224:227], v[96:99]
	v_mfma_f32_16x16x32_bf16 v[92:95], v[158:161], v[224:227], v[92:95]
	v_mfma_f32_16x16x32_bf16 v[80:83], v[138:141], v[232:235], v[80:83]
	v_mfma_f32_16x16x32_bf16 v[76:79], v[158:161], v[232:235], v[76:79]
	s_setprio 0
	s_setprio 1
	v_mfma_f32_16x16x32_bf16 v[120:123], v[166:169], v[182:185], v[120:123]
	v_mfma_f32_16x16x32_bf16 v[116:119], v[174:177], v[182:185], v[116:119]
	v_mfma_f32_16x16x32_bf16 v[104:107], v[166:169], v[190:193], v[104:107]
	v_mfma_f32_16x16x32_bf16 v[100:103], v[174:177], v[190:193], v[100:103]
	v_mfma_f32_16x16x32_bf16 v[88:91], v[166:169], v[206:209], v[88:91]
	v_mfma_f32_16x16x32_bf16 v[84:87], v[174:177], v[206:209], v[84:87]
	v_mfma_f32_16x16x32_bf16 v[72:75], v[166:169], v[228:231], v[72:75]
	v_mfma_f32_16x16x32_bf16 v[68:71], v[174:177], v[228:231], v[68:71]
	v_mfma_f32_16x16x32_bf16 v[120:123], v[170:173], v[186:189], v[120:123]
	v_mfma_f32_16x16x32_bf16 v[116:119], v[178:181], v[186:189], v[116:119]
	v_mfma_f32_16x16x32_bf16 v[104:107], v[170:173], v[194:197], v[104:107]
	v_mfma_f32_16x16x32_bf16 v[100:103], v[178:181], v[194:197], v[100:103]
	v_mfma_f32_16x16x32_bf16 v[88:91], v[170:173], v[224:227], v[88:91]
	v_mfma_f32_16x16x32_bf16 v[84:87], v[178:181], v[224:227], v[84:87]
	v_mfma_f32_16x16x32_bf16 v[72:75], v[170:173], v[232:235], v[72:75]
	v_mfma_f32_16x16x32_bf16 v[68:71], v[178:181], v[232:235], v[68:71]
	s_setprio 0
	s_barrier
	s_add_i32 s70, s70, s35
	s_mov_b32 m0, s70
	ds_read_b128 v[182:185], v164 offset:16384
	ds_read_b128 v[186:189], v164 offset:17408
	ds_read_b128 v[190:193], v164 offset:18432
	ds_read_b128 v[194:197], v164 offset:19456
	ds_read_b128 v[206:209], v164 offset:20480
	ds_read_b128 v[224:227], v164 offset:21504
	ds_read_b128 v[228:231], v164 offset:22528
	ds_read_b128 v[232:235], v164 offset:23552
	global_load_lds_dwordx4 v2, s[26:27]
	s_add_i32 m0, s70, 0x2000
	s_add_u32 s70, s26, 0x10000
	s_addc_u32 s71, s27, 0
	s_add_i32 s72, s72, s35
	global_load_lds_dwordx4 v148, s[26:27]
	s_mov_b32 m0, s72
	s_nop 0
	global_load_lds_dwordx4 v2, s[70:71]
	s_add_i32 m0, s72, 0x2000
	s_nop 0
	global_load_lds_dwordx4 v148, s[70:71]
	s_cmp_eq_u32 s73, 0
	s_cbranch_scc1 .Lrw9
	s_waitcnt vmcnt(6)
; #define PG8_STAGE(bufoff, gbase, voff) do { _Pragma("unroll") for (int _i = 0; _i < 2; ++_i) \
;         __builtin_amdgcn_global_load_lds((const unsigned*)((const char*)(gbase) + (voff)[_i]), (LAS unsigned*)(lds + (bufoff) + ldsw + _i * 8192), 16, 0, 0); } while (0)
; #define PG8_LDA(dst, b, h) do { _Pragma("unroll") for (int m = 0; m < 4; ++m) _Pragma("unroll") for (int k = 0; k < 2; ++k) dst[m][k] = *(const LAS bf16x8*)(lds + PG8_SA(b, h) + aoff + m * 2048 + k * 1024); } while (0)
; #define PG8_LDB(dst, b, h) do { _Pragma("unroll") for (int n = 0; n < 2; ++n) _Pragma("unroll") for (int k = 0; k < 2; ++k) dst[n][k] = *(const LAS bf16x8*)(lds + PG8_SB(b, h) + boff + n * 2048 + k * 1024); } while (0)
; #define PG8_MMA(ai, bj, At, Bt) do { __builtin_amdgcn_s_setprio(1); _Pragma("unroll") for (int m = 0; m < 4; ++m) _Pragma("unroll") for (int n = 0; n < 2; ++n) _Pragma("unroll") for (int k = 0; k < 2; ++k) \
;         acc[ai][bj][m][n] = __builtin_amdgcn_mfma_f32_16x16x32_bf16(Bt[n][k], At[m][k], acc[ai][bj][m][n], 0, 0, 0); __builtin_amdgcn_s_setprio(0); } while (0)
; #define PG8_WAIT_V(n) asm volatile("s_waitcnt vmcnt(" #n ")" ::: "memory")
; #define PG8_WAIT_L(n) asm volatile("s_waitcnt lgkmcnt(" #n ")" ::: "memory")
; #define PG8_BAR __builtin_amdgcn_s_barrier()
; #define PG8_SCHED __builtin_amdgcn_sched_barrier(0)
; template <class Epi, bool ALIGN_EPI = true>
; __device__ __forceinline__ void gemm_phase(LAS unsigned char* lds, const Gemm g, const Sched& S, const Epi& E) {
;     ...
;             PG8_WAIT_L(0); PG8_BAR; PG8_MMA(1, 0, At, B0); PG8_MMA(1, 1, At, B1); PG8_BAR; PG8_SCHED;
;             PG8_LDB(B0, 1, 0); PG8_LDB(B1, 1, 1); PG8_SCHED; PG8_LDA(At, 1, 0); PG8_STAGE(PG8_SA(0, 1), a2 + hstepA, voffA);
;             PG8_WAIT_V(8); PG8_WAIT_L(0); PG8_BAR; PG8_MMA(0, 0, At, B0); PG8_MMA(0, 1, At, B1); PG8_BAR; PG8_SCHED;
.Lrw9:
	s_waitcnt vmcnt(6)
	s_waitcnt lgkmcnt(0)
	s_barrier
	s_setprio 1
	s_waitcnt lgkmcnt(0)
	v_mfma_f32_16x16x32_bf16 v[64:67], v[134:137], v[182:185], v[64:67]
	v_mfma_f32_16x16x32_bf16 v[60:63], v[142:145], v[182:185], v[60:63]
	v_mfma_f32_16x16x32_bf16 v[48:51], v[134:137], v[190:193], v[48:51]
	v_mfma_f32_16x16x32_bf16 v[44:47], v[142:145], v[190:193], v[44:47]
	v_mfma_f32_16x16x32_bf16 v[32:35], v[134:137], v[206:209], v[32:35]
	v_mfma_f32_16x16x32_bf16 v[28:31], v[142:145], v[206:209], v[28:31]
	v_mfma_f32_16x16x32_bf16 v[16:19], v[134:137], v[228:231], v[16:19]
	v_mfma_f32_16x16x32_bf16 v[12:15], v[142:145], v[228:231], v[12:15]
	v_mfma_f32_16x16x32_bf16 v[64:67], v[138:141], v[186:189], v[64:67]
	v_mfma_f32_16x16x32_bf16 v[60:63], v[158:161], v[186:189], v[60:63]
	v_mfma_f32_16x16x32_bf16 v[48:51], v[138:141], v[194:197], v[48:51]
	v_mfma_f32_16x16x32_bf16 v[44:47], v[158:161], v[194:197], v[44:47]
	v_mfma_f32_16x16x32_bf16 v[32:35], v[138:141], v[224:227], v[32:35]
	v_mfma_f32_16x16x32_bf16 v[28:31], v[158:161], v[224:227], v[28:31]
	v_mfma_f32_16x16x32_bf16 v[16:19], v[138:141], v[232:235], v[16:19]
	v_mfma_f32_16x16x32_bf16 v[12:15], v[158:161], v[232:235], v[12:15]
	s_setprio 0
	s_setprio 1
	v_mfma_f32_16x16x32_bf16 v[56:59], v[166:169], v[182:185], v[56:59]
	v_mfma_f32_16x16x32_bf16 v[52:55], v[174:177], v[182:185], v[52:55]
	v_mfma_f32_16x16x32_bf16 v[40:43], v[166:169], v[190:193], v[40:43]
	v_mfma_f32_16x16x32_bf16 v[36:39], v[174:177], v[190:193], v[36:39]
	v_mfma_f32_16x16x32_bf16 v[24:27], v[166:169], v[206:209], v[24:27]
	v_mfma_f32_16x16x32_bf16 v[20:23], v[174:177], v[206:209], v[20:23]
	v_mfma_f32_16x16x32_bf16 v[8:11], v[166:169], v[228:231], v[8:11]
	v_mfma_f32_16x16x32_bf16 v[4:7], v[174:177], v[228:231], v[4:7]
	v_mfma_f32_16x16x32_bf16 v[56:59], v[170:173], v[186:189], v[56:59]
	v_mfma_f32_16x16x32_bf16 v[52:55], v[178:181], v[186:189], v[52:55]
	v_mfma_f32_16x16x32_bf16 v[40:43], v[170:173], v[194:197], v[40:43]
	v_mfma_f32_16x16x32_bf16 v[36:39], v[178:181], v[194:197], v[36:39]
	v_mfma_f32_16x16x32_bf16 v[24:27], v[170:173], v[224:227], v[24:27]
	v_mfma_f32_16x16x32_bf16 v[20:23], v[178:181], v[224:227], v[20:23]
	v_mfma_f32_16x16x32_bf16 v[8:11], v[170:173], v[232:235], v[8:11]
	v_mfma_f32_16x16x32_bf16 v[4:7], v[178:181], v[232:235], v[4:7]
	s_setprio 0
	s_barrier
	s_add_i32 s70, 0, 0x18000
	v_add_u32_e32 v133, s70, v163
	s_add_i32 s71, 0, 0x1c000
	ds_read_b128 v[134:137], v133
	ds_read_b128 v[138:141], v133 offset:1024
	ds_read_b128 v[142:145], v133 offset:2048
	ds_read_b128 v[158:161], v133 offset:3072
	v_add_u32_e32 v133, s71, v163
	ds_read_b128 v[166:169], v133
	ds_read_b128 v[170:173], v133 offset:1024
	ds_read_b128 v[174:177], v133 offset:2048
	ds_read_b128 v[178:181], v133 offset:3072
	s_add_u32 s48, s48, 0x40000
	s_addc_u32 s49, s49, 0
	s_mov_b32 m0, s50
	ds_read_b128 v[182:185], v164 offset:32768
	ds_read_b128 v[186:189], v164 offset:33792
	ds_read_b128 v[190:193], v164 offset:34816
	ds_read_b128 v[194:197], v164 offset:35840
	ds_read_b128 v[206:209], v164 offset:36864
	ds_read_b128 v[224:227], v164 offset:37888
	ds_read_b128 v[228:231], v164 offset:38912
	ds_read_b128 v[232:235], v164 offset:39936
	s_add_u32 s100, s48, 0xfffc0000
	s_addc_u32 s101, s49, -1
	s_mov_b32 m0, s36
	s_nop 0
	global_load_lds_dwordx4 v152, s[100:101]
	s_mov_b32 m0, s37
	s_nop 0
	global_load_lds_dwordx4 v150, s[100:101]
	s_mov_b32 m0, s50
	s_nop 0
	global_load_lds_dwordx4 v152, s[48:49]
	s_mov_b32 m0, s51
	s_nop 0
	global_load_lds_dwordx4 v150, s[48:49]
	s_waitcnt vmcnt(8)
	s_waitcnt lgkmcnt(0)
	s_barrier
; #define PG8_STAGE(bufoff, gbase, voff) do { _Pragma("unroll") for (int _i = 0; _i < 2; ++_i) \
;         __builtin_amdgcn_global_load_lds((const unsigned*)((const char*)(gbase) + (voff)[_i]), (LAS unsigned*)(lds + (bufoff) + ldsw + _i * 8192), 16, 0, 0); } while (0)
; #define PG8_LDA(dst, b, h) do { _Pragma("unroll") for (int m = 0; m < 4; ++m) _Pragma("unroll") for (int k = 0; k < 2; ++k) dst[m][k] = *(const LAS bf16x8*)(lds + PG8_SA(b, h) + aoff + m * 2048 + k * 1024); } while (0)
; #define PG8_MMA(ai, bj, At, Bt) do { __builtin_amdgcn_s_setprio(1); _Pragma("unroll") for (int m = 0; m < 4; ++m) _Pragma("unroll") for (int n = 0; n < 2; ++n) _Pragma("unroll") for (int k = 0; k < 2; ++k) \
;         acc[ai][bj][m][n] = __builtin_amdgcn_mfma_f32_16x16x32_bf16(Bt[n][k], At[m][k], acc[ai][bj][m][n], 0, 0, 0); __builtin_amdgcn_s_setprio(0); } while (0)
; #define PG8_WAIT_V(n) asm volatile("s_waitcnt vmcnt(" #n ")" ::: "memory")
; #define PG8_WAIT_L(n) asm volatile("s_waitcnt lgkmcnt(" #n ")" ::: "memory")
; #define PG8_BAR __builtin_amdgcn_s_barrier()
; #define PG8_SCHED __builtin_amdgcn_sched_barrier(0)
; template <class Epi, bool ALIGN_EPI = true>
; __device__ __forceinline__ void gemm_phase(LAS unsigned char* lds, const Gemm g, const Sched& S, const Epi& E) {
;     ...
;             PG8_WAIT_V(8); PG8_WAIT_L(0); PG8_BAR; PG8_MMA(0, 0, At, B0); PG8_MMA(0, 1, At, B1); PG8_BAR; PG8_SCHED;
;             PG8_LDA(At, 1, 1); PG8_STAGE(PG8_SB(1, 0), b3, voffB); PG8_STAGE(PG8_SB(1, 1), b3 + hstepB, voffB); PG8_STAGE(PG8_SA(1, 0), a3, voffA);
;             PG8_WAIT_V(8); PG8_WAIT_L(0); PG8_BAR; PG8_MMA(1, 0, At, B0); PG8_MMA(1, 1, At, B1); PG8_BAR; PG8_SCHED;
;         }
	s_setprio 1
	s_waitcnt lgkmcnt(0)
	v_mfma_f32_16x16x32_bf16 v[128:131], v[134:137], v[182:185], v[128:131]
	v_mfma_f32_16x16x32_bf16 v[124:127], v[142:145], v[182:185], v[124:127]
	v_mfma_f32_16x16x32_bf16 v[112:115], v[134:137], v[190:193], v[112:115]
	v_mfma_f32_16x16x32_bf16 v[108:111], v[142:145], v[190:193], v[108:111]
	v_mfma_f32_16x16x32_bf16 v[96:99], v[134:137], v[206:209], v[96:99]
	v_mfma_f32_16x16x32_bf16 v[92:95], v[142:145], v[206:209], v[92:95]
	v_mfma_f32_16x16x32_bf16 v[80:83], v[134:137], v[228:231], v[80:83]
	v_mfma_f32_16x16x32_bf16 v[76:79], v[142:145], v[228:231], v[76:79]
	v_mfma_f32_16x16x32_bf16 v[128:131], v[138:141], v[186:189], v[128:131]
	v_mfma_f32_16x16x32_bf16 v[124:127], v[158:161], v[186:189], v[124:127]
	v_mfma_f32_16x16x32_bf16 v[112:115], v[138:141], v[194:197], v[112:115]
	v_mfma_f32_16x16x32_bf16 v[108:111], v[158:161], v[194:197], v[108:111]
	v_mfma_f32_16x16x32_bf16 v[96:99], v[138:141], v[224:227], v[96:99]
	v_mfma_f32_16x16x32_bf16 v[92:95], v[158:161], v[224:227], v[92:95]
	v_mfma_f32_16x16x32_bf16 v[80:83], v[138:141], v[232:235], v[80:83]
	v_mfma_f32_16x16x32_bf16 v[76:79], v[158:161], v[232:235], v[76:79]
	s_setprio 0
	s_setprio 1
	v_mfma_f32_16x16x32_bf16 v[120:123], v[166:169], v[182:185], v[120:123]
	v_mfma_f32_16x16x32_bf16 v[116:119], v[174:177], v[182:185], v[116:119]
	v_mfma_f32_16x16x32_bf16 v[104:107], v[166:169], v[190:193], v[104:107]
	v_mfma_f32_16x16x32_bf16 v[100:103], v[174:177], v[190:193], v[100:103]
	v_mfma_f32_16x16x32_bf16 v[88:91], v[166:169], v[206:209], v[88:91]
	v_mfma_f32_16x16x32_bf16 v[84:87], v[174:177], v[206:209], v[84:87]
	v_mfma_f32_16x16x32_bf16 v[72:75], v[166:169], v[228:231], v[72:75]
	v_mfma_f32_16x16x32_bf16 v[68:71], v[174:177], v[228:231], v[68:71]
	v_mfma_f32_16x16x32_bf16 v[120:123], v[170:173], v[186:189], v[120:123]
	v_mfma_f32_16x16x32_bf16 v[116:119], v[178:181], v[186:189], v[116:119]
	v_mfma_f32_16x16x32_bf16 v[104:107], v[170:173], v[194:197], v[104:107]
	v_mfma_f32_16x16x32_bf16 v[100:103], v[178:181], v[194:197], v[100:103]
	v_mfma_f32_16x16x32_bf16 v[88:91], v[170:173], v[224:227], v[88:91]
	v_mfma_f32_16x16x32_bf16 v[84:87], v[178:181], v[224:227], v[84:87]
	v_mfma_f32_16x16x32_bf16 v[72:75], v[170:173], v[232:235], v[72:75]
	v_mfma_f32_16x16x32_bf16 v[68:71], v[178:181], v[232:235], v[68:71]
	s_setprio 0
	s_barrier
	s_add_u32 s100, s26, 0x80
	s_addc_u32 s101, s27, 0
	s_add_i32 s48, s70, s35
	s_mov_b32 m0, s48
	ds_read_b128 v[182:185], v164 offset:49152
	ds_read_b128 v[186:189], v164 offset:50176
	ds_read_b128 v[190:193], v164 offset:51200
	ds_read_b128 v[194:197], v164 offset:52224
	ds_read_b128 v[206:209], v164 offset:53248
	ds_read_b128 v[224:227], v164 offset:54272
	ds_read_b128 v[228:231], v164 offset:55296
	ds_read_b128 v[232:235], v164 offset:56320
	global_load_lds_dwordx4 v2, s[100:101]
	s_add_i32 m0, s48, 0x2000
	s_add_u32 s26, s26, 0x10080
	s_addc_u32 s27, s27, 0
	s_add_i32 s48, s71, s35
	global_load_lds_dwordx4 v148, s[100:101]
	s_mov_b32 m0, s48
	s_nop 0
	global_load_lds_dwordx4 v2, s[26:27]
	s_add_i32 m0, s48, 0x2000
	s_nop 0
	global_load_lds_dwordx4 v148, s[26:27]
	s_waitcnt vmcnt(6)
	s_waitcnt lgkmcnt(0)
	s_barrier
	s_setprio 1
	s_waitcnt lgkmcnt(0)
	v_mfma_f32_16x16x32_bf16 v[64:67], v[134:137], v[182:185], v[64:67]
	v_mfma_f32_16x16x32_bf16 v[60:63], v[142:145], v[182:185], v[60:63]
	v_mfma_f32_16x16x32_bf16 v[48:51], v[134:137], v[190:193], v[48:51]
	v_mfma_f32_16x16x32_bf16 v[44:47], v[142:145], v[190:193], v[44:47]
	v_mfma_f32_16x16x32_bf16 v[32:35], v[134:137], v[206:209], v[32:35]
	v_mfma_f32_16x16x32_bf16 v[28:31], v[142:145], v[206:209], v[28:31]
	v_mfma_f32_16x16x32_bf16 v[16:19], v[134:137], v[228:231], v[16:19]
	v_mfma_f32_16x16x32_bf16 v[12:15], v[142:145], v[228:231], v[12:15]
	v_mfma_f32_16x16x32_bf16 v[64:67], v[138:141], v[186:189], v[64:67]
	v_mfma_f32_16x16x32_bf16 v[60:63], v[158:161], v[186:189], v[60:63]
	v_mfma_f32_16x16x32_bf16 v[48:51], v[138:141], v[194:197], v[48:51]
	v_mfma_f32_16x16x32_bf16 v[44:47], v[158:161], v[194:197], v[44:47]
	v_mfma_f32_16x16x32_bf16 v[32:35], v[138:141], v[224:227], v[32:35]
	v_mfma_f32_16x16x32_bf16 v[28:31], v[158:161], v[224:227], v[28:31]
	v_mfma_f32_16x16x32_bf16 v[16:19], v[138:141], v[232:235], v[16:19]
	v_mfma_f32_16x16x32_bf16 v[12:15], v[158:161], v[232:235], v[12:15]
	s_setprio 0
	s_setprio 1
	v_mfma_f32_16x16x32_bf16 v[56:59], v[166:169], v[182:185], v[56:59]
	v_mfma_f32_16x16x32_bf16 v[52:55], v[174:177], v[182:185], v[52:55]
	v_mfma_f32_16x16x32_bf16 v[40:43], v[166:169], v[190:193], v[40:43]
	v_mfma_f32_16x16x32_bf16 v[36:39], v[174:177], v[190:193], v[36:39]
	v_mfma_f32_16x16x32_bf16 v[24:27], v[166:169], v[206:209], v[24:27]
	v_mfma_f32_16x16x32_bf16 v[20:23], v[174:177], v[206:209], v[20:23]
	v_mfma_f32_16x16x32_bf16 v[8:11], v[166:169], v[228:231], v[8:11]
	v_mfma_f32_16x16x32_bf16 v[4:7], v[174:177], v[228:231], v[4:7]
	v_mfma_f32_16x16x32_bf16 v[56:59], v[170:173], v[186:189], v[56:59]
	v_mfma_f32_16x16x32_bf16 v[52:55], v[178:181], v[186:189], v[52:55]
	v_mfma_f32_16x16x32_bf16 v[40:43], v[170:173], v[194:197], v[40:43]
	v_mfma_f32_16x16x32_bf16 v[36:39], v[178:181], v[194:197], v[36:39]
	v_mfma_f32_16x16x32_bf16 v[24:27], v[170:173], v[224:227], v[24:27]
	v_mfma_f32_16x16x32_bf16 v[20:23], v[178:181], v[224:227], v[20:23]
	v_mfma_f32_16x16x32_bf16 v[8:11], v[170:173], v[232:235], v[8:11]
	v_mfma_f32_16x16x32_bf16 v[4:7], v[178:181], v[232:235], v[4:7]
	s_setprio 0
	s_barrier
	s_add_u32 s40, s40, 0x100
	s_addc_u32 s41, s41, 0
	s_add_u32 s67, s67, 0x100
	s_addc_u32 s68, s68, 0
	s_cmp_ge_i32 s69, s54
	s_mov_b32 s48, s69
	s_cbranch_scc0 .LBB0_752

; #define PG8_STAGE(bufoff, gbase, voff) do { _Pragma("unroll") for (int _i = 0; _i < 2; ++_i) \
;         __builtin_amdgcn_global_load_lds((const unsigned*)((const char*)(gbase) + (voff)[_i]), (LAS unsigned*)(lds + (bufoff) + ldsw + _i * 8192), 16, 0, 0); } while (0)
; #define PG8_LDA(dst, b, h) do { _Pragma("unroll") for (int m = 0; m < 4; ++m) _Pragma("unroll") for (int k = 0; k < 2; ++k) dst[m][k] = *(const LAS bf16x8*)(lds + PG8_SA(b, h) + aoff + m * 2048 + k * 1024); } while (0)
; #define PG8_LDB(dst, b, h) do { _Pragma("unroll") for (int n = 0; n < 2; ++n) _Pragma("unroll") for (int k = 0; k < 2; ++k) dst[n][k] = *(const LAS bf16x8*)(lds + PG8_SB(b, h) + boff + n * 2048 + k * 1024); } while (0)
; #define PG8_MMA(ai, bj, At, Bt) do { __builtin_amdgcn_s_setprio(1); _Pragma("unroll") for (int m = 0; m < 4; ++m) _Pragma("unroll") for (int n = 0; n < 2; ++n) _Pragma("unroll") for (int k = 0; k < 2; ++k) \
;         acc[ai][bj][m][n] = __builtin_amdgcn_mfma_f32_16x16x32_bf16(Bt[n][k], At[m][k], acc[ai][bj][m][n], 0, 0, 0); __builtin_amdgcn_s_setprio(0); } while (0)
; #define PG8_WAIT_V(n) asm volatile("s_waitcnt vmcnt(" #n ")" ::: "memory")
; template <class Epi, bool ALIGN_EPI = true>
; __device__ __forceinline__ void gemm_phase(LAS unsigned char* lds, const Gemm g, const Sched& S, const Epi& E) {
;     ...
;         for (int t = t_lo; t < t_hi; t += 2) {
;             const bool last = (t == nt - 2);
;             const char* a1 = cA + (size_t)(t + 1) * kstep;
;             const char* a2 = last ? nA : cA + (size_t)(t + 2) * kstep; const char* b2 = last ? nB : cB + (size_t)(t + 2) * kstep;
;             const char* a3 = a2 + kstep; const char* b3 = b2 + kstep;
;             const int rflag = __builtin_amdgcn_readfirstlane(t | (int)(ui == 0));
;             PG8_LDB(B0, 0, 0); PG8_LDB(B1, 0, 1); PG8_SCHED; PG8_LDA(At, 0, 0); PG8_STAGE(PG8_SA(1, 1), a1 + hstepA, voffA);
;             if constexpr (Epi::NSTORES > 0) PG8_WAIT_RELAX(rflag, 8 + Epi::NSTORES); else PG8_WAIT_V(8);
;             PG8_WAIT_L(0); PG8_BAR; PG8_MMA(0, 0, At, B0); PG8_MMA(0, 1, At, B1); PG8_BAR; PG8_SCHED;
;             PG8_LDA(At, 0, 1); PG8_STAGE(PG8_SB(0, 0), b2, voffB); PG8_STAGE(PG8_SB(0, 1), b2 + hstepB, voffB); PG8_STAGE(PG8_SA(0, 0), a2, voffA);
;             if constexpr (Epi::NSTORES > 0) PG8_WAIT_RELAX(rflag, 8 + Epi::NSTORES); else PG8_WAIT_V(8);
.LBB0_919:
	s_add_i32 s65, s46, 2
	s_add_u32 s26, s40, 0xfffc0080
	s_addc_u32 s27, s41, -1
	s_add_i32 s66, 0, 0x10000
	s_cmp_eq_u32 s57, s46
	v_add_u32_e32 v133, s46, v132
	s_cselect_b32 s47, s17, s27
	s_cselect_b32 s46, s19, s26
	v_add_u32_e32 v146, s66, v163
	s_cselect_b32 s27, s61, s64
	s_cselect_b32 s26, s62, s63
	s_add_i32 s68, 0, 0x14000
	ds_read_b128 v[134:137], v146
	ds_read_b128 v[138:141], v146 offset:1024
	ds_read_b128 v[142:145], v146 offset:2048
	ds_read_b128 v[158:161], v146 offset:3072
	v_add_u32_e32 v146, s68, v163
	ds_read_b128 v[166:169], v146
	ds_read_b128 v[170:173], v146 offset:1024
	ds_read_b128 v[174:177], v146 offset:2048
	ds_read_b128 v[178:181], v146 offset:3072
	s_add_i32 m0, s36, 0xc000
	ds_read_b128 v[182:185], v164
	ds_read_b128 v[186:189], v164 offset:1024
	ds_read_b128 v[190:193], v164 offset:2048
	ds_read_b128 v[194:197], v164 offset:3072
	ds_read_b128 v[206:209], v164 offset:4096
	ds_read_b128 v[224:227], v164 offset:5120
	ds_read_b128 v[228:231], v164 offset:6144
	ds_read_b128 v[232:235], v164 offset:7168
	s_add_u32 s100, s40, 0xfffc0000
	s_addc_u32 s101, s41, -1
	s_mov_b32 m0, s55
	s_nop 0
	global_load_lds_dwordx4 v154, s[100:101]
	s_mov_b32 m0, s56
	s_nop 0
	global_load_lds_dwordx4 v156, s[100:101]
	s_add_i32 m0, s36, 0xc000
	s_nop 0
	global_load_lds_dwordx4 v154, s[40:41]
	s_add_i32 m0, s36, 0xe000
	v_readfirstlane_b32 s69, v133
	global_load_lds_dwordx4 v156, s[40:41]
	s_cmp_eq_u32 s69, 0
	s_cbranch_scc1 .Lrw10
	s_waitcnt vmcnt(8)
.Lrw10:
	s_waitcnt vmcnt(24)
	s_waitcnt lgkmcnt(0)
	s_barrier
	s_setprio 1
	s_waitcnt lgkmcnt(0)
	v_mfma_f32_16x16x32_bf16 v[128:131], v[134:137], v[182:185], v[128:131]
	v_mfma_f32_16x16x32_bf16 v[124:127], v[142:145], v[182:185], v[124:127]
	v_mfma_f32_16x16x32_bf16 v[112:115], v[134:137], v[190:193], v[112:115]
	v_mfma_f32_16x16x32_bf16 v[108:111], v[142:145], v[190:193], v[108:111]
	v_mfma_f32_16x16x32_bf16 v[96:99], v[134:137], v[206:209], v[96:99]
	v_mfma_f32_16x16x32_bf16 v[92:95], v[142:145], v[206:209], v[92:95]
	v_mfma_f32_16x16x32_bf16 v[80:83], v[134:137], v[228:231], v[80:83]
	v_mfma_f32_16x16x32_bf16 v[76:79], v[142:145], v[228:231], v[76:79]
	v_mfma_f32_16x16x32_bf16 v[128:131], v[138:141], v[186:189], v[128:131]
	v_mfma_f32_16x16x32_bf16 v[124:127], v[158:161], v[186:189], v[124:127]
	v_mfma_f32_16x16x32_bf16 v[112:115], v[138:141], v[194:197], v[112:115]
	v_mfma_f32_16x16x32_bf16 v[108:111], v[158:161], v[194:197], v[108:111]
	v_mfma_f32_16x16x32_bf16 v[96:99], v[138:141], v[224:227], v[96:99]
	v_mfma_f32_16x16x32_bf16 v[92:95], v[158:161], v[224:227], v[92:95]
	v_mfma_f32_16x16x32_bf16 v[80:83], v[138:141], v[232:235], v[80:83]
	v_mfma_f32_16x16x32_bf16 v[76:79], v[158:161], v[232:235], v[76:79]
	s_setprio 0
	s_setprio 1
	v_mfma_f32_16x16x32_bf16 v[120:123], v[166:169], v[182:185], v[120:123]
	v_mfma_f32_16x16x32_bf16 v[116:119], v[174:177], v[182:185], v[116:119]
	v_mfma_f32_16x16x32_bf16 v[104:107], v[166:169], v[190:193], v[104:107]
	v_mfma_f32_16x16x32_bf16 v[100:103], v[174:177], v[190:193], v[100:103]
	v_mfma_f32_16x16x32_bf16 v[88:91], v[166:169], v[206:209], v[88:91]
	v_mfma_f32_16x16x32_bf16 v[84:87], v[174:177], v[206:209], v[84:87]
	v_mfma_f32_16x16x32_bf16 v[72:75], v[166:169], v[228:231], v[72:75]
	v_mfma_f32_16x16x32_bf16 v[68:71], v[174:177], v[228:231], v[68:71]
	v_mfma_f32_16x16x32_bf16 v[120:123], v[170:173], v[186:189], v[120:123]
	v_mfma_f32_16x16x32_bf16 v[116:119], v[178:181], v[186:189], v[116:119]
	v_mfma_f32_16x16x32_bf16 v[104:107], v[170:173], v[194:197], v[104:107]
	v_mfma_f32_16x16x32_bf16 v[100:103], v[178:181], v[194:197], v[100:103]
	v_mfma_f32_16x16x32_bf16 v[88:91], v[170:173], v[224:227], v[88:91]
	v_mfma_f32_16x16x32_bf16 v[84:87], v[178:181], v[224:227], v[84:87]
	v_mfma_f32_16x16x32_bf16 v[72:75], v[170:173], v[232:235], v[72:75]
	v_mfma_f32_16x16x32_bf16 v[68:71], v[178:181], v[232:235], v[68:71]
	s_setprio 0
	s_barrier
	s_add_i32 s66, s66, s35
	s_mov_b32 m0, s66
	ds_read_b128 v[182:185], v164 offset:16384
	ds_read_b128 v[186:189], v164 offset:17408
	ds_read_b128 v[190:193], v164 offset:18432
	ds_read_b128 v[194:197], v164 offset:19456
	ds_read_b128 v[206:209], v164 offset:20480
	ds_read_b128 v[224:227], v164 offset:21504
	ds_read_b128 v[228:231], v164 offset:22528
	ds_read_b128 v[232:235], v164 offset:23552
	global_load_lds_dwordx4 v2, s[26:27]
	s_add_i32 m0, s66, 0x2000
	s_add_u32 s66, s26, 0x10000
	s_addc_u32 s67, s27, 0
	s_add_i32 s68, s68, s35
	global_load_lds_dwordx4 v148, s[26:27]
	s_mov_b32 m0, s68
	s_nop 0
	global_load_lds_dwordx4 v2, s[66:67]
	s_add_i32 m0, s68, 0x2000
	s_nop 0
	global_load_lds_dwordx4 v148, s[66:67]
	s_cmp_eq_u32 s69, 0
	s_cbranch_scc1 .Lrw11
	s_waitcnt vmcnt(6)
; #define PG8_STAGE(bufoff, gbase, voff) do { _Pragma("unroll") for (int _i = 0; _i < 2; ++_i) \
;         __builtin_amdgcn_global_load_lds((const unsigned*)((const char*)(gbase) + (voff)[_i]), (LAS unsigned*)(lds + (bufoff) + ldsw + _i * 8192), 16, 0, 0); } while (0)
; #define PG8_LDA(dst, b, h) do { _Pragma("unroll") for (int m = 0; m < 4; ++m) _Pragma("unroll") for (int k = 0; k < 2; ++k) dst[m][k] = *(const LAS bf16x8*)(lds + PG8_SA(b, h) + aoff + m * 2048 + k * 1024); } while (0)
; #define PG8_LDB(dst, b, h) do { _Pragma("unroll") for (int n = 0; n < 2; ++n) _Pragma("unroll") for (int k = 0; k < 2; ++k) dst[n][k] = *(const LAS bf16x8*)(lds + PG8_SB(b, h) + boff + n * 2048 + k * 1024); } while (0)
; #define PG8_MMA(ai, bj, At, Bt) do { __builtin_amdgcn_s_setprio(1); _Pragma("unroll") for (int m = 0; m < 4; ++m) _Pragma("unroll") for (int n = 0; n < 2; ++n) _Pragma("unroll") for (int k = 0; k < 2; ++k) \
;         acc[ai][bj][m][n] = __builtin_amdgcn_mfma_f32_16x16x32_bf16(Bt[n][k], At[m][k], acc[ai][bj][m][n], 0, 0, 0); __builtin_amdgcn_s_setprio(0); } while (0)
; #define PG8_WAIT_V(n) asm volatile("s_waitcnt vmcnt(" #n ")" ::: "memory")
; #define PG8_WAIT_L(n) asm volatile("s_waitcnt lgkmcnt(" #n ")" ::: "memory")
; #define PG8_BAR __builtin_amdgcn_s_barrier()
; #define PG8_SCHED __builtin_amdgcn_sched_barrier(0)
; template <class Epi, bool ALIGN_EPI = true>
; __device__ __forceinline__ void gemm_phase(LAS unsigned char* lds, const Gemm g, const Sched& S, const Epi& E) {
;     ...
;             PG8_WAIT_L(0); PG8_BAR; PG8_MMA(1, 0, At, B0); PG8_MMA(1, 1, At, B1); PG8_BAR; PG8_SCHED;
;             PG8_LDB(B0, 1, 0); PG8_LDB(B1, 1, 1); PG8_SCHED; PG8_LDA(At, 1, 0); PG8_STAGE(PG8_SA(0, 1), a2 + hstepA, voffA);
;             PG8_WAIT_V(8); PG8_WAIT_L(0); PG8_BAR; PG8_MMA(0, 0, At, B0); PG8_MMA(0, 1, At, B1); PG8_BAR; PG8_SCHED;
.Lrw11:
	s_waitcnt vmcnt(6)
	s_waitcnt lgkmcnt(0)
	s_barrier
	s_setprio 1
	s_waitcnt lgkmcnt(0)
	v_mfma_f32_16x16x32_bf16 v[64:67], v[134:137], v[182:185], v[64:67]
	v_mfma_f32_16x16x32_bf16 v[60:63], v[142:145], v[182:185], v[60:63]
	v_mfma_f32_16x16x32_bf16 v[48:51], v[134:137], v[190:193], v[48:51]
	v_mfma_f32_16x16x32_bf16 v[44:47], v[142:145], v[190:193], v[44:47]
	v_mfma_f32_16x16x32_bf16 v[32:35], v[134:137], v[206:209], v[32:35]
	v_mfma_f32_16x16x32_bf16 v[28:31], v[142:145], v[206:209], v[28:31]
	v_mfma_f32_16x16x32_bf16 v[16:19], v[134:137], v[228:231], v[16:19]
	v_mfma_f32_16x16x32_bf16 v[12:15], v[142:145], v[228:231], v[12:15]
	v_mfma_f32_16x16x32_bf16 v[64:67], v[138:141], v[186:189], v[64:67]
	v_mfma_f32_16x16x32_bf16 v[60:63], v[158:161], v[186:189], v[60:63]
	v_mfma_f32_16x16x32_bf16 v[48:51], v[138:141], v[194:197], v[48:51]
	v_mfma_f32_16x16x32_bf16 v[44:47], v[158:161], v[194:197], v[44:47]
	v_mfma_f32_16x16x32_bf16 v[32:35], v[138:141], v[224:227], v[32:35]
	v_mfma_f32_16x16x32_bf16 v[28:31], v[158:161], v[224:227], v[28:31]
	v_mfma_f32_16x16x32_bf16 v[16:19], v[138:141], v[232:235], v[16:19]
	v_mfma_f32_16x16x32_bf16 v[12:15], v[158:161], v[232:235], v[12:15]
	s_setprio 0
	s_setprio 1
	v_mfma_f32_16x16x32_bf16 v[56:59], v[166:169], v[182:185], v[56:59]
	v_mfma_f32_16x16x32_bf16 v[52:55], v[174:177], v[182:185], v[52:55]
	v_mfma_f32_16x16x32_bf16 v[40:43], v[166:169], v[190:193], v[40:43]
	v_mfma_f32_16x16x32_bf16 v[36:39], v[174:177], v[190:193], v[36:39]
	v_mfma_f32_16x16x32_bf16 v[24:27], v[166:169], v[206:209], v[24:27]
	v_mfma_f32_16x16x32_bf16 v[20:23], v[174:177], v[206:209], v[20:23]
	v_mfma_f32_16x16x32_bf16 v[8:11], v[166:169], v[228:231], v[8:11]
	v_mfma_f32_16x16x32_bf16 v[4:7], v[174:177], v[228:231], v[4:7]
	v_mfma_f32_16x16x32_bf16 v[56:59], v[170:173], v[186:189], v[56:59]
	v_mfma_f32_16x16x32_bf16 v[52:55], v[178:181], v[186:189], v[52:55]
	v_mfma_f32_16x16x32_bf16 v[40:43], v[170:173], v[194:197], v[40:43]
	v_mfma_f32_16x16x32_bf16 v[36:39], v[178:181], v[194:197], v[36:39]
	v_mfma_f32_16x16x32_bf16 v[24:27], v[170:173], v[224:227], v[24:27]
	v_mfma_f32_16x16x32_bf16 v[20:23], v[178:181], v[224:227], v[20:23]
	v_mfma_f32_16x16x32_bf16 v[8:11], v[170:173], v[232:235], v[8:11]
	v_mfma_f32_16x16x32_bf16 v[4:7], v[178:181], v[232:235], v[4:7]
	s_setprio 0
	s_barrier
	s_add_i32 s66, 0, 0x18000
	v_add_u32_e32 v133, s66, v163
	s_add_i32 s67, 0, 0x1c000
	ds_read_b128 v[134:137], v133
	ds_read_b128 v[138:141], v133 offset:1024
	ds_read_b128 v[142:145], v133 offset:2048
	ds_read_b128 v[158:161], v133 offset:3072
	v_add_u32_e32 v133, s67, v163
	ds_read_b128 v[166:169], v133
	ds_read_b128 v[170:173], v133 offset:1024
	ds_read_b128 v[174:177], v133 offset:2048
	ds_read_b128 v[178:181], v133 offset:3072
	s_add_u32 s46, s46, 0x40000
	s_addc_u32 s47, s47, 0
	s_mov_b32 m0, s48
	ds_read_b128 v[182:185], v164 offset:32768
	ds_read_b128 v[186:189], v164 offset:33792
	ds_read_b128 v[190:193], v164 offset:34816
	ds_read_b128 v[194:197], v164 offset:35840
	ds_read_b128 v[206:209], v164 offset:36864
	ds_read_b128 v[224:227], v164 offset:37888
	ds_read_b128 v[228:231], v164 offset:38912
	ds_read_b128 v[232:235], v164 offset:39936
	s_add_u32 s100, s46, 0xfffc0000
	s_addc_u32 s101, s47, -1
	s_mov_b32 m0, s36
	s_nop 0
	global_load_lds_dwordx4 v152, s[100:101]
	s_mov_b32 m0, s37
	s_nop 0
	global_load_lds_dwordx4 v150, s[100:101]
	s_mov_b32 m0, s48
	s_nop 0
	global_load_lds_dwordx4 v152, s[46:47]
	s_mov_b32 m0, s49
	s_nop 0
	global_load_lds_dwordx4 v150, s[46:47]
	s_waitcnt vmcnt(8)
	s_waitcnt lgkmcnt(0)
	s_barrier
; #define PG8_STAGE(bufoff, gbase, voff) do { _Pragma("unroll") for (int _i = 0; _i < 2; ++_i) \
;         __builtin_amdgcn_global_load_lds((const unsigned*)((const char*)(gbase) + (voff)[_i]), (LAS unsigned*)(lds + (bufoff) + ldsw + _i * 8192), 16, 0, 0); } while (0)
; #define PG8_LDA(dst, b, h) do { _Pragma("unroll") for (int m = 0; m < 4; ++m) _Pragma("unroll") for (int k = 0; k < 2; ++k) dst[m][k] = *(const LAS bf16x8*)(lds + PG8_SA(b, h) + aoff + m * 2048 + k * 1024); } while (0)
; #define PG8_MMA(ai, bj, At, Bt) do { __builtin_amdgcn_s_setprio(1); _Pragma("unroll") for (int m = 0; m < 4; ++m) _Pragma("unroll") for (int n = 0; n < 2; ++n) _Pragma("unroll") for (int k = 0; k < 2; ++k) \
;         acc[ai][bj][m][n] = __builtin_amdgcn_mfma_f32_16x16x32_bf16(Bt[n][k], At[m][k], acc[ai][bj][m][n], 0, 0, 0); __builtin_amdgcn_s_setprio(0); } while (0)
; #define PG8_WAIT_V(n) asm volatile("s_waitcnt vmcnt(" #n ")" ::: "memory")
; #define PG8_WAIT_L(n) asm volatile("s_waitcnt lgkmcnt(" #n ")" ::: "memory")
; #define PG8_BAR __builtin_amdgcn_s_barrier()
; #define PG8_SCHED __builtin_amdgcn_sched_barrier(0)
; template <class Epi, bool ALIGN_EPI = true>
; __device__ __forceinline__ void gemm_phase(LAS unsigned char* lds, const Gemm g, const Sched& S, const Epi& E) {
;     ...
;             PG8_WAIT_V(8); PG8_WAIT_L(0); PG8_BAR; PG8_MMA(0, 0, At, B0); PG8_MMA(0, 1, At, B1); PG8_BAR; PG8_SCHED;
;             PG8_LDA(At, 1, 1); PG8_STAGE(PG8_SB(1, 0), b3, voffB); PG8_STAGE(PG8_SB(1, 1), b3 + hstepB, voffB); PG8_STAGE(PG8_SA(1, 0), a3, voffA);
;             PG8_WAIT_V(8); PG8_WAIT_L(0); PG8_BAR; PG8_MMA(1, 0, At, B0); PG8_MMA(1, 1, At, B1); PG8_BAR; PG8_SCHED;
;         }
	s_setprio 1
	s_waitcnt lgkmcnt(0)
	v_mfma_f32_16x16x32_bf16 v[128:131], v[134:137], v[182:185], v[128:131]
	v_mfma_f32_16x16x32_bf16 v[124:127], v[142:145], v[182:185], v[124:127]
	v_mfma_f32_16x16x32_bf16 v[112:115], v[134:137], v[190:193], v[112:115]
	v_mfma_f32_16x16x32_bf16 v[108:111], v[142:145], v[190:193], v[108:111]
	v_mfma_f32_16x16x32_bf16 v[96:99], v[134:137], v[206:209], v[96:99]
	v_mfma_f32_16x16x32_bf16 v[92:95], v[142:145], v[206:209], v[92:95]
	v_mfma_f32_16x16x32_bf16 v[80:83], v[134:137], v[228:231], v[80:83]
	v_mfma_f32_16x16x32_bf16 v[76:79], v[142:145], v[228:231], v[76:79]
	v_mfma_f32_16x16x32_bf16 v[128:131], v[138:141], v[186:189], v[128:131]
	v_mfma_f32_16x16x32_bf16 v[124:127], v[158:161], v[186:189], v[124:127]
	v_mfma_f32_16x16x32_bf16 v[112:115], v[138:141], v[194:197], v[112:115]
	v_mfma_f32_16x16x32_bf16 v[108:111], v[158:161], v[194:197], v[108:111]
	v_mfma_f32_16x16x32_bf16 v[96:99], v[138:141], v[224:227], v[96:99]
	v_mfma_f32_16x16x32_bf16 v[92:95], v[158:161], v[224:227], v[92:95]
	v_mfma_f32_16x16x32_bf16 v[80:83], v[138:141], v[232:235], v[80:83]
	v_mfma_f32_16x16x32_bf16 v[76:79], v[158:161], v[232:235], v[76:79]
	s_setprio 0
	s_setprio 1
	v_mfma_f32_16x16x32_bf16 v[120:123], v[166:169], v[182:185], v[120:123]
	v_mfma_f32_16x16x32_bf16 v[116:119], v[174:177], v[182:185], v[116:119]
	v_mfma_f32_16x16x32_bf16 v[104:107], v[166:169], v[190:193], v[104:107]
	v_mfma_f32_16x16x32_bf16 v[100:103], v[174:177], v[190:193], v[100:103]
	v_mfma_f32_16x16x32_bf16 v[88:91], v[166:169], v[206:209], v[88:91]
	v_mfma_f32_16x16x32_bf16 v[84:87], v[174:177], v[206:209], v[84:87]
	v_mfma_f32_16x16x32_bf16 v[72:75], v[166:169], v[228:231], v[72:75]
	v_mfma_f32_16x16x32_bf16 v[68:71], v[174:177], v[228:231], v[68:71]
	v_mfma_f32_16x16x32_bf16 v[120:123], v[170:173], v[186:189], v[120:123]
	v_mfma_f32_16x16x32_bf16 v[116:119], v[178:181], v[186:189], v[116:119]
	v_mfma_f32_16x16x32_bf16 v[104:107], v[170:173], v[194:197], v[104:107]
	v_mfma_f32_16x16x32_bf16 v[100:103], v[178:181], v[194:197], v[100:103]
	v_mfma_f32_16x16x32_bf16 v[88:91], v[170:173], v[224:227], v[88:91]
	v_mfma_f32_16x16x32_bf16 v[84:87], v[178:181], v[224:227], v[84:87]
	v_mfma_f32_16x16x32_bf16 v[72:75], v[170:173], v[232:235], v[72:75]
	v_mfma_f32_16x16x32_bf16 v[68:71], v[178:181], v[232:235], v[68:71]
	s_setprio 0
	s_barrier
	s_add_u32 s100, s26, 0x80
	s_addc_u32 s101, s27, 0
	s_add_i32 s46, s66, s35
	s_mov_b32 m0, s46
	ds_read_b128 v[182:185], v164 offset:49152
	ds_read_b128 v[186:189], v164 offset:50176
	ds_read_b128 v[190:193], v164 offset:51200
	ds_read_b128 v[194:197], v164 offset:52224
	ds_read_b128 v[206:209], v164 offset:53248
	ds_read_b128 v[224:227], v164 offset:54272
	ds_read_b128 v[228:231], v164 offset:55296
	ds_read_b128 v[232:235], v164 offset:56320
	global_load_lds_dwordx4 v2, s[100:101]
	s_add_i32 m0, s46, 0x2000
	s_add_u32 s26, s26, 0x10080
	s_addc_u32 s27, s27, 0
	s_add_i32 s46, s67, s35
	global_load_lds_dwordx4 v148, s[100:101]
	s_mov_b32 m0, s46
	s_nop 0
	global_load_lds_dwordx4 v2, s[26:27]
	s_add_i32 m0, s46, 0x2000
	s_nop 0
	global_load_lds_dwordx4 v148, s[26:27]
	s_waitcnt vmcnt(6)
	s_waitcnt lgkmcnt(0)
	s_barrier
	s_setprio 1
	s_waitcnt lgkmcnt(0)
	v_mfma_f32_16x16x32_bf16 v[64:67], v[134:137], v[182:185], v[64:67]
	v_mfma_f32_16x16x32_bf16 v[60:63], v[142:145], v[182:185], v[60:63]
	v_mfma_f32_16x16x32_bf16 v[48:51], v[134:137], v[190:193], v[48:51]
	v_mfma_f32_16x16x32_bf16 v[44:47], v[142:145], v[190:193], v[44:47]
	v_mfma_f32_16x16x32_bf16 v[32:35], v[134:137], v[206:209], v[32:35]
	v_mfma_f32_16x16x32_bf16 v[28:31], v[142:145], v[206:209], v[28:31]
	v_mfma_f32_16x16x32_bf16 v[16:19], v[134:137], v[228:231], v[16:19]
	v_mfma_f32_16x16x32_bf16 v[12:15], v[142:145], v[228:231], v[12:15]
	v_mfma_f32_16x16x32_bf16 v[64:67], v[138:141], v[186:189], v[64:67]
	v_mfma_f32_16x16x32_bf16 v[60:63], v[158:161], v[186:189], v[60:63]
	v_mfma_f32_16x16x32_bf16 v[48:51], v[138:141], v[194:197], v[48:51]
	v_mfma_f32_16x16x32_bf16 v[44:47], v[158:161], v[194:197], v[44:47]
	v_mfma_f32_16x16x32_bf16 v[32:35], v[138:141], v[224:227], v[32:35]
	v_mfma_f32_16x16x32_bf16 v[28:31], v[158:161], v[224:227], v[28:31]
	v_mfma_f32_16x16x32_bf16 v[16:19], v[138:141], v[232:235], v[16:19]
	v_mfma_f32_16x16x32_bf16 v[12:15], v[158:161], v[232:235], v[12:15]
	s_setprio 0
	s_setprio 1
	v_mfma_f32_16x16x32_bf16 v[56:59], v[166:169], v[182:185], v[56:59]
	v_mfma_f32_16x16x32_bf16 v[52:55], v[174:177], v[182:185], v[52:55]
	v_mfma_f32_16x16x32_bf16 v[40:43], v[166:169], v[190:193], v[40:43]
	v_mfma_f32_16x16x32_bf16 v[36:39], v[174:177], v[190:193], v[36:39]
	v_mfma_f32_16x16x32_bf16 v[24:27], v[166:169], v[206:209], v[24:27]
	v_mfma_f32_16x16x32_bf16 v[20:23], v[174:177], v[206:209], v[20:23]
	v_mfma_f32_16x16x32_bf16 v[8:11], v[166:169], v[228:231], v[8:11]
	v_mfma_f32_16x16x32_bf16 v[4:7], v[174:177], v[228:231], v[4:7]
	v_mfma_f32_16x16x32_bf16 v[56:59], v[170:173], v[186:189], v[56:59]
	v_mfma_f32_16x16x32_bf16 v[52:55], v[178:181], v[186:189], v[52:55]
	v_mfma_f32_16x16x32_bf16 v[40:43], v[170:173], v[194:197], v[40:43]
	v_mfma_f32_16x16x32_bf16 v[36:39], v[178:181], v[194:197], v[36:39]
	v_mfma_f32_16x16x32_bf16 v[24:27], v[170:173], v[224:227], v[24:27]
	v_mfma_f32_16x16x32_bf16 v[20:23], v[178:181], v[224:227], v[20:23]
	v_mfma_f32_16x16x32_bf16 v[8:11], v[170:173], v[232:235], v[8:11]
	v_mfma_f32_16x16x32_bf16 v[4:7], v[178:181], v[232:235], v[4:7]
	s_setprio 0
	s_barrier
	s_add_u32 s40, s40, 0x100
	s_addc_u32 s41, s41, 0
	s_add_u32 s63, s63, 0x100
	s_addc_u32 s64, s64, 0
	s_cmp_ge_i32 s65, s52
	s_mov_b32 s46, s65
	s_cbranch_scc0 .LBB0_919

; #define PG8_STAGE(bufoff, gbase, voff) do { _Pragma("unroll") for (int _i = 0; _i < 2; ++_i) \
;         __builtin_amdgcn_global_load_lds((const unsigned*)((const char*)(gbase) + (voff)[_i]), (LAS unsigned*)(lds + (bufoff) + ldsw + _i * 8192), 16, 0, 0); } while (0)
; #define PG8_LDA(dst, b, h) do { _Pragma("unroll") for (int m = 0; m < 4; ++m) _Pragma("unroll") for (int k = 0; k < 2; ++k) dst[m][k] = *(const LAS bf16x8*)(lds + PG8_SA(b, h) + aoff + m * 2048 + k * 1024); } while (0)
; #define PG8_LDB(dst, b, h) do { _Pragma("unroll") for (int n = 0; n < 2; ++n) _Pragma("unroll") for (int k = 0; k < 2; ++k) dst[n][k] = *(const LAS bf16x8*)(lds + PG8_SB(b, h) + boff + n * 2048 + k * 1024); } while (0)
; #define PG8_MMA(ai, bj, At, Bt) do { __builtin_amdgcn_s_setprio(1); _Pragma("unroll") for (int m = 0; m < 4; ++m) _Pragma("unroll") for (int n = 0; n < 2; ++n) _Pragma("unroll") for (int k = 0; k < 2; ++k) \
;         acc[ai][bj][m][n] = __builtin_amdgcn_mfma_f32_16x16x32_bf16(Bt[n][k], At[m][k], acc[ai][bj][m][n], 0, 0, 0); __builtin_amdgcn_s_setprio(0); } while (0)
; #define PG8_WAIT_V(n) asm volatile("s_waitcnt vmcnt(" #n ")" ::: "memory")
; template <class Epi, bool ALIGN_EPI = true>
; __device__ __forceinline__ void gemm_phase(LAS unsigned char* lds, const Gemm g, const Sched& S, const Epi& E) {
;     ...
;         for (int t = t_lo; t < t_hi; t += 2) {
;             const bool last = (t == nt - 2);
;             const char* a1 = cA + (size_t)(t + 1) * kstep;
;             const char* a2 = last ? nA : cA + (size_t)(t + 2) * kstep; const char* b2 = last ? nB : cB + (size_t)(t + 2) * kstep;
;             const char* a3 = a2 + kstep; const char* b3 = b2 + kstep;
;             const int rflag = __builtin_amdgcn_readfirstlane(t | (int)(ui == 0));
;             PG8_LDB(B0, 0, 0); PG8_LDB(B1, 0, 1); PG8_SCHED; PG8_LDA(At, 0, 0); PG8_STAGE(PG8_SA(1, 1), a1 + hstepA, voffA);
;             if constexpr (Epi::NSTORES > 0) PG8_WAIT_RELAX(rflag, 8 + Epi::NSTORES); else PG8_WAIT_V(8);
;             PG8_WAIT_L(0); PG8_BAR; PG8_MMA(0, 0, At, B0); PG8_MMA(0, 1, At, B1); PG8_BAR; PG8_SCHED;
;             PG8_LDA(At, 0, 1); PG8_STAGE(PG8_SB(0, 0), b2, voffB); PG8_STAGE(PG8_SB(0, 1), b2 + hstepB, voffB); PG8_STAGE(PG8_SA(0, 0), a2, voffA);
;             if constexpr (Epi::NSTORES > 0) PG8_WAIT_RELAX(rflag, 8 + Epi::NSTORES); else PG8_WAIT_V(8);
.LBB0_954:
	s_add_i32 s22, s6, 2
	s_add_u32 s7, s4, 0xfff80080
	s_addc_u32 s14, s5, -1
	s_add_i32 s23, 0, 0x10000
	s_cmp_eq_u32 s88, s6
	v_add_u32_e32 v182, s6, v2
	s_cselect_b32 s15, s16, s14
	s_cselect_b32 s14, s17, s7
	s_waitcnt lgkmcnt(0)
	v_add_u32_e32 v4, s23, v185
	s_cselect_b32 s7, s18, s21
	s_cselect_b32 s6, s19, s20
	s_add_i32 s58, 0, 0x14000
	ds_read_b128 v[134:137], v4
	ds_read_b128 v[138:141], v4 offset:1024
	ds_read_b128 v[142:145], v4 offset:2048
	ds_read_b128 v[146:149], v4 offset:3072
	v_add_u32_e32 v4, s58, v185
	ds_read_b128 v[162:165], v4
	ds_read_b128 v[166:169], v4 offset:1024
	ds_read_b128 v[170:173], v4 offset:2048
	ds_read_b128 v[174:177], v4 offset:3072
	s_add_i32 m0, s48, 0xc000
	ds_read_b128 v[178:181], v186
	ds_read_b128 v[188:191], v186 offset:1024
	ds_read_b128 v[192:195], v186 offset:2048
	ds_read_b128 v[206:209], v186 offset:3072
	ds_read_b128 v[224:227], v186 offset:4096
	ds_read_b128 v[228:231], v186 offset:5120
	ds_read_b128 v[232:235], v186 offset:6144
	ds_read_b128 v[236:239], v186 offset:7168
	s_add_u32 s100, s4, 0xfff80000
	s_addc_u32 s101, s5, -1
	s_mov_b32 m0, s30
	s_nop 0
	global_load_lds_dwordx4 v158, s[100:101]
	s_mov_b32 m0, s33
	s_nop 0
	global_load_lds_dwordx4 v160, s[100:101]
	s_add_i32 m0, s48, 0xc000
	s_nop 0
	global_load_lds_dwordx4 v158, s[4:5]
	s_add_i32 m0, s48, 0xe000
	v_readfirstlane_b32 s59, v182
	global_load_lds_dwordx4 v160, s[4:5]
	s_cmp_eq_u32 s59, 0
	s_cbranch_scc1 .Lrw12
	s_waitcnt vmcnt(8)
.Lrw12:
	s_waitcnt vmcnt(24)
	s_waitcnt lgkmcnt(0)
	s_barrier
	s_setprio 1
	s_waitcnt lgkmcnt(0)
	v_mfma_f32_16x16x32_bf16 v[130:133], v[134:137], v[178:181], v[130:133]
	v_mfma_f32_16x16x32_bf16 v[126:129], v[142:145], v[178:181], v[126:129]
	v_mfma_f32_16x16x32_bf16 v[122:125], v[134:137], v[192:195], v[122:125]
	v_mfma_f32_16x16x32_bf16 v[118:121], v[142:145], v[192:195], v[118:121]
	v_mfma_f32_16x16x32_bf16 v[114:117], v[134:137], v[224:227], v[114:117]
	v_mfma_f32_16x16x32_bf16 v[110:113], v[142:145], v[224:227], v[110:113]
	v_mfma_f32_16x16x32_bf16 v[106:109], v[134:137], v[232:235], v[106:109]
	v_mfma_f32_16x16x32_bf16 v[102:105], v[142:145], v[232:235], v[102:105]
	v_mfma_f32_16x16x32_bf16 v[130:133], v[138:141], v[188:191], v[130:133]
	v_mfma_f32_16x16x32_bf16 v[126:129], v[146:149], v[188:191], v[126:129]
	v_mfma_f32_16x16x32_bf16 v[122:125], v[138:141], v[206:209], v[122:125]
	v_mfma_f32_16x16x32_bf16 v[118:121], v[146:149], v[206:209], v[118:121]
	v_mfma_f32_16x16x32_bf16 v[114:117], v[138:141], v[228:231], v[114:117]
	v_mfma_f32_16x16x32_bf16 v[110:113], v[146:149], v[228:231], v[110:113]
	v_mfma_f32_16x16x32_bf16 v[106:109], v[138:141], v[236:239], v[106:109]
	v_mfma_f32_16x16x32_bf16 v[102:105], v[146:149], v[236:239], v[102:105]
	s_setprio 0
	s_setprio 1
	v_mfma_f32_16x16x32_bf16 v[98:101], v[162:165], v[178:181], v[98:101]
	v_mfma_f32_16x16x32_bf16 v[94:97], v[170:173], v[178:181], v[94:97]
	v_mfma_f32_16x16x32_bf16 v[90:93], v[162:165], v[192:195], v[90:93]
	v_mfma_f32_16x16x32_bf16 v[86:89], v[170:173], v[192:195], v[86:89]
	v_mfma_f32_16x16x32_bf16 v[82:85], v[162:165], v[224:227], v[82:85]
	v_mfma_f32_16x16x32_bf16 v[78:81], v[170:173], v[224:227], v[78:81]
	v_mfma_f32_16x16x32_bf16 v[74:77], v[162:165], v[232:235], v[74:77]
	v_mfma_f32_16x16x32_bf16 v[70:73], v[170:173], v[232:235], v[70:73]
	v_mfma_f32_16x16x32_bf16 v[98:101], v[166:169], v[188:191], v[98:101]
	v_mfma_f32_16x16x32_bf16 v[94:97], v[174:177], v[188:191], v[94:97]
	v_mfma_f32_16x16x32_bf16 v[90:93], v[166:169], v[206:209], v[90:93]
	v_mfma_f32_16x16x32_bf16 v[86:89], v[174:177], v[206:209], v[86:89]
	v_mfma_f32_16x16x32_bf16 v[82:85], v[166:169], v[228:231], v[82:85]
	v_mfma_f32_16x16x32_bf16 v[78:81], v[174:177], v[228:231], v[78:81]
	v_mfma_f32_16x16x32_bf16 v[74:77], v[166:169], v[236:239], v[74:77]
	v_mfma_f32_16x16x32_bf16 v[70:73], v[174:177], v[236:239], v[70:73]
	s_setprio 0
	s_barrier
	s_add_i32 s23, s23, s94
	s_mov_b32 m0, s23
	ds_read_b128 v[178:181], v186 offset:16384
	ds_read_b128 v[188:191], v186 offset:17408
	ds_read_b128 v[192:195], v186 offset:18432
	ds_read_b128 v[206:209], v186 offset:19456
	ds_read_b128 v[224:227], v186 offset:20480
	ds_read_b128 v[228:231], v186 offset:21504
	ds_read_b128 v[232:235], v186 offset:22528
	ds_read_b128 v[236:239], v186 offset:23552
	global_load_lds_dwordx4 v152, s[6:7]
	s_add_i32 m0, s23, 0x2000
	s_add_u32 s24, s6, 0x80000
	s_addc_u32 s25, s7, 0
	s_add_i32 s23, s58, s94
	global_load_lds_dwordx4 v156, s[6:7]
	s_mov_b32 m0, s23
	s_nop 0
	global_load_lds_dwordx4 v152, s[24:25]
	s_add_i32 m0, s23, 0x2000
	s_nop 0
	global_load_lds_dwordx4 v156, s[24:25]
	s_cmp_eq_u32 s59, 0
	s_cbranch_scc1 .Lrw13
	s_waitcnt vmcnt(6)
; #define PG8_STAGE(bufoff, gbase, voff) do { _Pragma("unroll") for (int _i = 0; _i < 2; ++_i) \
;         __builtin_amdgcn_global_load_lds((const unsigned*)((const char*)(gbase) + (voff)[_i]), (LAS unsigned*)(lds + (bufoff) + ldsw + _i * 8192), 16, 0, 0); } while (0)
; #define PG8_LDA(dst, b, h) do { _Pragma("unroll") for (int m = 0; m < 4; ++m) _Pragma("unroll") for (int k = 0; k < 2; ++k) dst[m][k] = *(const LAS bf16x8*)(lds + PG8_SA(b, h) + aoff + m * 2048 + k * 1024); } while (0)
; #define PG8_LDB(dst, b, h) do { _Pragma("unroll") for (int n = 0; n < 2; ++n) _Pragma("unroll") for (int k = 0; k < 2; ++k) dst[n][k] = *(const LAS bf16x8*)(lds + PG8_SB(b, h) + boff + n * 2048 + k * 1024); } while (0)
; #define PG8_MMA(ai, bj, At, Bt) do { __builtin_amdgcn_s_setprio(1); _Pragma("unroll") for (int m = 0; m < 4; ++m) _Pragma("unroll") for (int n = 0; n < 2; ++n) _Pragma("unroll") for (int k = 0; k < 2; ++k) \
;         acc[ai][bj][m][n] = __builtin_amdgcn_mfma_f32_16x16x32_bf16(Bt[n][k], At[m][k], acc[ai][bj][m][n], 0, 0, 0); __builtin_amdgcn_s_setprio(0); } while (0)
; #define PG8_WAIT_V(n) asm volatile("s_waitcnt vmcnt(" #n ")" ::: "memory")
; #define PG8_WAIT_L(n) asm volatile("s_waitcnt lgkmcnt(" #n ")" ::: "memory")
; #define PG8_BAR __builtin_amdgcn_s_barrier()
; #define PG8_SCHED __builtin_amdgcn_sched_barrier(0)
; template <class Epi, bool ALIGN_EPI = true>
; __device__ __forceinline__ void gemm_phase(LAS unsigned char* lds, const Gemm g, const Sched& S, const Epi& E) {
;     ...
;             PG8_WAIT_L(0); PG8_BAR; PG8_MMA(1, 0, At, B0); PG8_MMA(1, 1, At, B1); PG8_BAR; PG8_SCHED;
;             PG8_LDB(B0, 1, 0); PG8_LDB(B1, 1, 1); PG8_SCHED; PG8_LDA(At, 1, 0); PG8_STAGE(PG8_SA(0, 1), a2 + hstepA, voffA);
;             PG8_WAIT_V(8); PG8_WAIT_L(0); PG8_BAR; PG8_MMA(0, 0, At, B0); PG8_MMA(0, 1, At, B1); PG8_BAR; PG8_SCHED;
.Lrw13:
	s_waitcnt vmcnt(6)
	s_waitcnt lgkmcnt(0)
	s_barrier
	s_setprio 1
	s_waitcnt lgkmcnt(0)
	v_mfma_f32_16x16x32_bf16 v[66:69], v[134:137], v[178:181], v[66:69]
	v_mfma_f32_16x16x32_bf16 v[62:65], v[142:145], v[178:181], v[62:65]
	v_mfma_f32_16x16x32_bf16 v[58:61], v[134:137], v[192:195], v[58:61]
	v_mfma_f32_16x16x32_bf16 v[54:57], v[142:145], v[192:195], v[54:57]
	v_mfma_f32_16x16x32_bf16 v[50:53], v[134:137], v[224:227], v[50:53]
	v_mfma_f32_16x16x32_bf16 v[46:49], v[142:145], v[224:227], v[46:49]
	v_mfma_f32_16x16x32_bf16 v[42:45], v[134:137], v[232:235], v[42:45]
	v_mfma_f32_16x16x32_bf16 v[38:41], v[142:145], v[232:235], v[38:41]
	v_mfma_f32_16x16x32_bf16 v[66:69], v[138:141], v[188:191], v[66:69]
	v_mfma_f32_16x16x32_bf16 v[62:65], v[146:149], v[188:191], v[62:65]
	v_mfma_f32_16x16x32_bf16 v[58:61], v[138:141], v[206:209], v[58:61]
	v_mfma_f32_16x16x32_bf16 v[54:57], v[146:149], v[206:209], v[54:57]
	v_mfma_f32_16x16x32_bf16 v[50:53], v[138:141], v[228:231], v[50:53]
	v_mfma_f32_16x16x32_bf16 v[46:49], v[146:149], v[228:231], v[46:49]
	v_mfma_f32_16x16x32_bf16 v[42:45], v[138:141], v[236:239], v[42:45]
	v_mfma_f32_16x16x32_bf16 v[38:41], v[146:149], v[236:239], v[38:41]
	s_setprio 0
	s_setprio 1
	v_mfma_f32_16x16x32_bf16 v[34:37], v[162:165], v[178:181], v[34:37]
	v_mfma_f32_16x16x32_bf16 v[30:33], v[170:173], v[178:181], v[30:33]
	v_mfma_f32_16x16x32_bf16 v[26:29], v[162:165], v[192:195], v[26:29]
	v_mfma_f32_16x16x32_bf16 v[22:25], v[170:173], v[192:195], v[22:25]
	v_mfma_f32_16x16x32_bf16 v[18:21], v[162:165], v[224:227], v[18:21]
	v_mfma_f32_16x16x32_bf16 v[14:17], v[170:173], v[224:227], v[14:17]
	v_mfma_f32_16x16x32_bf16 v[10:13], v[162:165], v[232:235], v[10:13]
	v_mfma_f32_16x16x32_bf16 v[4:7], v[170:173], v[232:235], v[6:9]
	v_mfma_f32_16x16x32_bf16 v[34:37], v[166:169], v[188:191], v[34:37]
	v_mfma_f32_16x16x32_bf16 v[30:33], v[174:177], v[188:191], v[30:33]
	v_mfma_f32_16x16x32_bf16 v[26:29], v[166:169], v[206:209], v[26:29]
	v_mfma_f32_16x16x32_bf16 v[22:25], v[174:177], v[206:209], v[22:25]
	v_mfma_f32_16x16x32_bf16 v[18:21], v[166:169], v[228:231], v[18:21]
	v_mfma_f32_16x16x32_bf16 v[14:17], v[174:177], v[228:231], v[14:17]
	v_mfma_f32_16x16x32_bf16 v[10:13], v[166:169], v[236:239], v[10:13]
	v_mfma_f32_16x16x32_bf16 v[4:7], v[174:177], v[236:239], v[4:7]
	s_setprio 0
	s_barrier
	s_add_i32 s23, 0, 0x18000
	v_add_u32_e32 v8, s23, v185
	s_add_i32 s24, 0, 0x1c000
	ds_read_b128 v[134:137], v8
	ds_read_b128 v[138:141], v8 offset:1024
	ds_read_b128 v[142:145], v8 offset:2048
	ds_read_b128 v[146:149], v8 offset:3072
	v_add_u32_e32 v8, s24, v185
	ds_read_b128 v[162:165], v8
	ds_read_b128 v[166:169], v8 offset:1024
	ds_read_b128 v[170:173], v8 offset:2048
	ds_read_b128 v[174:177], v8 offset:3072
	s_add_u32 s14, s14, 0x80000
	s_addc_u32 s15, s15, 0
	s_mov_b32 m0, s46
	ds_read_b128 v[178:181], v186 offset:32768
	ds_read_b128 v[188:191], v186 offset:33792
	ds_read_b128 v[192:195], v186 offset:34816
	ds_read_b128 v[206:209], v186 offset:35840
	ds_read_b128 v[224:227], v186 offset:36864
	ds_read_b128 v[228:231], v186 offset:37888
	ds_read_b128 v[232:235], v186 offset:38912
	ds_read_b128 v[236:239], v186 offset:39936
	s_add_u32 s100, s14, 0xfff80000
	s_addc_u32 s101, s15, -1
	s_mov_b32 m0, s48
	s_nop 0
	global_load_lds_dwordx4 v150, s[100:101]
	s_mov_b32 m0, s49
	s_nop 0
	global_load_lds_dwordx4 v154, s[100:101]
	s_mov_b32 m0, s46
	s_nop 0
	global_load_lds_dwordx4 v150, s[14:15]
	s_mov_b32 m0, s47
	s_nop 0
	global_load_lds_dwordx4 v154, s[14:15]
	s_waitcnt vmcnt(8)
	s_waitcnt lgkmcnt(0)
	s_barrier
; #define PG8_STAGE(bufoff, gbase, voff) do { _Pragma("unroll") for (int _i = 0; _i < 2; ++_i) \
;         __builtin_amdgcn_global_load_lds((const unsigned*)((const char*)(gbase) + (voff)[_i]), (LAS unsigned*)(lds + (bufoff) + ldsw + _i * 8192), 16, 0, 0); } while (0)
; #define PG8_LDA(dst, b, h) do { _Pragma("unroll") for (int m = 0; m < 4; ++m) _Pragma("unroll") for (int k = 0; k < 2; ++k) dst[m][k] = *(const LAS bf16x8*)(lds + PG8_SA(b, h) + aoff + m * 2048 + k * 1024); } while (0)
; #define PG8_MMA(ai, bj, At, Bt) do { __builtin_amdgcn_s_setprio(1); _Pragma("unroll") for (int m = 0; m < 4; ++m) _Pragma("unroll") for (int n = 0; n < 2; ++n) _Pragma("unroll") for (int k = 0; k < 2; ++k) \
;         acc[ai][bj][m][n] = __builtin_amdgcn_mfma_f32_16x16x32_bf16(Bt[n][k], At[m][k], acc[ai][bj][m][n], 0, 0, 0); __builtin_amdgcn_s_setprio(0); } while (0)
; #define PG8_WAIT_V(n) asm volatile("s_waitcnt vmcnt(" #n ")" ::: "memory")
; #define PG8_WAIT_L(n) asm volatile("s_waitcnt lgkmcnt(" #n ")" ::: "memory")
; #define PG8_BAR __builtin_amdgcn_s_barrier()
; #define PG8_SCHED __builtin_amdgcn_sched_barrier(0)
; template <class Epi, bool ALIGN_EPI = true>
; __device__ __forceinline__ void gemm_phase(LAS unsigned char* lds, const Gemm g, const Sched& S, const Epi& E) {
;     ...
;             PG8_WAIT_V(8); PG8_WAIT_L(0); PG8_BAR; PG8_MMA(0, 0, At, B0); PG8_MMA(0, 1, At, B1); PG8_BAR; PG8_SCHED;
;             PG8_LDA(At, 1, 1); PG8_STAGE(PG8_SB(1, 0), b3, voffB); PG8_STAGE(PG8_SB(1, 1), b3 + hstepB, voffB); PG8_STAGE(PG8_SA(1, 0), a3, voffA);
;             PG8_WAIT_V(8); PG8_WAIT_L(0); PG8_BAR; PG8_MMA(1, 0, At, B0); PG8_MMA(1, 1, At, B1); PG8_BAR; PG8_SCHED;
;         }
	s_setprio 1
	s_waitcnt lgkmcnt(0)
	v_mfma_f32_16x16x32_bf16 v[130:133], v[134:137], v[178:181], v[130:133]
	v_mfma_f32_16x16x32_bf16 v[126:129], v[142:145], v[178:181], v[126:129]
	v_mfma_f32_16x16x32_bf16 v[122:125], v[134:137], v[192:195], v[122:125]
	v_mfma_f32_16x16x32_bf16 v[118:121], v[142:145], v[192:195], v[118:121]
	v_mfma_f32_16x16x32_bf16 v[114:117], v[134:137], v[224:227], v[114:117]
	v_mfma_f32_16x16x32_bf16 v[110:113], v[142:145], v[224:227], v[110:113]
	v_mfma_f32_16x16x32_bf16 v[106:109], v[134:137], v[232:235], v[106:109]
	v_mfma_f32_16x16x32_bf16 v[102:105], v[142:145], v[232:235], v[102:105]
	v_mfma_f32_16x16x32_bf16 v[130:133], v[138:141], v[188:191], v[130:133]
	v_mfma_f32_16x16x32_bf16 v[126:129], v[146:149], v[188:191], v[126:129]
	v_mfma_f32_16x16x32_bf16 v[122:125], v[138:141], v[206:209], v[122:125]
	v_mfma_f32_16x16x32_bf16 v[118:121], v[146:149], v[206:209], v[118:121]
	v_mfma_f32_16x16x32_bf16 v[114:117], v[138:141], v[228:231], v[114:117]
	v_mfma_f32_16x16x32_bf16 v[110:113], v[146:149], v[228:231], v[110:113]
	v_mfma_f32_16x16x32_bf16 v[106:109], v[138:141], v[236:239], v[106:109]
	v_mfma_f32_16x16x32_bf16 v[102:105], v[146:149], v[236:239], v[102:105]
	s_setprio 0
	s_setprio 1
	v_mfma_f32_16x16x32_bf16 v[98:101], v[162:165], v[178:181], v[98:101]
	v_mfma_f32_16x16x32_bf16 v[94:97], v[170:173], v[178:181], v[94:97]
	v_mfma_f32_16x16x32_bf16 v[90:93], v[162:165], v[192:195], v[90:93]
	v_mfma_f32_16x16x32_bf16 v[86:89], v[170:173], v[192:195], v[86:89]
	v_mfma_f32_16x16x32_bf16 v[82:85], v[162:165], v[224:227], v[82:85]
	v_mfma_f32_16x16x32_bf16 v[78:81], v[170:173], v[224:227], v[78:81]
	v_mfma_f32_16x16x32_bf16 v[74:77], v[162:165], v[232:235], v[74:77]
	v_mfma_f32_16x16x32_bf16 v[70:73], v[170:173], v[232:235], v[70:73]
	v_mfma_f32_16x16x32_bf16 v[98:101], v[166:169], v[188:191], v[98:101]
	v_mfma_f32_16x16x32_bf16 v[94:97], v[174:177], v[188:191], v[94:97]
	v_mfma_f32_16x16x32_bf16 v[90:93], v[166:169], v[206:209], v[90:93]
	v_mfma_f32_16x16x32_bf16 v[86:89], v[174:177], v[206:209], v[86:89]
	v_mfma_f32_16x16x32_bf16 v[82:85], v[166:169], v[228:231], v[82:85]
	v_mfma_f32_16x16x32_bf16 v[78:81], v[174:177], v[228:231], v[78:81]
	v_mfma_f32_16x16x32_bf16 v[74:77], v[166:169], v[236:239], v[74:77]
	v_mfma_f32_16x16x32_bf16 v[70:73], v[174:177], v[236:239], v[70:73]
	s_setprio 0
	s_barrier
	s_add_u32 s100, s6, 0x80
	s_addc_u32 s101, s7, 0
	s_add_i32 s14, s23, s94
	s_mov_b32 m0, s14
	ds_read_b128 v[178:181], v186 offset:49152
	ds_read_b128 v[188:191], v186 offset:50176
	ds_read_b128 v[192:195], v186 offset:51200
	ds_read_b128 v[206:209], v186 offset:52224
	ds_read_b128 v[224:227], v186 offset:53248
	ds_read_b128 v[228:231], v186 offset:54272
	ds_read_b128 v[232:235], v186 offset:55296
	ds_read_b128 v[236:239], v186 offset:56320
	global_load_lds_dwordx4 v152, s[100:101]
	s_add_i32 m0, s14, 0x2000
	s_add_u32 s6, s6, 0x80080
	s_addc_u32 s7, s7, 0
	s_add_i32 s14, s24, s94
	global_load_lds_dwordx4 v156, s[100:101]
	s_mov_b32 m0, s14
	s_nop 0
	global_load_lds_dwordx4 v152, s[6:7]
	s_add_i32 m0, s14, 0x2000
	s_nop 0
	global_load_lds_dwordx4 v156, s[6:7]
	s_waitcnt vmcnt(6)
	s_waitcnt lgkmcnt(0)
	s_barrier
	s_setprio 1
	s_waitcnt lgkmcnt(0)
	v_mfma_f32_16x16x32_bf16 v[66:69], v[134:137], v[178:181], v[66:69]
	v_mfma_f32_16x16x32_bf16 v[62:65], v[142:145], v[178:181], v[62:65]
	v_mfma_f32_16x16x32_bf16 v[58:61], v[134:137], v[192:195], v[58:61]
	v_mfma_f32_16x16x32_bf16 v[54:57], v[142:145], v[192:195], v[54:57]
	v_mfma_f32_16x16x32_bf16 v[50:53], v[134:137], v[224:227], v[50:53]
	v_mfma_f32_16x16x32_bf16 v[46:49], v[142:145], v[224:227], v[46:49]
	v_mfma_f32_16x16x32_bf16 v[42:45], v[134:137], v[232:235], v[42:45]
	v_mfma_f32_16x16x32_bf16 v[38:41], v[142:145], v[232:235], v[38:41]
	v_mfma_f32_16x16x32_bf16 v[66:69], v[138:141], v[188:191], v[66:69]
	v_mfma_f32_16x16x32_bf16 v[62:65], v[146:149], v[188:191], v[62:65]
	v_mfma_f32_16x16x32_bf16 v[58:61], v[138:141], v[206:209], v[58:61]
	v_mfma_f32_16x16x32_bf16 v[54:57], v[146:149], v[206:209], v[54:57]
	v_mfma_f32_16x16x32_bf16 v[50:53], v[138:141], v[228:231], v[50:53]
	v_mfma_f32_16x16x32_bf16 v[46:49], v[146:149], v[228:231], v[46:49]
	v_mfma_f32_16x16x32_bf16 v[42:45], v[138:141], v[236:239], v[42:45]
	v_mfma_f32_16x16x32_bf16 v[38:41], v[146:149], v[236:239], v[38:41]
	s_setprio 0
	s_setprio 1
	v_mfma_f32_16x16x32_bf16 v[34:37], v[162:165], v[178:181], v[34:37]
	v_mfma_f32_16x16x32_bf16 v[30:33], v[170:173], v[178:181], v[30:33]
	v_mfma_f32_16x16x32_bf16 v[26:29], v[162:165], v[192:195], v[26:29]
	v_mfma_f32_16x16x32_bf16 v[22:25], v[170:173], v[192:195], v[22:25]
	v_mfma_f32_16x16x32_bf16 v[18:21], v[162:165], v[224:227], v[18:21]
	v_mfma_f32_16x16x32_bf16 v[14:17], v[170:173], v[224:227], v[14:17]
	v_mfma_f32_16x16x32_bf16 v[8:11], v[162:165], v[232:235], v[10:13]
	v_mfma_f32_16x16x32_bf16 v[4:7], v[170:173], v[232:235], v[4:7]
	v_mfma_f32_16x16x32_bf16 v[34:37], v[166:169], v[188:191], v[34:37]
	v_mfma_f32_16x16x32_bf16 v[30:33], v[174:177], v[188:191], v[30:33]
	v_mfma_f32_16x16x32_bf16 v[26:29], v[166:169], v[206:209], v[26:29]
	v_mfma_f32_16x16x32_bf16 v[22:25], v[174:177], v[206:209], v[22:25]
	v_mfma_f32_16x16x32_bf16 v[18:21], v[166:169], v[228:231], v[18:21]
	v_mfma_f32_16x16x32_bf16 v[14:17], v[174:177], v[228:231], v[14:17]
	v_mfma_f32_16x16x32_bf16 v[10:13], v[166:169], v[236:239], v[8:11]
	v_mfma_f32_16x16x32_bf16 v[6:9], v[174:177], v[236:239], v[4:7]
	s_setprio 0
	s_barrier
	s_add_u32 s4, s4, 0x100
	s_addc_u32 s5, s5, 0
	s_add_u32 s20, s20, 0x100
	s_addc_u32 s21, s21, 0
	s_cmp_ge_i32 s22, s31
	s_mov_b32 s6, s22
	s_cbranch_scc0 .LBB0_954

; #define PG8_STAGE(bufoff, gbase, voff) do { _Pragma("unroll") for (int _i = 0; _i < 2; ++_i) \
;         __builtin_amdgcn_global_load_lds((const unsigned*)((const char*)(gbase) + (voff)[_i]), (LAS unsigned*)(lds + (bufoff) + ldsw + _i * 8192), 16, 0, 0); } while (0)
; #define PG8_LDA(dst, b, h) do { _Pragma("unroll") for (int m = 0; m < 4; ++m) _Pragma("unroll") for (int k = 0; k < 2; ++k) dst[m][k] = *(const LAS bf16x8*)(lds + PG8_SA(b, h) + aoff + m * 2048 + k * 1024); } while (0)
; #define PG8_LDB(dst, b, h) do { _Pragma("unroll") for (int n = 0; n < 2; ++n) _Pragma("unroll") for (int k = 0; k < 2; ++k) dst[n][k] = *(const LAS bf16x8*)(lds + PG8_SB(b, h) + boff + n * 2048 + k * 1024); } while (0)
; #define PG8_MMA(ai, bj, At, Bt) do { __builtin_amdgcn_s_setprio(1); _Pragma("unroll") for (int m = 0; m < 4; ++m) _Pragma("unroll") for (int n = 0; n < 2; ++n) _Pragma("unroll") for (int k = 0; k < 2; ++k) \
;         acc[ai][bj][m][n] = __builtin_amdgcn_mfma_f32_16x16x32_bf16(Bt[n][k], At[m][k], acc[ai][bj][m][n], 0, 0, 0); __builtin_amdgcn_s_setprio(0); } while (0)
; #define PG8_WAIT_V(n) asm volatile("s_waitcnt vmcnt(" #n ")" ::: "memory")
; template <class Epi, bool ALIGN_EPI = true>
; __device__ __forceinline__ void gemm_phase(LAS unsigned char* lds, const Gemm g, const Sched& S, const Epi& E) {
;     ...
;         for (int t = t_lo; t < t_hi; t += 2) {
;             const bool last = (t == nt - 2);
;             const char* a1 = cA + (size_t)(t + 1) * kstep;
;             const char* a2 = last ? nA : cA + (size_t)(t + 2) * kstep; const char* b2 = last ? nB : cB + (size_t)(t + 2) * kstep;
;             const char* a3 = a2 + kstep; const char* b3 = b2 + kstep;
;             const int rflag = __builtin_amdgcn_readfirstlane(t | (int)(ui == 0));
;             PG8_LDB(B0, 0, 0); PG8_LDB(B1, 0, 1); PG8_SCHED; PG8_LDA(At, 0, 0); PG8_STAGE(PG8_SA(1, 1), a1 + hstepA, voffA);
;             if constexpr (Epi::NSTORES > 0) PG8_WAIT_RELAX(rflag, 8 + Epi::NSTORES); else PG8_WAIT_V(8);
;             PG8_WAIT_L(0); PG8_BAR; PG8_MMA(0, 0, At, B0); PG8_MMA(0, 1, At, B1); PG8_BAR; PG8_SCHED;
;             PG8_LDA(At, 0, 1); PG8_STAGE(PG8_SB(0, 0), b2, voffB); PG8_STAGE(PG8_SB(0, 1), b2 + hstepB, voffB); PG8_STAGE(PG8_SA(0, 0), a2, voffA);
;             if constexpr (Epi::NSTORES > 0) PG8_WAIT_RELAX(rflag, 8 + Epi::NSTORES); else PG8_WAIT_V(8);
.LBB0_1237:
	s_add_i32 s94, s24, 1
	s_lshl_b64 s[92:93], s[94:95], 7
	s_add_i32 s94, s24, 2
	s_lshl_b64 s[26:27], s[94:95], 7
	s_add_u32 s25, s56, s26
	s_addc_u32 s91, s57, s27
	s_add_u32 s96, s54, s26
	s_addc_u32 s97, s55, s27
	s_add_i32 vcc_lo, 0, 0x10000
	s_cmp_eq_u32 s85, s24
	s_cselect_b32 s27, s19, s91
	s_cselect_b32 s26, s87, s25
	v_add_u32_e32 v2, vcc_lo, v224
	s_cselect_b32 s25, s88, s97
	s_cselect_b32 s24, s89, s96
	s_add_i32 s91, 0, 0x14000
	ds_read_b128 v[134:137], v2
	ds_read_b128 v[138:141], v2 offset:1024
	ds_read_b128 v[142:145], v2 offset:2048
	ds_read_b128 v[146:149], v2 offset:3072
	v_add_u32_e32 v2, s91, v224
	ds_read_b128 v[150:153], v2
	ds_read_b128 v[154:157], v2 offset:1024
	ds_read_b128 v[158:161], v2 offset:2048
	ds_read_b128 v[162:165], v2 offset:3072
	s_add_u32 s92, s56, s92
	s_addc_u32 s93, s57, s93
	s_add_u32 s92, s92, 0x80000
	s_addc_u32 s93, s93, 0
	s_add_i32 m0, s36, 0xc000
	ds_read_b128 v[166:169], v225
	ds_read_b128 v[170:173], v225 offset:1024
	ds_read_b128 v[174:177], v225 offset:2048
	ds_read_b128 v[178:181], v225 offset:3072
	ds_read_b128 v[182:185], v225 offset:4096
	ds_read_b128 v[186:189], v225 offset:5120
	ds_read_b128 v[190:193], v225 offset:6144
	ds_read_b128 v[226:229], v225 offset:7168
	s_add_u32 s100, s92, 0xfff80000
	s_addc_u32 s101, s93, -1
	s_mov_b32 m0, s81
	s_nop 0
	global_load_lds_dwordx4 v208, s[100:101]
	s_mov_b32 m0, s82
	s_nop 0
	global_load_lds_dwordx4 v196, s[100:101]
	s_add_i32 m0, s36, 0xc000
	s_nop 0
	global_load_lds_dwordx4 v208, s[92:93]
	s_add_i32 m0, s36, 0xe000
	s_nop 0
	global_load_lds_dwordx4 v196, s[92:93]
	s_waitcnt vmcnt(8)
	s_waitcnt lgkmcnt(0)
	s_barrier
	s_setprio 1
	s_waitcnt lgkmcnt(0)
	v_mfma_f32_16x16x32_bf16 v[130:133], v[134:137], v[166:169], v[130:133]
	v_mfma_f32_16x16x32_bf16 v[126:129], v[142:145], v[166:169], v[126:129]
	v_mfma_f32_16x16x32_bf16 v[114:117], v[134:137], v[174:177], v[114:117]
	v_mfma_f32_16x16x32_bf16 v[110:113], v[142:145], v[174:177], v[110:113]
	v_mfma_f32_16x16x32_bf16 v[98:101], v[134:137], v[182:185], v[98:101]
	v_mfma_f32_16x16x32_bf16 v[94:97], v[142:145], v[182:185], v[94:97]
	v_mfma_f32_16x16x32_bf16 v[82:85], v[134:137], v[190:193], v[82:85]
	v_mfma_f32_16x16x32_bf16 v[78:81], v[142:145], v[190:193], v[78:81]
	v_mfma_f32_16x16x32_bf16 v[130:133], v[138:141], v[170:173], v[130:133]
	v_mfma_f32_16x16x32_bf16 v[126:129], v[146:149], v[170:173], v[126:129]
	v_mfma_f32_16x16x32_bf16 v[114:117], v[138:141], v[178:181], v[114:117]
	v_mfma_f32_16x16x32_bf16 v[110:113], v[146:149], v[178:181], v[110:113]
	v_mfma_f32_16x16x32_bf16 v[98:101], v[138:141], v[186:189], v[98:101]
	v_mfma_f32_16x16x32_bf16 v[94:97], v[146:149], v[186:189], v[94:97]
	v_mfma_f32_16x16x32_bf16 v[82:85], v[138:141], v[226:229], v[82:85]
	v_mfma_f32_16x16x32_bf16 v[78:81], v[146:149], v[226:229], v[78:81]
	s_setprio 0
	s_setprio 1
	v_mfma_f32_16x16x32_bf16 v[122:125], v[150:153], v[166:169], v[122:125]
	v_mfma_f32_16x16x32_bf16 v[118:121], v[158:161], v[166:169], v[118:121]
	v_mfma_f32_16x16x32_bf16 v[106:109], v[150:153], v[174:177], v[106:109]
	v_mfma_f32_16x16x32_bf16 v[102:105], v[158:161], v[174:177], v[102:105]
	v_mfma_f32_16x16x32_bf16 v[90:93], v[150:153], v[182:185], v[90:93]
	v_mfma_f32_16x16x32_bf16 v[86:89], v[158:161], v[182:185], v[86:89]
	v_mfma_f32_16x16x32_bf16 v[74:77], v[150:153], v[190:193], v[74:77]
	v_mfma_f32_16x16x32_bf16 v[70:73], v[158:161], v[190:193], v[70:73]
	v_mfma_f32_16x16x32_bf16 v[122:125], v[154:157], v[170:173], v[122:125]
	v_mfma_f32_16x16x32_bf16 v[118:121], v[162:165], v[170:173], v[118:121]
	v_mfma_f32_16x16x32_bf16 v[106:109], v[154:157], v[178:181], v[106:109]
	v_mfma_f32_16x16x32_bf16 v[102:105], v[162:165], v[178:181], v[102:105]
	v_mfma_f32_16x16x32_bf16 v[90:93], v[154:157], v[186:189], v[90:93]
	v_mfma_f32_16x16x32_bf16 v[86:89], v[162:165], v[186:189], v[86:89]
	v_mfma_f32_16x16x32_bf16 v[74:77], v[154:157], v[226:229], v[74:77]
	v_mfma_f32_16x16x32_bf16 v[70:73], v[162:165], v[226:229], v[70:73]
	s_setprio 0
	s_barrier
	s_add_i32 s92, vcc_lo, s35
	s_mov_b32 m0, s92
	ds_read_b128 v[166:169], v225 offset:16384
	ds_read_b128 v[170:173], v225 offset:17408
	ds_read_b128 v[174:177], v225 offset:18432
	ds_read_b128 v[178:181], v225 offset:19456
	ds_read_b128 v[182:185], v225 offset:20480
	ds_read_b128 v[186:189], v225 offset:21504
	ds_read_b128 v[190:193], v225 offset:22528
	ds_read_b128 v[226:229], v225 offset:23552
	global_load_lds_dwordx4 v206, s[24:25]
	s_add_i32 m0, s92, 0x2000
	s_add_u32 s92, s24, 0x80000
	s_addc_u32 s93, s25, 0
	s_add_i32 s91, s91, s35
	global_load_lds_dwordx4 v194, s[24:25]
	s_mov_b32 m0, s91
	s_nop 0
	global_load_lds_dwordx4 v206, s[92:93]
	s_add_i32 m0, s91, 0x2000
	s_nop 0
	global_load_lds_dwordx4 v194, s[92:93]
	s_waitcnt vmcnt(6)
	s_waitcnt lgkmcnt(0)
	s_barrier
; #define PG8_STAGE(bufoff, gbase, voff) do { _Pragma("unroll") for (int _i = 0; _i < 2; ++_i) \
;         __builtin_amdgcn_global_load_lds((const unsigned*)((const char*)(gbase) + (voff)[_i]), (LAS unsigned*)(lds + (bufoff) + ldsw + _i * 8192), 16, 0, 0); } while (0)
; #define PG8_LDA(dst, b, h) do { _Pragma("unroll") for (int m = 0; m < 4; ++m) _Pragma("unroll") for (int k = 0; k < 2; ++k) dst[m][k] = *(const LAS bf16x8*)(lds + PG8_SA(b, h) + aoff + m * 2048 + k * 1024); } while (0)
; #define PG8_LDB(dst, b, h) do { _Pragma("unroll") for (int n = 0; n < 2; ++n) _Pragma("unroll") for (int k = 0; k < 2; ++k) dst[n][k] = *(const LAS bf16x8*)(lds + PG8_SB(b, h) + boff + n * 2048 + k * 1024); } while (0)
; #define PG8_MMA(ai, bj, At, Bt) do { __builtin_amdgcn_s_setprio(1); _Pragma("unroll") for (int m = 0; m < 4; ++m) _Pragma("unroll") for (int n = 0; n < 2; ++n) _Pragma("unroll") for (int k = 0; k < 2; ++k) \
;         acc[ai][bj][m][n] = __builtin_amdgcn_mfma_f32_16x16x32_bf16(Bt[n][k], At[m][k], acc[ai][bj][m][n], 0, 0, 0); __builtin_amdgcn_s_setprio(0); } while (0)
; #define PG8_WAIT_V(n) asm volatile("s_waitcnt vmcnt(" #n ")" ::: "memory")
; #define PG8_WAIT_L(n) asm volatile("s_waitcnt lgkmcnt(" #n ")" ::: "memory")
; #define PG8_BAR __builtin_amdgcn_s_barrier()
; #define PG8_SCHED __builtin_amdgcn_sched_barrier(0)
; template <class Epi, bool ALIGN_EPI = true>
; __device__ __forceinline__ void gemm_phase(LAS unsigned char* lds, const Gemm g, const Sched& S, const Epi& E) {
;     ...
;             PG8_WAIT_L(0); PG8_BAR; PG8_MMA(1, 0, At, B0); PG8_MMA(1, 1, At, B1); PG8_BAR; PG8_SCHED;
;             PG8_LDB(B0, 1, 0); PG8_LDB(B1, 1, 1); PG8_SCHED; PG8_LDA(At, 1, 0); PG8_STAGE(PG8_SA(0, 1), a2 + hstepA, voffA);
;             PG8_WAIT_V(8); PG8_WAIT_L(0); PG8_BAR; PG8_MMA(0, 0, At, B0); PG8_MMA(0, 1, At, B1); PG8_BAR; PG8_SCHED;
	s_setprio 1
	s_waitcnt lgkmcnt(0)
	v_mfma_f32_16x16x32_bf16 v[66:69], v[134:137], v[166:169], v[66:69]
	v_mfma_f32_16x16x32_bf16 v[62:65], v[142:145], v[166:169], v[62:65]
	v_mfma_f32_16x16x32_bf16 v[50:53], v[134:137], v[174:177], v[50:53]
	v_mfma_f32_16x16x32_bf16 v[46:49], v[142:145], v[174:177], v[46:49]
	v_mfma_f32_16x16x32_bf16 v[34:37], v[134:137], v[182:185], v[34:37]
	v_mfma_f32_16x16x32_bf16 v[30:33], v[142:145], v[182:185], v[30:33]
	v_mfma_f32_16x16x32_bf16 v[18:21], v[134:137], v[190:193], v[18:21]
	v_mfma_f32_16x16x32_bf16 v[14:17], v[142:145], v[190:193], v[14:17]
	v_mfma_f32_16x16x32_bf16 v[66:69], v[138:141], v[170:173], v[66:69]
	v_mfma_f32_16x16x32_bf16 v[62:65], v[146:149], v[170:173], v[62:65]
	v_mfma_f32_16x16x32_bf16 v[50:53], v[138:141], v[178:181], v[50:53]
	v_mfma_f32_16x16x32_bf16 v[46:49], v[146:149], v[178:181], v[46:49]
	v_mfma_f32_16x16x32_bf16 v[34:37], v[138:141], v[186:189], v[34:37]
	v_mfma_f32_16x16x32_bf16 v[30:33], v[146:149], v[186:189], v[30:33]
	v_mfma_f32_16x16x32_bf16 v[18:21], v[138:141], v[226:229], v[18:21]
	v_mfma_f32_16x16x32_bf16 v[14:17], v[146:149], v[226:229], v[14:17]
	s_setprio 0
	s_setprio 1
	v_mfma_f32_16x16x32_bf16 v[58:61], v[150:153], v[166:169], v[58:61]
	v_mfma_f32_16x16x32_bf16 v[54:57], v[158:161], v[166:169], v[54:57]
	v_mfma_f32_16x16x32_bf16 v[42:45], v[150:153], v[174:177], v[42:45]
	v_mfma_f32_16x16x32_bf16 v[38:41], v[158:161], v[174:177], v[38:41]
	v_mfma_f32_16x16x32_bf16 v[26:29], v[150:153], v[182:185], v[26:29]
	v_mfma_f32_16x16x32_bf16 v[22:25], v[158:161], v[182:185], v[22:25]
	v_mfma_f32_16x16x32_bf16 v[10:13], v[150:153], v[190:193], v[10:13]
	v_mfma_f32_16x16x32_bf16 v[4:7], v[158:161], v[190:193], v[6:9]
	v_mfma_f32_16x16x32_bf16 v[58:61], v[154:157], v[170:173], v[58:61]
	v_mfma_f32_16x16x32_bf16 v[54:57], v[162:165], v[170:173], v[54:57]
	v_mfma_f32_16x16x32_bf16 v[42:45], v[154:157], v[178:181], v[42:45]
	v_mfma_f32_16x16x32_bf16 v[38:41], v[162:165], v[178:181], v[38:41]
	v_mfma_f32_16x16x32_bf16 v[26:29], v[154:157], v[186:189], v[26:29]
	v_mfma_f32_16x16x32_bf16 v[22:25], v[162:165], v[186:189], v[22:25]
	v_mfma_f32_16x16x32_bf16 v[10:13], v[154:157], v[226:229], v[10:13]
	v_mfma_f32_16x16x32_bf16 v[4:7], v[162:165], v[226:229], v[4:7]
	s_setprio 0
	s_barrier
	s_add_i32 s91, 0, 0x18000
	v_add_u32_e32 v2, s91, v224
	s_add_i32 s92, 0, 0x1c000
	ds_read_b128 v[134:137], v2
	ds_read_b128 v[138:141], v2 offset:1024
	ds_read_b128 v[142:145], v2 offset:2048
	ds_read_b128 v[146:149], v2 offset:3072
	v_add_u32_e32 v2, s92, v224
	ds_read_b128 v[150:153], v2
	ds_read_b128 v[154:157], v2 offset:1024
	ds_read_b128 v[158:161], v2 offset:2048
	ds_read_b128 v[162:165], v2 offset:3072
	s_add_u32 s26, s26, 0x80000
	s_addc_u32 s27, s27, 0
	s_mov_b32 m0, s76
	ds_read_b128 v[166:169], v225 offset:32768
	ds_read_b128 v[170:173], v225 offset:33792
	ds_read_b128 v[174:177], v225 offset:34816
	ds_read_b128 v[178:181], v225 offset:35840
	ds_read_b128 v[182:185], v225 offset:36864
	ds_read_b128 v[186:189], v225 offset:37888
	ds_read_b128 v[190:193], v225 offset:38912
	ds_read_b128 v[226:229], v225 offset:39936
	s_add_u32 s100, s26, 0xfff80000
	s_addc_u32 s101, s27, -1
	s_mov_b32 m0, s36
	s_nop 0
	global_load_lds_dwordx4 v208, s[100:101]
	s_mov_b32 m0, s37
	s_nop 0
	global_load_lds_dwordx4 v196, s[100:101]
	s_mov_b32 m0, s76
	s_nop 0
	global_load_lds_dwordx4 v208, s[26:27]
	s_mov_b32 m0, s77
	s_nop 0
	global_load_lds_dwordx4 v196, s[26:27]
	s_waitcnt vmcnt(8)
	s_waitcnt lgkmcnt(0)
	s_barrier
; #define PG8_STAGE(bufoff, gbase, voff) do { _Pragma("unroll") for (int _i = 0; _i < 2; ++_i) \
;         __builtin_amdgcn_global_load_lds((const unsigned*)((const char*)(gbase) + (voff)[_i]), (LAS unsigned*)(lds + (bufoff) + ldsw + _i * 8192), 16, 0, 0); } while (0)
; #define PG8_LDA(dst, b, h) do { _Pragma("unroll") for (int m = 0; m < 4; ++m) _Pragma("unroll") for (int k = 0; k < 2; ++k) dst[m][k] = *(const LAS bf16x8*)(lds + PG8_SA(b, h) + aoff + m * 2048 + k * 1024); } while (0)
; #define PG8_MMA(ai, bj, At, Bt) do { __builtin_amdgcn_s_setprio(1); _Pragma("unroll") for (int m = 0; m < 4; ++m) _Pragma("unroll") for (int n = 0; n < 2; ++n) _Pragma("unroll") for (int k = 0; k < 2; ++k) \
;         acc[ai][bj][m][n] = __builtin_amdgcn_mfma_f32_16x16x32_bf16(Bt[n][k], At[m][k], acc[ai][bj][m][n], 0, 0, 0); __builtin_amdgcn_s_setprio(0); } while (0)
; #define PG8_WAIT_V(n) asm volatile("s_waitcnt vmcnt(" #n ")" ::: "memory")
; #define PG8_WAIT_L(n) asm volatile("s_waitcnt lgkmcnt(" #n ")" ::: "memory")
; #define PG8_BAR __builtin_amdgcn_s_barrier()
; #define PG8_SCHED __builtin_amdgcn_sched_barrier(0)
; template <class Epi, bool ALIGN_EPI = true>
; __device__ __forceinline__ void gemm_phase(LAS unsigned char* lds, const Gemm g, const Sched& S, const Epi& E) {
;     ...
;             PG8_WAIT_V(8); PG8_WAIT_L(0); PG8_BAR; PG8_MMA(0, 0, At, B0); PG8_MMA(0, 1, At, B1); PG8_BAR; PG8_SCHED;
;             PG8_LDA(At, 1, 1); PG8_STAGE(PG8_SB(1, 0), b3, voffB); PG8_STAGE(PG8_SB(1, 1), b3 + hstepB, voffB); PG8_STAGE(PG8_SA(1, 0), a3, voffA);
;             PG8_WAIT_V(8); PG8_WAIT_L(0); PG8_BAR; PG8_MMA(1, 0, At, B0); PG8_MMA(1, 1, At, B1); PG8_BAR; PG8_SCHED;
;         }
	s_setprio 1
	s_waitcnt lgkmcnt(0)
	v_mfma_f32_16x16x32_bf16 v[130:133], v[134:137], v[166:169], v[130:133]
	v_mfma_f32_16x16x32_bf16 v[126:129], v[142:145], v[166:169], v[126:129]
	v_mfma_f32_16x16x32_bf16 v[114:117], v[134:137], v[174:177], v[114:117]
	v_mfma_f32_16x16x32_bf16 v[110:113], v[142:145], v[174:177], v[110:113]
	v_mfma_f32_16x16x32_bf16 v[98:101], v[134:137], v[182:185], v[98:101]
	v_mfma_f32_16x16x32_bf16 v[94:97], v[142:145], v[182:185], v[94:97]
	v_mfma_f32_16x16x32_bf16 v[82:85], v[134:137], v[190:193], v[82:85]
	v_mfma_f32_16x16x32_bf16 v[78:81], v[142:145], v[190:193], v[78:81]
	v_mfma_f32_16x16x32_bf16 v[130:133], v[138:141], v[170:173], v[130:133]
	v_mfma_f32_16x16x32_bf16 v[126:129], v[146:149], v[170:173], v[126:129]
	v_mfma_f32_16x16x32_bf16 v[114:117], v[138:141], v[178:181], v[114:117]
	v_mfma_f32_16x16x32_bf16 v[110:113], v[146:149], v[178:181], v[110:113]
	v_mfma_f32_16x16x32_bf16 v[98:101], v[138:141], v[186:189], v[98:101]
	v_mfma_f32_16x16x32_bf16 v[94:97], v[146:149], v[186:189], v[94:97]
	v_mfma_f32_16x16x32_bf16 v[82:85], v[138:141], v[226:229], v[82:85]
	v_mfma_f32_16x16x32_bf16 v[78:81], v[146:149], v[226:229], v[78:81]
	s_setprio 0
	s_setprio 1
	v_mfma_f32_16x16x32_bf16 v[122:125], v[150:153], v[166:169], v[122:125]
	v_mfma_f32_16x16x32_bf16 v[118:121], v[158:161], v[166:169], v[118:121]
	v_mfma_f32_16x16x32_bf16 v[106:109], v[150:153], v[174:177], v[106:109]
	v_mfma_f32_16x16x32_bf16 v[102:105], v[158:161], v[174:177], v[102:105]
	v_mfma_f32_16x16x32_bf16 v[90:93], v[150:153], v[182:185], v[90:93]
	v_mfma_f32_16x16x32_bf16 v[86:89], v[158:161], v[182:185], v[86:89]
	v_mfma_f32_16x16x32_bf16 v[74:77], v[150:153], v[190:193], v[74:77]
	v_mfma_f32_16x16x32_bf16 v[70:73], v[158:161], v[190:193], v[70:73]
	v_mfma_f32_16x16x32_bf16 v[122:125], v[154:157], v[170:173], v[122:125]
	v_mfma_f32_16x16x32_bf16 v[118:121], v[162:165], v[170:173], v[118:121]
	v_mfma_f32_16x16x32_bf16 v[106:109], v[154:157], v[178:181], v[106:109]
	v_mfma_f32_16x16x32_bf16 v[102:105], v[162:165], v[178:181], v[102:105]
	v_mfma_f32_16x16x32_bf16 v[90:93], v[154:157], v[186:189], v[90:93]
	v_mfma_f32_16x16x32_bf16 v[86:89], v[162:165], v[186:189], v[86:89]
	v_mfma_f32_16x16x32_bf16 v[74:77], v[154:157], v[226:229], v[74:77]
	v_mfma_f32_16x16x32_bf16 v[70:73], v[162:165], v[226:229], v[70:73]
	s_setprio 0
	s_barrier
	s_add_u32 s100, s24, 0x80
	s_addc_u32 s101, s25, 0
	s_add_i32 s26, s91, s35
	s_mov_b32 m0, s26
	ds_read_b128 v[166:169], v225 offset:49152
	ds_read_b128 v[170:173], v225 offset:50176
	ds_read_b128 v[174:177], v225 offset:51200
	ds_read_b128 v[178:181], v225 offset:52224
	ds_read_b128 v[182:185], v225 offset:53248
	ds_read_b128 v[186:189], v225 offset:54272
	ds_read_b128 v[190:193], v225 offset:55296
	ds_read_b128 v[226:229], v225 offset:56320
	global_load_lds_dwordx4 v206, s[100:101]
	s_add_i32 m0, s26, 0x2000
	s_add_u32 s24, s24, 0x80080
	s_addc_u32 s25, s25, 0
	s_add_i32 s26, s92, s35
	global_load_lds_dwordx4 v194, s[100:101]
	s_mov_b32 m0, s26
	s_nop 0
	global_load_lds_dwordx4 v206, s[24:25]
	s_add_i32 m0, s26, 0x2000
	s_nop 0
	global_load_lds_dwordx4 v194, s[24:25]
	s_waitcnt vmcnt(6)
	s_waitcnt lgkmcnt(0)
	s_barrier
	s_setprio 1
	s_waitcnt lgkmcnt(0)
	v_mfma_f32_16x16x32_bf16 v[66:69], v[134:137], v[166:169], v[66:69]
	v_mfma_f32_16x16x32_bf16 v[62:65], v[142:145], v[166:169], v[62:65]
	v_mfma_f32_16x16x32_bf16 v[50:53], v[134:137], v[174:177], v[50:53]
	v_mfma_f32_16x16x32_bf16 v[46:49], v[142:145], v[174:177], v[46:49]
	v_mfma_f32_16x16x32_bf16 v[34:37], v[134:137], v[182:185], v[34:37]
	v_mfma_f32_16x16x32_bf16 v[30:33], v[142:145], v[182:185], v[30:33]
	v_mfma_f32_16x16x32_bf16 v[18:21], v[134:137], v[190:193], v[18:21]
	v_mfma_f32_16x16x32_bf16 v[14:17], v[142:145], v[190:193], v[14:17]
	v_mfma_f32_16x16x32_bf16 v[66:69], v[138:141], v[170:173], v[66:69]
	v_mfma_f32_16x16x32_bf16 v[62:65], v[146:149], v[170:173], v[62:65]
	v_mfma_f32_16x16x32_bf16 v[50:53], v[138:141], v[178:181], v[50:53]
	v_mfma_f32_16x16x32_bf16 v[46:49], v[146:149], v[178:181], v[46:49]
	v_mfma_f32_16x16x32_bf16 v[34:37], v[138:141], v[186:189], v[34:37]
	v_mfma_f32_16x16x32_bf16 v[30:33], v[146:149], v[186:189], v[30:33]
	v_mfma_f32_16x16x32_bf16 v[18:21], v[138:141], v[226:229], v[18:21]
	v_mfma_f32_16x16x32_bf16 v[14:17], v[146:149], v[226:229], v[14:17]
	s_setprio 0
	s_setprio 1
	v_mfma_f32_16x16x32_bf16 v[58:61], v[150:153], v[166:169], v[58:61]
	v_mfma_f32_16x16x32_bf16 v[54:57], v[158:161], v[166:169], v[54:57]
	v_mfma_f32_16x16x32_bf16 v[42:45], v[150:153], v[174:177], v[42:45]
	v_mfma_f32_16x16x32_bf16 v[38:41], v[158:161], v[174:177], v[38:41]
	v_mfma_f32_16x16x32_bf16 v[26:29], v[150:153], v[182:185], v[26:29]
	v_mfma_f32_16x16x32_bf16 v[22:25], v[158:161], v[182:185], v[22:25]
	v_mfma_f32_16x16x32_bf16 v[8:11], v[150:153], v[190:193], v[10:13]
	v_mfma_f32_16x16x32_bf16 v[4:7], v[158:161], v[190:193], v[4:7]
	v_mfma_f32_16x16x32_bf16 v[58:61], v[154:157], v[170:173], v[58:61]
	v_mfma_f32_16x16x32_bf16 v[54:57], v[162:165], v[170:173], v[54:57]
	v_mfma_f32_16x16x32_bf16 v[42:45], v[154:157], v[178:181], v[42:45]
	v_mfma_f32_16x16x32_bf16 v[38:41], v[162:165], v[178:181], v[38:41]
	v_mfma_f32_16x16x32_bf16 v[26:29], v[154:157], v[186:189], v[26:29]
	v_mfma_f32_16x16x32_bf16 v[22:25], v[162:165], v[186:189], v[22:25]
	v_mfma_f32_16x16x32_bf16 v[10:13], v[154:157], v[226:229], v[8:11]
	v_mfma_f32_16x16x32_bf16 v[6:9], v[162:165], v[226:229], v[4:7]
	s_setprio 0
	s_barrier
	s_cmp_ge_i32 s94, s90
	s_mov_b32 s24, s94
	s_cbranch_scc0 .LBB0_1237
	s_branch .LBB0_1232

; #define PG8_STAGE(bufoff, gbase, voff) do { _Pragma("unroll") for (int _i = 0; _i < 2; ++_i) \
;         __builtin_amdgcn_global_load_lds((const unsigned*)((const char*)(gbase) + (voff)[_i]), (LAS unsigned*)(lds + (bufoff) + ldsw + _i * 8192), 16, 0, 0); } while (0)
; #define PG8_LDA(dst, b, h) do { _Pragma("unroll") for (int m = 0; m < 4; ++m) _Pragma("unroll") for (int k = 0; k < 2; ++k) dst[m][k] = *(const LAS bf16x8*)(lds + PG8_SA(b, h) + aoff + m * 2048 + k * 1024); } while (0)
; #define PG8_LDB(dst, b, h) do { _Pragma("unroll") for (int n = 0; n < 2; ++n) _Pragma("unroll") for (int k = 0; k < 2; ++k) dst[n][k] = *(const LAS bf16x8*)(lds + PG8_SB(b, h) + boff + n * 2048 + k * 1024); } while (0)
; #define PG8_MMA(ai, bj, At, Bt) do { __builtin_amdgcn_s_setprio(1); _Pragma("unroll") for (int m = 0; m < 4; ++m) _Pragma("unroll") for (int n = 0; n < 2; ++n) _Pragma("unroll") for (int k = 0; k < 2; ++k) \
;         acc[ai][bj][m][n] = __builtin_amdgcn_mfma_f32_16x16x32_bf16(Bt[n][k], At[m][k], acc[ai][bj][m][n], 0, 0, 0); __builtin_amdgcn_s_setprio(0); } while (0)
; #define PG8_WAIT_V(n) asm volatile("s_waitcnt vmcnt(" #n ")" ::: "memory")
; template <class Epi, bool ALIGN_EPI = true>
; __device__ __forceinline__ void gemm_phase(LAS unsigned char* lds, const Gemm g, const Sched& S, const Epi& E) {
;     ...
;         for (int t = t_lo; t < t_hi; t += 2) {
;             const bool last = (t == nt - 2);
;             const char* a1 = cA + (size_t)(t + 1) * kstep;
;             const char* a2 = last ? nA : cA + (size_t)(t + 2) * kstep; const char* b2 = last ? nB : cB + (size_t)(t + 2) * kstep;
;             const char* a3 = a2 + kstep; const char* b3 = b2 + kstep;
;             const int rflag = __builtin_amdgcn_readfirstlane(t | (int)(ui == 0));
;             PG8_LDB(B0, 0, 0); PG8_LDB(B1, 0, 1); PG8_SCHED; PG8_LDA(At, 0, 0); PG8_STAGE(PG8_SA(1, 1), a1 + hstepA, voffA);
;             if constexpr (Epi::NSTORES > 0) PG8_WAIT_RELAX(rflag, 8 + Epi::NSTORES); else PG8_WAIT_V(8);
;             PG8_WAIT_L(0); PG8_BAR; PG8_MMA(0, 0, At, B0); PG8_MMA(0, 1, At, B1); PG8_BAR; PG8_SCHED;
;             PG8_LDA(At, 0, 1); PG8_STAGE(PG8_SB(0, 0), b2, voffB); PG8_STAGE(PG8_SB(0, 1), b2 + hstepB, voffB); PG8_STAGE(PG8_SA(0, 0), a2, voffA);
;             if constexpr (Epi::NSTORES > 0) PG8_WAIT_RELAX(rflag, 8 + Epi::NSTORES); else PG8_WAIT_V(8);
.LBB0_1311:
	s_add_i32 s67, s48, 2
	s_add_u32 s49, s46, 0xfff80080
	s_addc_u32 s50, s47, -1
	s_add_i32 s68, 0, 0x10000
	s_cmp_eq_u32 s59, s48
	s_cselect_b32 s51, s21, s50
	s_cselect_b32 s50, s23, s49
	v_add_u32_e32 v2, s68, v147
	s_cselect_b32 s49, s63, s66
	s_cselect_b32 s48, s64, s65
	s_add_i32 s70, 0, 0x14000
	ds_read_b128 v[150:153], v2
	ds_read_b128 v[154:157], v2 offset:1024
	ds_read_b128 v[158:161], v2 offset:2048
	ds_read_b128 v[162:165], v2 offset:3072
	v_add_u32_e32 v2, s70, v147
	ds_read_b128 v[166:169], v2
	ds_read_b128 v[170:173], v2 offset:1024
	ds_read_b128 v[174:177], v2 offset:2048
	ds_read_b128 v[178:181], v2 offset:3072
	s_add_i32 m0, s52, 0xc000
	ds_read_b128 v[182:185], v148
	ds_read_b128 v[186:189], v148 offset:1024
	ds_read_b128 v[190:193], v148 offset:2048
	ds_read_b128 v[194:197], v148 offset:3072
	ds_read_b128 v[206:209], v148 offset:4096
	ds_read_b128 v[224:227], v148 offset:5120
	ds_read_b128 v[228:231], v148 offset:6144
	ds_read_b128 v[232:235], v148 offset:7168
	s_add_u32 s100, s46, 0xfff80000
	s_addc_u32 s101, s47, -1
	s_mov_b32 m0, s57
	s_nop 0
	global_load_lds_dwordx4 v142, s[100:101]
	s_mov_b32 m0, s58
	s_nop 0
	global_load_lds_dwordx4 v144, s[100:101]
	s_add_i32 m0, s52, 0xc000
	s_nop 0
	global_load_lds_dwordx4 v142, s[46:47]
	s_add_i32 m0, s52, 0xe000
	s_nop 0
	global_load_lds_dwordx4 v144, s[46:47]
	s_waitcnt vmcnt(8)
	s_waitcnt lgkmcnt(0)
	s_barrier
	s_setprio 1
	s_waitcnt lgkmcnt(0)
	v_mfma_f32_16x16x32_bf16 v[130:133], v[150:153], v[182:185], v[130:133]
	v_mfma_f32_16x16x32_bf16 v[126:129], v[158:161], v[182:185], v[126:129]
	v_mfma_f32_16x16x32_bf16 v[114:117], v[150:153], v[190:193], v[114:117]
	v_mfma_f32_16x16x32_bf16 v[110:113], v[158:161], v[190:193], v[110:113]
	v_mfma_f32_16x16x32_bf16 v[98:101], v[150:153], v[206:209], v[98:101]
	v_mfma_f32_16x16x32_bf16 v[94:97], v[158:161], v[206:209], v[94:97]
	v_mfma_f32_16x16x32_bf16 v[82:85], v[150:153], v[228:231], v[82:85]
	v_mfma_f32_16x16x32_bf16 v[78:81], v[158:161], v[228:231], v[78:81]
	v_mfma_f32_16x16x32_bf16 v[130:133], v[154:157], v[186:189], v[130:133]
	v_mfma_f32_16x16x32_bf16 v[126:129], v[162:165], v[186:189], v[126:129]
	v_mfma_f32_16x16x32_bf16 v[114:117], v[154:157], v[194:197], v[114:117]
	v_mfma_f32_16x16x32_bf16 v[110:113], v[162:165], v[194:197], v[110:113]
	v_mfma_f32_16x16x32_bf16 v[98:101], v[154:157], v[224:227], v[98:101]
	v_mfma_f32_16x16x32_bf16 v[94:97], v[162:165], v[224:227], v[94:97]
	v_mfma_f32_16x16x32_bf16 v[82:85], v[154:157], v[232:235], v[82:85]
	v_mfma_f32_16x16x32_bf16 v[78:81], v[162:165], v[232:235], v[78:81]
	s_setprio 0
	s_setprio 1
	v_mfma_f32_16x16x32_bf16 v[122:125], v[166:169], v[182:185], v[122:125]
	v_mfma_f32_16x16x32_bf16 v[118:121], v[174:177], v[182:185], v[118:121]
	v_mfma_f32_16x16x32_bf16 v[106:109], v[166:169], v[190:193], v[106:109]
	v_mfma_f32_16x16x32_bf16 v[102:105], v[174:177], v[190:193], v[102:105]
	v_mfma_f32_16x16x32_bf16 v[90:93], v[166:169], v[206:209], v[90:93]
	v_mfma_f32_16x16x32_bf16 v[86:89], v[174:177], v[206:209], v[86:89]
	v_mfma_f32_16x16x32_bf16 v[74:77], v[166:169], v[228:231], v[74:77]
	v_mfma_f32_16x16x32_bf16 v[70:73], v[174:177], v[228:231], v[70:73]
	v_mfma_f32_16x16x32_bf16 v[122:125], v[170:173], v[186:189], v[122:125]
	v_mfma_f32_16x16x32_bf16 v[118:121], v[178:181], v[186:189], v[118:121]
	v_mfma_f32_16x16x32_bf16 v[106:109], v[170:173], v[194:197], v[106:109]
	v_mfma_f32_16x16x32_bf16 v[102:105], v[178:181], v[194:197], v[102:105]
	v_mfma_f32_16x16x32_bf16 v[90:93], v[170:173], v[224:227], v[90:93]
	v_mfma_f32_16x16x32_bf16 v[86:89], v[178:181], v[224:227], v[86:89]
	v_mfma_f32_16x16x32_bf16 v[74:77], v[170:173], v[232:235], v[74:77]
	v_mfma_f32_16x16x32_bf16 v[70:73], v[178:181], v[232:235], v[70:73]
	s_setprio 0
	s_barrier
	s_add_i32 s68, s68, s37
	s_mov_b32 m0, s68
	ds_read_b128 v[182:185], v148 offset:16384
	ds_read_b128 v[186:189], v148 offset:17408
	ds_read_b128 v[190:193], v148 offset:18432
	ds_read_b128 v[194:197], v148 offset:19456
	ds_read_b128 v[206:209], v148 offset:20480
	ds_read_b128 v[224:227], v148 offset:21504
	ds_read_b128 v[228:231], v148 offset:22528
	ds_read_b128 v[232:235], v148 offset:23552
	global_load_lds_dwordx4 v138, s[48:49]
	s_add_i32 m0, s68, 0x2000
	s_add_u32 s68, s48, 0x80000
	s_addc_u32 s69, s49, 0
	s_add_i32 s70, s70, s37
	global_load_lds_dwordx4 v134, s[48:49]
	s_mov_b32 m0, s70
	s_nop 0
	global_load_lds_dwordx4 v138, s[68:69]
	s_add_i32 m0, s70, 0x2000
	s_nop 0
	global_load_lds_dwordx4 v134, s[68:69]
	s_waitcnt vmcnt(6)
	s_waitcnt lgkmcnt(0)
	s_barrier
; #define PG8_STAGE(bufoff, gbase, voff) do { _Pragma("unroll") for (int _i = 0; _i < 2; ++_i) \
;         __builtin_amdgcn_global_load_lds((const unsigned*)((const char*)(gbase) + (voff)[_i]), (LAS unsigned*)(lds + (bufoff) + ldsw + _i * 8192), 16, 0, 0); } while (0)
; #define PG8_LDA(dst, b, h) do { _Pragma("unroll") for (int m = 0; m < 4; ++m) _Pragma("unroll") for (int k = 0; k < 2; ++k) dst[m][k] = *(const LAS bf16x8*)(lds + PG8_SA(b, h) + aoff + m * 2048 + k * 1024); } while (0)
; #define PG8_LDB(dst, b, h) do { _Pragma("unroll") for (int n = 0; n < 2; ++n) _Pragma("unroll") for (int k = 0; k < 2; ++k) dst[n][k] = *(const LAS bf16x8*)(lds + PG8_SB(b, h) + boff + n * 2048 + k * 1024); } while (0)
; #define PG8_MMA(ai, bj, At, Bt) do { __builtin_amdgcn_s_setprio(1); _Pragma("unroll") for (int m = 0; m < 4; ++m) _Pragma("unroll") for (int n = 0; n < 2; ++n) _Pragma("unroll") for (int k = 0; k < 2; ++k) \
;         acc[ai][bj][m][n] = __builtin_amdgcn_mfma_f32_16x16x32_bf16(Bt[n][k], At[m][k], acc[ai][bj][m][n], 0, 0, 0); __builtin_amdgcn_s_setprio(0); } while (0)
; #define PG8_WAIT_V(n) asm volatile("s_waitcnt vmcnt(" #n ")" ::: "memory")
; #define PG8_WAIT_L(n) asm volatile("s_waitcnt lgkmcnt(" #n ")" ::: "memory")
; #define PG8_BAR __builtin_amdgcn_s_barrier()
; #define PG8_SCHED __builtin_amdgcn_sched_barrier(0)
; template <class Epi, bool ALIGN_EPI = true>
; __device__ __forceinline__ void gemm_phase(LAS unsigned char* lds, const Gemm g, const Sched& S, const Epi& E) {
;     ...
;             PG8_WAIT_L(0); PG8_BAR; PG8_MMA(1, 0, At, B0); PG8_MMA(1, 1, At, B1); PG8_BAR; PG8_SCHED;
;             PG8_LDB(B0, 1, 0); PG8_LDB(B1, 1, 1); PG8_SCHED; PG8_LDA(At, 1, 0); PG8_STAGE(PG8_SA(0, 1), a2 + hstepA, voffA);
;             PG8_WAIT_V(8); PG8_WAIT_L(0); PG8_BAR; PG8_MMA(0, 0, At, B0); PG8_MMA(0, 1, At, B1); PG8_BAR; PG8_SCHED;
	s_setprio 1
	s_waitcnt lgkmcnt(0)
	v_mfma_f32_16x16x32_bf16 v[66:69], v[150:153], v[182:185], v[66:69]
	v_mfma_f32_16x16x32_bf16 v[62:65], v[158:161], v[182:185], v[62:65]
	v_mfma_f32_16x16x32_bf16 v[50:53], v[150:153], v[190:193], v[50:53]
	v_mfma_f32_16x16x32_bf16 v[46:49], v[158:161], v[190:193], v[46:49]
	v_mfma_f32_16x16x32_bf16 v[34:37], v[150:153], v[206:209], v[34:37]
	v_mfma_f32_16x16x32_bf16 v[30:33], v[158:161], v[206:209], v[30:33]
	v_mfma_f32_16x16x32_bf16 v[18:21], v[150:153], v[228:231], v[18:21]
	v_mfma_f32_16x16x32_bf16 v[14:17], v[158:161], v[228:231], v[14:17]
	v_mfma_f32_16x16x32_bf16 v[66:69], v[154:157], v[186:189], v[66:69]
	v_mfma_f32_16x16x32_bf16 v[62:65], v[162:165], v[186:189], v[62:65]
	v_mfma_f32_16x16x32_bf16 v[50:53], v[154:157], v[194:197], v[50:53]
	v_mfma_f32_16x16x32_bf16 v[46:49], v[162:165], v[194:197], v[46:49]
	v_mfma_f32_16x16x32_bf16 v[34:37], v[154:157], v[224:227], v[34:37]
	v_mfma_f32_16x16x32_bf16 v[30:33], v[162:165], v[224:227], v[30:33]
	v_mfma_f32_16x16x32_bf16 v[18:21], v[154:157], v[232:235], v[18:21]
	v_mfma_f32_16x16x32_bf16 v[14:17], v[162:165], v[232:235], v[14:17]
	s_setprio 0
	s_setprio 1
	v_mfma_f32_16x16x32_bf16 v[58:61], v[166:169], v[182:185], v[58:61]
	v_mfma_f32_16x16x32_bf16 v[54:57], v[174:177], v[182:185], v[54:57]
	v_mfma_f32_16x16x32_bf16 v[42:45], v[166:169], v[190:193], v[42:45]
	v_mfma_f32_16x16x32_bf16 v[38:41], v[174:177], v[190:193], v[38:41]
	v_mfma_f32_16x16x32_bf16 v[26:29], v[166:169], v[206:209], v[26:29]
	v_mfma_f32_16x16x32_bf16 v[22:25], v[174:177], v[206:209], v[22:25]
	v_mfma_f32_16x16x32_bf16 v[10:13], v[166:169], v[228:231], v[10:13]
	v_mfma_f32_16x16x32_bf16 v[4:7], v[174:177], v[228:231], v[6:9]
	v_mfma_f32_16x16x32_bf16 v[58:61], v[170:173], v[186:189], v[58:61]
	v_mfma_f32_16x16x32_bf16 v[54:57], v[178:181], v[186:189], v[54:57]
	v_mfma_f32_16x16x32_bf16 v[42:45], v[170:173], v[194:197], v[42:45]
	v_mfma_f32_16x16x32_bf16 v[38:41], v[178:181], v[194:197], v[38:41]
	v_mfma_f32_16x16x32_bf16 v[26:29], v[170:173], v[224:227], v[26:29]
	v_mfma_f32_16x16x32_bf16 v[22:25], v[178:181], v[224:227], v[22:25]
	v_mfma_f32_16x16x32_bf16 v[10:13], v[170:173], v[232:235], v[10:13]
	v_mfma_f32_16x16x32_bf16 v[4:7], v[178:181], v[232:235], v[4:7]
	s_setprio 0
	s_barrier
	s_add_i32 s68, 0, 0x18000
	v_add_u32_e32 v2, s68, v147
	s_add_i32 s69, 0, 0x1c000
	ds_read_b128 v[150:153], v2
	ds_read_b128 v[154:157], v2 offset:1024
	ds_read_b128 v[158:161], v2 offset:2048
	ds_read_b128 v[162:165], v2 offset:3072
	v_add_u32_e32 v2, s69, v147
	ds_read_b128 v[166:169], v2
	ds_read_b128 v[170:173], v2 offset:1024
	ds_read_b128 v[174:177], v2 offset:2048
	ds_read_b128 v[178:181], v2 offset:3072
	s_add_u32 s50, s50, 0x80000
	s_addc_u32 s51, s51, 0
	s_mov_b32 m0, s54
	ds_read_b128 v[182:185], v148 offset:32768
	ds_read_b128 v[186:189], v148 offset:33792
	ds_read_b128 v[190:193], v148 offset:34816
	ds_read_b128 v[194:197], v148 offset:35840
	ds_read_b128 v[206:209], v148 offset:36864
	ds_read_b128 v[224:227], v148 offset:37888
	ds_read_b128 v[228:231], v148 offset:38912
	ds_read_b128 v[232:235], v148 offset:39936
	s_add_u32 s100, s50, 0xfff80000
	s_addc_u32 s101, s51, -1
	s_mov_b32 m0, s52
	s_nop 0
	global_load_lds_dwordx4 v140, s[100:101]
	s_mov_b32 m0, s53
	s_nop 0
	global_load_lds_dwordx4 v136, s[100:101]
	s_mov_b32 m0, s54
	s_nop 0
	global_load_lds_dwordx4 v140, s[50:51]
	s_mov_b32 m0, s55
	s_nop 0
	global_load_lds_dwordx4 v136, s[50:51]
	s_waitcnt vmcnt(8)
	s_waitcnt lgkmcnt(0)
	s_barrier
; #define PG8_STAGE(bufoff, gbase, voff) do { _Pragma("unroll") for (int _i = 0; _i < 2; ++_i) \
;         __builtin_amdgcn_global_load_lds((const unsigned*)((const char*)(gbase) + (voff)[_i]), (LAS unsigned*)(lds + (bufoff) + ldsw + _i * 8192), 16, 0, 0); } while (0)
; #define PG8_LDA(dst, b, h) do { _Pragma("unroll") for (int m = 0; m < 4; ++m) _Pragma("unroll") for (int k = 0; k < 2; ++k) dst[m][k] = *(const LAS bf16x8*)(lds + PG8_SA(b, h) + aoff + m * 2048 + k * 1024); } while (0)
; #define PG8_MMA(ai, bj, At, Bt) do { __builtin_amdgcn_s_setprio(1); _Pragma("unroll") for (int m = 0; m < 4; ++m) _Pragma("unroll") for (int n = 0; n < 2; ++n) _Pragma("unroll") for (int k = 0; k < 2; ++k) \
;         acc[ai][bj][m][n] = __builtin_amdgcn_mfma_f32_16x16x32_bf16(Bt[n][k], At[m][k], acc[ai][bj][m][n], 0, 0, 0); __builtin_amdgcn_s_setprio(0); } while (0)
; #define PG8_WAIT_V(n) asm volatile("s_waitcnt vmcnt(" #n ")" ::: "memory")
; #define PG8_WAIT_L(n) asm volatile("s_waitcnt lgkmcnt(" #n ")" ::: "memory")
; #define PG8_BAR __builtin_amdgcn_s_barrier()
; #define PG8_SCHED __builtin_amdgcn_sched_barrier(0)
; template <class Epi, bool ALIGN_EPI = true>
; __device__ __forceinline__ void gemm_phase(LAS unsigned char* lds, const Gemm g, const Sched& S, const Epi& E) {
;     ...
;             PG8_WAIT_V(8); PG8_WAIT_L(0); PG8_BAR; PG8_MMA(0, 0, At, B0); PG8_MMA(0, 1, At, B1); PG8_BAR; PG8_SCHED;
;             PG8_LDA(At, 1, 1); PG8_STAGE(PG8_SB(1, 0), b3, voffB); PG8_STAGE(PG8_SB(1, 1), b3 + hstepB, voffB); PG8_STAGE(PG8_SA(1, 0), a3, voffA);
;             PG8_WAIT_V(8); PG8_WAIT_L(0); PG8_BAR; PG8_MMA(1, 0, At, B0); PG8_MMA(1, 1, At, B1); PG8_BAR; PG8_SCHED;
;         }
	s_setprio 1
	s_waitcnt lgkmcnt(0)
	v_mfma_f32_16x16x32_bf16 v[130:133], v[150:153], v[182:185], v[130:133]
	v_mfma_f32_16x16x32_bf16 v[126:129], v[158:161], v[182:185], v[126:129]
	v_mfma_f32_16x16x32_bf16 v[114:117], v[150:153], v[190:193], v[114:117]
	v_mfma_f32_16x16x32_bf16 v[110:113], v[158:161], v[190:193], v[110:113]
	v_mfma_f32_16x16x32_bf16 v[98:101], v[150:153], v[206:209], v[98:101]
	v_mfma_f32_16x16x32_bf16 v[94:97], v[158:161], v[206:209], v[94:97]
	v_mfma_f32_16x16x32_bf16 v[82:85], v[150:153], v[228:231], v[82:85]
	v_mfma_f32_16x16x32_bf16 v[78:81], v[158:161], v[228:231], v[78:81]
	v_mfma_f32_16x16x32_bf16 v[130:133], v[154:157], v[186:189], v[130:133]
	v_mfma_f32_16x16x32_bf16 v[126:129], v[162:165], v[186:189], v[126:129]
	v_mfma_f32_16x16x32_bf16 v[114:117], v[154:157], v[194:197], v[114:117]
	v_mfma_f32_16x16x32_bf16 v[110:113], v[162:165], v[194:197], v[110:113]
	v_mfma_f32_16x16x32_bf16 v[98:101], v[154:157], v[224:227], v[98:101]
	v_mfma_f32_16x16x32_bf16 v[94:97], v[162:165], v[224:227], v[94:97]
	v_mfma_f32_16x16x32_bf16 v[82:85], v[154:157], v[232:235], v[82:85]
	v_mfma_f32_16x16x32_bf16 v[78:81], v[162:165], v[232:235], v[78:81]
	s_setprio 0
	s_setprio 1
	v_mfma_f32_16x16x32_bf16 v[122:125], v[166:169], v[182:185], v[122:125]
	v_mfma_f32_16x16x32_bf16 v[118:121], v[174:177], v[182:185], v[118:121]
	v_mfma_f32_16x16x32_bf16 v[106:109], v[166:169], v[190:193], v[106:109]
	v_mfma_f32_16x16x32_bf16 v[102:105], v[174:177], v[190:193], v[102:105]
	v_mfma_f32_16x16x32_bf16 v[90:93], v[166:169], v[206:209], v[90:93]
	v_mfma_f32_16x16x32_bf16 v[86:89], v[174:177], v[206:209], v[86:89]
	v_mfma_f32_16x16x32_bf16 v[74:77], v[166:169], v[228:231], v[74:77]
	v_mfma_f32_16x16x32_bf16 v[70:73], v[174:177], v[228:231], v[70:73]
	v_mfma_f32_16x16x32_bf16 v[122:125], v[170:173], v[186:189], v[122:125]
	v_mfma_f32_16x16x32_bf16 v[118:121], v[178:181], v[186:189], v[118:121]
	v_mfma_f32_16x16x32_bf16 v[106:109], v[170:173], v[194:197], v[106:109]
	v_mfma_f32_16x16x32_bf16 v[102:105], v[178:181], v[194:197], v[102:105]
	v_mfma_f32_16x16x32_bf16 v[90:93], v[170:173], v[224:227], v[90:93]
	v_mfma_f32_16x16x32_bf16 v[86:89], v[178:181], v[224:227], v[86:89]
	v_mfma_f32_16x16x32_bf16 v[74:77], v[170:173], v[232:235], v[74:77]
	v_mfma_f32_16x16x32_bf16 v[70:73], v[178:181], v[232:235], v[70:73]
	s_setprio 0
	s_barrier
	s_add_u32 s100, s48, 0x80
	s_addc_u32 s101, s49, 0
	s_add_i32 s50, s68, s37
	s_mov_b32 m0, s50
	ds_read_b128 v[182:185], v148 offset:49152
	ds_read_b128 v[186:189], v148 offset:50176
	ds_read_b128 v[190:193], v148 offset:51200
	ds_read_b128 v[194:197], v148 offset:52224
	ds_read_b128 v[206:209], v148 offset:53248
	ds_read_b128 v[224:227], v148 offset:54272
	ds_read_b128 v[228:231], v148 offset:55296
	ds_read_b128 v[232:235], v148 offset:56320
	global_load_lds_dwordx4 v138, s[100:101]
	s_add_i32 m0, s50, 0x2000
	s_add_u32 s48, s48, 0x80080
	s_addc_u32 s49, s49, 0
	s_add_i32 s50, s69, s37
	global_load_lds_dwordx4 v134, s[100:101]
	s_mov_b32 m0, s50
	s_nop 0
	global_load_lds_dwordx4 v138, s[48:49]
	s_add_i32 m0, s50, 0x2000
	s_nop 0
	global_load_lds_dwordx4 v134, s[48:49]
	s_waitcnt vmcnt(6)
	s_waitcnt lgkmcnt(0)
	s_barrier
	s_setprio 1
	s_waitcnt lgkmcnt(0)
	v_mfma_f32_16x16x32_bf16 v[66:69], v[150:153], v[182:185], v[66:69]
	v_mfma_f32_16x16x32_bf16 v[62:65], v[158:161], v[182:185], v[62:65]
	v_mfma_f32_16x16x32_bf16 v[50:53], v[150:153], v[190:193], v[50:53]
	v_mfma_f32_16x16x32_bf16 v[46:49], v[158:161], v[190:193], v[46:49]
	v_mfma_f32_16x16x32_bf16 v[34:37], v[150:153], v[206:209], v[34:37]
	v_mfma_f32_16x16x32_bf16 v[30:33], v[158:161], v[206:209], v[30:33]
	v_mfma_f32_16x16x32_bf16 v[18:21], v[150:153], v[228:231], v[18:21]
	v_mfma_f32_16x16x32_bf16 v[14:17], v[158:161], v[228:231], v[14:17]
	v_mfma_f32_16x16x32_bf16 v[66:69], v[154:157], v[186:189], v[66:69]
	v_mfma_f32_16x16x32_bf16 v[62:65], v[162:165], v[186:189], v[62:65]
	v_mfma_f32_16x16x32_bf16 v[50:53], v[154:157], v[194:197], v[50:53]
	v_mfma_f32_16x16x32_bf16 v[46:49], v[162:165], v[194:197], v[46:49]
	v_mfma_f32_16x16x32_bf16 v[34:37], v[154:157], v[224:227], v[34:37]
	v_mfma_f32_16x16x32_bf16 v[30:33], v[162:165], v[224:227], v[30:33]
	v_mfma_f32_16x16x32_bf16 v[18:21], v[154:157], v[232:235], v[18:21]
	v_mfma_f32_16x16x32_bf16 v[14:17], v[162:165], v[232:235], v[14:17]
	s_setprio 0
	s_setprio 1
	v_mfma_f32_16x16x32_bf16 v[58:61], v[166:169], v[182:185], v[58:61]
	v_mfma_f32_16x16x32_bf16 v[54:57], v[174:177], v[182:185], v[54:57]
	v_mfma_f32_16x16x32_bf16 v[42:45], v[166:169], v[190:193], v[42:45]
	v_mfma_f32_16x16x32_bf16 v[38:41], v[174:177], v[190:193], v[38:41]
	v_mfma_f32_16x16x32_bf16 v[26:29], v[166:169], v[206:209], v[26:29]
	v_mfma_f32_16x16x32_bf16 v[22:25], v[174:177], v[206:209], v[22:25]
	v_mfma_f32_16x16x32_bf16 v[8:11], v[166:169], v[228:231], v[10:13]
	v_mfma_f32_16x16x32_bf16 v[4:7], v[174:177], v[228:231], v[4:7]
	v_mfma_f32_16x16x32_bf16 v[58:61], v[170:173], v[186:189], v[58:61]
	v_mfma_f32_16x16x32_bf16 v[54:57], v[178:181], v[186:189], v[54:57]
	v_mfma_f32_16x16x32_bf16 v[42:45], v[170:173], v[194:197], v[42:45]
	v_mfma_f32_16x16x32_bf16 v[38:41], v[178:181], v[194:197], v[38:41]
	v_mfma_f32_16x16x32_bf16 v[26:29], v[170:173], v[224:227], v[26:29]
	v_mfma_f32_16x16x32_bf16 v[22:25], v[178:181], v[224:227], v[22:25]
	v_mfma_f32_16x16x32_bf16 v[10:13], v[170:173], v[232:235], v[8:11]
	v_mfma_f32_16x16x32_bf16 v[6:9], v[178:181], v[232:235], v[4:7]
	s_setprio 0
	s_barrier
	s_add_u32 s46, s46, 0x100
	s_addc_u32 s47, s47, 0
	s_add_u32 s65, s65, 0x100
	s_addc_u32 s66, s66, 0
	s_cmp_ge_i32 s67, s56
	s_mov_b32 s48, s67
	s_cbranch_scc0 .LBB0_1311

; #define PG8_STAGE(bufoff, gbase, voff) do { _Pragma("unroll") for (int _i = 0; _i < 2; ++_i) \
;         __builtin_amdgcn_global_load_lds((const unsigned*)((const char*)(gbase) + (voff)[_i]), (LAS unsigned*)(lds + (bufoff) + ldsw + _i * 8192), 16, 0, 0); } while (0)
; #define PG8_LDA(dst, b, h) do { _Pragma("unroll") for (int m = 0; m < 4; ++m) _Pragma("unroll") for (int k = 0; k < 2; ++k) dst[m][k] = *(const LAS bf16x8*)(lds + PG8_SA(b, h) + aoff + m * 2048 + k * 1024); } while (0)
; #define PG8_LDB(dst, b, h) do { _Pragma("unroll") for (int n = 0; n < 2; ++n) _Pragma("unroll") for (int k = 0; k < 2; ++k) dst[n][k] = *(const LAS bf16x8*)(lds + PG8_SB(b, h) + boff + n * 2048 + k * 1024); } while (0)
; #define PG8_MMA(ai, bj, At, Bt) do { __builtin_amdgcn_s_setprio(1); _Pragma("unroll") for (int m = 0; m < 4; ++m) _Pragma("unroll") for (int n = 0; n < 2; ++n) _Pragma("unroll") for (int k = 0; k < 2; ++k) \
;         acc[ai][bj][m][n] = __builtin_amdgcn_mfma_f32_16x16x32_bf16(Bt[n][k], At[m][k], acc[ai][bj][m][n], 0, 0, 0); __builtin_amdgcn_s_setprio(0); } while (0)
; #define PG8_WAIT_V(n) asm volatile("s_waitcnt vmcnt(" #n ")" ::: "memory")
; template <class Epi, bool ALIGN_EPI = true>
; __device__ __forceinline__ void gemm_phase(LAS unsigned char* lds, const Gemm g, const Sched& S, const Epi& E) {
;     ...
;         for (int t = t_lo; t < t_hi; t += 2) {
;             const bool last = (t == nt - 2);
;             const char* a1 = cA + (size_t)(t + 1) * kstep;
;             const char* a2 = last ? nA : cA + (size_t)(t + 2) * kstep; const char* b2 = last ? nB : cB + (size_t)(t + 2) * kstep;
;             const char* a3 = a2 + kstep; const char* b3 = b2 + kstep;
;             const int rflag = __builtin_amdgcn_readfirstlane(t | (int)(ui == 0));
;             PG8_LDB(B0, 0, 0); PG8_LDB(B1, 0, 1); PG8_SCHED; PG8_LDA(At, 0, 0); PG8_STAGE(PG8_SA(1, 1), a1 + hstepA, voffA);
;             if constexpr (Epi::NSTORES > 0) PG8_WAIT_RELAX(rflag, 8 + Epi::NSTORES); else PG8_WAIT_V(8);
;             PG8_WAIT_L(0); PG8_BAR; PG8_MMA(0, 0, At, B0); PG8_MMA(0, 1, At, B1); PG8_BAR; PG8_SCHED;
;             PG8_LDA(At, 0, 1); PG8_STAGE(PG8_SB(0, 0), b2, voffB); PG8_STAGE(PG8_SB(0, 1), b2 + hstepB, voffB); PG8_STAGE(PG8_SA(0, 0), a2, voffA);
;             if constexpr (Epi::NSTORES > 0) PG8_WAIT_RELAX(rflag, 8 + Epi::NSTORES); else PG8_WAIT_V(8);
.LBB0_1402:
	s_add_i32 s67, s46, 2
	s_add_u32 s47, s44, 0xfff80080
	s_addc_u32 s48, s45, -1
	s_add_i32 s68, 0, 0x10000
	s_cmp_eq_u32 s59, s46
	s_cselect_b32 s49, s19, s48
	s_cselect_b32 s48, s21, s47
	v_add_u32_e32 v2, s68, v147
	s_cselect_b32 s47, s63, s66
	s_cselect_b32 s46, s64, s65
	s_add_i32 s70, 0, 0x14000
	ds_read_b128 v[150:153], v2
	ds_read_b128 v[154:157], v2 offset:1024
	ds_read_b128 v[158:161], v2 offset:2048
	ds_read_b128 v[162:165], v2 offset:3072
	v_add_u32_e32 v2, s70, v147
	ds_read_b128 v[166:169], v2
	ds_read_b128 v[170:173], v2 offset:1024
	ds_read_b128 v[174:177], v2 offset:2048
	ds_read_b128 v[178:181], v2 offset:3072
	s_add_i32 m0, s52, 0xc000
	ds_read_b128 v[182:185], v148
	ds_read_b128 v[186:189], v148 offset:1024
	ds_read_b128 v[190:193], v148 offset:2048
	ds_read_b128 v[194:197], v148 offset:3072
	ds_read_b128 v[206:209], v148 offset:4096
	ds_read_b128 v[224:227], v148 offset:5120
	ds_read_b128 v[228:231], v148 offset:6144
	ds_read_b128 v[232:235], v148 offset:7168
	s_add_u32 s100, s44, 0xfff80000
	s_addc_u32 s101, s45, -1
	s_mov_b32 m0, s57
	s_nop 0
	global_load_lds_dwordx4 v142, s[100:101]
	s_mov_b32 m0, s58
	s_nop 0
	global_load_lds_dwordx4 v144, s[100:101]
	s_add_i32 m0, s52, 0xc000
	s_nop 0
	global_load_lds_dwordx4 v142, s[44:45]
	s_add_i32 m0, s52, 0xe000
	s_nop 0
	global_load_lds_dwordx4 v144, s[44:45]
	s_waitcnt vmcnt(8)
	s_waitcnt lgkmcnt(0)
	s_barrier
	s_setprio 1
	s_waitcnt lgkmcnt(0)
	v_mfma_f32_16x16x32_bf16 v[130:133], v[150:153], v[182:185], v[130:133]
	v_mfma_f32_16x16x32_bf16 v[126:129], v[158:161], v[182:185], v[126:129]
	v_mfma_f32_16x16x32_bf16 v[114:117], v[150:153], v[190:193], v[114:117]
	v_mfma_f32_16x16x32_bf16 v[110:113], v[158:161], v[190:193], v[110:113]
	v_mfma_f32_16x16x32_bf16 v[98:101], v[150:153], v[206:209], v[98:101]
	v_mfma_f32_16x16x32_bf16 v[94:97], v[158:161], v[206:209], v[94:97]
	v_mfma_f32_16x16x32_bf16 v[82:85], v[150:153], v[228:231], v[82:85]
	v_mfma_f32_16x16x32_bf16 v[78:81], v[158:161], v[228:231], v[78:81]
	v_mfma_f32_16x16x32_bf16 v[130:133], v[154:157], v[186:189], v[130:133]
	v_mfma_f32_16x16x32_bf16 v[126:129], v[162:165], v[186:189], v[126:129]
	v_mfma_f32_16x16x32_bf16 v[114:117], v[154:157], v[194:197], v[114:117]
	v_mfma_f32_16x16x32_bf16 v[110:113], v[162:165], v[194:197], v[110:113]
	v_mfma_f32_16x16x32_bf16 v[98:101], v[154:157], v[224:227], v[98:101]
	v_mfma_f32_16x16x32_bf16 v[94:97], v[162:165], v[224:227], v[94:97]
	v_mfma_f32_16x16x32_bf16 v[82:85], v[154:157], v[232:235], v[82:85]
	v_mfma_f32_16x16x32_bf16 v[78:81], v[162:165], v[232:235], v[78:81]
	s_setprio 0
	s_setprio 1
	v_mfma_f32_16x16x32_bf16 v[122:125], v[166:169], v[182:185], v[122:125]
	v_mfma_f32_16x16x32_bf16 v[118:121], v[174:177], v[182:185], v[118:121]
	v_mfma_f32_16x16x32_bf16 v[106:109], v[166:169], v[190:193], v[106:109]
	v_mfma_f32_16x16x32_bf16 v[102:105], v[174:177], v[190:193], v[102:105]
	v_mfma_f32_16x16x32_bf16 v[90:93], v[166:169], v[206:209], v[90:93]
	v_mfma_f32_16x16x32_bf16 v[86:89], v[174:177], v[206:209], v[86:89]
	v_mfma_f32_16x16x32_bf16 v[74:77], v[166:169], v[228:231], v[74:77]
	v_mfma_f32_16x16x32_bf16 v[70:73], v[174:177], v[228:231], v[70:73]
	v_mfma_f32_16x16x32_bf16 v[122:125], v[170:173], v[186:189], v[122:125]
	v_mfma_f32_16x16x32_bf16 v[118:121], v[178:181], v[186:189], v[118:121]
	v_mfma_f32_16x16x32_bf16 v[106:109], v[170:173], v[194:197], v[106:109]
	v_mfma_f32_16x16x32_bf16 v[102:105], v[178:181], v[194:197], v[102:105]
	v_mfma_f32_16x16x32_bf16 v[90:93], v[170:173], v[224:227], v[90:93]
	v_mfma_f32_16x16x32_bf16 v[86:89], v[178:181], v[224:227], v[86:89]
	v_mfma_f32_16x16x32_bf16 v[74:77], v[170:173], v[232:235], v[74:77]
	v_mfma_f32_16x16x32_bf16 v[70:73], v[178:181], v[232:235], v[70:73]
	s_setprio 0
	s_barrier
	s_add_i32 s68, s68, s51
	s_mov_b32 m0, s68
	ds_read_b128 v[182:185], v148 offset:16384
	ds_read_b128 v[186:189], v148 offset:17408
	ds_read_b128 v[190:193], v148 offset:18432
	ds_read_b128 v[194:197], v148 offset:19456
	ds_read_b128 v[206:209], v148 offset:20480
	ds_read_b128 v[224:227], v148 offset:21504
	ds_read_b128 v[228:231], v148 offset:22528
	ds_read_b128 v[232:235], v148 offset:23552
	global_load_lds_dwordx4 v138, s[46:47]
	s_add_i32 m0, s68, 0x2000
	s_add_u32 s68, s46, 0x80000
	s_addc_u32 s69, s47, 0
	s_add_i32 s70, s70, s51
	global_load_lds_dwordx4 v134, s[46:47]
	s_mov_b32 m0, s70
	s_nop 0
	global_load_lds_dwordx4 v138, s[68:69]
	s_add_i32 m0, s70, 0x2000
	s_nop 0
	global_load_lds_dwordx4 v134, s[68:69]
	s_waitcnt vmcnt(6)
	s_waitcnt lgkmcnt(0)
	s_barrier
; #define PG8_STAGE(bufoff, gbase, voff) do { _Pragma("unroll") for (int _i = 0; _i < 2; ++_i) \
;         __builtin_amdgcn_global_load_lds((const unsigned*)((const char*)(gbase) + (voff)[_i]), (LAS unsigned*)(lds + (bufoff) + ldsw + _i * 8192), 16, 0, 0); } while (0)
; #define PG8_LDA(dst, b, h) do { _Pragma("unroll") for (int m = 0; m < 4; ++m) _Pragma("unroll") for (int k = 0; k < 2; ++k) dst[m][k] = *(const LAS bf16x8*)(lds + PG8_SA(b, h) + aoff + m * 2048 + k * 1024); } while (0)
; #define PG8_LDB(dst, b, h) do { _Pragma("unroll") for (int n = 0; n < 2; ++n) _Pragma("unroll") for (int k = 0; k < 2; ++k) dst[n][k] = *(const LAS bf16x8*)(lds + PG8_SB(b, h) + boff + n * 2048 + k * 1024); } while (0)
; #define PG8_MMA(ai, bj, At, Bt) do { __builtin_amdgcn_s_setprio(1); _Pragma("unroll") for (int m = 0; m < 4; ++m) _Pragma("unroll") for (int n = 0; n < 2; ++n) _Pragma("unroll") for (int k = 0; k < 2; ++k) \
;         acc[ai][bj][m][n] = __builtin_amdgcn_mfma_f32_16x16x32_bf16(Bt[n][k], At[m][k], acc[ai][bj][m][n], 0, 0, 0); __builtin_amdgcn_s_setprio(0); } while (0)
; #define PG8_WAIT_V(n) asm volatile("s_waitcnt vmcnt(" #n ")" ::: "memory")
; #define PG8_WAIT_L(n) asm volatile("s_waitcnt lgkmcnt(" #n ")" ::: "memory")
; #define PG8_BAR __builtin_amdgcn_s_barrier()
; #define PG8_SCHED __builtin_amdgcn_sched_barrier(0)
; template <class Epi, bool ALIGN_EPI = true>
; __device__ __forceinline__ void gemm_phase(LAS unsigned char* lds, const Gemm g, const Sched& S, const Epi& E) {
;     ...
;             PG8_WAIT_L(0); PG8_BAR; PG8_MMA(1, 0, At, B0); PG8_MMA(1, 1, At, B1); PG8_BAR; PG8_SCHED;
;             PG8_LDB(B0, 1, 0); PG8_LDB(B1, 1, 1); PG8_SCHED; PG8_LDA(At, 1, 0); PG8_STAGE(PG8_SA(0, 1), a2 + hstepA, voffA);
;             PG8_WAIT_V(8); PG8_WAIT_L(0); PG8_BAR; PG8_MMA(0, 0, At, B0); PG8_MMA(0, 1, At, B1); PG8_BAR; PG8_SCHED;
	s_setprio 1
	s_waitcnt lgkmcnt(0)
	v_mfma_f32_16x16x32_bf16 v[66:69], v[150:153], v[182:185], v[66:69]
	v_mfma_f32_16x16x32_bf16 v[62:65], v[158:161], v[182:185], v[62:65]
	v_mfma_f32_16x16x32_bf16 v[50:53], v[150:153], v[190:193], v[50:53]
	v_mfma_f32_16x16x32_bf16 v[46:49], v[158:161], v[190:193], v[46:49]
	v_mfma_f32_16x16x32_bf16 v[34:37], v[150:153], v[206:209], v[34:37]
	v_mfma_f32_16x16x32_bf16 v[30:33], v[158:161], v[206:209], v[30:33]
	v_mfma_f32_16x16x32_bf16 v[18:21], v[150:153], v[228:231], v[18:21]
	v_mfma_f32_16x16x32_bf16 v[14:17], v[158:161], v[228:231], v[14:17]
	v_mfma_f32_16x16x32_bf16 v[66:69], v[154:157], v[186:189], v[66:69]
	v_mfma_f32_16x16x32_bf16 v[62:65], v[162:165], v[186:189], v[62:65]
	v_mfma_f32_16x16x32_bf16 v[50:53], v[154:157], v[194:197], v[50:53]
	v_mfma_f32_16x16x32_bf16 v[46:49], v[162:165], v[194:197], v[46:49]
	v_mfma_f32_16x16x32_bf16 v[34:37], v[154:157], v[224:227], v[34:37]
	v_mfma_f32_16x16x32_bf16 v[30:33], v[162:165], v[224:227], v[30:33]
	v_mfma_f32_16x16x32_bf16 v[18:21], v[154:157], v[232:235], v[18:21]
	v_mfma_f32_16x16x32_bf16 v[14:17], v[162:165], v[232:235], v[14:17]
	s_setprio 0
	s_setprio 1
	v_mfma_f32_16x16x32_bf16 v[58:61], v[166:169], v[182:185], v[58:61]
	v_mfma_f32_16x16x32_bf16 v[54:57], v[174:177], v[182:185], v[54:57]
	v_mfma_f32_16x16x32_bf16 v[42:45], v[166:169], v[190:193], v[42:45]
	v_mfma_f32_16x16x32_bf16 v[38:41], v[174:177], v[190:193], v[38:41]
	v_mfma_f32_16x16x32_bf16 v[26:29], v[166:169], v[206:209], v[26:29]
	v_mfma_f32_16x16x32_bf16 v[22:25], v[174:177], v[206:209], v[22:25]
	v_mfma_f32_16x16x32_bf16 v[10:13], v[166:169], v[228:231], v[10:13]
	v_mfma_f32_16x16x32_bf16 v[4:7], v[174:177], v[228:231], v[6:9]
	v_mfma_f32_16x16x32_bf16 v[58:61], v[170:173], v[186:189], v[58:61]
	v_mfma_f32_16x16x32_bf16 v[54:57], v[178:181], v[186:189], v[54:57]
	v_mfma_f32_16x16x32_bf16 v[42:45], v[170:173], v[194:197], v[42:45]
	v_mfma_f32_16x16x32_bf16 v[38:41], v[178:181], v[194:197], v[38:41]
	v_mfma_f32_16x16x32_bf16 v[26:29], v[170:173], v[224:227], v[26:29]
	v_mfma_f32_16x16x32_bf16 v[22:25], v[178:181], v[224:227], v[22:25]
	v_mfma_f32_16x16x32_bf16 v[10:13], v[170:173], v[232:235], v[10:13]
	v_mfma_f32_16x16x32_bf16 v[4:7], v[178:181], v[232:235], v[4:7]
	s_setprio 0
	s_barrier
	s_add_i32 s68, 0, 0x18000
	v_add_u32_e32 v2, s68, v147
	s_add_i32 s69, 0, 0x1c000
	ds_read_b128 v[150:153], v2
	ds_read_b128 v[154:157], v2 offset:1024
	ds_read_b128 v[158:161], v2 offset:2048
	ds_read_b128 v[162:165], v2 offset:3072
	v_add_u32_e32 v2, s69, v147
	ds_read_b128 v[166:169], v2
	ds_read_b128 v[170:173], v2 offset:1024
	ds_read_b128 v[174:177], v2 offset:2048
	ds_read_b128 v[178:181], v2 offset:3072
	s_add_u32 s48, s48, 0x80000
	s_addc_u32 s49, s49, 0
	s_mov_b32 m0, s54
	ds_read_b128 v[182:185], v148 offset:32768
	ds_read_b128 v[186:189], v148 offset:33792
	ds_read_b128 v[190:193], v148 offset:34816
	ds_read_b128 v[194:197], v148 offset:35840
	ds_read_b128 v[206:209], v148 offset:36864
	ds_read_b128 v[224:227], v148 offset:37888
	ds_read_b128 v[228:231], v148 offset:38912
	ds_read_b128 v[232:235], v148 offset:39936
	s_add_u32 s100, s48, 0xfff80000
	s_addc_u32 s101, s49, -1
	s_mov_b32 m0, s52
	s_nop 0
	global_load_lds_dwordx4 v140, s[100:101]
	s_mov_b32 m0, s53
	s_nop 0
	global_load_lds_dwordx4 v136, s[100:101]
	s_mov_b32 m0, s54
	s_nop 0
	global_load_lds_dwordx4 v140, s[48:49]
	s_mov_b32 m0, s55
	s_nop 0
	global_load_lds_dwordx4 v136, s[48:49]
	s_waitcnt vmcnt(8)
	s_waitcnt lgkmcnt(0)
	s_barrier
; #define PG8_STAGE(bufoff, gbase, voff) do { _Pragma("unroll") for (int _i = 0; _i < 2; ++_i) \
;         __builtin_amdgcn_global_load_lds((const unsigned*)((const char*)(gbase) + (voff)[_i]), (LAS unsigned*)(lds + (bufoff) + ldsw + _i * 8192), 16, 0, 0); } while (0)
; #define PG8_LDA(dst, b, h) do { _Pragma("unroll") for (int m = 0; m < 4; ++m) _Pragma("unroll") for (int k = 0; k < 2; ++k) dst[m][k] = *(const LAS bf16x8*)(lds + PG8_SA(b, h) + aoff + m * 2048 + k * 1024); } while (0)
; #define PG8_MMA(ai, bj, At, Bt) do { __builtin_amdgcn_s_setprio(1); _Pragma("unroll") for (int m = 0; m < 4; ++m) _Pragma("unroll") for (int n = 0; n < 2; ++n) _Pragma("unroll") for (int k = 0; k < 2; ++k) \
;         acc[ai][bj][m][n] = __builtin_amdgcn_mfma_f32_16x16x32_bf16(Bt[n][k], At[m][k], acc[ai][bj][m][n], 0, 0, 0); __builtin_amdgcn_s_setprio(0); } while (0)
; #define PG8_WAIT_V(n) asm volatile("s_waitcnt vmcnt(" #n ")" ::: "memory")
; #define PG8_WAIT_L(n) asm volatile("s_waitcnt lgkmcnt(" #n ")" ::: "memory")
; #define PG8_BAR __builtin_amdgcn_s_barrier()
; #define PG8_SCHED __builtin_amdgcn_sched_barrier(0)
; template <class Epi, bool ALIGN_EPI = true>
; __device__ __forceinline__ void gemm_phase(LAS unsigned char* lds, const Gemm g, const Sched& S, const Epi& E) {
;     ...
;             PG8_WAIT_V(8); PG8_WAIT_L(0); PG8_BAR; PG8_MMA(0, 0, At, B0); PG8_MMA(0, 1, At, B1); PG8_BAR; PG8_SCHED;
;             PG8_LDA(At, 1, 1); PG8_STAGE(PG8_SB(1, 0), b3, voffB); PG8_STAGE(PG8_SB(1, 1), b3 + hstepB, voffB); PG8_STAGE(PG8_SA(1, 0), a3, voffA);
;             PG8_WAIT_V(8); PG8_WAIT_L(0); PG8_BAR; PG8_MMA(1, 0, At, B0); PG8_MMA(1, 1, At, B1); PG8_BAR; PG8_SCHED;
;         }
	s_setprio 1
	s_waitcnt lgkmcnt(0)
	v_mfma_f32_16x16x32_bf16 v[130:133], v[150:153], v[182:185], v[130:133]
	v_mfma_f32_16x16x32_bf16 v[126:129], v[158:161], v[182:185], v[126:129]
	v_mfma_f32_16x16x32_bf16 v[114:117], v[150:153], v[190:193], v[114:117]
	v_mfma_f32_16x16x32_bf16 v[110:113], v[158:161], v[190:193], v[110:113]
	v_mfma_f32_16x16x32_bf16 v[98:101], v[150:153], v[206:209], v[98:101]
	v_mfma_f32_16x16x32_bf16 v[94:97], v[158:161], v[206:209], v[94:97]
	v_mfma_f32_16x16x32_bf16 v[82:85], v[150:153], v[228:231], v[82:85]
	v_mfma_f32_16x16x32_bf16 v[78:81], v[158:161], v[228:231], v[78:81]
	v_mfma_f32_16x16x32_bf16 v[130:133], v[154:157], v[186:189], v[130:133]
	v_mfma_f32_16x16x32_bf16 v[126:129], v[162:165], v[186:189], v[126:129]
	v_mfma_f32_16x16x32_bf16 v[114:117], v[154:157], v[194:197], v[114:117]
	v_mfma_f32_16x16x32_bf16 v[110:113], v[162:165], v[194:197], v[110:113]
	v_mfma_f32_16x16x32_bf16 v[98:101], v[154:157], v[224:227], v[98:101]
	v_mfma_f32_16x16x32_bf16 v[94:97], v[162:165], v[224:227], v[94:97]
	v_mfma_f32_16x16x32_bf16 v[82:85], v[154:157], v[232:235], v[82:85]
	v_mfma_f32_16x16x32_bf16 v[78:81], v[162:165], v[232:235], v[78:81]
	s_setprio 0
	s_setprio 1
	v_mfma_f32_16x16x32_bf16 v[122:125], v[166:169], v[182:185], v[122:125]
	v_mfma_f32_16x16x32_bf16 v[118:121], v[174:177], v[182:185], v[118:121]
	v_mfma_f32_16x16x32_bf16 v[106:109], v[166:169], v[190:193], v[106:109]
	v_mfma_f32_16x16x32_bf16 v[102:105], v[174:177], v[190:193], v[102:105]
	v_mfma_f32_16x16x32_bf16 v[90:93], v[166:169], v[206:209], v[90:93]
	v_mfma_f32_16x16x32_bf16 v[86:89], v[174:177], v[206:209], v[86:89]
	v_mfma_f32_16x16x32_bf16 v[74:77], v[166:169], v[228:231], v[74:77]
	v_mfma_f32_16x16x32_bf16 v[70:73], v[174:177], v[228:231], v[70:73]
	v_mfma_f32_16x16x32_bf16 v[122:125], v[170:173], v[186:189], v[122:125]
	v_mfma_f32_16x16x32_bf16 v[118:121], v[178:181], v[186:189], v[118:121]
	v_mfma_f32_16x16x32_bf16 v[106:109], v[170:173], v[194:197], v[106:109]
	v_mfma_f32_16x16x32_bf16 v[102:105], v[178:181], v[194:197], v[102:105]
	v_mfma_f32_16x16x32_bf16 v[90:93], v[170:173], v[224:227], v[90:93]
	v_mfma_f32_16x16x32_bf16 v[86:89], v[178:181], v[224:227], v[86:89]
	v_mfma_f32_16x16x32_bf16 v[74:77], v[170:173], v[232:235], v[74:77]
	v_mfma_f32_16x16x32_bf16 v[70:73], v[178:181], v[232:235], v[70:73]
	s_setprio 0
	s_barrier
	s_add_u32 s100, s46, 0x80
	s_addc_u32 s101, s47, 0
	s_add_i32 s48, s68, s51
	s_mov_b32 m0, s48
	ds_read_b128 v[182:185], v148 offset:49152
	ds_read_b128 v[186:189], v148 offset:50176
	ds_read_b128 v[190:193], v148 offset:51200
	ds_read_b128 v[194:197], v148 offset:52224
	ds_read_b128 v[206:209], v148 offset:53248
	ds_read_b128 v[224:227], v148 offset:54272
	ds_read_b128 v[228:231], v148 offset:55296
	ds_read_b128 v[232:235], v148 offset:56320
	global_load_lds_dwordx4 v138, s[100:101]
	s_add_i32 m0, s48, 0x2000
	s_add_u32 s46, s46, 0x80080
	s_addc_u32 s47, s47, 0
	s_add_i32 s48, s69, s51
	global_load_lds_dwordx4 v134, s[100:101]
	s_mov_b32 m0, s48
	s_nop 0
	global_load_lds_dwordx4 v138, s[46:47]
	s_add_i32 m0, s48, 0x2000
	s_nop 0
	global_load_lds_dwordx4 v134, s[46:47]
	s_waitcnt vmcnt(6)
	s_waitcnt lgkmcnt(0)
	s_barrier
	s_setprio 1
	s_waitcnt lgkmcnt(0)
	v_mfma_f32_16x16x32_bf16 v[66:69], v[150:153], v[182:185], v[66:69]
	v_mfma_f32_16x16x32_bf16 v[62:65], v[158:161], v[182:185], v[62:65]
	v_mfma_f32_16x16x32_bf16 v[50:53], v[150:153], v[190:193], v[50:53]
	v_mfma_f32_16x16x32_bf16 v[46:49], v[158:161], v[190:193], v[46:49]
	v_mfma_f32_16x16x32_bf16 v[34:37], v[150:153], v[206:209], v[34:37]
	v_mfma_f32_16x16x32_bf16 v[30:33], v[158:161], v[206:209], v[30:33]
	v_mfma_f32_16x16x32_bf16 v[18:21], v[150:153], v[228:231], v[18:21]
	v_mfma_f32_16x16x32_bf16 v[14:17], v[158:161], v[228:231], v[14:17]
	v_mfma_f32_16x16x32_bf16 v[66:69], v[154:157], v[186:189], v[66:69]
	v_mfma_f32_16x16x32_bf16 v[62:65], v[162:165], v[186:189], v[62:65]
	v_mfma_f32_16x16x32_bf16 v[50:53], v[154:157], v[194:197], v[50:53]
	v_mfma_f32_16x16x32_bf16 v[46:49], v[162:165], v[194:197], v[46:49]
	v_mfma_f32_16x16x32_bf16 v[34:37], v[154:157], v[224:227], v[34:37]
	v_mfma_f32_16x16x32_bf16 v[30:33], v[162:165], v[224:227], v[30:33]
	v_mfma_f32_16x16x32_bf16 v[18:21], v[154:157], v[232:235], v[18:21]
	v_mfma_f32_16x16x32_bf16 v[14:17], v[162:165], v[232:235], v[14:17]
	s_setprio 0
	s_setprio 1
	v_mfma_f32_16x16x32_bf16 v[58:61], v[166:169], v[182:185], v[58:61]
	v_mfma_f32_16x16x32_bf16 v[54:57], v[174:177], v[182:185], v[54:57]
	v_mfma_f32_16x16x32_bf16 v[42:45], v[166:169], v[190:193], v[42:45]
	v_mfma_f32_16x16x32_bf16 v[38:41], v[174:177], v[190:193], v[38:41]
	v_mfma_f32_16x16x32_bf16 v[26:29], v[166:169], v[206:209], v[26:29]
	v_mfma_f32_16x16x32_bf16 v[22:25], v[174:177], v[206:209], v[22:25]
	v_mfma_f32_16x16x32_bf16 v[8:11], v[166:169], v[228:231], v[10:13]
	v_mfma_f32_16x16x32_bf16 v[4:7], v[174:177], v[228:231], v[4:7]
	v_mfma_f32_16x16x32_bf16 v[58:61], v[170:173], v[186:189], v[58:61]
	v_mfma_f32_16x16x32_bf16 v[54:57], v[178:181], v[186:189], v[54:57]
	v_mfma_f32_16x16x32_bf16 v[42:45], v[170:173], v[194:197], v[42:45]
	v_mfma_f32_16x16x32_bf16 v[38:41], v[178:181], v[194:197], v[38:41]
	v_mfma_f32_16x16x32_bf16 v[26:29], v[170:173], v[224:227], v[26:29]
	v_mfma_f32_16x16x32_bf16 v[22:25], v[178:181], v[224:227], v[22:25]
	v_mfma_f32_16x16x32_bf16 v[10:13], v[170:173], v[232:235], v[8:11]
	v_mfma_f32_16x16x32_bf16 v[6:9], v[178:181], v[232:235], v[4:7]
	s_setprio 0
	s_barrier
	s_add_u32 s44, s44, 0x100
	s_addc_u32 s45, s45, 0
	s_add_u32 s65, s65, 0x100
	s_addc_u32 s66, s66, 0
	s_cmp_ge_i32 s67, s56
	s_mov_b32 s46, s67
	s_cbranch_scc0 .LBB0_1402

; #define PG8_STAGE(bufoff, gbase, voff) do { _Pragma("unroll") for (int _i = 0; _i < 2; ++_i) \
;         __builtin_amdgcn_global_load_lds((const unsigned*)((const char*)(gbase) + (voff)[_i]), (LAS unsigned*)(lds + (bufoff) + ldsw + _i * 8192), 16, 0, 0); } while (0)
; #define PG8_LDA(dst, b, h) do { _Pragma("unroll") for (int m = 0; m < 4; ++m) _Pragma("unroll") for (int k = 0; k < 2; ++k) dst[m][k] = *(const LAS bf16x8*)(lds + PG8_SA(b, h) + aoff + m * 2048 + k * 1024); } while (0)
; #define PG8_LDB(dst, b, h) do { _Pragma("unroll") for (int n = 0; n < 2; ++n) _Pragma("unroll") for (int k = 0; k < 2; ++k) dst[n][k] = *(const LAS bf16x8*)(lds + PG8_SB(b, h) + boff + n * 2048 + k * 1024); } while (0)
; #define PG8_MMA(ai, bj, At, Bt) do { __builtin_amdgcn_s_setprio(1); _Pragma("unroll") for (int m = 0; m < 4; ++m) _Pragma("unroll") for (int n = 0; n < 2; ++n) _Pragma("unroll") for (int k = 0; k < 2; ++k) \
;         acc[ai][bj][m][n] = __builtin_amdgcn_mfma_f32_16x16x32_bf16(Bt[n][k], At[m][k], acc[ai][bj][m][n], 0, 0, 0); __builtin_amdgcn_s_setprio(0); } while (0)
; #define PG8_WAIT_V(n) asm volatile("s_waitcnt vmcnt(" #n ")" ::: "memory")
; template <class Epi, bool ALIGN_EPI = true>
; __device__ __forceinline__ void gemm_phase(LAS unsigned char* lds, const Gemm g, const Sched& S, const Epi& E) {
;     ...
;         for (int t = t_lo; t < t_hi; t += 2) {
;             const bool last = (t == nt - 2);
;             const char* a1 = cA + (size_t)(t + 1) * kstep;
;             const char* a2 = last ? nA : cA + (size_t)(t + 2) * kstep; const char* b2 = last ? nB : cB + (size_t)(t + 2) * kstep;
;             const char* a3 = a2 + kstep; const char* b3 = b2 + kstep;
;             const int rflag = __builtin_amdgcn_readfirstlane(t | (int)(ui == 0));
;             PG8_LDB(B0, 0, 0); PG8_LDB(B1, 0, 1); PG8_SCHED; PG8_LDA(At, 0, 0); PG8_STAGE(PG8_SA(1, 1), a1 + hstepA, voffA);
;             if constexpr (Epi::NSTORES > 0) PG8_WAIT_RELAX(rflag, 8 + Epi::NSTORES); else PG8_WAIT_V(8);
;             PG8_WAIT_L(0); PG8_BAR; PG8_MMA(0, 0, At, B0); PG8_MMA(0, 1, At, B1); PG8_BAR; PG8_SCHED;
;             PG8_LDA(At, 0, 1); PG8_STAGE(PG8_SB(0, 0), b2, voffB); PG8_STAGE(PG8_SB(0, 1), b2 + hstepB, voffB); PG8_STAGE(PG8_SA(0, 0), a2, voffA);
;             if constexpr (Epi::NSTORES > 0) PG8_WAIT_RELAX(rflag, 8 + Epi::NSTORES); else PG8_WAIT_V(8);
.LBB0_1457:
	s_add_i32 s69, s46, 2
	s_add_u32 s26, s44, 0xffc00080
	s_addc_u32 s27, s45, -1
	s_add_i32 s70, 0, 0x10000
	s_cmp_eq_u32 s59, s46
	v_add_u32_e32 v223, s46, v145
	s_cselect_b32 s47, s19, s27
	s_cselect_b32 s46, s64, s26
	s_cselect_b32 s27, s65, s68
	s_cselect_b32 s26, s66, s67
	s_add_i32 s72, 0, 0x14000
	v_add_u32_e32 v158, s70, v143
	v_add_u32_e32 v174, s72, v143
	ds_read_b128 v[146:149], v158
	ds_read_b128 v[150:153], v158 offset:1024
	ds_read_b128 v[154:157], v158 offset:2048
	ds_read_b128 v[158:161], v158 offset:3072
	ds_read_b128 v[162:165], v174
	ds_read_b128 v[166:169], v174 offset:1024
	ds_read_b128 v[170:173], v174 offset:2048
	ds_read_b128 v[174:177], v174 offset:3072
	s_add_i32 m0, s48, 0xc000
	ds_read_b128 v[178:181], v144
	ds_read_b128 v[182:185], v144 offset:1024
	ds_read_b128 v[186:189], v144 offset:2048
	ds_read_b128 v[190:193], v144 offset:3072
	ds_read_b128 v[194:197], v144 offset:4096
	ds_read_b128 v[206:209], v144 offset:5120
	ds_read_b128 v[224:227], v144 offset:6144
	ds_read_b128 v[228:231], v144 offset:7168
	s_add_u32 s100, s44, 0xffc00000
	s_addc_u32 s101, s45, -1
	s_mov_b32 m0, s57
	s_nop 0
	global_load_lds_dwordx4 v138, s[100:101]
	s_mov_b32 m0, s58
	s_nop 0
	global_load_lds_dwordx4 v140, s[100:101]
	s_add_i32 m0, s48, 0xc000
	s_nop 0
	global_load_lds_dwordx4 v138, s[44:45]
	s_add_i32 m0, s48, 0xe000
	v_readfirstlane_b32 s73, v223
	global_load_lds_dwordx4 v140, s[44:45]
	s_cmp_eq_u32 s73, 0
	s_cbranch_scc1 .Lrw14
	s_waitcnt vmcnt(8)
.Lrw14:
	s_waitcnt vmcnt(24)
	s_waitcnt lgkmcnt(0)
	s_barrier
	s_setprio 1
	s_waitcnt lgkmcnt(0)
	v_mfma_f32_16x16x32_bf16 v[124:127], v[146:149], v[178:181], v[124:127]
	v_mfma_f32_16x16x32_bf16 v[128:131], v[154:157], v[178:181], v[128:131]
	v_mfma_f32_16x16x32_bf16 v[112:115], v[146:149], v[186:189], v[112:115]
	v_mfma_f32_16x16x32_bf16 v[108:111], v[154:157], v[186:189], v[108:111]
	v_mfma_f32_16x16x32_bf16 v[96:99], v[146:149], v[194:197], v[96:99]
	v_mfma_f32_16x16x32_bf16 v[92:95], v[154:157], v[194:197], v[92:95]
	v_mfma_f32_16x16x32_bf16 v[80:83], v[146:149], v[224:227], v[80:83]
	v_mfma_f32_16x16x32_bf16 v[76:79], v[154:157], v[224:227], v[76:79]
	v_mfma_f32_16x16x32_bf16 v[124:127], v[150:153], v[182:185], v[124:127]
	v_mfma_f32_16x16x32_bf16 v[128:131], v[158:161], v[182:185], v[128:131]
	v_mfma_f32_16x16x32_bf16 v[112:115], v[150:153], v[190:193], v[112:115]
	v_mfma_f32_16x16x32_bf16 v[108:111], v[158:161], v[190:193], v[108:111]
	v_mfma_f32_16x16x32_bf16 v[96:99], v[150:153], v[206:209], v[96:99]
	v_mfma_f32_16x16x32_bf16 v[92:95], v[158:161], v[206:209], v[92:95]
	v_mfma_f32_16x16x32_bf16 v[80:83], v[150:153], v[228:231], v[80:83]
	v_mfma_f32_16x16x32_bf16 v[76:79], v[158:161], v[228:231], v[76:79]
	s_setprio 0
	s_setprio 1
	v_mfma_f32_16x16x32_bf16 v[120:123], v[162:165], v[178:181], v[120:123]
	v_mfma_f32_16x16x32_bf16 v[116:119], v[170:173], v[178:181], v[116:119]
	v_mfma_f32_16x16x32_bf16 v[104:107], v[162:165], v[186:189], v[104:107]
	v_mfma_f32_16x16x32_bf16 v[100:103], v[170:173], v[186:189], v[100:103]
	v_mfma_f32_16x16x32_bf16 v[88:91], v[162:165], v[194:197], v[88:91]
	v_mfma_f32_16x16x32_bf16 v[84:87], v[170:173], v[194:197], v[84:87]
	v_mfma_f32_16x16x32_bf16 v[72:75], v[162:165], v[224:227], v[72:75]
	v_mfma_f32_16x16x32_bf16 v[68:71], v[170:173], v[224:227], v[68:71]
	v_mfma_f32_16x16x32_bf16 v[120:123], v[166:169], v[182:185], v[120:123]
	v_mfma_f32_16x16x32_bf16 v[116:119], v[174:177], v[182:185], v[116:119]
	v_mfma_f32_16x16x32_bf16 v[104:107], v[166:169], v[190:193], v[104:107]
	v_mfma_f32_16x16x32_bf16 v[100:103], v[174:177], v[190:193], v[100:103]
	v_mfma_f32_16x16x32_bf16 v[88:91], v[166:169], v[206:209], v[88:91]
	v_mfma_f32_16x16x32_bf16 v[84:87], v[174:177], v[206:209], v[84:87]
	v_mfma_f32_16x16x32_bf16 v[72:75], v[166:169], v[228:231], v[72:75]
	v_mfma_f32_16x16x32_bf16 v[68:71], v[174:177], v[228:231], v[68:71]
	s_setprio 0
	s_barrier
	s_add_i32 s70, s70, s37
	s_mov_b32 m0, s70
	ds_read_b128 v[178:181], v144 offset:16384
	ds_read_b128 v[182:185], v144 offset:17408
	ds_read_b128 v[186:189], v144 offset:18432
	ds_read_b128 v[190:193], v144 offset:19456
	ds_read_b128 v[194:197], v144 offset:20480
	ds_read_b128 v[206:209], v144 offset:21504
	ds_read_b128 v[224:227], v144 offset:22528
	ds_read_b128 v[228:231], v144 offset:23552
	global_load_lds_dwordx4 v2, s[26:27]
	s_add_i32 m0, s70, 0x2000
	s_add_u32 s70, s26, 0x80000
	s_addc_u32 s71, s27, 0
	s_add_i32 s72, s72, s37
	global_load_lds_dwordx4 v132, s[26:27]
	s_mov_b32 m0, s72
	s_nop 0
	global_load_lds_dwordx4 v2, s[70:71]
	s_add_i32 m0, s72, 0x2000
	s_nop 0
	global_load_lds_dwordx4 v132, s[70:71]
	s_cmp_eq_u32 s73, 0
	s_cbranch_scc1 .Lrw15
	s_waitcnt vmcnt(6)
; #define PG8_STAGE(bufoff, gbase, voff) do { _Pragma("unroll") for (int _i = 0; _i < 2; ++_i) \
;         __builtin_amdgcn_global_load_lds((const unsigned*)((const char*)(gbase) + (voff)[_i]), (LAS unsigned*)(lds + (bufoff) + ldsw + _i * 8192), 16, 0, 0); } while (0)
; #define PG8_LDA(dst, b, h) do { _Pragma("unroll") for (int m = 0; m < 4; ++m) _Pragma("unroll") for (int k = 0; k < 2; ++k) dst[m][k] = *(const LAS bf16x8*)(lds + PG8_SA(b, h) + aoff + m * 2048 + k * 1024); } while (0)
; #define PG8_LDB(dst, b, h) do { _Pragma("unroll") for (int n = 0; n < 2; ++n) _Pragma("unroll") for (int k = 0; k < 2; ++k) dst[n][k] = *(const LAS bf16x8*)(lds + PG8_SB(b, h) + boff + n * 2048 + k * 1024); } while (0)
; #define PG8_MMA(ai, bj, At, Bt) do { __builtin_amdgcn_s_setprio(1); _Pragma("unroll") for (int m = 0; m < 4; ++m) _Pragma("unroll") for (int n = 0; n < 2; ++n) _Pragma("unroll") for (int k = 0; k < 2; ++k) \
;         acc[ai][bj][m][n] = __builtin_amdgcn_mfma_f32_16x16x32_bf16(Bt[n][k], At[m][k], acc[ai][bj][m][n], 0, 0, 0); __builtin_amdgcn_s_setprio(0); } while (0)
; #define PG8_WAIT_V(n) asm volatile("s_waitcnt vmcnt(" #n ")" ::: "memory")
; #define PG8_WAIT_L(n) asm volatile("s_waitcnt lgkmcnt(" #n ")" ::: "memory")
; #define PG8_BAR __builtin_amdgcn_s_barrier()
; #define PG8_WAIT_RELAX(flag, n) asm volatile("s_cmp_eq_u32 %0, 0\n\ts_cbranch_scc1 .Lrw%=\n\ts_waitcnt vmcnt(8)\n.Lrw%=:\n\ts_waitcnt vmcnt(%1)" :: "s"(flag), "n"(n) : "scc", "memory")
; #define PG8_SCHED __builtin_amdgcn_sched_barrier(0)
; template <class Epi, bool ALIGN_EPI = true>
; __device__ __forceinline__ void gemm_phase(LAS unsigned char* lds, const Gemm g, const Sched& S, const Epi& E) {
;     ...
;             if constexpr (Epi::NSTORES > 0) PG8_WAIT_RELAX(rflag, 8 + Epi::NSTORES); else PG8_WAIT_V(8);
;             PG8_WAIT_L(0); PG8_BAR; PG8_MMA(1, 0, At, B0); PG8_MMA(1, 1, At, B1); PG8_BAR; PG8_SCHED;
;             PG8_LDB(B0, 1, 0); PG8_LDB(B1, 1, 1); PG8_SCHED; PG8_LDA(At, 1, 0); PG8_STAGE(PG8_SA(0, 1), a2 + hstepA, voffA);
;             PG8_WAIT_V(8); PG8_WAIT_L(0); PG8_BAR; PG8_MMA(0, 0, At, B0); PG8_MMA(0, 1, At, B1); PG8_BAR; PG8_SCHED;
.Lrw15:
	s_waitcnt vmcnt(6)
	s_waitcnt lgkmcnt(0)
	s_barrier
	s_setprio 1
	s_waitcnt lgkmcnt(0)
	v_mfma_f32_16x16x32_bf16 v[64:67], v[146:149], v[178:181], v[64:67]
	v_mfma_f32_16x16x32_bf16 v[60:63], v[154:157], v[178:181], v[60:63]
	v_mfma_f32_16x16x32_bf16 v[48:51], v[146:149], v[186:189], v[48:51]
	v_mfma_f32_16x16x32_bf16 v[44:47], v[154:157], v[186:189], v[44:47]
	v_mfma_f32_16x16x32_bf16 v[32:35], v[146:149], v[194:197], v[32:35]
	v_mfma_f32_16x16x32_bf16 v[28:31], v[154:157], v[194:197], v[28:31]
	v_mfma_f32_16x16x32_bf16 v[16:19], v[146:149], v[224:227], v[16:19]
	v_mfma_f32_16x16x32_bf16 v[12:15], v[154:157], v[224:227], v[12:15]
	v_mfma_f32_16x16x32_bf16 v[64:67], v[150:153], v[182:185], v[64:67]
	v_mfma_f32_16x16x32_bf16 v[60:63], v[158:161], v[182:185], v[60:63]
	v_mfma_f32_16x16x32_bf16 v[48:51], v[150:153], v[190:193], v[48:51]
	v_mfma_f32_16x16x32_bf16 v[44:47], v[158:161], v[190:193], v[44:47]
	v_mfma_f32_16x16x32_bf16 v[32:35], v[150:153], v[206:209], v[32:35]
	v_mfma_f32_16x16x32_bf16 v[28:31], v[158:161], v[206:209], v[28:31]
	v_mfma_f32_16x16x32_bf16 v[16:19], v[150:153], v[228:231], v[16:19]
	v_mfma_f32_16x16x32_bf16 v[12:15], v[158:161], v[228:231], v[12:15]
	s_setprio 0
	s_setprio 1
	v_mfma_f32_16x16x32_bf16 v[56:59], v[162:165], v[178:181], v[56:59]
	v_mfma_f32_16x16x32_bf16 v[52:55], v[170:173], v[178:181], v[52:55]
	v_mfma_f32_16x16x32_bf16 v[40:43], v[162:165], v[186:189], v[40:43]
	v_mfma_f32_16x16x32_bf16 v[36:39], v[170:173], v[186:189], v[36:39]
	v_mfma_f32_16x16x32_bf16 v[24:27], v[162:165], v[194:197], v[24:27]
	v_mfma_f32_16x16x32_bf16 v[20:23], v[170:173], v[194:197], v[20:23]
	v_mfma_f32_16x16x32_bf16 v[8:11], v[162:165], v[224:227], v[8:11]
	v_mfma_f32_16x16x32_bf16 v[4:7], v[170:173], v[224:227], v[4:7]
	v_mfma_f32_16x16x32_bf16 v[56:59], v[166:169], v[182:185], v[56:59]
	v_mfma_f32_16x16x32_bf16 v[52:55], v[174:177], v[182:185], v[52:55]
	v_mfma_f32_16x16x32_bf16 v[40:43], v[166:169], v[190:193], v[40:43]
	v_mfma_f32_16x16x32_bf16 v[36:39], v[174:177], v[190:193], v[36:39]
	v_mfma_f32_16x16x32_bf16 v[24:27], v[166:169], v[206:209], v[24:27]
	v_mfma_f32_16x16x32_bf16 v[20:23], v[174:177], v[206:209], v[20:23]
	v_mfma_f32_16x16x32_bf16 v[8:11], v[166:169], v[228:231], v[8:11]
	v_mfma_f32_16x16x32_bf16 v[4:7], v[174:177], v[228:231], v[4:7]
	s_setprio 0
	s_barrier
	s_add_i32 s70, 0, 0x18000
	s_add_i32 s71, 0, 0x1c000
	v_add_u32_e32 v158, s70, v143
	v_add_u32_e32 v174, s71, v143
	ds_read_b128 v[146:149], v158
	ds_read_b128 v[150:153], v158 offset:1024
	ds_read_b128 v[154:157], v158 offset:2048
	ds_read_b128 v[158:161], v158 offset:3072
	ds_read_b128 v[162:165], v174
	ds_read_b128 v[166:169], v174 offset:1024
	ds_read_b128 v[170:173], v174 offset:2048
	ds_read_b128 v[174:177], v174 offset:3072
	s_add_u32 s46, s46, 0x400000
	s_addc_u32 s47, s47, 0
	s_mov_b32 m0, s50
	ds_read_b128 v[178:181], v144 offset:32768
	ds_read_b128 v[182:185], v144 offset:33792
	ds_read_b128 v[186:189], v144 offset:34816
	ds_read_b128 v[190:193], v144 offset:35840
	ds_read_b128 v[194:197], v144 offset:36864
	ds_read_b128 v[206:209], v144 offset:37888
	ds_read_b128 v[224:227], v144 offset:38912
	ds_read_b128 v[228:231], v144 offset:39936
	s_add_u32 s100, s46, 0xffc00000
	s_addc_u32 s101, s47, -1
	s_mov_b32 m0, s48
	s_nop 0
	global_load_lds_dwordx4 v136, s[100:101]
	s_mov_b32 m0, s49
	s_nop 0
	global_load_lds_dwordx4 v134, s[100:101]
	s_mov_b32 m0, s50
	s_nop 0
	global_load_lds_dwordx4 v136, s[46:47]
	s_mov_b32 m0, s51
	s_nop 0
	global_load_lds_dwordx4 v134, s[46:47]
	s_waitcnt vmcnt(8)
	s_waitcnt lgkmcnt(0)
	s_barrier
; #define PG8_STAGE(bufoff, gbase, voff) do { _Pragma("unroll") for (int _i = 0; _i < 2; ++_i) \
;         __builtin_amdgcn_global_load_lds((const unsigned*)((const char*)(gbase) + (voff)[_i]), (LAS unsigned*)(lds + (bufoff) + ldsw + _i * 8192), 16, 0, 0); } while (0)
; #define PG8_LDA(dst, b, h) do { _Pragma("unroll") for (int m = 0; m < 4; ++m) _Pragma("unroll") for (int k = 0; k < 2; ++k) dst[m][k] = *(const LAS bf16x8*)(lds + PG8_SA(b, h) + aoff + m * 2048 + k * 1024); } while (0)
; #define PG8_MMA(ai, bj, At, Bt) do { __builtin_amdgcn_s_setprio(1); _Pragma("unroll") for (int m = 0; m < 4; ++m) _Pragma("unroll") for (int n = 0; n < 2; ++n) _Pragma("unroll") for (int k = 0; k < 2; ++k) \
;         acc[ai][bj][m][n] = __builtin_amdgcn_mfma_f32_16x16x32_bf16(Bt[n][k], At[m][k], acc[ai][bj][m][n], 0, 0, 0); __builtin_amdgcn_s_setprio(0); } while (0)
; #define PG8_WAIT_V(n) asm volatile("s_waitcnt vmcnt(" #n ")" ::: "memory")
; #define PG8_WAIT_L(n) asm volatile("s_waitcnt lgkmcnt(" #n ")" ::: "memory")
; #define PG8_BAR __builtin_amdgcn_s_barrier()
; #define PG8_SCHED __builtin_amdgcn_sched_barrier(0)
; template <class Epi, bool ALIGN_EPI = true>
; __device__ __forceinline__ void gemm_phase(LAS unsigned char* lds, const Gemm g, const Sched& S, const Epi& E) {
;     ...
;             PG8_WAIT_V(8); PG8_WAIT_L(0); PG8_BAR; PG8_MMA(0, 0, At, B0); PG8_MMA(0, 1, At, B1); PG8_BAR; PG8_SCHED;
;             PG8_LDA(At, 1, 1); PG8_STAGE(PG8_SB(1, 0), b3, voffB); PG8_STAGE(PG8_SB(1, 1), b3 + hstepB, voffB); PG8_STAGE(PG8_SA(1, 0), a3, voffA);
;             PG8_WAIT_V(8); PG8_WAIT_L(0); PG8_BAR; PG8_MMA(1, 0, At, B0); PG8_MMA(1, 1, At, B1); PG8_BAR; PG8_SCHED;
;         }
	s_setprio 1
	s_waitcnt lgkmcnt(0)
	v_mfma_f32_16x16x32_bf16 v[124:127], v[146:149], v[178:181], v[124:127]
	v_mfma_f32_16x16x32_bf16 v[128:131], v[154:157], v[178:181], v[128:131]
	v_mfma_f32_16x16x32_bf16 v[112:115], v[146:149], v[186:189], v[112:115]
	v_mfma_f32_16x16x32_bf16 v[108:111], v[154:157], v[186:189], v[108:111]
	v_mfma_f32_16x16x32_bf16 v[96:99], v[146:149], v[194:197], v[96:99]
	v_mfma_f32_16x16x32_bf16 v[92:95], v[154:157], v[194:197], v[92:95]
	v_mfma_f32_16x16x32_bf16 v[80:83], v[146:149], v[224:227], v[80:83]
	v_mfma_f32_16x16x32_bf16 v[76:79], v[154:157], v[224:227], v[76:79]
	v_mfma_f32_16x16x32_bf16 v[124:127], v[150:153], v[182:185], v[124:127]
	v_mfma_f32_16x16x32_bf16 v[128:131], v[158:161], v[182:185], v[128:131]
	v_mfma_f32_16x16x32_bf16 v[112:115], v[150:153], v[190:193], v[112:115]
	v_mfma_f32_16x16x32_bf16 v[108:111], v[158:161], v[190:193], v[108:111]
	v_mfma_f32_16x16x32_bf16 v[96:99], v[150:153], v[206:209], v[96:99]
	v_mfma_f32_16x16x32_bf16 v[92:95], v[158:161], v[206:209], v[92:95]
	v_mfma_f32_16x16x32_bf16 v[80:83], v[150:153], v[228:231], v[80:83]
	v_mfma_f32_16x16x32_bf16 v[76:79], v[158:161], v[228:231], v[76:79]
	s_setprio 0
	s_setprio 1
	v_mfma_f32_16x16x32_bf16 v[120:123], v[162:165], v[178:181], v[120:123]
	v_mfma_f32_16x16x32_bf16 v[116:119], v[170:173], v[178:181], v[116:119]
	v_mfma_f32_16x16x32_bf16 v[104:107], v[162:165], v[186:189], v[104:107]
	v_mfma_f32_16x16x32_bf16 v[100:103], v[170:173], v[186:189], v[100:103]
	v_mfma_f32_16x16x32_bf16 v[88:91], v[162:165], v[194:197], v[88:91]
	v_mfma_f32_16x16x32_bf16 v[84:87], v[170:173], v[194:197], v[84:87]
	v_mfma_f32_16x16x32_bf16 v[72:75], v[162:165], v[224:227], v[72:75]
	v_mfma_f32_16x16x32_bf16 v[68:71], v[170:173], v[224:227], v[68:71]
	v_mfma_f32_16x16x32_bf16 v[120:123], v[166:169], v[182:185], v[120:123]
	v_mfma_f32_16x16x32_bf16 v[116:119], v[174:177], v[182:185], v[116:119]
	v_mfma_f32_16x16x32_bf16 v[104:107], v[166:169], v[190:193], v[104:107]
	v_mfma_f32_16x16x32_bf16 v[100:103], v[174:177], v[190:193], v[100:103]
	v_mfma_f32_16x16x32_bf16 v[88:91], v[166:169], v[206:209], v[88:91]
	v_mfma_f32_16x16x32_bf16 v[84:87], v[174:177], v[206:209], v[84:87]
	v_mfma_f32_16x16x32_bf16 v[72:75], v[166:169], v[228:231], v[72:75]
	v_mfma_f32_16x16x32_bf16 v[68:71], v[174:177], v[228:231], v[68:71]
	s_setprio 0
	s_barrier
	s_add_u32 s100, s26, 0x80
	s_addc_u32 s101, s27, 0
	s_add_i32 s46, s70, s37
	s_mov_b32 m0, s46
	ds_read_b128 v[178:181], v144 offset:49152
	ds_read_b128 v[182:185], v144 offset:50176
	ds_read_b128 v[186:189], v144 offset:51200
	ds_read_b128 v[190:193], v144 offset:52224
	ds_read_b128 v[194:197], v144 offset:53248
	ds_read_b128 v[206:209], v144 offset:54272
	ds_read_b128 v[224:227], v144 offset:55296
	ds_read_b128 v[228:231], v144 offset:56320
	global_load_lds_dwordx4 v2, s[100:101]
	s_add_i32 m0, s46, 0x2000
	s_add_u32 s26, s26, 0x80080
	s_addc_u32 s27, s27, 0
	s_add_i32 s46, s71, s37
	global_load_lds_dwordx4 v132, s[100:101]
	s_mov_b32 m0, s46
	s_nop 0
	global_load_lds_dwordx4 v2, s[26:27]
	s_add_i32 m0, s46, 0x2000
	s_nop 0
	global_load_lds_dwordx4 v132, s[26:27]
	s_waitcnt vmcnt(6)
	s_waitcnt lgkmcnt(0)
	s_barrier
	s_setprio 1
	s_waitcnt lgkmcnt(0)
	v_mfma_f32_16x16x32_bf16 v[64:67], v[146:149], v[178:181], v[64:67]
	v_mfma_f32_16x16x32_bf16 v[60:63], v[154:157], v[178:181], v[60:63]
	v_mfma_f32_16x16x32_bf16 v[48:51], v[146:149], v[186:189], v[48:51]
	v_mfma_f32_16x16x32_bf16 v[44:47], v[154:157], v[186:189], v[44:47]
	v_mfma_f32_16x16x32_bf16 v[32:35], v[146:149], v[194:197], v[32:35]
	v_mfma_f32_16x16x32_bf16 v[28:31], v[154:157], v[194:197], v[28:31]
	v_mfma_f32_16x16x32_bf16 v[16:19], v[146:149], v[224:227], v[16:19]
	v_mfma_f32_16x16x32_bf16 v[12:15], v[154:157], v[224:227], v[12:15]
	v_mfma_f32_16x16x32_bf16 v[64:67], v[150:153], v[182:185], v[64:67]
	v_mfma_f32_16x16x32_bf16 v[60:63], v[158:161], v[182:185], v[60:63]
	v_mfma_f32_16x16x32_bf16 v[48:51], v[150:153], v[190:193], v[48:51]
	v_mfma_f32_16x16x32_bf16 v[44:47], v[158:161], v[190:193], v[44:47]
	v_mfma_f32_16x16x32_bf16 v[32:35], v[150:153], v[206:209], v[32:35]
	v_mfma_f32_16x16x32_bf16 v[28:31], v[158:161], v[206:209], v[28:31]
	v_mfma_f32_16x16x32_bf16 v[16:19], v[150:153], v[228:231], v[16:19]
	v_mfma_f32_16x16x32_bf16 v[12:15], v[158:161], v[228:231], v[12:15]
	s_setprio 0
	s_setprio 1
	v_mfma_f32_16x16x32_bf16 v[56:59], v[162:165], v[178:181], v[56:59]
	v_mfma_f32_16x16x32_bf16 v[52:55], v[170:173], v[178:181], v[52:55]
	v_mfma_f32_16x16x32_bf16 v[40:43], v[162:165], v[186:189], v[40:43]
	v_mfma_f32_16x16x32_bf16 v[36:39], v[170:173], v[186:189], v[36:39]
	v_mfma_f32_16x16x32_bf16 v[24:27], v[162:165], v[194:197], v[24:27]
	v_mfma_f32_16x16x32_bf16 v[20:23], v[170:173], v[194:197], v[20:23]
	v_mfma_f32_16x16x32_bf16 v[8:11], v[162:165], v[224:227], v[8:11]
	v_mfma_f32_16x16x32_bf16 v[4:7], v[170:173], v[224:227], v[4:7]
	v_mfma_f32_16x16x32_bf16 v[56:59], v[166:169], v[182:185], v[56:59]
	v_mfma_f32_16x16x32_bf16 v[52:55], v[174:177], v[182:185], v[52:55]
	v_mfma_f32_16x16x32_bf16 v[40:43], v[166:169], v[190:193], v[40:43]
	v_mfma_f32_16x16x32_bf16 v[36:39], v[174:177], v[190:193], v[36:39]
	v_mfma_f32_16x16x32_bf16 v[24:27], v[166:169], v[206:209], v[24:27]
	v_mfma_f32_16x16x32_bf16 v[20:23], v[174:177], v[206:209], v[20:23]
	v_mfma_f32_16x16x32_bf16 v[8:11], v[166:169], v[228:231], v[8:11]
	v_mfma_f32_16x16x32_bf16 v[4:7], v[174:177], v[228:231], v[4:7]
	s_setprio 0
	s_barrier
	s_add_u32 s44, s44, 0x100
	s_addc_u32 s45, s45, 0
	s_add_u32 s67, s67, 0x100
	s_addc_u32 s68, s68, 0
	s_cmp_ge_i32 s69, s54
	s_mov_b32 s46, s69
	s_cbranch_scc0 .LBB0_1457

; #define PG8_STAGE(bufoff, gbase, voff) do { _Pragma("unroll") for (int _i = 0; _i < 2; ++_i) \
;         __builtin_amdgcn_global_load_lds((const unsigned*)((const char*)(gbase) + (voff)[_i]), (LAS unsigned*)(lds + (bufoff) + ldsw + _i * 8192), 16, 0, 0); } while (0)
; #define PG8_LDA(dst, b, h) do { _Pragma("unroll") for (int m = 0; m < 4; ++m) _Pragma("unroll") for (int k = 0; k < 2; ++k) dst[m][k] = *(const LAS bf16x8*)(lds + PG8_SA(b, h) + aoff + m * 2048 + k * 1024); } while (0)
; #define PG8_LDB(dst, b, h) do { _Pragma("unroll") for (int n = 0; n < 2; ++n) _Pragma("unroll") for (int k = 0; k < 2; ++k) dst[n][k] = *(const LAS bf16x8*)(lds + PG8_SB(b, h) + boff + n * 2048 + k * 1024); } while (0)
; #define PG8_MMA(ai, bj, At, Bt) do { __builtin_amdgcn_s_setprio(1); _Pragma("unroll") for (int m = 0; m < 4; ++m) _Pragma("unroll") for (int n = 0; n < 2; ++n) _Pragma("unroll") for (int k = 0; k < 2; ++k) \
;         acc[ai][bj][m][n] = __builtin_amdgcn_mfma_f32_16x16x32_bf16(Bt[n][k], At[m][k], acc[ai][bj][m][n], 0, 0, 0); __builtin_amdgcn_s_setprio(0); } while (0)
; #define PG8_WAIT_V(n) asm volatile("s_waitcnt vmcnt(" #n ")" ::: "memory")
; template <class Epi, bool ALIGN_EPI = true>
; __device__ __forceinline__ void gemm_phase(LAS unsigned char* lds, const Gemm g, const Sched& S, const Epi& E) {
;     ...
;         for (int t = t_lo; t < t_hi; t += 2) {
;             const bool last = (t == nt - 2);
;             const char* a1 = cA + (size_t)(t + 1) * kstep;
;             const char* a2 = last ? nA : cA + (size_t)(t + 2) * kstep; const char* b2 = last ? nB : cB + (size_t)(t + 2) * kstep;
;             const char* a3 = a2 + kstep; const char* b3 = b2 + kstep;
;             const int rflag = __builtin_amdgcn_readfirstlane(t | (int)(ui == 0));
;             PG8_LDB(B0, 0, 0); PG8_LDB(B1, 0, 1); PG8_SCHED; PG8_LDA(At, 0, 0); PG8_STAGE(PG8_SA(1, 1), a1 + hstepA, voffA);
;             if constexpr (Epi::NSTORES > 0) PG8_WAIT_RELAX(rflag, 8 + Epi::NSTORES); else PG8_WAIT_V(8);
;             PG8_WAIT_L(0); PG8_BAR; PG8_MMA(0, 0, At, B0); PG8_MMA(0, 1, At, B1); PG8_BAR; PG8_SCHED;
;             PG8_LDA(At, 0, 1); PG8_STAGE(PG8_SB(0, 0), b2, voffB); PG8_STAGE(PG8_SB(0, 1), b2 + hstepB, voffB); PG8_STAGE(PG8_SA(0, 0), a2, voffA);
;             if constexpr (Epi::NSTORES > 0) PG8_WAIT_RELAX(rflag, 8 + Epi::NSTORES); else PG8_WAIT_V(8);
.LBB0_1479:
	s_add_i32 s67, s44, 2
	s_add_u32 s26, s42, 0xfff80080
	s_addc_u32 s27, s43, -1
	s_add_i32 s68, 0, 0x10000
	s_cmp_eq_u32 s57, s44
	v_add_u32_e32 v223, s44, v145
	s_cselect_b32 s45, s17, s27
	s_cselect_b32 s44, s62, s26
	s_cselect_b32 s27, s63, s66
	s_cselect_b32 s26, s64, s65
	s_add_i32 s70, 0, 0x14000
	v_add_u32_e32 v158, s68, v143
	v_add_u32_e32 v174, s70, v143
	ds_read_b128 v[146:149], v158
	ds_read_b128 v[150:153], v158 offset:1024
	ds_read_b128 v[154:157], v158 offset:2048
	ds_read_b128 v[158:161], v158 offset:3072
	ds_read_b128 v[162:165], v174
	ds_read_b128 v[166:169], v174 offset:1024
	ds_read_b128 v[170:173], v174 offset:2048
	ds_read_b128 v[174:177], v174 offset:3072
	s_add_i32 m0, s46, 0xc000
	ds_read_b128 v[178:181], v144
	ds_read_b128 v[182:185], v144 offset:1024
	ds_read_b128 v[186:189], v144 offset:2048
	ds_read_b128 v[190:193], v144 offset:3072
	ds_read_b128 v[194:197], v144 offset:4096
	ds_read_b128 v[206:209], v144 offset:5120
	ds_read_b128 v[224:227], v144 offset:6144
	ds_read_b128 v[228:231], v144 offset:7168
	s_add_u32 s100, s42, 0xfff80000
	s_addc_u32 s101, s43, -1
	s_mov_b32 m0, s55
	s_nop 0
	global_load_lds_dwordx4 v138, s[100:101]
	s_mov_b32 m0, s56
	s_nop 0
	global_load_lds_dwordx4 v140, s[100:101]
	s_add_i32 m0, s46, 0xc000
	s_nop 0
	global_load_lds_dwordx4 v138, s[42:43]
	s_add_i32 m0, s46, 0xe000
	v_readfirstlane_b32 s71, v223
	global_load_lds_dwordx4 v140, s[42:43]
	s_cmp_eq_u32 s71, 0
	s_cbranch_scc1 .Lrw16
	s_waitcnt vmcnt(8)
.Lrw16:
	s_waitcnt vmcnt(24)
	s_waitcnt lgkmcnt(0)
	s_barrier
	s_setprio 1
	s_waitcnt lgkmcnt(0)
	v_mfma_f32_16x16x32_bf16 v[124:127], v[146:149], v[178:181], v[124:127]
	v_mfma_f32_16x16x32_bf16 v[128:131], v[154:157], v[178:181], v[128:131]
	v_mfma_f32_16x16x32_bf16 v[112:115], v[146:149], v[186:189], v[112:115]
	v_mfma_f32_16x16x32_bf16 v[108:111], v[154:157], v[186:189], v[108:111]
	v_mfma_f32_16x16x32_bf16 v[96:99], v[146:149], v[194:197], v[96:99]
	v_mfma_f32_16x16x32_bf16 v[92:95], v[154:157], v[194:197], v[92:95]
	v_mfma_f32_16x16x32_bf16 v[80:83], v[146:149], v[224:227], v[80:83]
	v_mfma_f32_16x16x32_bf16 v[76:79], v[154:157], v[224:227], v[76:79]
	v_mfma_f32_16x16x32_bf16 v[124:127], v[150:153], v[182:185], v[124:127]
	v_mfma_f32_16x16x32_bf16 v[128:131], v[158:161], v[182:185], v[128:131]
	v_mfma_f32_16x16x32_bf16 v[112:115], v[150:153], v[190:193], v[112:115]
	v_mfma_f32_16x16x32_bf16 v[108:111], v[158:161], v[190:193], v[108:111]
	v_mfma_f32_16x16x32_bf16 v[96:99], v[150:153], v[206:209], v[96:99]
	v_mfma_f32_16x16x32_bf16 v[92:95], v[158:161], v[206:209], v[92:95]
	v_mfma_f32_16x16x32_bf16 v[80:83], v[150:153], v[228:231], v[80:83]
	v_mfma_f32_16x16x32_bf16 v[76:79], v[158:161], v[228:231], v[76:79]
	s_setprio 0
	s_setprio 1
	v_mfma_f32_16x16x32_bf16 v[120:123], v[162:165], v[178:181], v[120:123]
	v_mfma_f32_16x16x32_bf16 v[116:119], v[170:173], v[178:181], v[116:119]
	v_mfma_f32_16x16x32_bf16 v[104:107], v[162:165], v[186:189], v[104:107]
	v_mfma_f32_16x16x32_bf16 v[100:103], v[170:173], v[186:189], v[100:103]
	v_mfma_f32_16x16x32_bf16 v[88:91], v[162:165], v[194:197], v[88:91]
	v_mfma_f32_16x16x32_bf16 v[84:87], v[170:173], v[194:197], v[84:87]
	v_mfma_f32_16x16x32_bf16 v[72:75], v[162:165], v[224:227], v[72:75]
	v_mfma_f32_16x16x32_bf16 v[68:71], v[170:173], v[224:227], v[68:71]
	v_mfma_f32_16x16x32_bf16 v[120:123], v[166:169], v[182:185], v[120:123]
	v_mfma_f32_16x16x32_bf16 v[116:119], v[174:177], v[182:185], v[116:119]
	v_mfma_f32_16x16x32_bf16 v[104:107], v[166:169], v[190:193], v[104:107]
	v_mfma_f32_16x16x32_bf16 v[100:103], v[174:177], v[190:193], v[100:103]
	v_mfma_f32_16x16x32_bf16 v[88:91], v[166:169], v[206:209], v[88:91]
	v_mfma_f32_16x16x32_bf16 v[84:87], v[174:177], v[206:209], v[84:87]
	v_mfma_f32_16x16x32_bf16 v[72:75], v[166:169], v[228:231], v[72:75]
	v_mfma_f32_16x16x32_bf16 v[68:71], v[174:177], v[228:231], v[68:71]
	s_setprio 0
	s_barrier
	s_add_i32 s68, s68, s37
	s_mov_b32 m0, s68
	ds_read_b128 v[178:181], v144 offset:16384
	ds_read_b128 v[182:185], v144 offset:17408
	ds_read_b128 v[186:189], v144 offset:18432
	ds_read_b128 v[190:193], v144 offset:19456
	ds_read_b128 v[194:197], v144 offset:20480
	ds_read_b128 v[206:209], v144 offset:21504
	ds_read_b128 v[224:227], v144 offset:22528
	ds_read_b128 v[228:231], v144 offset:23552
	global_load_lds_dwordx4 v2, s[26:27]
	s_add_i32 m0, s68, 0x2000
	s_add_u32 s68, s26, 0x400000
	s_addc_u32 s69, s27, 0
	s_add_i32 s70, s70, s37
	global_load_lds_dwordx4 v132, s[26:27]
	s_mov_b32 m0, s70
	s_nop 0
	global_load_lds_dwordx4 v2, s[68:69]
	s_add_i32 m0, s70, 0x2000
	s_nop 0
	global_load_lds_dwordx4 v132, s[68:69]
	s_cmp_eq_u32 s71, 0
	s_cbranch_scc1 .Lrw17
	s_waitcnt vmcnt(6)
; #define PG8_STAGE(bufoff, gbase, voff) do { _Pragma("unroll") for (int _i = 0; _i < 2; ++_i) \
;         __builtin_amdgcn_global_load_lds((const unsigned*)((const char*)(gbase) + (voff)[_i]), (LAS unsigned*)(lds + (bufoff) + ldsw + _i * 8192), 16, 0, 0); } while (0)
; #define PG8_LDA(dst, b, h) do { _Pragma("unroll") for (int m = 0; m < 4; ++m) _Pragma("unroll") for (int k = 0; k < 2; ++k) dst[m][k] = *(const LAS bf16x8*)(lds + PG8_SA(b, h) + aoff + m * 2048 + k * 1024); } while (0)
; #define PG8_LDB(dst, b, h) do { _Pragma("unroll") for (int n = 0; n < 2; ++n) _Pragma("unroll") for (int k = 0; k < 2; ++k) dst[n][k] = *(const LAS bf16x8*)(lds + PG8_SB(b, h) + boff + n * 2048 + k * 1024); } while (0)
; #define PG8_MMA(ai, bj, At, Bt) do { __builtin_amdgcn_s_setprio(1); _Pragma("unroll") for (int m = 0; m < 4; ++m) _Pragma("unroll") for (int n = 0; n < 2; ++n) _Pragma("unroll") for (int k = 0; k < 2; ++k) \
;         acc[ai][bj][m][n] = __builtin_amdgcn_mfma_f32_16x16x32_bf16(Bt[n][k], At[m][k], acc[ai][bj][m][n], 0, 0, 0); __builtin_amdgcn_s_setprio(0); } while (0)
; #define PG8_WAIT_V(n) asm volatile("s_waitcnt vmcnt(" #n ")" ::: "memory")
; #define PG8_WAIT_L(n) asm volatile("s_waitcnt lgkmcnt(" #n ")" ::: "memory")
; #define PG8_BAR __builtin_amdgcn_s_barrier()
; #define PG8_WAIT_RELAX(flag, n) asm volatile("s_cmp_eq_u32 %0, 0\n\ts_cbranch_scc1 .Lrw%=\n\ts_waitcnt vmcnt(8)\n.Lrw%=:\n\ts_waitcnt vmcnt(%1)" :: "s"(flag), "n"(n) : "scc", "memory")
; #define PG8_SCHED __builtin_amdgcn_sched_barrier(0)
; template <class Epi, bool ALIGN_EPI = true>
; __device__ __forceinline__ void gemm_phase(LAS unsigned char* lds, const Gemm g, const Sched& S, const Epi& E) {
;     ...
;             if constexpr (Epi::NSTORES > 0) PG8_WAIT_RELAX(rflag, 8 + Epi::NSTORES); else PG8_WAIT_V(8);
;             PG8_WAIT_L(0); PG8_BAR; PG8_MMA(1, 0, At, B0); PG8_MMA(1, 1, At, B1); PG8_BAR; PG8_SCHED;
;             PG8_LDB(B0, 1, 0); PG8_LDB(B1, 1, 1); PG8_SCHED; PG8_LDA(At, 1, 0); PG8_STAGE(PG8_SA(0, 1), a2 + hstepA, voffA);
;             PG8_WAIT_V(8); PG8_WAIT_L(0); PG8_BAR; PG8_MMA(0, 0, At, B0); PG8_MMA(0, 1, At, B1); PG8_BAR; PG8_SCHED;
.Lrw17:
	s_waitcnt vmcnt(6)
	s_waitcnt lgkmcnt(0)
	s_barrier
	s_setprio 1
	s_waitcnt lgkmcnt(0)
	v_mfma_f32_16x16x32_bf16 v[64:67], v[146:149], v[178:181], v[64:67]
	v_mfma_f32_16x16x32_bf16 v[60:63], v[154:157], v[178:181], v[60:63]
	v_mfma_f32_16x16x32_bf16 v[48:51], v[146:149], v[186:189], v[48:51]
	v_mfma_f32_16x16x32_bf16 v[44:47], v[154:157], v[186:189], v[44:47]
	v_mfma_f32_16x16x32_bf16 v[32:35], v[146:149], v[194:197], v[32:35]
	v_mfma_f32_16x16x32_bf16 v[28:31], v[154:157], v[194:197], v[28:31]
	v_mfma_f32_16x16x32_bf16 v[16:19], v[146:149], v[224:227], v[16:19]
	v_mfma_f32_16x16x32_bf16 v[12:15], v[154:157], v[224:227], v[12:15]
	v_mfma_f32_16x16x32_bf16 v[64:67], v[150:153], v[182:185], v[64:67]
	v_mfma_f32_16x16x32_bf16 v[60:63], v[158:161], v[182:185], v[60:63]
	v_mfma_f32_16x16x32_bf16 v[48:51], v[150:153], v[190:193], v[48:51]
	v_mfma_f32_16x16x32_bf16 v[44:47], v[158:161], v[190:193], v[44:47]
	v_mfma_f32_16x16x32_bf16 v[32:35], v[150:153], v[206:209], v[32:35]
	v_mfma_f32_16x16x32_bf16 v[28:31], v[158:161], v[206:209], v[28:31]
	v_mfma_f32_16x16x32_bf16 v[16:19], v[150:153], v[228:231], v[16:19]
	v_mfma_f32_16x16x32_bf16 v[12:15], v[158:161], v[228:231], v[12:15]
	s_setprio 0
	s_setprio 1
	v_mfma_f32_16x16x32_bf16 v[56:59], v[162:165], v[178:181], v[56:59]
	v_mfma_f32_16x16x32_bf16 v[52:55], v[170:173], v[178:181], v[52:55]
	v_mfma_f32_16x16x32_bf16 v[40:43], v[162:165], v[186:189], v[40:43]
	v_mfma_f32_16x16x32_bf16 v[36:39], v[170:173], v[186:189], v[36:39]
	v_mfma_f32_16x16x32_bf16 v[24:27], v[162:165], v[194:197], v[24:27]
	v_mfma_f32_16x16x32_bf16 v[20:23], v[170:173], v[194:197], v[20:23]
	v_mfma_f32_16x16x32_bf16 v[8:11], v[162:165], v[224:227], v[8:11]
	v_mfma_f32_16x16x32_bf16 v[4:7], v[170:173], v[224:227], v[4:7]
	v_mfma_f32_16x16x32_bf16 v[56:59], v[166:169], v[182:185], v[56:59]
	v_mfma_f32_16x16x32_bf16 v[52:55], v[174:177], v[182:185], v[52:55]
	v_mfma_f32_16x16x32_bf16 v[40:43], v[166:169], v[190:193], v[40:43]
	v_mfma_f32_16x16x32_bf16 v[36:39], v[174:177], v[190:193], v[36:39]
	v_mfma_f32_16x16x32_bf16 v[24:27], v[166:169], v[206:209], v[24:27]
	v_mfma_f32_16x16x32_bf16 v[20:23], v[174:177], v[206:209], v[20:23]
	v_mfma_f32_16x16x32_bf16 v[8:11], v[166:169], v[228:231], v[8:11]
	v_mfma_f32_16x16x32_bf16 v[4:7], v[174:177], v[228:231], v[4:7]
	s_setprio 0
	s_barrier
	s_add_i32 s68, 0, 0x18000
	s_add_i32 s69, 0, 0x1c000
	v_add_u32_e32 v158, s68, v143
	v_add_u32_e32 v174, s69, v143
	ds_read_b128 v[146:149], v158
	ds_read_b128 v[150:153], v158 offset:1024
	ds_read_b128 v[154:157], v158 offset:2048
	ds_read_b128 v[158:161], v158 offset:3072
	ds_read_b128 v[162:165], v174
	ds_read_b128 v[166:169], v174 offset:1024
	ds_read_b128 v[170:173], v174 offset:2048
	ds_read_b128 v[174:177], v174 offset:3072
	s_add_u32 s44, s44, 0x80000
	s_addc_u32 s45, s45, 0
	s_mov_b32 m0, s48
	ds_read_b128 v[178:181], v144 offset:32768
	ds_read_b128 v[182:185], v144 offset:33792
	ds_read_b128 v[186:189], v144 offset:34816
	ds_read_b128 v[190:193], v144 offset:35840
	ds_read_b128 v[194:197], v144 offset:36864
	ds_read_b128 v[206:209], v144 offset:37888
	ds_read_b128 v[224:227], v144 offset:38912
	ds_read_b128 v[228:231], v144 offset:39936
	s_add_u32 s100, s44, 0xfff80000
	s_addc_u32 s101, s45, -1
	s_mov_b32 m0, s46
	s_nop 0
	global_load_lds_dwordx4 v136, s[100:101]
	s_mov_b32 m0, s47
	s_nop 0
	global_load_lds_dwordx4 v134, s[100:101]
	s_mov_b32 m0, s48
	s_nop 0
	global_load_lds_dwordx4 v136, s[44:45]
	s_mov_b32 m0, s49
	s_nop 0
	global_load_lds_dwordx4 v134, s[44:45]
	s_waitcnt vmcnt(8)
	s_waitcnt lgkmcnt(0)
	s_barrier
; #define PG8_STAGE(bufoff, gbase, voff) do { _Pragma("unroll") for (int _i = 0; _i < 2; ++_i) \
;         __builtin_amdgcn_global_load_lds((const unsigned*)((const char*)(gbase) + (voff)[_i]), (LAS unsigned*)(lds + (bufoff) + ldsw + _i * 8192), 16, 0, 0); } while (0)
; #define PG8_LDA(dst, b, h) do { _Pragma("unroll") for (int m = 0; m < 4; ++m) _Pragma("unroll") for (int k = 0; k < 2; ++k) dst[m][k] = *(const LAS bf16x8*)(lds + PG8_SA(b, h) + aoff + m * 2048 + k * 1024); } while (0)
; #define PG8_MMA(ai, bj, At, Bt) do { __builtin_amdgcn_s_setprio(1); _Pragma("unroll") for (int m = 0; m < 4; ++m) _Pragma("unroll") for (int n = 0; n < 2; ++n) _Pragma("unroll") for (int k = 0; k < 2; ++k) \
;         acc[ai][bj][m][n] = __builtin_amdgcn_mfma_f32_16x16x32_bf16(Bt[n][k], At[m][k], acc[ai][bj][m][n], 0, 0, 0); __builtin_amdgcn_s_setprio(0); } while (0)
; #define PG8_WAIT_V(n) asm volatile("s_waitcnt vmcnt(" #n ")" ::: "memory")
; #define PG8_WAIT_L(n) asm volatile("s_waitcnt lgkmcnt(" #n ")" ::: "memory")
; #define PG8_BAR __builtin_amdgcn_s_barrier()
; #define PG8_SCHED __builtin_amdgcn_sched_barrier(0)
; template <class Epi, bool ALIGN_EPI = true>
; __device__ __forceinline__ void gemm_phase(LAS unsigned char* lds, const Gemm g, const Sched& S, const Epi& E) {
;     ...
;             PG8_WAIT_V(8); PG8_WAIT_L(0); PG8_BAR; PG8_MMA(0, 0, At, B0); PG8_MMA(0, 1, At, B1); PG8_BAR; PG8_SCHED;
;             PG8_LDA(At, 1, 1); PG8_STAGE(PG8_SB(1, 0), b3, voffB); PG8_STAGE(PG8_SB(1, 1), b3 + hstepB, voffB); PG8_STAGE(PG8_SA(1, 0), a3, voffA);
;             PG8_WAIT_V(8); PG8_WAIT_L(0); PG8_BAR; PG8_MMA(1, 0, At, B0); PG8_MMA(1, 1, At, B1); PG8_BAR; PG8_SCHED;
;         }
	s_setprio 1
	s_waitcnt lgkmcnt(0)
	v_mfma_f32_16x16x32_bf16 v[124:127], v[146:149], v[178:181], v[124:127]
	v_mfma_f32_16x16x32_bf16 v[128:131], v[154:157], v[178:181], v[128:131]
	v_mfma_f32_16x16x32_bf16 v[112:115], v[146:149], v[186:189], v[112:115]
	v_mfma_f32_16x16x32_bf16 v[108:111], v[154:157], v[186:189], v[108:111]
	v_mfma_f32_16x16x32_bf16 v[96:99], v[146:149], v[194:197], v[96:99]
	v_mfma_f32_16x16x32_bf16 v[92:95], v[154:157], v[194:197], v[92:95]
	v_mfma_f32_16x16x32_bf16 v[80:83], v[146:149], v[224:227], v[80:83]
	v_mfma_f32_16x16x32_bf16 v[76:79], v[154:157], v[224:227], v[76:79]
	v_mfma_f32_16x16x32_bf16 v[124:127], v[150:153], v[182:185], v[124:127]
	v_mfma_f32_16x16x32_bf16 v[128:131], v[158:161], v[182:185], v[128:131]
	v_mfma_f32_16x16x32_bf16 v[112:115], v[150:153], v[190:193], v[112:115]
	v_mfma_f32_16x16x32_bf16 v[108:111], v[158:161], v[190:193], v[108:111]
	v_mfma_f32_16x16x32_bf16 v[96:99], v[150:153], v[206:209], v[96:99]
	v_mfma_f32_16x16x32_bf16 v[92:95], v[158:161], v[206:209], v[92:95]
	v_mfma_f32_16x16x32_bf16 v[80:83], v[150:153], v[228:231], v[80:83]
	v_mfma_f32_16x16x32_bf16 v[76:79], v[158:161], v[228:231], v[76:79]
	s_setprio 0
	s_setprio 1
	v_mfma_f32_16x16x32_bf16 v[120:123], v[162:165], v[178:181], v[120:123]
	v_mfma_f32_16x16x32_bf16 v[116:119], v[170:173], v[178:181], v[116:119]
	v_mfma_f32_16x16x32_bf16 v[104:107], v[162:165], v[186:189], v[104:107]
	v_mfma_f32_16x16x32_bf16 v[100:103], v[170:173], v[186:189], v[100:103]
	v_mfma_f32_16x16x32_bf16 v[88:91], v[162:165], v[194:197], v[88:91]
	v_mfma_f32_16x16x32_bf16 v[84:87], v[170:173], v[194:197], v[84:87]
	v_mfma_f32_16x16x32_bf16 v[72:75], v[162:165], v[224:227], v[72:75]
	v_mfma_f32_16x16x32_bf16 v[68:71], v[170:173], v[224:227], v[68:71]
	v_mfma_f32_16x16x32_bf16 v[120:123], v[166:169], v[182:185], v[120:123]
	v_mfma_f32_16x16x32_bf16 v[116:119], v[174:177], v[182:185], v[116:119]
	v_mfma_f32_16x16x32_bf16 v[104:107], v[166:169], v[190:193], v[104:107]
	v_mfma_f32_16x16x32_bf16 v[100:103], v[174:177], v[190:193], v[100:103]
	v_mfma_f32_16x16x32_bf16 v[88:91], v[166:169], v[206:209], v[88:91]
	v_mfma_f32_16x16x32_bf16 v[84:87], v[174:177], v[206:209], v[84:87]
	v_mfma_f32_16x16x32_bf16 v[72:75], v[166:169], v[228:231], v[72:75]
	v_mfma_f32_16x16x32_bf16 v[68:71], v[174:177], v[228:231], v[68:71]
	s_setprio 0
	s_barrier
	s_add_u32 s100, s26, 0x80
	s_addc_u32 s101, s27, 0
	s_add_i32 s44, s68, s37
	s_mov_b32 m0, s44
	ds_read_b128 v[178:181], v144 offset:49152
	ds_read_b128 v[182:185], v144 offset:50176
	ds_read_b128 v[186:189], v144 offset:51200
	ds_read_b128 v[190:193], v144 offset:52224
	ds_read_b128 v[194:197], v144 offset:53248
	ds_read_b128 v[206:209], v144 offset:54272
	ds_read_b128 v[224:227], v144 offset:55296
	ds_read_b128 v[228:231], v144 offset:56320
	global_load_lds_dwordx4 v2, s[100:101]
	s_add_i32 m0, s44, 0x2000
	s_add_u32 s26, s26, 0x400080
	s_addc_u32 s27, s27, 0
	s_add_i32 s44, s69, s37
	global_load_lds_dwordx4 v132, s[100:101]
	s_mov_b32 m0, s44
	s_nop 0
	global_load_lds_dwordx4 v2, s[26:27]
	s_add_i32 m0, s44, 0x2000
	s_nop 0
	global_load_lds_dwordx4 v132, s[26:27]
	s_waitcnt vmcnt(6)
	s_waitcnt lgkmcnt(0)
	s_barrier
	s_setprio 1
	s_waitcnt lgkmcnt(0)
	v_mfma_f32_16x16x32_bf16 v[64:67], v[146:149], v[178:181], v[64:67]
	v_mfma_f32_16x16x32_bf16 v[60:63], v[154:157], v[178:181], v[60:63]
	v_mfma_f32_16x16x32_bf16 v[48:51], v[146:149], v[186:189], v[48:51]
	v_mfma_f32_16x16x32_bf16 v[44:47], v[154:157], v[186:189], v[44:47]
	v_mfma_f32_16x16x32_bf16 v[32:35], v[146:149], v[194:197], v[32:35]
	v_mfma_f32_16x16x32_bf16 v[28:31], v[154:157], v[194:197], v[28:31]
	v_mfma_f32_16x16x32_bf16 v[16:19], v[146:149], v[224:227], v[16:19]
	v_mfma_f32_16x16x32_bf16 v[12:15], v[154:157], v[224:227], v[12:15]
	v_mfma_f32_16x16x32_bf16 v[64:67], v[150:153], v[182:185], v[64:67]
	v_mfma_f32_16x16x32_bf16 v[60:63], v[158:161], v[182:185], v[60:63]
	v_mfma_f32_16x16x32_bf16 v[48:51], v[150:153], v[190:193], v[48:51]
	v_mfma_f32_16x16x32_bf16 v[44:47], v[158:161], v[190:193], v[44:47]
	v_mfma_f32_16x16x32_bf16 v[32:35], v[150:153], v[206:209], v[32:35]
	v_mfma_f32_16x16x32_bf16 v[28:31], v[158:161], v[206:209], v[28:31]
	v_mfma_f32_16x16x32_bf16 v[16:19], v[150:153], v[228:231], v[16:19]
	v_mfma_f32_16x16x32_bf16 v[12:15], v[158:161], v[228:231], v[12:15]
	s_setprio 0
	s_setprio 1
	v_mfma_f32_16x16x32_bf16 v[56:59], v[162:165], v[178:181], v[56:59]
	v_mfma_f32_16x16x32_bf16 v[52:55], v[170:173], v[178:181], v[52:55]
	v_mfma_f32_16x16x32_bf16 v[40:43], v[162:165], v[186:189], v[40:43]
	v_mfma_f32_16x16x32_bf16 v[36:39], v[170:173], v[186:189], v[36:39]
	v_mfma_f32_16x16x32_bf16 v[24:27], v[162:165], v[194:197], v[24:27]
	v_mfma_f32_16x16x32_bf16 v[20:23], v[170:173], v[194:197], v[20:23]
	v_mfma_f32_16x16x32_bf16 v[8:11], v[162:165], v[224:227], v[8:11]
	v_mfma_f32_16x16x32_bf16 v[4:7], v[170:173], v[224:227], v[4:7]
	v_mfma_f32_16x16x32_bf16 v[56:59], v[166:169], v[182:185], v[56:59]
	v_mfma_f32_16x16x32_bf16 v[52:55], v[174:177], v[182:185], v[52:55]
	v_mfma_f32_16x16x32_bf16 v[40:43], v[166:169], v[190:193], v[40:43]
	v_mfma_f32_16x16x32_bf16 v[36:39], v[174:177], v[190:193], v[36:39]
	v_mfma_f32_16x16x32_bf16 v[24:27], v[166:169], v[206:209], v[24:27]
	v_mfma_f32_16x16x32_bf16 v[20:23], v[174:177], v[206:209], v[20:23]
	v_mfma_f32_16x16x32_bf16 v[8:11], v[166:169], v[228:231], v[8:11]
	v_mfma_f32_16x16x32_bf16 v[4:7], v[174:177], v[228:231], v[4:7]
	s_setprio 0
	s_barrier
	s_add_u32 s42, s42, 0x100
	s_addc_u32 s43, s43, 0
	s_add_u32 s65, s65, 0x100
	s_addc_u32 s66, s66, 0
	s_cmp_ge_i32 s67, s52
	s_mov_b32 s44, s67
	s_cbranch_scc0 .LBB0_1479

; #define PG8_STAGE(bufoff, gbase, voff) do { _Pragma("unroll") for (int _i = 0; _i < 2; ++_i) \
;         __builtin_amdgcn_global_load_lds((const unsigned*)((const char*)(gbase) + (voff)[_i]), (LAS unsigned*)(lds + (bufoff) + ldsw + _i * 8192), 16, 0, 0); } while (0)
; #define PG8_LDA(dst, b, h) do { _Pragma("unroll") for (int m = 0; m < 4; ++m) _Pragma("unroll") for (int k = 0; k < 2; ++k) dst[m][k] = *(const LAS bf16x8*)(lds + PG8_SA(b, h) + aoff + m * 2048 + k * 1024); } while (0)
; #define PG8_LDB(dst, b, h) do { _Pragma("unroll") for (int n = 0; n < 2; ++n) _Pragma("unroll") for (int k = 0; k < 2; ++k) dst[n][k] = *(const LAS bf16x8*)(lds + PG8_SB(b, h) + boff + n * 2048 + k * 1024); } while (0)
; #define PG8_MMA(ai, bj, At, Bt) do { __builtin_amdgcn_s_setprio(1); _Pragma("unroll") for (int m = 0; m < 4; ++m) _Pragma("unroll") for (int n = 0; n < 2; ++n) _Pragma("unroll") for (int k = 0; k < 2; ++k) \
;         acc[ai][bj][m][n] = __builtin_amdgcn_mfma_f32_16x16x32_bf16(Bt[n][k], At[m][k], acc[ai][bj][m][n], 0, 0, 0); __builtin_amdgcn_s_setprio(0); } while (0)
; #define PG8_WAIT_V(n) asm volatile("s_waitcnt vmcnt(" #n ")" ::: "memory")
; template <class Epi, bool ALIGN_EPI = true>
; __device__ __forceinline__ void gemm_phase(LAS unsigned char* lds, const Gemm g, const Sched& S, const Epi& E) {
;     ...
;         for (int t = t_lo; t < t_hi; t += 2) {
;             const bool last = (t == nt - 2);
;             const char* a1 = cA + (size_t)(t + 1) * kstep;
;             const char* a2 = last ? nA : cA + (size_t)(t + 2) * kstep; const char* b2 = last ? nB : cB + (size_t)(t + 2) * kstep;
;             const char* a3 = a2 + kstep; const char* b3 = b2 + kstep;
;             const int rflag = __builtin_amdgcn_readfirstlane(t | (int)(ui == 0));
;             PG8_LDB(B0, 0, 0); PG8_LDB(B1, 0, 1); PG8_SCHED; PG8_LDA(At, 0, 0); PG8_STAGE(PG8_SA(1, 1), a1 + hstepA, voffA);
;             if constexpr (Epi::NSTORES > 0) PG8_WAIT_RELAX(rflag, 8 + Epi::NSTORES); else PG8_WAIT_V(8);
;             PG8_WAIT_L(0); PG8_BAR; PG8_MMA(0, 0, At, B0); PG8_MMA(0, 1, At, B1); PG8_BAR; PG8_SCHED;
;             PG8_LDA(At, 0, 1); PG8_STAGE(PG8_SB(0, 0), b2, voffB); PG8_STAGE(PG8_SB(0, 1), b2 + hstepB, voffB); PG8_STAGE(PG8_SA(0, 0), a2, voffA);
;             if constexpr (Epi::NSTORES > 0) PG8_WAIT_RELAX(rflag, 8 + Epi::NSTORES); else PG8_WAIT_V(8);
.LBB0_1929:
	s_add_i32 s67, s48, 2
	s_add_u32 s49, s46, 0xfffc0080
	s_addc_u32 s50, s47, -1
	s_add_i32 s68, 0, 0x10000
	s_cmp_eq_u32 s59, s48
	s_cselect_b32 s51, s21, s50
	s_cselect_b32 s50, s23, s49
	v_add_u32_e32 v2, s68, v147
	s_cselect_b32 s49, s63, s66
	s_cselect_b32 s48, s64, s65
	s_add_i32 s70, 0, 0x14000
	ds_read_b128 v[150:153], v2
	ds_read_b128 v[154:157], v2 offset:1024
	ds_read_b128 v[158:161], v2 offset:2048
	ds_read_b128 v[162:165], v2 offset:3072
	v_add_u32_e32 v2, s70, v147
	ds_read_b128 v[166:169], v2
	ds_read_b128 v[170:173], v2 offset:1024
	ds_read_b128 v[174:177], v2 offset:2048
	ds_read_b128 v[178:181], v2 offset:3072
	s_add_i32 m0, s52, 0xc000
	ds_read_b128 v[182:185], v148
	ds_read_b128 v[186:189], v148 offset:1024
	ds_read_b128 v[190:193], v148 offset:2048
	ds_read_b128 v[194:197], v148 offset:3072
	ds_read_b128 v[206:209], v148 offset:4096
	ds_read_b128 v[224:227], v148 offset:5120
	ds_read_b128 v[228:231], v148 offset:6144
	ds_read_b128 v[232:235], v148 offset:7168
	s_add_u32 s100, s46, 0xfffc0000
	s_addc_u32 s101, s47, -1
	s_mov_b32 m0, s57
	s_nop 0
	global_load_lds_dwordx4 v142, s[100:101]
	s_mov_b32 m0, s58
	s_nop 0
	global_load_lds_dwordx4 v144, s[100:101]
	s_add_i32 m0, s52, 0xc000
	s_nop 0
	global_load_lds_dwordx4 v142, s[46:47]
	s_add_i32 m0, s52, 0xe000
	s_nop 0
	global_load_lds_dwordx4 v144, s[46:47]
	s_waitcnt vmcnt(8)
	s_waitcnt lgkmcnt(0)
	s_barrier
	s_setprio 1
	s_waitcnt lgkmcnt(0)
	v_mfma_f32_16x16x32_bf16 v[130:133], v[150:153], v[182:185], v[130:133]
	v_mfma_f32_16x16x32_bf16 v[126:129], v[158:161], v[182:185], v[126:129]
	v_mfma_f32_16x16x32_bf16 v[114:117], v[150:153], v[190:193], v[114:117]
	v_mfma_f32_16x16x32_bf16 v[110:113], v[158:161], v[190:193], v[110:113]
	v_mfma_f32_16x16x32_bf16 v[98:101], v[150:153], v[206:209], v[98:101]
	v_mfma_f32_16x16x32_bf16 v[94:97], v[158:161], v[206:209], v[94:97]
	v_mfma_f32_16x16x32_bf16 v[82:85], v[150:153], v[228:231], v[82:85]
	v_mfma_f32_16x16x32_bf16 v[78:81], v[158:161], v[228:231], v[78:81]
	v_mfma_f32_16x16x32_bf16 v[130:133], v[154:157], v[186:189], v[130:133]
	v_mfma_f32_16x16x32_bf16 v[126:129], v[162:165], v[186:189], v[126:129]
	v_mfma_f32_16x16x32_bf16 v[114:117], v[154:157], v[194:197], v[114:117]
	v_mfma_f32_16x16x32_bf16 v[110:113], v[162:165], v[194:197], v[110:113]
	v_mfma_f32_16x16x32_bf16 v[98:101], v[154:157], v[224:227], v[98:101]
	v_mfma_f32_16x16x32_bf16 v[94:97], v[162:165], v[224:227], v[94:97]
	v_mfma_f32_16x16x32_bf16 v[82:85], v[154:157], v[232:235], v[82:85]
	v_mfma_f32_16x16x32_bf16 v[78:81], v[162:165], v[232:235], v[78:81]
	s_setprio 0
	s_setprio 1
	v_mfma_f32_16x16x32_bf16 v[122:125], v[166:169], v[182:185], v[122:125]
	v_mfma_f32_16x16x32_bf16 v[118:121], v[174:177], v[182:185], v[118:121]
	v_mfma_f32_16x16x32_bf16 v[106:109], v[166:169], v[190:193], v[106:109]
	v_mfma_f32_16x16x32_bf16 v[102:105], v[174:177], v[190:193], v[102:105]
	v_mfma_f32_16x16x32_bf16 v[90:93], v[166:169], v[206:209], v[90:93]
	v_mfma_f32_16x16x32_bf16 v[86:89], v[174:177], v[206:209], v[86:89]
	v_mfma_f32_16x16x32_bf16 v[74:77], v[166:169], v[228:231], v[74:77]
	v_mfma_f32_16x16x32_bf16 v[70:73], v[174:177], v[228:231], v[70:73]
	v_mfma_f32_16x16x32_bf16 v[122:125], v[170:173], v[186:189], v[122:125]
	v_mfma_f32_16x16x32_bf16 v[118:121], v[178:181], v[186:189], v[118:121]
	v_mfma_f32_16x16x32_bf16 v[106:109], v[170:173], v[194:197], v[106:109]
	v_mfma_f32_16x16x32_bf16 v[102:105], v[178:181], v[194:197], v[102:105]
	v_mfma_f32_16x16x32_bf16 v[90:93], v[170:173], v[224:227], v[90:93]
	v_mfma_f32_16x16x32_bf16 v[86:89], v[178:181], v[224:227], v[86:89]
	v_mfma_f32_16x16x32_bf16 v[74:77], v[170:173], v[232:235], v[74:77]
	v_mfma_f32_16x16x32_bf16 v[70:73], v[178:181], v[232:235], v[70:73]
	s_setprio 0
	s_barrier
	s_add_i32 s68, s68, s37
	s_mov_b32 m0, s68
	ds_read_b128 v[182:185], v148 offset:16384
	ds_read_b128 v[186:189], v148 offset:17408
	ds_read_b128 v[190:193], v148 offset:18432
	ds_read_b128 v[194:197], v148 offset:19456
	ds_read_b128 v[206:209], v148 offset:20480
	ds_read_b128 v[224:227], v148 offset:21504
	ds_read_b128 v[228:231], v148 offset:22528
	ds_read_b128 v[232:235], v148 offset:23552
	global_load_lds_dwordx4 v138, s[48:49]
	s_add_i32 m0, s68, 0x2000
	s_add_u32 s68, s48, 0x40000
	s_addc_u32 s69, s49, 0
	s_add_i32 s70, s70, s37
	global_load_lds_dwordx4 v134, s[48:49]
	s_mov_b32 m0, s70
	s_nop 0
	global_load_lds_dwordx4 v138, s[68:69]
	s_add_i32 m0, s70, 0x2000
	s_nop 0
	global_load_lds_dwordx4 v134, s[68:69]
	s_waitcnt vmcnt(6)
	s_waitcnt lgkmcnt(0)
	s_barrier
; #define PG8_STAGE(bufoff, gbase, voff) do { _Pragma("unroll") for (int _i = 0; _i < 2; ++_i) \
;         __builtin_amdgcn_global_load_lds((const unsigned*)((const char*)(gbase) + (voff)[_i]), (LAS unsigned*)(lds + (bufoff) + ldsw + _i * 8192), 16, 0, 0); } while (0)
; #define PG8_LDA(dst, b, h) do { _Pragma("unroll") for (int m = 0; m < 4; ++m) _Pragma("unroll") for (int k = 0; k < 2; ++k) dst[m][k] = *(const LAS bf16x8*)(lds + PG8_SA(b, h) + aoff + m * 2048 + k * 1024); } while (0)
; #define PG8_LDB(dst, b, h) do { _Pragma("unroll") for (int n = 0; n < 2; ++n) _Pragma("unroll") for (int k = 0; k < 2; ++k) dst[n][k] = *(const LAS bf16x8*)(lds + PG8_SB(b, h) + boff + n * 2048 + k * 1024); } while (0)
; #define PG8_MMA(ai, bj, At, Bt) do { __builtin_amdgcn_s_setprio(1); _Pragma("unroll") for (int m = 0; m < 4; ++m) _Pragma("unroll") for (int n = 0; n < 2; ++n) _Pragma("unroll") for (int k = 0; k < 2; ++k) \
;         acc[ai][bj][m][n] = __builtin_amdgcn_mfma_f32_16x16x32_bf16(Bt[n][k], At[m][k], acc[ai][bj][m][n], 0, 0, 0); __builtin_amdgcn_s_setprio(0); } while (0)
; #define PG8_WAIT_V(n) asm volatile("s_waitcnt vmcnt(" #n ")" ::: "memory")
; #define PG8_WAIT_L(n) asm volatile("s_waitcnt lgkmcnt(" #n ")" ::: "memory")
; #define PG8_BAR __builtin_amdgcn_s_barrier()
; #define PG8_SCHED __builtin_amdgcn_sched_barrier(0)
; template <class Epi, bool ALIGN_EPI = true>
; __device__ __forceinline__ void gemm_phase(LAS unsigned char* lds, const Gemm g, const Sched& S, const Epi& E) {
;     ...
;             PG8_WAIT_L(0); PG8_BAR; PG8_MMA(1, 0, At, B0); PG8_MMA(1, 1, At, B1); PG8_BAR; PG8_SCHED;
;             PG8_LDB(B0, 1, 0); PG8_LDB(B1, 1, 1); PG8_SCHED; PG8_LDA(At, 1, 0); PG8_STAGE(PG8_SA(0, 1), a2 + hstepA, voffA);
;             PG8_WAIT_V(8); PG8_WAIT_L(0); PG8_BAR; PG8_MMA(0, 0, At, B0); PG8_MMA(0, 1, At, B1); PG8_BAR; PG8_SCHED;
	s_setprio 1
	s_waitcnt lgkmcnt(0)
	v_mfma_f32_16x16x32_bf16 v[66:69], v[150:153], v[182:185], v[66:69]
	v_mfma_f32_16x16x32_bf16 v[62:65], v[158:161], v[182:185], v[62:65]
	v_mfma_f32_16x16x32_bf16 v[50:53], v[150:153], v[190:193], v[50:53]
	v_mfma_f32_16x16x32_bf16 v[46:49], v[158:161], v[190:193], v[46:49]
	v_mfma_f32_16x16x32_bf16 v[34:37], v[150:153], v[206:209], v[34:37]
	v_mfma_f32_16x16x32_bf16 v[30:33], v[158:161], v[206:209], v[30:33]
	v_mfma_f32_16x16x32_bf16 v[18:21], v[150:153], v[228:231], v[18:21]
	v_mfma_f32_16x16x32_bf16 v[14:17], v[158:161], v[228:231], v[14:17]
	v_mfma_f32_16x16x32_bf16 v[66:69], v[154:157], v[186:189], v[66:69]
	v_mfma_f32_16x16x32_bf16 v[62:65], v[162:165], v[186:189], v[62:65]
	v_mfma_f32_16x16x32_bf16 v[50:53], v[154:157], v[194:197], v[50:53]
	v_mfma_f32_16x16x32_bf16 v[46:49], v[162:165], v[194:197], v[46:49]
	v_mfma_f32_16x16x32_bf16 v[34:37], v[154:157], v[224:227], v[34:37]
	v_mfma_f32_16x16x32_bf16 v[30:33], v[162:165], v[224:227], v[30:33]
	v_mfma_f32_16x16x32_bf16 v[18:21], v[154:157], v[232:235], v[18:21]
	v_mfma_f32_16x16x32_bf16 v[14:17], v[162:165], v[232:235], v[14:17]
	s_setprio 0
	s_setprio 1
	v_mfma_f32_16x16x32_bf16 v[58:61], v[166:169], v[182:185], v[58:61]
	v_mfma_f32_16x16x32_bf16 v[54:57], v[174:177], v[182:185], v[54:57]
	v_mfma_f32_16x16x32_bf16 v[42:45], v[166:169], v[190:193], v[42:45]
	v_mfma_f32_16x16x32_bf16 v[38:41], v[174:177], v[190:193], v[38:41]
	v_mfma_f32_16x16x32_bf16 v[26:29], v[166:169], v[206:209], v[26:29]
	v_mfma_f32_16x16x32_bf16 v[22:25], v[174:177], v[206:209], v[22:25]
	v_mfma_f32_16x16x32_bf16 v[10:13], v[166:169], v[228:231], v[10:13]
	v_mfma_f32_16x16x32_bf16 v[4:7], v[174:177], v[228:231], v[6:9]
	v_mfma_f32_16x16x32_bf16 v[58:61], v[170:173], v[186:189], v[58:61]
	v_mfma_f32_16x16x32_bf16 v[54:57], v[178:181], v[186:189], v[54:57]
	v_mfma_f32_16x16x32_bf16 v[42:45], v[170:173], v[194:197], v[42:45]
	v_mfma_f32_16x16x32_bf16 v[38:41], v[178:181], v[194:197], v[38:41]
	v_mfma_f32_16x16x32_bf16 v[26:29], v[170:173], v[224:227], v[26:29]
	v_mfma_f32_16x16x32_bf16 v[22:25], v[178:181], v[224:227], v[22:25]
	v_mfma_f32_16x16x32_bf16 v[10:13], v[170:173], v[232:235], v[10:13]
	v_mfma_f32_16x16x32_bf16 v[4:7], v[178:181], v[232:235], v[4:7]
	s_setprio 0
	s_barrier
	s_add_i32 s68, 0, 0x18000
	v_add_u32_e32 v2, s68, v147
	s_add_i32 s69, 0, 0x1c000
	ds_read_b128 v[150:153], v2
	ds_read_b128 v[154:157], v2 offset:1024
	ds_read_b128 v[158:161], v2 offset:2048
	ds_read_b128 v[162:165], v2 offset:3072
	v_add_u32_e32 v2, s69, v147
	ds_read_b128 v[166:169], v2
	ds_read_b128 v[170:173], v2 offset:1024
	ds_read_b128 v[174:177], v2 offset:2048
	ds_read_b128 v[178:181], v2 offset:3072
	s_add_u32 s50, s50, 0x40000
	s_addc_u32 s51, s51, 0
	s_mov_b32 m0, s54
	ds_read_b128 v[182:185], v148 offset:32768
	ds_read_b128 v[186:189], v148 offset:33792
	ds_read_b128 v[190:193], v148 offset:34816
	ds_read_b128 v[194:197], v148 offset:35840
	ds_read_b128 v[206:209], v148 offset:36864
	ds_read_b128 v[224:227], v148 offset:37888
	ds_read_b128 v[228:231], v148 offset:38912
	ds_read_b128 v[232:235], v148 offset:39936
	s_add_u32 s100, s50, 0xfffc0000
	s_addc_u32 s101, s51, -1
	s_mov_b32 m0, s52
	s_nop 0
	global_load_lds_dwordx4 v140, s[100:101]
	s_mov_b32 m0, s53
	s_nop 0
	global_load_lds_dwordx4 v136, s[100:101]
	s_mov_b32 m0, s54
	s_nop 0
	global_load_lds_dwordx4 v140, s[50:51]
	s_mov_b32 m0, s55
	s_nop 0
	global_load_lds_dwordx4 v136, s[50:51]
	s_waitcnt vmcnt(8)
	s_waitcnt lgkmcnt(0)
	s_barrier
; #define PG8_STAGE(bufoff, gbase, voff) do { _Pragma("unroll") for (int _i = 0; _i < 2; ++_i) \
;         __builtin_amdgcn_global_load_lds((const unsigned*)((const char*)(gbase) + (voff)[_i]), (LAS unsigned*)(lds + (bufoff) + ldsw + _i * 8192), 16, 0, 0); } while (0)
; #define PG8_LDA(dst, b, h) do { _Pragma("unroll") for (int m = 0; m < 4; ++m) _Pragma("unroll") for (int k = 0; k < 2; ++k) dst[m][k] = *(const LAS bf16x8*)(lds + PG8_SA(b, h) + aoff + m * 2048 + k * 1024); } while (0)
; #define PG8_MMA(ai, bj, At, Bt) do { __builtin_amdgcn_s_setprio(1); _Pragma("unroll") for (int m = 0; m < 4; ++m) _Pragma("unroll") for (int n = 0; n < 2; ++n) _Pragma("unroll") for (int k = 0; k < 2; ++k) \
;         acc[ai][bj][m][n] = __builtin_amdgcn_mfma_f32_16x16x32_bf16(Bt[n][k], At[m][k], acc[ai][bj][m][n], 0, 0, 0); __builtin_amdgcn_s_setprio(0); } while (0)
; #define PG8_WAIT_V(n) asm volatile("s_waitcnt vmcnt(" #n ")" ::: "memory")
; #define PG8_WAIT_L(n) asm volatile("s_waitcnt lgkmcnt(" #n ")" ::: "memory")
; #define PG8_BAR __builtin_amdgcn_s_barrier()
; #define PG8_SCHED __builtin_amdgcn_sched_barrier(0)
; template <class Epi, bool ALIGN_EPI = true>
; __device__ __forceinline__ void gemm_phase(LAS unsigned char* lds, const Gemm g, const Sched& S, const Epi& E) {
;     ...
;             PG8_WAIT_V(8); PG8_WAIT_L(0); PG8_BAR; PG8_MMA(0, 0, At, B0); PG8_MMA(0, 1, At, B1); PG8_BAR; PG8_SCHED;
;             PG8_LDA(At, 1, 1); PG8_STAGE(PG8_SB(1, 0), b3, voffB); PG8_STAGE(PG8_SB(1, 1), b3 + hstepB, voffB); PG8_STAGE(PG8_SA(1, 0), a3, voffA);
;             PG8_WAIT_V(8); PG8_WAIT_L(0); PG8_BAR; PG8_MMA(1, 0, At, B0); PG8_MMA(1, 1, At, B1); PG8_BAR; PG8_SCHED;
;         }
	s_setprio 1
	s_waitcnt lgkmcnt(0)
	v_mfma_f32_16x16x32_bf16 v[130:133], v[150:153], v[182:185], v[130:133]
	v_mfma_f32_16x16x32_bf16 v[126:129], v[158:161], v[182:185], v[126:129]
	v_mfma_f32_16x16x32_bf16 v[114:117], v[150:153], v[190:193], v[114:117]
	v_mfma_f32_16x16x32_bf16 v[110:113], v[158:161], v[190:193], v[110:113]
	v_mfma_f32_16x16x32_bf16 v[98:101], v[150:153], v[206:209], v[98:101]
	v_mfma_f32_16x16x32_bf16 v[94:97], v[158:161], v[206:209], v[94:97]
	v_mfma_f32_16x16x32_bf16 v[82:85], v[150:153], v[228:231], v[82:85]
	v_mfma_f32_16x16x32_bf16 v[78:81], v[158:161], v[228:231], v[78:81]
	v_mfma_f32_16x16x32_bf16 v[130:133], v[154:157], v[186:189], v[130:133]
	v_mfma_f32_16x16x32_bf16 v[126:129], v[162:165], v[186:189], v[126:129]
	v_mfma_f32_16x16x32_bf16 v[114:117], v[154:157], v[194:197], v[114:117]
	v_mfma_f32_16x16x32_bf16 v[110:113], v[162:165], v[194:197], v[110:113]
	v_mfma_f32_16x16x32_bf16 v[98:101], v[154:157], v[224:227], v[98:101]
	v_mfma_f32_16x16x32_bf16 v[94:97], v[162:165], v[224:227], v[94:97]
	v_mfma_f32_16x16x32_bf16 v[82:85], v[154:157], v[232:235], v[82:85]
	v_mfma_f32_16x16x32_bf16 v[78:81], v[162:165], v[232:235], v[78:81]
	s_setprio 0
	s_setprio 1
	v_mfma_f32_16x16x32_bf16 v[122:125], v[166:169], v[182:185], v[122:125]
	v_mfma_f32_16x16x32_bf16 v[118:121], v[174:177], v[182:185], v[118:121]
	v_mfma_f32_16x16x32_bf16 v[106:109], v[166:169], v[190:193], v[106:109]
	v_mfma_f32_16x16x32_bf16 v[102:105], v[174:177], v[190:193], v[102:105]
	v_mfma_f32_16x16x32_bf16 v[90:93], v[166:169], v[206:209], v[90:93]
	v_mfma_f32_16x16x32_bf16 v[86:89], v[174:177], v[206:209], v[86:89]
	v_mfma_f32_16x16x32_bf16 v[74:77], v[166:169], v[228:231], v[74:77]
	v_mfma_f32_16x16x32_bf16 v[70:73], v[174:177], v[228:231], v[70:73]
	v_mfma_f32_16x16x32_bf16 v[122:125], v[170:173], v[186:189], v[122:125]
	v_mfma_f32_16x16x32_bf16 v[118:121], v[178:181], v[186:189], v[118:121]
	v_mfma_f32_16x16x32_bf16 v[106:109], v[170:173], v[194:197], v[106:109]
	v_mfma_f32_16x16x32_bf16 v[102:105], v[178:181], v[194:197], v[102:105]
	v_mfma_f32_16x16x32_bf16 v[90:93], v[170:173], v[224:227], v[90:93]
	v_mfma_f32_16x16x32_bf16 v[86:89], v[178:181], v[224:227], v[86:89]
	v_mfma_f32_16x16x32_bf16 v[74:77], v[170:173], v[232:235], v[74:77]
	v_mfma_f32_16x16x32_bf16 v[70:73], v[178:181], v[232:235], v[70:73]
	s_setprio 0
	s_barrier
	s_add_u32 s100, s48, 0x80
	s_addc_u32 s101, s49, 0
	s_add_i32 s50, s68, s37
	s_mov_b32 m0, s50
	ds_read_b128 v[182:185], v148 offset:49152
	ds_read_b128 v[186:189], v148 offset:50176
	ds_read_b128 v[190:193], v148 offset:51200
	ds_read_b128 v[194:197], v148 offset:52224
	ds_read_b128 v[206:209], v148 offset:53248
	ds_read_b128 v[224:227], v148 offset:54272
	ds_read_b128 v[228:231], v148 offset:55296
	ds_read_b128 v[232:235], v148 offset:56320
	global_load_lds_dwordx4 v138, s[100:101]
	s_add_i32 m0, s50, 0x2000
	s_add_u32 s48, s48, 0x40080
	s_addc_u32 s49, s49, 0
	s_add_i32 s50, s69, s37
	global_load_lds_dwordx4 v134, s[100:101]
	s_mov_b32 m0, s50
	s_nop 0
	global_load_lds_dwordx4 v138, s[48:49]
	s_add_i32 m0, s50, 0x2000
	s_nop 0
	global_load_lds_dwordx4 v134, s[48:49]
	s_waitcnt vmcnt(6)
	s_waitcnt lgkmcnt(0)
	s_barrier
	s_setprio 1
	s_waitcnt lgkmcnt(0)
	v_mfma_f32_16x16x32_bf16 v[66:69], v[150:153], v[182:185], v[66:69]
	v_mfma_f32_16x16x32_bf16 v[62:65], v[158:161], v[182:185], v[62:65]
	v_mfma_f32_16x16x32_bf16 v[50:53], v[150:153], v[190:193], v[50:53]
	v_mfma_f32_16x16x32_bf16 v[46:49], v[158:161], v[190:193], v[46:49]
	v_mfma_f32_16x16x32_bf16 v[34:37], v[150:153], v[206:209], v[34:37]
	v_mfma_f32_16x16x32_bf16 v[30:33], v[158:161], v[206:209], v[30:33]
	v_mfma_f32_16x16x32_bf16 v[18:21], v[150:153], v[228:231], v[18:21]
	v_mfma_f32_16x16x32_bf16 v[14:17], v[158:161], v[228:231], v[14:17]
	v_mfma_f32_16x16x32_bf16 v[66:69], v[154:157], v[186:189], v[66:69]
	v_mfma_f32_16x16x32_bf16 v[62:65], v[162:165], v[186:189], v[62:65]
	v_mfma_f32_16x16x32_bf16 v[50:53], v[154:157], v[194:197], v[50:53]
	v_mfma_f32_16x16x32_bf16 v[46:49], v[162:165], v[194:197], v[46:49]
	v_mfma_f32_16x16x32_bf16 v[34:37], v[154:157], v[224:227], v[34:37]
	v_mfma_f32_16x16x32_bf16 v[30:33], v[162:165], v[224:227], v[30:33]
	v_mfma_f32_16x16x32_bf16 v[18:21], v[154:157], v[232:235], v[18:21]
	v_mfma_f32_16x16x32_bf16 v[14:17], v[162:165], v[232:235], v[14:17]
	s_setprio 0
	s_setprio 1
	v_mfma_f32_16x16x32_bf16 v[58:61], v[166:169], v[182:185], v[58:61]
	v_mfma_f32_16x16x32_bf16 v[54:57], v[174:177], v[182:185], v[54:57]
	v_mfma_f32_16x16x32_bf16 v[42:45], v[166:169], v[190:193], v[42:45]
	v_mfma_f32_16x16x32_bf16 v[38:41], v[174:177], v[190:193], v[38:41]
	v_mfma_f32_16x16x32_bf16 v[26:29], v[166:169], v[206:209], v[26:29]
	v_mfma_f32_16x16x32_bf16 v[22:25], v[174:177], v[206:209], v[22:25]
	v_mfma_f32_16x16x32_bf16 v[8:11], v[166:169], v[228:231], v[10:13]
	v_mfma_f32_16x16x32_bf16 v[4:7], v[174:177], v[228:231], v[4:7]
	v_mfma_f32_16x16x32_bf16 v[58:61], v[170:173], v[186:189], v[58:61]
	v_mfma_f32_16x16x32_bf16 v[54:57], v[178:181], v[186:189], v[54:57]
	v_mfma_f32_16x16x32_bf16 v[42:45], v[170:173], v[194:197], v[42:45]
	v_mfma_f32_16x16x32_bf16 v[38:41], v[178:181], v[194:197], v[38:41]
	v_mfma_f32_16x16x32_bf16 v[26:29], v[170:173], v[224:227], v[26:29]
	v_mfma_f32_16x16x32_bf16 v[22:25], v[178:181], v[224:227], v[22:25]
	v_mfma_f32_16x16x32_bf16 v[10:13], v[170:173], v[232:235], v[8:11]
	v_mfma_f32_16x16x32_bf16 v[6:9], v[178:181], v[232:235], v[4:7]
	s_setprio 0
	s_barrier
	s_add_u32 s46, s46, 0x100
	s_addc_u32 s47, s47, 0
	s_add_u32 s65, s65, 0x100
	s_addc_u32 s66, s66, 0
	s_cmp_ge_i32 s67, s56
	s_mov_b32 s48, s67
	s_cbranch_scc0 .LBB0_1929

; #define PG8_STAGE(bufoff, gbase, voff) do { _Pragma("unroll") for (int _i = 0; _i < 2; ++_i) \
;         __builtin_amdgcn_global_load_lds((const unsigned*)((const char*)(gbase) + (voff)[_i]), (LAS unsigned*)(lds + (bufoff) + ldsw + _i * 8192), 16, 0, 0); } while (0)
; #define PG8_LDA(dst, b, h) do { _Pragma("unroll") for (int m = 0; m < 4; ++m) _Pragma("unroll") for (int k = 0; k < 2; ++k) dst[m][k] = *(const LAS bf16x8*)(lds + PG8_SA(b, h) + aoff + m * 2048 + k * 1024); } while (0)
; #define PG8_LDB(dst, b, h) do { _Pragma("unroll") for (int n = 0; n < 2; ++n) _Pragma("unroll") for (int k = 0; k < 2; ++k) dst[n][k] = *(const LAS bf16x8*)(lds + PG8_SB(b, h) + boff + n * 2048 + k * 1024); } while (0)
; #define PG8_MMA(ai, bj, At, Bt) do { __builtin_amdgcn_s_setprio(1); _Pragma("unroll") for (int m = 0; m < 4; ++m) _Pragma("unroll") for (int n = 0; n < 2; ++n) _Pragma("unroll") for (int k = 0; k < 2; ++k) \
;         acc[ai][bj][m][n] = __builtin_amdgcn_mfma_f32_16x16x32_bf16(Bt[n][k], At[m][k], acc[ai][bj][m][n], 0, 0, 0); __builtin_amdgcn_s_setprio(0); } while (0)
; #define PG8_WAIT_V(n) asm volatile("s_waitcnt vmcnt(" #n ")" ::: "memory")
; template <class Epi, bool ALIGN_EPI = true>
; __device__ __forceinline__ void gemm_phase(LAS unsigned char* lds, const Gemm g, const Sched& S, const Epi& E) {
;     ...
;         for (int t = t_lo; t < t_hi; t += 2) {
;             const bool last = (t == nt - 2);
;             const char* a1 = cA + (size_t)(t + 1) * kstep;
;             const char* a2 = last ? nA : cA + (size_t)(t + 2) * kstep; const char* b2 = last ? nB : cB + (size_t)(t + 2) * kstep;
;             const char* a3 = a2 + kstep; const char* b3 = b2 + kstep;
;             const int rflag = __builtin_amdgcn_readfirstlane(t | (int)(ui == 0));
;             PG8_LDB(B0, 0, 0); PG8_LDB(B1, 0, 1); PG8_SCHED; PG8_LDA(At, 0, 0); PG8_STAGE(PG8_SA(1, 1), a1 + hstepA, voffA);
;             if constexpr (Epi::NSTORES > 0) PG8_WAIT_RELAX(rflag, 8 + Epi::NSTORES); else PG8_WAIT_V(8);
;             PG8_WAIT_L(0); PG8_BAR; PG8_MMA(0, 0, At, B0); PG8_MMA(0, 1, At, B1); PG8_BAR; PG8_SCHED;
;             PG8_LDA(At, 0, 1); PG8_STAGE(PG8_SB(0, 0), b2, voffB); PG8_STAGE(PG8_SB(0, 1), b2 + hstepB, voffB); PG8_STAGE(PG8_SA(0, 0), a2, voffA);
;             if constexpr (Epi::NSTORES > 0) PG8_WAIT_RELAX(rflag, 8 + Epi::NSTORES); else PG8_WAIT_V(8);
.LBB0_2023:
	s_add_i32 s69, s46, 2
	s_add_u32 s47, s26, 0xfff80080
	s_addc_u32 s48, s27, -1
	s_add_i32 s70, 0, 0x10000
	s_cmp_eq_u32 s58, s46
	v_add_u32_e32 v153, s46, v2
	s_cselect_b32 s49, s19, s48
	s_cselect_b32 s48, s21, s47
	v_add_u32_e32 v4, s70, v151
	s_cselect_b32 s47, s65, s68
	s_cselect_b32 s46, s66, s67
	s_add_i32 s72, 0, 0x14000
	ds_read_b128 v[146:149], v4
	ds_read_b128 v[154:157], v4 offset:1024
	ds_read_b128 v[158:161], v4 offset:2048
	ds_read_b128 v[162:165], v4 offset:3072
	v_add_u32_e32 v4, s72, v151
	ds_read_b128 v[166:169], v4
	ds_read_b128 v[170:173], v4 offset:1024
	ds_read_b128 v[174:177], v4 offset:2048
	ds_read_b128 v[178:181], v4 offset:3072
	s_add_i32 m0, s36, 0xc000
	ds_read_b128 v[182:185], v152
	ds_read_b128 v[186:189], v152 offset:1024
	ds_read_b128 v[190:193], v152 offset:2048
	ds_read_b128 v[194:197], v152 offset:3072
	ds_read_b128 v[206:209], v152 offset:4096
	ds_read_b128 v[224:227], v152 offset:5120
	ds_read_b128 v[228:231], v152 offset:6144
	ds_read_b128 v[232:235], v152 offset:7168
	s_add_u32 s100, s26, 0xfff80000
	s_addc_u32 s101, s27, -1
	s_mov_b32 m0, s56
	s_nop 0
	global_load_lds_dwordx4 v142, s[100:101]
	s_mov_b32 m0, s57
	s_nop 0
	global_load_lds_dwordx4 v144, s[100:101]
	s_add_i32 m0, s36, 0xc000
	s_nop 0
	global_load_lds_dwordx4 v142, s[26:27]
	s_add_i32 m0, s36, 0xe000
	v_readfirstlane_b32 s73, v153
	global_load_lds_dwordx4 v144, s[26:27]
	s_cmp_eq_u32 s73, 0
	s_cbranch_scc1 .Lrw18
	s_waitcnt vmcnt(8)
.Lrw18:
	s_waitcnt vmcnt(16)
	s_waitcnt lgkmcnt(0)
	s_barrier
	s_setprio 1
	s_waitcnt lgkmcnt(0)
	v_mfma_f32_16x16x32_bf16 v[130:133], v[146:149], v[182:185], v[130:133]
	v_mfma_f32_16x16x32_bf16 v[126:129], v[158:161], v[182:185], v[126:129]
	v_mfma_f32_16x16x32_bf16 v[122:125], v[146:149], v[190:193], v[122:125]
	v_mfma_f32_16x16x32_bf16 v[118:121], v[158:161], v[190:193], v[118:121]
	v_mfma_f32_16x16x32_bf16 v[114:117], v[146:149], v[206:209], v[114:117]
	v_mfma_f32_16x16x32_bf16 v[110:113], v[158:161], v[206:209], v[110:113]
	v_mfma_f32_16x16x32_bf16 v[106:109], v[146:149], v[228:231], v[106:109]
	v_mfma_f32_16x16x32_bf16 v[102:105], v[158:161], v[228:231], v[102:105]
	v_mfma_f32_16x16x32_bf16 v[130:133], v[154:157], v[186:189], v[130:133]
	v_mfma_f32_16x16x32_bf16 v[126:129], v[162:165], v[186:189], v[126:129]
	v_mfma_f32_16x16x32_bf16 v[122:125], v[154:157], v[194:197], v[122:125]
	v_mfma_f32_16x16x32_bf16 v[118:121], v[162:165], v[194:197], v[118:121]
	v_mfma_f32_16x16x32_bf16 v[114:117], v[154:157], v[224:227], v[114:117]
	v_mfma_f32_16x16x32_bf16 v[110:113], v[162:165], v[224:227], v[110:113]
	v_mfma_f32_16x16x32_bf16 v[106:109], v[154:157], v[232:235], v[106:109]
	v_mfma_f32_16x16x32_bf16 v[102:105], v[162:165], v[232:235], v[102:105]
	s_setprio 0
	s_setprio 1
	v_mfma_f32_16x16x32_bf16 v[98:101], v[166:169], v[182:185], v[98:101]
	v_mfma_f32_16x16x32_bf16 v[94:97], v[174:177], v[182:185], v[94:97]
	v_mfma_f32_16x16x32_bf16 v[90:93], v[166:169], v[190:193], v[90:93]
	v_mfma_f32_16x16x32_bf16 v[86:89], v[174:177], v[190:193], v[86:89]
	v_mfma_f32_16x16x32_bf16 v[82:85], v[166:169], v[206:209], v[82:85]
	v_mfma_f32_16x16x32_bf16 v[78:81], v[174:177], v[206:209], v[78:81]
	v_mfma_f32_16x16x32_bf16 v[74:77], v[166:169], v[228:231], v[74:77]
	v_mfma_f32_16x16x32_bf16 v[70:73], v[174:177], v[228:231], v[70:73]
	v_mfma_f32_16x16x32_bf16 v[98:101], v[170:173], v[186:189], v[98:101]
	v_mfma_f32_16x16x32_bf16 v[94:97], v[178:181], v[186:189], v[94:97]
	v_mfma_f32_16x16x32_bf16 v[90:93], v[170:173], v[194:197], v[90:93]
	v_mfma_f32_16x16x32_bf16 v[86:89], v[178:181], v[194:197], v[86:89]
	v_mfma_f32_16x16x32_bf16 v[82:85], v[170:173], v[224:227], v[82:85]
	v_mfma_f32_16x16x32_bf16 v[78:81], v[178:181], v[224:227], v[78:81]
	v_mfma_f32_16x16x32_bf16 v[74:77], v[170:173], v[232:235], v[74:77]
	v_mfma_f32_16x16x32_bf16 v[70:73], v[178:181], v[232:235], v[70:73]
	s_setprio 0
	s_barrier
	s_add_i32 s70, s70, s35
	s_mov_b32 m0, s70
	ds_read_b128 v[182:185], v152 offset:16384
	ds_read_b128 v[186:189], v152 offset:17408
	ds_read_b128 v[190:193], v152 offset:18432
	ds_read_b128 v[194:197], v152 offset:19456
	ds_read_b128 v[206:209], v152 offset:20480
	ds_read_b128 v[224:227], v152 offset:21504
	ds_read_b128 v[228:231], v152 offset:22528
	ds_read_b128 v[232:235], v152 offset:23552
	global_load_lds_dwordx4 v136, s[46:47]
	s_add_i32 m0, s70, 0x2000
	s_add_u32 s70, s46, 0x80000
	s_addc_u32 s71, s47, 0
	s_add_i32 s72, s72, s35
	global_load_lds_dwordx4 v140, s[46:47]
	s_mov_b32 m0, s72
	s_nop 0
	global_load_lds_dwordx4 v136, s[70:71]
	s_add_i32 m0, s72, 0x2000
	s_nop 0
	global_load_lds_dwordx4 v140, s[70:71]
	s_cmp_eq_u32 s73, 0
	s_cbranch_scc1 .Lrw19
	s_waitcnt vmcnt(6)
; #define PG8_STAGE(bufoff, gbase, voff) do { _Pragma("unroll") for (int _i = 0; _i < 2; ++_i) \
;         __builtin_amdgcn_global_load_lds((const unsigned*)((const char*)(gbase) + (voff)[_i]), (LAS unsigned*)(lds + (bufoff) + ldsw + _i * 8192), 16, 0, 0); } while (0)
; #define PG8_LDA(dst, b, h) do { _Pragma("unroll") for (int m = 0; m < 4; ++m) _Pragma("unroll") for (int k = 0; k < 2; ++k) dst[m][k] = *(const LAS bf16x8*)(lds + PG8_SA(b, h) + aoff + m * 2048 + k * 1024); } while (0)
; #define PG8_LDB(dst, b, h) do { _Pragma("unroll") for (int n = 0; n < 2; ++n) _Pragma("unroll") for (int k = 0; k < 2; ++k) dst[n][k] = *(const LAS bf16x8*)(lds + PG8_SB(b, h) + boff + n * 2048 + k * 1024); } while (0)
; #define PG8_MMA(ai, bj, At, Bt) do { __builtin_amdgcn_s_setprio(1); _Pragma("unroll") for (int m = 0; m < 4; ++m) _Pragma("unroll") for (int n = 0; n < 2; ++n) _Pragma("unroll") for (int k = 0; k < 2; ++k) \
;         acc[ai][bj][m][n] = __builtin_amdgcn_mfma_f32_16x16x32_bf16(Bt[n][k], At[m][k], acc[ai][bj][m][n], 0, 0, 0); __builtin_amdgcn_s_setprio(0); } while (0)
; #define PG8_WAIT_V(n) asm volatile("s_waitcnt vmcnt(" #n ")" ::: "memory")
; #define PG8_WAIT_L(n) asm volatile("s_waitcnt lgkmcnt(" #n ")" ::: "memory")
; #define PG8_BAR __builtin_amdgcn_s_barrier()
; #define PG8_WAIT_RELAX(flag, n) asm volatile("s_cmp_eq_u32 %0, 0\n\ts_cbranch_scc1 .Lrw%=\n\ts_waitcnt vmcnt(8)\n.Lrw%=:\n\ts_waitcnt vmcnt(%1)" :: "s"(flag), "n"(n) : "scc", "memory")
; #define PG8_SCHED __builtin_amdgcn_sched_barrier(0)
; template <class Epi, bool ALIGN_EPI = true>
; __device__ __forceinline__ void gemm_phase(LAS unsigned char* lds, const Gemm g, const Sched& S, const Epi& E) {
;     ...
;             if constexpr (Epi::NSTORES > 0) PG8_WAIT_RELAX(rflag, 8 + Epi::NSTORES); else PG8_WAIT_V(8);
;             PG8_WAIT_L(0); PG8_BAR; PG8_MMA(1, 0, At, B0); PG8_MMA(1, 1, At, B1); PG8_BAR; PG8_SCHED;
;             PG8_LDB(B0, 1, 0); PG8_LDB(B1, 1, 1); PG8_SCHED; PG8_LDA(At, 1, 0); PG8_STAGE(PG8_SA(0, 1), a2 + hstepA, voffA);
;             PG8_WAIT_V(8); PG8_WAIT_L(0); PG8_BAR; PG8_MMA(0, 0, At, B0); PG8_MMA(0, 1, At, B1); PG8_BAR; PG8_SCHED;
.Lrw19:
	s_waitcnt vmcnt(6)
	s_waitcnt lgkmcnt(0)
	s_barrier
	s_setprio 1
	s_waitcnt lgkmcnt(0)
	v_mfma_f32_16x16x32_bf16 v[66:69], v[146:149], v[182:185], v[66:69]
	v_mfma_f32_16x16x32_bf16 v[62:65], v[158:161], v[182:185], v[62:65]
	v_mfma_f32_16x16x32_bf16 v[58:61], v[146:149], v[190:193], v[58:61]
	v_mfma_f32_16x16x32_bf16 v[54:57], v[158:161], v[190:193], v[54:57]
	v_mfma_f32_16x16x32_bf16 v[50:53], v[146:149], v[206:209], v[50:53]
	v_mfma_f32_16x16x32_bf16 v[46:49], v[158:161], v[206:209], v[46:49]
	v_mfma_f32_16x16x32_bf16 v[42:45], v[146:149], v[228:231], v[42:45]
	v_mfma_f32_16x16x32_bf16 v[38:41], v[158:161], v[228:231], v[38:41]
	v_mfma_f32_16x16x32_bf16 v[66:69], v[154:157], v[186:189], v[66:69]
	v_mfma_f32_16x16x32_bf16 v[62:65], v[162:165], v[186:189], v[62:65]
	v_mfma_f32_16x16x32_bf16 v[58:61], v[154:157], v[194:197], v[58:61]
	v_mfma_f32_16x16x32_bf16 v[54:57], v[162:165], v[194:197], v[54:57]
	v_mfma_f32_16x16x32_bf16 v[50:53], v[154:157], v[224:227], v[50:53]
	v_mfma_f32_16x16x32_bf16 v[46:49], v[162:165], v[224:227], v[46:49]
	v_mfma_f32_16x16x32_bf16 v[42:45], v[154:157], v[232:235], v[42:45]
	v_mfma_f32_16x16x32_bf16 v[38:41], v[162:165], v[232:235], v[38:41]
	s_setprio 0
	s_setprio 1
	v_mfma_f32_16x16x32_bf16 v[34:37], v[166:169], v[182:185], v[34:37]
	v_mfma_f32_16x16x32_bf16 v[30:33], v[174:177], v[182:185], v[30:33]
	v_mfma_f32_16x16x32_bf16 v[26:29], v[166:169], v[190:193], v[26:29]
	v_mfma_f32_16x16x32_bf16 v[22:25], v[174:177], v[190:193], v[22:25]
	v_mfma_f32_16x16x32_bf16 v[18:21], v[166:169], v[206:209], v[18:21]
	v_mfma_f32_16x16x32_bf16 v[14:17], v[174:177], v[206:209], v[14:17]
	v_mfma_f32_16x16x32_bf16 v[10:13], v[166:169], v[228:231], v[10:13]
	v_mfma_f32_16x16x32_bf16 v[4:7], v[174:177], v[228:231], v[6:9]
	v_mfma_f32_16x16x32_bf16 v[34:37], v[170:173], v[186:189], v[34:37]
	v_mfma_f32_16x16x32_bf16 v[30:33], v[178:181], v[186:189], v[30:33]
	v_mfma_f32_16x16x32_bf16 v[26:29], v[170:173], v[194:197], v[26:29]
	v_mfma_f32_16x16x32_bf16 v[22:25], v[178:181], v[194:197], v[22:25]
	v_mfma_f32_16x16x32_bf16 v[18:21], v[170:173], v[224:227], v[18:21]
	v_mfma_f32_16x16x32_bf16 v[14:17], v[178:181], v[224:227], v[14:17]
	v_mfma_f32_16x16x32_bf16 v[10:13], v[170:173], v[232:235], v[10:13]
	v_mfma_f32_16x16x32_bf16 v[4:7], v[178:181], v[232:235], v[4:7]
	s_setprio 0
	s_barrier
	s_add_i32 s70, 0, 0x18000
	v_add_u32_e32 v8, s70, v151
	s_add_i32 s71, 0, 0x1c000
	ds_read_b128 v[146:149], v8
	ds_read_b128 v[154:157], v8 offset:1024
	ds_read_b128 v[158:161], v8 offset:2048
	ds_read_b128 v[162:165], v8 offset:3072
	v_add_u32_e32 v8, s71, v151
	ds_read_b128 v[166:169], v8
	ds_read_b128 v[170:173], v8 offset:1024
	ds_read_b128 v[174:177], v8 offset:2048
	ds_read_b128 v[178:181], v8 offset:3072
	s_add_u32 s48, s48, 0x80000
	s_addc_u32 s49, s49, 0
	s_mov_b32 m0, s50
	ds_read_b128 v[182:185], v152 offset:32768
	ds_read_b128 v[186:189], v152 offset:33792
	ds_read_b128 v[190:193], v152 offset:34816
	ds_read_b128 v[194:197], v152 offset:35840
	ds_read_b128 v[206:209], v152 offset:36864
	ds_read_b128 v[224:227], v152 offset:37888
	ds_read_b128 v[228:231], v152 offset:38912
	ds_read_b128 v[232:235], v152 offset:39936
	s_add_u32 s100, s48, 0xfff80000
	s_addc_u32 s101, s49, -1
	s_mov_b32 m0, s36
	s_nop 0
	global_load_lds_dwordx4 v134, s[100:101]
	s_mov_b32 m0, s37
	s_nop 0
	global_load_lds_dwordx4 v138, s[100:101]
	s_mov_b32 m0, s50
	s_nop 0
	global_load_lds_dwordx4 v134, s[48:49]
	s_mov_b32 m0, s51
	s_nop 0
	global_load_lds_dwordx4 v138, s[48:49]
	s_waitcnt vmcnt(8)
	s_waitcnt lgkmcnt(0)
	s_barrier
; #define PG8_STAGE(bufoff, gbase, voff) do { _Pragma("unroll") for (int _i = 0; _i < 2; ++_i) \
;         __builtin_amdgcn_global_load_lds((const unsigned*)((const char*)(gbase) + (voff)[_i]), (LAS unsigned*)(lds + (bufoff) + ldsw + _i * 8192), 16, 0, 0); } while (0)
; #define PG8_LDA(dst, b, h) do { _Pragma("unroll") for (int m = 0; m < 4; ++m) _Pragma("unroll") for (int k = 0; k < 2; ++k) dst[m][k] = *(const LAS bf16x8*)(lds + PG8_SA(b, h) + aoff + m * 2048 + k * 1024); } while (0)
; #define PG8_MMA(ai, bj, At, Bt) do { __builtin_amdgcn_s_setprio(1); _Pragma("unroll") for (int m = 0; m < 4; ++m) _Pragma("unroll") for (int n = 0; n < 2; ++n) _Pragma("unroll") for (int k = 0; k < 2; ++k) \
;         acc[ai][bj][m][n] = __builtin_amdgcn_mfma_f32_16x16x32_bf16(Bt[n][k], At[m][k], acc[ai][bj][m][n], 0, 0, 0); __builtin_amdgcn_s_setprio(0); } while (0)
; #define PG8_WAIT_V(n) asm volatile("s_waitcnt vmcnt(" #n ")" ::: "memory")
; #define PG8_WAIT_L(n) asm volatile("s_waitcnt lgkmcnt(" #n ")" ::: "memory")
; #define PG8_BAR __builtin_amdgcn_s_barrier()
; #define PG8_SCHED __builtin_amdgcn_sched_barrier(0)
; template <class Epi, bool ALIGN_EPI = true>
; __device__ __forceinline__ void gemm_phase(LAS unsigned char* lds, const Gemm g, const Sched& S, const Epi& E) {
;     ...
;             PG8_WAIT_V(8); PG8_WAIT_L(0); PG8_BAR; PG8_MMA(0, 0, At, B0); PG8_MMA(0, 1, At, B1); PG8_BAR; PG8_SCHED;
;             PG8_LDA(At, 1, 1); PG8_STAGE(PG8_SB(1, 0), b3, voffB); PG8_STAGE(PG8_SB(1, 1), b3 + hstepB, voffB); PG8_STAGE(PG8_SA(1, 0), a3, voffA);
;             PG8_WAIT_V(8); PG8_WAIT_L(0); PG8_BAR; PG8_MMA(1, 0, At, B0); PG8_MMA(1, 1, At, B1); PG8_BAR; PG8_SCHED;
;         }
	s_setprio 1
	s_waitcnt lgkmcnt(0)
	v_mfma_f32_16x16x32_bf16 v[130:133], v[146:149], v[182:185], v[130:133]
	v_mfma_f32_16x16x32_bf16 v[126:129], v[158:161], v[182:185], v[126:129]
	v_mfma_f32_16x16x32_bf16 v[122:125], v[146:149], v[190:193], v[122:125]
	v_mfma_f32_16x16x32_bf16 v[118:121], v[158:161], v[190:193], v[118:121]
	v_mfma_f32_16x16x32_bf16 v[114:117], v[146:149], v[206:209], v[114:117]
	v_mfma_f32_16x16x32_bf16 v[110:113], v[158:161], v[206:209], v[110:113]
	v_mfma_f32_16x16x32_bf16 v[106:109], v[146:149], v[228:231], v[106:109]
	v_mfma_f32_16x16x32_bf16 v[102:105], v[158:161], v[228:231], v[102:105]
	v_mfma_f32_16x16x32_bf16 v[130:133], v[154:157], v[186:189], v[130:133]
	v_mfma_f32_16x16x32_bf16 v[126:129], v[162:165], v[186:189], v[126:129]
	v_mfma_f32_16x16x32_bf16 v[122:125], v[154:157], v[194:197], v[122:125]
	v_mfma_f32_16x16x32_bf16 v[118:121], v[162:165], v[194:197], v[118:121]
	v_mfma_f32_16x16x32_bf16 v[114:117], v[154:157], v[224:227], v[114:117]
	v_mfma_f32_16x16x32_bf16 v[110:113], v[162:165], v[224:227], v[110:113]
	v_mfma_f32_16x16x32_bf16 v[106:109], v[154:157], v[232:235], v[106:109]
	v_mfma_f32_16x16x32_bf16 v[102:105], v[162:165], v[232:235], v[102:105]
	s_setprio 0
	s_setprio 1
	v_mfma_f32_16x16x32_bf16 v[98:101], v[166:169], v[182:185], v[98:101]
	v_mfma_f32_16x16x32_bf16 v[94:97], v[174:177], v[182:185], v[94:97]
	v_mfma_f32_16x16x32_bf16 v[90:93], v[166:169], v[190:193], v[90:93]
	v_mfma_f32_16x16x32_bf16 v[86:89], v[174:177], v[190:193], v[86:89]
	v_mfma_f32_16x16x32_bf16 v[82:85], v[166:169], v[206:209], v[82:85]
	v_mfma_f32_16x16x32_bf16 v[78:81], v[174:177], v[206:209], v[78:81]
	v_mfma_f32_16x16x32_bf16 v[74:77], v[166:169], v[228:231], v[74:77]
	v_mfma_f32_16x16x32_bf16 v[70:73], v[174:177], v[228:231], v[70:73]
	v_mfma_f32_16x16x32_bf16 v[98:101], v[170:173], v[186:189], v[98:101]
	v_mfma_f32_16x16x32_bf16 v[94:97], v[178:181], v[186:189], v[94:97]
	v_mfma_f32_16x16x32_bf16 v[90:93], v[170:173], v[194:197], v[90:93]
	v_mfma_f32_16x16x32_bf16 v[86:89], v[178:181], v[194:197], v[86:89]
	v_mfma_f32_16x16x32_bf16 v[82:85], v[170:173], v[224:227], v[82:85]
	v_mfma_f32_16x16x32_bf16 v[78:81], v[178:181], v[224:227], v[78:81]
	v_mfma_f32_16x16x32_bf16 v[74:77], v[170:173], v[232:235], v[74:77]
	v_mfma_f32_16x16x32_bf16 v[70:73], v[178:181], v[232:235], v[70:73]
	s_setprio 0
	s_barrier
	s_add_u32 s100, s46, 0x80
	s_addc_u32 s101, s47, 0
	s_add_i32 s48, s70, s35
	s_mov_b32 m0, s48
	ds_read_b128 v[182:185], v152 offset:49152
	ds_read_b128 v[186:189], v152 offset:50176
	ds_read_b128 v[190:193], v152 offset:51200
	ds_read_b128 v[194:197], v152 offset:52224
	ds_read_b128 v[206:209], v152 offset:53248
	ds_read_b128 v[224:227], v152 offset:54272
	ds_read_b128 v[228:231], v152 offset:55296
	ds_read_b128 v[232:235], v152 offset:56320
	global_load_lds_dwordx4 v136, s[100:101]
	s_add_i32 m0, s48, 0x2000
	s_add_u32 s46, s46, 0x80080
	s_addc_u32 s47, s47, 0
	s_add_i32 s48, s71, s35
	global_load_lds_dwordx4 v140, s[100:101]
	s_mov_b32 m0, s48
	s_nop 0
	global_load_lds_dwordx4 v136, s[46:47]
	s_add_i32 m0, s48, 0x2000
	s_nop 0
	global_load_lds_dwordx4 v140, s[46:47]
	s_waitcnt vmcnt(6)
	s_waitcnt lgkmcnt(0)
	s_barrier
	s_setprio 1
	s_waitcnt lgkmcnt(0)
	v_mfma_f32_16x16x32_bf16 v[66:69], v[146:149], v[182:185], v[66:69]
	v_mfma_f32_16x16x32_bf16 v[62:65], v[158:161], v[182:185], v[62:65]
	v_mfma_f32_16x16x32_bf16 v[58:61], v[146:149], v[190:193], v[58:61]
	v_mfma_f32_16x16x32_bf16 v[54:57], v[158:161], v[190:193], v[54:57]
	v_mfma_f32_16x16x32_bf16 v[50:53], v[146:149], v[206:209], v[50:53]
	v_mfma_f32_16x16x32_bf16 v[46:49], v[158:161], v[206:209], v[46:49]
	v_mfma_f32_16x16x32_bf16 v[42:45], v[146:149], v[228:231], v[42:45]
	v_mfma_f32_16x16x32_bf16 v[38:41], v[158:161], v[228:231], v[38:41]
	v_mfma_f32_16x16x32_bf16 v[66:69], v[154:157], v[186:189], v[66:69]
	v_mfma_f32_16x16x32_bf16 v[62:65], v[162:165], v[186:189], v[62:65]
	v_mfma_f32_16x16x32_bf16 v[58:61], v[154:157], v[194:197], v[58:61]
	v_mfma_f32_16x16x32_bf16 v[54:57], v[162:165], v[194:197], v[54:57]
	v_mfma_f32_16x16x32_bf16 v[50:53], v[154:157], v[224:227], v[50:53]
	v_mfma_f32_16x16x32_bf16 v[46:49], v[162:165], v[224:227], v[46:49]
	v_mfma_f32_16x16x32_bf16 v[42:45], v[154:157], v[232:235], v[42:45]
	v_mfma_f32_16x16x32_bf16 v[38:41], v[162:165], v[232:235], v[38:41]
	s_setprio 0
	s_setprio 1
	v_mfma_f32_16x16x32_bf16 v[34:37], v[166:169], v[182:185], v[34:37]
	v_mfma_f32_16x16x32_bf16 v[30:33], v[174:177], v[182:185], v[30:33]
	v_mfma_f32_16x16x32_bf16 v[26:29], v[166:169], v[190:193], v[26:29]
	v_mfma_f32_16x16x32_bf16 v[22:25], v[174:177], v[190:193], v[22:25]
	v_mfma_f32_16x16x32_bf16 v[18:21], v[166:169], v[206:209], v[18:21]
	v_mfma_f32_16x16x32_bf16 v[14:17], v[174:177], v[206:209], v[14:17]
	v_mfma_f32_16x16x32_bf16 v[8:11], v[166:169], v[228:231], v[10:13]
	v_mfma_f32_16x16x32_bf16 v[4:7], v[174:177], v[228:231], v[4:7]
	v_mfma_f32_16x16x32_bf16 v[34:37], v[170:173], v[186:189], v[34:37]
	v_mfma_f32_16x16x32_bf16 v[30:33], v[178:181], v[186:189], v[30:33]
	v_mfma_f32_16x16x32_bf16 v[26:29], v[170:173], v[194:197], v[26:29]
	v_mfma_f32_16x16x32_bf16 v[22:25], v[178:181], v[194:197], v[22:25]
	v_mfma_f32_16x16x32_bf16 v[18:21], v[170:173], v[224:227], v[18:21]
	v_mfma_f32_16x16x32_bf16 v[14:17], v[178:181], v[224:227], v[14:17]
	v_mfma_f32_16x16x32_bf16 v[10:13], v[170:173], v[232:235], v[8:11]
	v_mfma_f32_16x16x32_bf16 v[6:9], v[178:181], v[232:235], v[4:7]
	s_setprio 0
	s_barrier
	s_add_u32 s26, s26, 0x100
	s_addc_u32 s27, s27, 0
	s_add_u32 s67, s67, 0x100
	s_addc_u32 s68, s68, 0
	s_cmp_ge_i32 s69, s54
	s_mov_b32 s46, s69
	s_cbranch_scc0 .LBB0_2023
	s_mov_b32 s72, 0x8000

; #define PG8_STAGE(bufoff, gbase, voff) do { _Pragma("unroll") for (int _i = 0; _i < 2; ++_i) \
;         __builtin_amdgcn_global_load_lds((const unsigned*)((const char*)(gbase) + (voff)[_i]), (LAS unsigned*)(lds + (bufoff) + ldsw + _i * 8192), 16, 0, 0); } while (0)
; #define PG8_LDA(dst, b, h) do { _Pragma("unroll") for (int m = 0; m < 4; ++m) _Pragma("unroll") for (int k = 0; k < 2; ++k) dst[m][k] = *(const LAS bf16x8*)(lds + PG8_SA(b, h) + aoff + m * 2048 + k * 1024); } while (0)
; #define PG8_LDB(dst, b, h) do { _Pragma("unroll") for (int n = 0; n < 2; ++n) _Pragma("unroll") for (int k = 0; k < 2; ++k) dst[n][k] = *(const LAS bf16x8*)(lds + PG8_SB(b, h) + boff + n * 2048 + k * 1024); } while (0)
; #define PG8_MMA(ai, bj, At, Bt) do { __builtin_amdgcn_s_setprio(1); _Pragma("unroll") for (int m = 0; m < 4; ++m) _Pragma("unroll") for (int n = 0; n < 2; ++n) _Pragma("unroll") for (int k = 0; k < 2; ++k) \
;         acc[ai][bj][m][n] = __builtin_amdgcn_mfma_f32_16x16x32_bf16(Bt[n][k], At[m][k], acc[ai][bj][m][n], 0, 0, 0); __builtin_amdgcn_s_setprio(0); } while (0)
; #define PG8_WAIT_V(n) asm volatile("s_waitcnt vmcnt(" #n ")" ::: "memory")
; template <class Epi, bool ALIGN_EPI = true>
; __device__ __forceinline__ void gemm_phase(LAS unsigned char* lds, const Gemm g, const Sched& S, const Epi& E) {
;     ...
;         for (int t = t_lo; t < t_hi; t += 2) {
;             const bool last = (t == nt - 2);
;             const char* a1 = cA + (size_t)(t + 1) * kstep;
;             const char* a2 = last ? nA : cA + (size_t)(t + 2) * kstep; const char* b2 = last ? nB : cB + (size_t)(t + 2) * kstep;
;             const char* a3 = a2 + kstep; const char* b3 = b2 + kstep;
;             const int rflag = __builtin_amdgcn_readfirstlane(t | (int)(ui == 0));
;             PG8_LDB(B0, 0, 0); PG8_LDB(B1, 0, 1); PG8_SCHED; PG8_LDA(At, 0, 0); PG8_STAGE(PG8_SA(1, 1), a1 + hstepA, voffA);
;             if constexpr (Epi::NSTORES > 0) PG8_WAIT_RELAX(rflag, 8 + Epi::NSTORES); else PG8_WAIT_V(8);
;             PG8_WAIT_L(0); PG8_BAR; PG8_MMA(0, 0, At, B0); PG8_MMA(0, 1, At, B1); PG8_BAR; PG8_SCHED;
;             PG8_LDA(At, 0, 1); PG8_STAGE(PG8_SB(0, 0), b2, voffB); PG8_STAGE(PG8_SB(0, 1), b2 + hstepB, voffB); PG8_STAGE(PG8_SA(0, 0), a2, voffA);
;             if constexpr (Epi::NSTORES > 0) PG8_WAIT_RELAX(rflag, 8 + Epi::NSTORES); else PG8_WAIT_V(8);
.LBB0_2287:
	s_add_i32 s69, s44, 2
	s_add_u32 s42, s48, 0x100
	s_addc_u32 s43, s49, 0
	s_add_i32 s70, 0, 0x10000
	s_cmp_eq_u32 s57, s44
	s_cselect_b32 s47, s63, s43
	s_cselect_b32 s46, s64, s42
	v_add_u32_e32 v2, s70, v147
	s_cselect_b32 s45, s65, s68
	s_cselect_b32 s44, s66, s67
	s_add_i32 s71, 0, 0x14000
	ds_read_b128 v[150:153], v2
	ds_read_b128 v[154:157], v2 offset:1024
	ds_read_b128 v[158:161], v2 offset:2048
	ds_read_b128 v[162:165], v2 offset:3072
	v_add_u32_e32 v2, s71, v147
	ds_read_b128 v[166:169], v2
	ds_read_b128 v[170:173], v2 offset:1024
	ds_read_b128 v[174:177], v2 offset:2048
	ds_read_b128 v[178:181], v2 offset:3072
	s_add_i32 m0, s50, 0xc000
	ds_read_b128 v[182:185], v148
	ds_read_b128 v[186:189], v148 offset:1024
	ds_read_b128 v[190:193], v148 offset:2048
	ds_read_b128 v[194:197], v148 offset:3072
	ds_read_b128 v[206:209], v148 offset:4096
	ds_read_b128 v[224:227], v148 offset:5120
	ds_read_b128 v[228:231], v148 offset:6144
	ds_read_b128 v[232:235], v148 offset:7168
	s_add_u32 s100, s48, 0xffea0000
	s_addc_u32 s101, s49, -1
	s_mov_b32 m0, s55
	s_nop 0
	global_load_lds_dwordx4 v142, s[100:101]
	s_mov_b32 m0, s56
	s_nop 0
	global_load_lds_dwordx4 v144, s[100:101]
	s_add_i32 m0, s50, 0xc000
	s_nop 0
	global_load_lds_dwordx4 v142, s[48:49]
	s_add_i32 m0, s50, 0xe000
	s_nop 0
	global_load_lds_dwordx4 v144, s[48:49]
	s_waitcnt vmcnt(8)
	s_waitcnt lgkmcnt(0)
	s_barrier
	s_setprio 1
	s_waitcnt lgkmcnt(0)
	v_mfma_f32_16x16x32_bf16 v[130:133], v[150:153], v[182:185], v[130:133]
	v_mfma_f32_16x16x32_bf16 v[126:129], v[158:161], v[182:185], v[126:129]
	v_mfma_f32_16x16x32_bf16 v[114:117], v[150:153], v[190:193], v[114:117]
	v_mfma_f32_16x16x32_bf16 v[110:113], v[158:161], v[190:193], v[110:113]
	v_mfma_f32_16x16x32_bf16 v[98:101], v[150:153], v[206:209], v[98:101]
	v_mfma_f32_16x16x32_bf16 v[94:97], v[158:161], v[206:209], v[94:97]
	v_mfma_f32_16x16x32_bf16 v[82:85], v[150:153], v[228:231], v[82:85]
	v_mfma_f32_16x16x32_bf16 v[78:81], v[158:161], v[228:231], v[78:81]
	v_mfma_f32_16x16x32_bf16 v[130:133], v[154:157], v[186:189], v[130:133]
	v_mfma_f32_16x16x32_bf16 v[126:129], v[162:165], v[186:189], v[126:129]
	v_mfma_f32_16x16x32_bf16 v[114:117], v[154:157], v[194:197], v[114:117]
	v_mfma_f32_16x16x32_bf16 v[110:113], v[162:165], v[194:197], v[110:113]
	v_mfma_f32_16x16x32_bf16 v[98:101], v[154:157], v[224:227], v[98:101]
	v_mfma_f32_16x16x32_bf16 v[94:97], v[162:165], v[224:227], v[94:97]
	v_mfma_f32_16x16x32_bf16 v[82:85], v[154:157], v[232:235], v[82:85]
	v_mfma_f32_16x16x32_bf16 v[78:81], v[162:165], v[232:235], v[78:81]
	s_setprio 0
	s_setprio 1
	v_mfma_f32_16x16x32_bf16 v[122:125], v[166:169], v[182:185], v[122:125]
	v_mfma_f32_16x16x32_bf16 v[118:121], v[174:177], v[182:185], v[118:121]
	v_mfma_f32_16x16x32_bf16 v[106:109], v[166:169], v[190:193], v[106:109]
	v_mfma_f32_16x16x32_bf16 v[102:105], v[174:177], v[190:193], v[102:105]
	v_mfma_f32_16x16x32_bf16 v[90:93], v[166:169], v[206:209], v[90:93]
	v_mfma_f32_16x16x32_bf16 v[86:89], v[174:177], v[206:209], v[86:89]
	v_mfma_f32_16x16x32_bf16 v[74:77], v[166:169], v[228:231], v[74:77]
	v_mfma_f32_16x16x32_bf16 v[70:73], v[174:177], v[228:231], v[70:73]
	v_mfma_f32_16x16x32_bf16 v[122:125], v[170:173], v[186:189], v[122:125]
	v_mfma_f32_16x16x32_bf16 v[118:121], v[178:181], v[186:189], v[118:121]
	v_mfma_f32_16x16x32_bf16 v[106:109], v[170:173], v[194:197], v[106:109]
	v_mfma_f32_16x16x32_bf16 v[102:105], v[178:181], v[194:197], v[102:105]
	v_mfma_f32_16x16x32_bf16 v[90:93], v[170:173], v[224:227], v[90:93]
	v_mfma_f32_16x16x32_bf16 v[86:89], v[178:181], v[224:227], v[86:89]
	v_mfma_f32_16x16x32_bf16 v[74:77], v[170:173], v[232:235], v[74:77]
	v_mfma_f32_16x16x32_bf16 v[70:73], v[178:181], v[232:235], v[70:73]
	s_setprio 0
	s_barrier
	s_add_i32 s48, s70, s37
	s_mov_b32 m0, s48
	ds_read_b128 v[182:185], v148 offset:16384
	ds_read_b128 v[186:189], v148 offset:17408
	ds_read_b128 v[190:193], v148 offset:18432
	ds_read_b128 v[194:197], v148 offset:19456
	ds_read_b128 v[206:209], v148 offset:20480
	ds_read_b128 v[224:227], v148 offset:21504
	ds_read_b128 v[228:231], v148 offset:22528
	ds_read_b128 v[232:235], v148 offset:23552
	global_load_lds_dwordx4 v138, s[44:45]
	s_add_i32 m0, s48, 0x2000
	s_add_u32 s48, s44, 0x160000
	s_addc_u32 s49, s45, 0
	s_add_i32 s70, s71, s37
	global_load_lds_dwordx4 v134, s[44:45]
	s_mov_b32 m0, s70
	s_nop 0
	global_load_lds_dwordx4 v138, s[48:49]
	s_add_i32 m0, s70, 0x2000
	s_nop 0
	global_load_lds_dwordx4 v134, s[48:49]
	s_waitcnt vmcnt(6)
	s_waitcnt lgkmcnt(0)
	s_barrier
; #define PG8_STAGE(bufoff, gbase, voff) do { _Pragma("unroll") for (int _i = 0; _i < 2; ++_i) \
;         __builtin_amdgcn_global_load_lds((const unsigned*)((const char*)(gbase) + (voff)[_i]), (LAS unsigned*)(lds + (bufoff) + ldsw + _i * 8192), 16, 0, 0); } while (0)
; #define PG8_LDA(dst, b, h) do { _Pragma("unroll") for (int m = 0; m < 4; ++m) _Pragma("unroll") for (int k = 0; k < 2; ++k) dst[m][k] = *(const LAS bf16x8*)(lds + PG8_SA(b, h) + aoff + m * 2048 + k * 1024); } while (0)
; #define PG8_LDB(dst, b, h) do { _Pragma("unroll") for (int n = 0; n < 2; ++n) _Pragma("unroll") for (int k = 0; k < 2; ++k) dst[n][k] = *(const LAS bf16x8*)(lds + PG8_SB(b, h) + boff + n * 2048 + k * 1024); } while (0)
; #define PG8_MMA(ai, bj, At, Bt) do { __builtin_amdgcn_s_setprio(1); _Pragma("unroll") for (int m = 0; m < 4; ++m) _Pragma("unroll") for (int n = 0; n < 2; ++n) _Pragma("unroll") for (int k = 0; k < 2; ++k) \
;         acc[ai][bj][m][n] = __builtin_amdgcn_mfma_f32_16x16x32_bf16(Bt[n][k], At[m][k], acc[ai][bj][m][n], 0, 0, 0); __builtin_amdgcn_s_setprio(0); } while (0)
; #define PG8_WAIT_V(n) asm volatile("s_waitcnt vmcnt(" #n ")" ::: "memory")
; #define PG8_WAIT_L(n) asm volatile("s_waitcnt lgkmcnt(" #n ")" ::: "memory")
; #define PG8_BAR __builtin_amdgcn_s_barrier()
; #define PG8_SCHED __builtin_amdgcn_sched_barrier(0)
; template <class Epi, bool ALIGN_EPI = true>
; __device__ __forceinline__ void gemm_phase(LAS unsigned char* lds, const Gemm g, const Sched& S, const Epi& E) {
;     ...
;             PG8_WAIT_L(0); PG8_BAR; PG8_MMA(1, 0, At, B0); PG8_MMA(1, 1, At, B1); PG8_BAR; PG8_SCHED;
;             PG8_LDB(B0, 1, 0); PG8_LDB(B1, 1, 1); PG8_SCHED; PG8_LDA(At, 1, 0); PG8_STAGE(PG8_SA(0, 1), a2 + hstepA, voffA);
;             PG8_WAIT_V(8); PG8_WAIT_L(0); PG8_BAR; PG8_MMA(0, 0, At, B0); PG8_MMA(0, 1, At, B1); PG8_BAR; PG8_SCHED;
	s_setprio 1
	s_waitcnt lgkmcnt(0)
	v_mfma_f32_16x16x32_bf16 v[66:69], v[150:153], v[182:185], v[66:69]
	v_mfma_f32_16x16x32_bf16 v[62:65], v[158:161], v[182:185], v[62:65]
	v_mfma_f32_16x16x32_bf16 v[50:53], v[150:153], v[190:193], v[50:53]
	v_mfma_f32_16x16x32_bf16 v[46:49], v[158:161], v[190:193], v[46:49]
	v_mfma_f32_16x16x32_bf16 v[34:37], v[150:153], v[206:209], v[34:37]
	v_mfma_f32_16x16x32_bf16 v[30:33], v[158:161], v[206:209], v[30:33]
	v_mfma_f32_16x16x32_bf16 v[18:21], v[150:153], v[228:231], v[18:21]
	v_mfma_f32_16x16x32_bf16 v[14:17], v[158:161], v[228:231], v[14:17]
	v_mfma_f32_16x16x32_bf16 v[66:69], v[154:157], v[186:189], v[66:69]
	v_mfma_f32_16x16x32_bf16 v[62:65], v[162:165], v[186:189], v[62:65]
	v_mfma_f32_16x16x32_bf16 v[50:53], v[154:157], v[194:197], v[50:53]
	v_mfma_f32_16x16x32_bf16 v[46:49], v[162:165], v[194:197], v[46:49]
	v_mfma_f32_16x16x32_bf16 v[34:37], v[154:157], v[224:227], v[34:37]
	v_mfma_f32_16x16x32_bf16 v[30:33], v[162:165], v[224:227], v[30:33]
	v_mfma_f32_16x16x32_bf16 v[18:21], v[154:157], v[232:235], v[18:21]
	v_mfma_f32_16x16x32_bf16 v[14:17], v[162:165], v[232:235], v[14:17]
	s_setprio 0
	s_setprio 1
	v_mfma_f32_16x16x32_bf16 v[58:61], v[166:169], v[182:185], v[58:61]
	v_mfma_f32_16x16x32_bf16 v[54:57], v[174:177], v[182:185], v[54:57]
	v_mfma_f32_16x16x32_bf16 v[42:45], v[166:169], v[190:193], v[42:45]
	v_mfma_f32_16x16x32_bf16 v[38:41], v[174:177], v[190:193], v[38:41]
	v_mfma_f32_16x16x32_bf16 v[26:29], v[166:169], v[206:209], v[26:29]
	v_mfma_f32_16x16x32_bf16 v[22:25], v[174:177], v[206:209], v[22:25]
	v_mfma_f32_16x16x32_bf16 v[10:13], v[166:169], v[228:231], v[10:13]
	v_mfma_f32_16x16x32_bf16 v[4:7], v[174:177], v[228:231], v[6:9]
	v_mfma_f32_16x16x32_bf16 v[58:61], v[170:173], v[186:189], v[58:61]
	v_mfma_f32_16x16x32_bf16 v[54:57], v[178:181], v[186:189], v[54:57]
	v_mfma_f32_16x16x32_bf16 v[42:45], v[170:173], v[194:197], v[42:45]
	v_mfma_f32_16x16x32_bf16 v[38:41], v[178:181], v[194:197], v[38:41]
	v_mfma_f32_16x16x32_bf16 v[26:29], v[170:173], v[224:227], v[26:29]
	v_mfma_f32_16x16x32_bf16 v[22:25], v[178:181], v[224:227], v[22:25]
	v_mfma_f32_16x16x32_bf16 v[10:13], v[170:173], v[232:235], v[10:13]
	v_mfma_f32_16x16x32_bf16 v[4:7], v[178:181], v[232:235], v[4:7]
	s_setprio 0
	s_barrier
	s_add_i32 s48, 0, 0x18000
	v_add_u32_e32 v2, s48, v147
	s_add_i32 s49, 0, 0x1c000
	ds_read_b128 v[150:153], v2
	ds_read_b128 v[154:157], v2 offset:1024
	ds_read_b128 v[158:161], v2 offset:2048
	ds_read_b128 v[162:165], v2 offset:3072
	v_add_u32_e32 v2, s49, v147
	ds_read_b128 v[166:169], v2
	ds_read_b128 v[170:173], v2 offset:1024
	ds_read_b128 v[174:177], v2 offset:2048
	ds_read_b128 v[178:181], v2 offset:3072
	s_add_u32 s46, s46, 0x160000
	s_addc_u32 s47, s47, 0
	s_mov_b32 m0, s52
	ds_read_b128 v[182:185], v148 offset:32768
	ds_read_b128 v[186:189], v148 offset:33792
	ds_read_b128 v[190:193], v148 offset:34816
	ds_read_b128 v[194:197], v148 offset:35840
	ds_read_b128 v[206:209], v148 offset:36864
	ds_read_b128 v[224:227], v148 offset:37888
	ds_read_b128 v[228:231], v148 offset:38912
	ds_read_b128 v[232:235], v148 offset:39936
	s_add_u32 s100, s46, 0xffea0000
	s_addc_u32 s101, s47, -1
	s_mov_b32 m0, s50
	s_nop 0
	global_load_lds_dwordx4 v140, s[100:101]
	s_mov_b32 m0, s51
	s_nop 0
	global_load_lds_dwordx4 v136, s[100:101]
	s_mov_b32 m0, s52
	s_nop 0
	global_load_lds_dwordx4 v140, s[46:47]
	s_mov_b32 m0, s53
	s_nop 0
	global_load_lds_dwordx4 v136, s[46:47]
	s_waitcnt vmcnt(8)
	s_waitcnt lgkmcnt(0)
	s_barrier
; #define PG8_STAGE(bufoff, gbase, voff) do { _Pragma("unroll") for (int _i = 0; _i < 2; ++_i) \
;         __builtin_amdgcn_global_load_lds((const unsigned*)((const char*)(gbase) + (voff)[_i]), (LAS unsigned*)(lds + (bufoff) + ldsw + _i * 8192), 16, 0, 0); } while (0)
; #define PG8_LDA(dst, b, h) do { _Pragma("unroll") for (int m = 0; m < 4; ++m) _Pragma("unroll") for (int k = 0; k < 2; ++k) dst[m][k] = *(const LAS bf16x8*)(lds + PG8_SA(b, h) + aoff + m * 2048 + k * 1024); } while (0)
; #define PG8_MMA(ai, bj, At, Bt) do { __builtin_amdgcn_s_setprio(1); _Pragma("unroll") for (int m = 0; m < 4; ++m) _Pragma("unroll") for (int n = 0; n < 2; ++n) _Pragma("unroll") for (int k = 0; k < 2; ++k) \
;         acc[ai][bj][m][n] = __builtin_amdgcn_mfma_f32_16x16x32_bf16(Bt[n][k], At[m][k], acc[ai][bj][m][n], 0, 0, 0); __builtin_amdgcn_s_setprio(0); } while (0)
; #define PG8_WAIT_V(n) asm volatile("s_waitcnt vmcnt(" #n ")" ::: "memory")
; #define PG8_WAIT_L(n) asm volatile("s_waitcnt lgkmcnt(" #n ")" ::: "memory")
; #define PG8_BAR __builtin_amdgcn_s_barrier()
; #define PG8_SCHED __builtin_amdgcn_sched_barrier(0)
; template <class Epi, bool ALIGN_EPI = true>
; __device__ __forceinline__ void gemm_phase(LAS unsigned char* lds, const Gemm g, const Sched& S, const Epi& E) {
;     ...
;             PG8_WAIT_V(8); PG8_WAIT_L(0); PG8_BAR; PG8_MMA(0, 0, At, B0); PG8_MMA(0, 1, At, B1); PG8_BAR; PG8_SCHED;
;             PG8_LDA(At, 1, 1); PG8_STAGE(PG8_SB(1, 0), b3, voffB); PG8_STAGE(PG8_SB(1, 1), b3 + hstepB, voffB); PG8_STAGE(PG8_SA(1, 0), a3, voffA);
;             PG8_WAIT_V(8); PG8_WAIT_L(0); PG8_BAR; PG8_MMA(1, 0, At, B0); PG8_MMA(1, 1, At, B1); PG8_BAR; PG8_SCHED;
;         }
	s_setprio 1
	s_waitcnt lgkmcnt(0)
	v_mfma_f32_16x16x32_bf16 v[130:133], v[150:153], v[182:185], v[130:133]
	v_mfma_f32_16x16x32_bf16 v[126:129], v[158:161], v[182:185], v[126:129]
	v_mfma_f32_16x16x32_bf16 v[114:117], v[150:153], v[190:193], v[114:117]
	v_mfma_f32_16x16x32_bf16 v[110:113], v[158:161], v[190:193], v[110:113]
	v_mfma_f32_16x16x32_bf16 v[98:101], v[150:153], v[206:209], v[98:101]
	v_mfma_f32_16x16x32_bf16 v[94:97], v[158:161], v[206:209], v[94:97]
	v_mfma_f32_16x16x32_bf16 v[82:85], v[150:153], v[228:231], v[82:85]
	v_mfma_f32_16x16x32_bf16 v[78:81], v[158:161], v[228:231], v[78:81]
	v_mfma_f32_16x16x32_bf16 v[130:133], v[154:157], v[186:189], v[130:133]
	v_mfma_f32_16x16x32_bf16 v[126:129], v[162:165], v[186:189], v[126:129]
	v_mfma_f32_16x16x32_bf16 v[114:117], v[154:157], v[194:197], v[114:117]
	v_mfma_f32_16x16x32_bf16 v[110:113], v[162:165], v[194:197], v[110:113]
	v_mfma_f32_16x16x32_bf16 v[98:101], v[154:157], v[224:227], v[98:101]
	v_mfma_f32_16x16x32_bf16 v[94:97], v[162:165], v[224:227], v[94:97]
	v_mfma_f32_16x16x32_bf16 v[82:85], v[154:157], v[232:235], v[82:85]
	v_mfma_f32_16x16x32_bf16 v[78:81], v[162:165], v[232:235], v[78:81]
	s_setprio 0
	s_setprio 1
	v_mfma_f32_16x16x32_bf16 v[122:125], v[166:169], v[182:185], v[122:125]
	v_mfma_f32_16x16x32_bf16 v[118:121], v[174:177], v[182:185], v[118:121]
	v_mfma_f32_16x16x32_bf16 v[106:109], v[166:169], v[190:193], v[106:109]
	v_mfma_f32_16x16x32_bf16 v[102:105], v[174:177], v[190:193], v[102:105]
	v_mfma_f32_16x16x32_bf16 v[90:93], v[166:169], v[206:209], v[90:93]
	v_mfma_f32_16x16x32_bf16 v[86:89], v[174:177], v[206:209], v[86:89]
	v_mfma_f32_16x16x32_bf16 v[74:77], v[166:169], v[228:231], v[74:77]
	v_mfma_f32_16x16x32_bf16 v[70:73], v[174:177], v[228:231], v[70:73]
	v_mfma_f32_16x16x32_bf16 v[122:125], v[170:173], v[186:189], v[122:125]
	v_mfma_f32_16x16x32_bf16 v[118:121], v[178:181], v[186:189], v[118:121]
	v_mfma_f32_16x16x32_bf16 v[106:109], v[170:173], v[194:197], v[106:109]
	v_mfma_f32_16x16x32_bf16 v[102:105], v[178:181], v[194:197], v[102:105]
	v_mfma_f32_16x16x32_bf16 v[90:93], v[170:173], v[224:227], v[90:93]
	v_mfma_f32_16x16x32_bf16 v[86:89], v[178:181], v[224:227], v[86:89]
	v_mfma_f32_16x16x32_bf16 v[74:77], v[170:173], v[232:235], v[74:77]
	v_mfma_f32_16x16x32_bf16 v[70:73], v[178:181], v[232:235], v[70:73]
	s_setprio 0
	s_barrier
	s_add_u32 s100, s44, 0x80
	s_addc_u32 s101, s45, 0
	s_add_i32 s46, s48, s37
	s_mov_b32 m0, s46
	ds_read_b128 v[182:185], v148 offset:49152
	ds_read_b128 v[186:189], v148 offset:50176
	ds_read_b128 v[190:193], v148 offset:51200
	ds_read_b128 v[194:197], v148 offset:52224
	ds_read_b128 v[206:209], v148 offset:53248
	ds_read_b128 v[224:227], v148 offset:54272
	ds_read_b128 v[228:231], v148 offset:55296
	ds_read_b128 v[232:235], v148 offset:56320
	global_load_lds_dwordx4 v138, s[100:101]
	s_add_i32 m0, s46, 0x2000
	s_add_u32 s44, s44, 0x160080
	s_addc_u32 s45, s45, 0
	s_add_i32 s46, s49, s37
	global_load_lds_dwordx4 v134, s[100:101]
	s_mov_b32 m0, s46
	s_nop 0
	global_load_lds_dwordx4 v138, s[44:45]
	s_add_i32 m0, s46, 0x2000
	s_nop 0
	global_load_lds_dwordx4 v134, s[44:45]
	s_waitcnt vmcnt(6)
	s_waitcnt lgkmcnt(0)
	s_barrier
	s_setprio 1
	s_waitcnt lgkmcnt(0)
	v_mfma_f32_16x16x32_bf16 v[66:69], v[150:153], v[182:185], v[66:69]
	v_mfma_f32_16x16x32_bf16 v[62:65], v[158:161], v[182:185], v[62:65]
	v_mfma_f32_16x16x32_bf16 v[50:53], v[150:153], v[190:193], v[50:53]
	v_mfma_f32_16x16x32_bf16 v[46:49], v[158:161], v[190:193], v[46:49]
	v_mfma_f32_16x16x32_bf16 v[34:37], v[150:153], v[206:209], v[34:37]
	v_mfma_f32_16x16x32_bf16 v[30:33], v[158:161], v[206:209], v[30:33]
	v_mfma_f32_16x16x32_bf16 v[18:21], v[150:153], v[228:231], v[18:21]
	v_mfma_f32_16x16x32_bf16 v[14:17], v[158:161], v[228:231], v[14:17]
	v_mfma_f32_16x16x32_bf16 v[66:69], v[154:157], v[186:189], v[66:69]
	v_mfma_f32_16x16x32_bf16 v[62:65], v[162:165], v[186:189], v[62:65]
	v_mfma_f32_16x16x32_bf16 v[50:53], v[154:157], v[194:197], v[50:53]
	v_mfma_f32_16x16x32_bf16 v[46:49], v[162:165], v[194:197], v[46:49]
	v_mfma_f32_16x16x32_bf16 v[34:37], v[154:157], v[224:227], v[34:37]
	v_mfma_f32_16x16x32_bf16 v[30:33], v[162:165], v[224:227], v[30:33]
	v_mfma_f32_16x16x32_bf16 v[18:21], v[154:157], v[232:235], v[18:21]
	v_mfma_f32_16x16x32_bf16 v[14:17], v[162:165], v[232:235], v[14:17]
	s_setprio 0
	s_setprio 1
	v_mfma_f32_16x16x32_bf16 v[58:61], v[166:169], v[182:185], v[58:61]
	v_mfma_f32_16x16x32_bf16 v[54:57], v[174:177], v[182:185], v[54:57]
	v_mfma_f32_16x16x32_bf16 v[42:45], v[166:169], v[190:193], v[42:45]
	v_mfma_f32_16x16x32_bf16 v[38:41], v[174:177], v[190:193], v[38:41]
	v_mfma_f32_16x16x32_bf16 v[26:29], v[166:169], v[206:209], v[26:29]
	v_mfma_f32_16x16x32_bf16 v[22:25], v[174:177], v[206:209], v[22:25]
	v_mfma_f32_16x16x32_bf16 v[8:11], v[166:169], v[228:231], v[10:13]
	v_mfma_f32_16x16x32_bf16 v[4:7], v[174:177], v[228:231], v[4:7]
	v_mfma_f32_16x16x32_bf16 v[58:61], v[170:173], v[186:189], v[58:61]
	v_mfma_f32_16x16x32_bf16 v[54:57], v[178:181], v[186:189], v[54:57]
	v_mfma_f32_16x16x32_bf16 v[42:45], v[170:173], v[194:197], v[42:45]
	v_mfma_f32_16x16x32_bf16 v[38:41], v[178:181], v[194:197], v[38:41]
	v_mfma_f32_16x16x32_bf16 v[26:29], v[170:173], v[224:227], v[26:29]
	v_mfma_f32_16x16x32_bf16 v[22:25], v[178:181], v[224:227], v[22:25]
	v_mfma_f32_16x16x32_bf16 v[10:13], v[170:173], v[232:235], v[8:11]
	v_mfma_f32_16x16x32_bf16 v[6:9], v[178:181], v[232:235], v[4:7]
	s_setprio 0
	s_barrier
	s_add_u32 s67, s67, 0x100
	s_addc_u32 s68, s68, 0
	s_cmp_ge_i32 s69, s54
	s_mov_b64 s[48:49], s[42:43]
	s_mov_b32 s44, s69
	s_cbranch_scc0 .LBB0_2287

; __global__ void __launch_bounds__(NWAVES * 64, 2) mk_fwd(Args args) {
	.amdhsa_kernel _Z6mk_fwd4Args
		.amdhsa_group_segment_fixed_size 0
		.amdhsa_private_segment_fixed_size 0
		.amdhsa_kernarg_size 440
		.amdhsa_user_sgpr_count 2
		.amdhsa_user_sgpr_dispatch_ptr 0
		.amdhsa_user_sgpr_queue_ptr 0
		.amdhsa_user_sgpr_kernarg_segment_ptr 1
		.amdhsa_user_sgpr_dispatch_id 0
		.amdhsa_user_sgpr_kernarg_preload_length 0
		.amdhsa_user_sgpr_kernarg_preload_offset 0
		.amdhsa_user_sgpr_private_segment_size 0
		.amdhsa_uses_dynamic_stack 0
		.amdhsa_enable_private_segment 0
		.amdhsa_system_sgpr_workgroup_id_x 1
		.amdhsa_system_sgpr_workgroup_id_y 0
		.amdhsa_system_sgpr_workgroup_id_z 0
		.amdhsa_system_sgpr_workgroup_info 0
		.amdhsa_system_vgpr_workitem_id 0
		.amdhsa_next_free_vgpr 247
		.amdhsa_next_free_sgpr 102
		.amdhsa_accum_offset 248
		.amdhsa_reserve_vcc 1
		.amdhsa_float_round_mode_32 0
		.amdhsa_float_round_mode_16_64 0
		.amdhsa_float_denorm_mode_32 3
		.amdhsa_float_denorm_mode_16_64 3
		.amdhsa_dx10_clamp 1
		.amdhsa_ieee_mode 1
		.amdhsa_fp16_overflow 0
		.amdhsa_tg_split 0
		.amdhsa_exception_fp_ieee_invalid_op 0
		.amdhsa_exception_fp_denorm_src 0
		.amdhsa_exception_fp_ieee_div_zero 0
		.amdhsa_exception_fp_ieee_overflow 0
		.amdhsa_exception_fp_ieee_underflow 0
		.amdhsa_exception_fp_ieee_inexact 0
		.amdhsa_exception_int_div_zero 0
	.end_amdhsa_kernel

; __global__ void __launch_bounds__(NWAVES * 64, 2) mk_fwd(Args args) {
amdhsa.kernels:
  - .agpr_count:     0
    .args:
      - .offset:         0
        .size:           184
        .value_kind:     by_value
      - .offset:         184
        .size:           4
        .value_kind:     hidden_block_count_x
      - .offset:         188
        .size:           4
        .value_kind:     hidden_block_count_y
      - .offset:         192
        .size:           4
        .value_kind:     hidden_block_count_z
      - .offset:         196
        .size:           2
        .value_kind:     hidden_group_size_x
      - .offset:         198
        .size:           2
        .value_kind:     hidden_group_size_y
      - .offset:         200
        .size:           2
        .value_kind:     hidden_group_size_z
      - .offset:         202
        .size:           2
        .value_kind:     hidden_remainder_x
      - .offset:         204
        .size:           2
        .value_kind:     hidden_remainder_y
      - .offset:         206
        .size:           2
        .value_kind:     hidden_remainder_z
      - .offset:         224
        .size:           8
        .value_kind:     hidden_global_offset_x
      - .offset:         232
        .size:           8
        .value_kind:     hidden_global_offset_y
      - .offset:         240
        .size:           8
        .value_kind:     hidden_global_offset_z
      - .offset:         248
        .size:           2
        .value_kind:     hidden_grid_dims
      - .offset:         304
        .size:           4
        .value_kind:     hidden_dynamic_lds_size
    .group_segment_fixed_size: 0
    .kernarg_segment_align: 8
    .kernarg_segment_size: 440
    .language:       OpenCL C
    .language_version:
      - 2
      - 0
    .max_flat_workgroup_size: 512
    .name:           _Z6mk_fwd4Args
    .private_segment_fixed_size: 0
    .sgpr_count:     108
    .sgpr_spill_count: 351
    .symbol:         _Z6mk_fwd4Args.kd
    .uniform_work_group_size: 1
    .uses_dynamic_stack: false
    .vgpr_count:     247
    .vgpr_spill_count: 0
    .wavefront_size: 64
